# static s_setprio 1 for waves 4-7 during big GEMM instances
# baseline (speedup 1.0000x reference)
.LBB0_463:
	s_or_b64 exec, exec, s[14:15]
	s_mov_b64 s[6:7], s[60:61]
	s_waitcnt lgkmcnt(0)
	s_barrier
	s_load_dwordx2 s[16:17], s[6:7], 0x130
	v_mov_b32_e32 v2, v172
	s_mov_b32 s11, s42
	s_mov_b32 s20, s94
	s_waitcnt lgkmcnt(0)
	s_add_u32 s14, s16, 0x6035800
	s_addc_u32 s15, s17, 0
	s_add_u32 s18, s16, 0x3200000
	s_addc_u32 s19, s17, 0
	s_cmpk_lt_i32 s20, 0x600
	s_cbranch_scc0 .LBB0_468
	v_ashrrev_i32_e32 v204, 3, v2
	v_bfe_u32 v3, v2, 4, 2
	v_and_b32_e32 v4, 15, v2
	v_lshlrev_b32_e32 v0, 4, v2
	v_ashrrev_i32_e32 v5, 1, v2
	s_movk_i32 s2, 0xffc0
	v_lshlrev_b32_e32 v2, 1, v2
	v_and_b32_e32 v0, 0x70, v0
	v_and_or_b32 v205, v5, s2, v4
	v_and_b32_e32 v207, 0x80, v2
	s_movk_i32 s2, 0x90
	v_or_b32_e32 v2, v207, v4
	v_and_b32_e32 v100, 7, v204
	v_lshlrev_b32_e32 v100, 4, v100
	v_xor_b32_e32 v100, v100, v0
	v_lshl_add_u32 v166, v204, 7, v100
	v_lshl_add_u64 v[162:163], s[18:19], 0, v[0:1]
	v_lshl_add_u64 v[164:165], s[16:17], 0, v[0:1]
	v_and_b32_e32 v100, 7, v4
	v_xor_b32_e32 v100, v100, v3
	v_lshlrev_b32_e32 v206, 4, v100
	v_lshlrev_b32_e32 v208, 2, v3
	v_lshlrev_b32_e32 v0, 7, v205
	v_lshlrev_b32_e32 v167, 7, v2
	v_readfirstlane_b32 s100, v172
	s_nop 0
	s_cmpk_ge_u32 s100, 0x100
	s_cbranch_scc0 .Lprio_skip_P2
	s_setprio 1
.Lprio_skip_P2:
.LBB0_465:
	s_mul_hi_i32 s4, s20, 0x38e38e39
	s_lshr_b32 s6, s4, 31
	s_ashr_i32 s4, s4, 4
	s_add_i32 s4, s4, s6
	s_mul_i32 s6, s4, 0x48
	s_sub_i32 s6, s20, s6
	s_lshl_b32 s6, s6, 8
	v_add_u32_e32 v2, s6, v204
	v_ashrrev_i32_e32 v3, 31, v2
	v_lshlrev_b64 v[2:3], 11, v[2:3]
	v_lshl_add_u64 v[168:169], v[162:163], 0, v[2:3]
	v_add_co_u32_e32 v56, vcc, s34, v168
	s_lshl_b32 s7, s4, 8
	s_nop 0
	v_addc_co_u32_e32 v57, vcc, 0, v169, vcc
	v_add_u32_e32 v2, s7, v204
	s_waitcnt vmcnt(9)
	v_add_co_u32_e32 v58, vcc, s35, v168
	v_ashrrev_i32_e32 v3, 31, v2
	s_nop 0
	v_addc_co_u32_e32 v59, vcc, 0, v169, vcc
	v_lshlrev_b64 v[2:3], 11, v[2:3]
	v_add_co_u32_e32 v60, vcc, s36, v168
	v_lshl_add_u64 v[170:171], v[164:165], 0, v[2:3]
	s_nop 0
	v_addc_co_u32_e32 v61, vcc, 0, v169, vcc
	s_waitcnt vmcnt(8)
	v_add_co_u32_e32 v62, vcc, s35, v170
	global_load_dwordx4 v[24:27], v[56:57], off
	global_load_dwordx4 v[28:31], v[58:59], off
	v_addc_co_u32_e32 v63, vcc, 0, v171, vcc
	v_add_co_u32_e32 v64, vcc, s36, v170
	global_load_dwordx4 v[32:35], v[168:169], off
	global_load_dwordx4 v[36:39], v[170:171], off
	v_addc_co_u32_e32 v65, vcc, 0, v171, vcc
	v_add_co_u32_e32 v66, vcc, s34, v170
	global_load_dwordx4 v[40:43], v[62:63], off
	global_load_dwordx4 v[44:47], v[64:65], off
	v_addc_co_u32_e32 v67, vcc, 0, v171, vcc
	global_load_dwordx4 v[48:51], v[60:61], off
	global_load_dwordx4 v[52:55], v[66:67], off
	s_barrier
	global_load_dwordx4 v[114:117], v[168:169], off offset:128
	global_load_dwordx4 v[106:109], v[56:57], off offset:128
	global_load_dwordx4 v[110:113], v[58:59], off offset:128
	global_load_dwordx4 v[126:129], v[60:61], off offset:128
	global_load_dwordx4 v[122:125], v[170:171], off offset:128
	global_load_dwordx4 v[118:121], v[66:67], off offset:128
	global_load_dwordx4 v[134:137], v[62:63], off offset:128
	global_load_dwordx4 v[130:133], v[64:65], off offset:128
	v_readfirstlane_b32 vcc_lo, v168
	v_readfirstlane_b32 vcc_hi, v169
	v_readfirstlane_b32 s100, v170
	v_readfirstlane_b32 s101, v171
	s_nop 1
	v_subrev_u32_e32 v168, vcc_lo, v168
	v_subrev_u32_e32 v170, s100, v170
	v_mov_b32_e32 v2, 0
	s_mov_b32 s4, 0
	v_mov_b32_e32 v3, v2
	v_mov_b32_e32 v4, v2
	v_mov_b32_e32 v5, v2
	v_mov_b32_e32 v6, v2
	v_mov_b32_e32 v7, v2
	v_mov_b32_e32 v8, v2
	v_mov_b32_e32 v9, v2
	v_mov_b32_e32 v10, v2
	v_mov_b32_e32 v11, v2
	v_mov_b32_e32 v12, v2
	v_mov_b32_e32 v13, v2
	v_mov_b32_e32 v14, v2
	v_mov_b32_e32 v15, v2
	v_mov_b32_e32 v16, v2
	v_mov_b32_e32 v17, v2
	v_mov_b32_e32 v18, v2
	v_mov_b32_e32 v19, v2
	v_mov_b32_e32 v20, v2
	v_mov_b32_e32 v21, v2
	v_mov_b32_e32 v22, v2
	v_mov_b32_e32 v23, v2
	v_mov_b32_e32 v56, v2
	v_mov_b32_e32 v57, v2
	v_mov_b32_e32 v58, v2
	v_mov_b32_e32 v59, v2
	v_mov_b32_e32 v60, v2
	v_mov_b32_e32 v61, v2
	v_mov_b32_e32 v62, v2
	v_mov_b32_e32 v63, v2
	v_mov_b32_e32 v64, v2
	v_mov_b32_e32 v65, v2
	v_mov_b32_e32 v66, v2
	v_mov_b32_e32 v67, v2
	v_mov_b32_e32 v68, v2
	v_mov_b32_e32 v69, v2
	v_mov_b32_e32 v70, v2
	v_mov_b32_e32 v71, v2
	v_mov_b32_e32 v72, v2
	v_mov_b32_e32 v73, v2
	v_mov_b32_e32 v74, v2
	v_mov_b32_e32 v75, v2
	v_mov_b32_e32 v76, v2
	v_mov_b32_e32 v77, v2
	v_mov_b32_e32 v78, v2
	v_mov_b32_e32 v79, v2
	v_mov_b32_e32 v80, v2
	v_mov_b32_e32 v81, v2
	v_mov_b32_e32 v82, v2
	v_mov_b32_e32 v83, v2
	v_mov_b32_e32 v84, v2
	v_mov_b32_e32 v85, v2
	s_waitcnt vmcnt(11)
	ds_write_b128 v166, v[40:43] offset:49152
	s_waitcnt vmcnt(10)
	ds_write_b128 v166, v[44:47] offset:57344
	ds_write_b128 v166, v[32:35]
	ds_write_b128 v166, v[36:39] offset:32768
	ds_write_b128 v166, v[24:27] offset:8192
	ds_write_b128 v166, v[28:31] offset:16384
	s_waitcnt vmcnt(9)
	ds_write_b128 v166, v[48:51] offset:24576
	s_waitcnt vmcnt(8)
	ds_write_b128 v166, v[52:55] offset:40960
	v_mov_b32_e32 v24, v2
	v_mov_b32_e32 v25, v2
	v_mov_b32_e32 v26, v2
	v_mov_b32_e32 v27, v2
	v_mov_b32_e32 v28, v2
	v_mov_b32_e32 v29, v2
	v_mov_b32_e32 v30, v2
	v_mov_b32_e32 v31, v2
	v_mov_b32_e32 v32, v2
	v_mov_b32_e32 v33, v2
	v_mov_b32_e32 v34, v2
	v_mov_b32_e32 v35, v2
	v_mov_b32_e32 v36, v2
	v_mov_b32_e32 v37, v2
	v_mov_b32_e32 v38, v2
	v_mov_b32_e32 v39, v2
	v_mov_b32_e32 v40, v2
	v_mov_b32_e32 v41, v2
	v_mov_b32_e32 v42, v2
	v_mov_b32_e32 v43, v2
	v_mov_b32_e32 v44, v2
	v_mov_b32_e32 v45, v2
	v_mov_b32_e32 v46, v2
	v_mov_b32_e32 v47, v2
	v_mov_b32_e32 v48, v2
	v_mov_b32_e32 v49, v2
	v_mov_b32_e32 v50, v2
	v_mov_b32_e32 v51, v2
	v_mov_b32_e32 v52, v2
	v_mov_b32_e32 v53, v2
	v_mov_b32_e32 v54, v2
	v_mov_b32_e32 v55, v2
	v_mov_b32_e32 v86, v2
	v_mov_b32_e32 v87, v2
	v_mov_b32_e32 v88, v2
	v_mov_b32_e32 v89, v2
	v_mov_b32_e32 v90, v2
	v_mov_b32_e32 v91, v2
	v_mov_b32_e32 v92, v2
	v_mov_b32_e32 v93, v2
	v_mov_b32_e32 v94, v2
	v_mov_b32_e32 v95, v2
	v_mov_b32_e32 v96, v2
	v_mov_b32_e32 v97, v2
	v_mov_b32_e32 v98, v2
	v_mov_b32_e32 v99, v2
	v_mov_b32_e32 v100, v2
	v_mov_b32_e32 v101, v2
	v_mov_b32_e32 v102, v2
	v_mov_b32_e32 v103, v2
	v_mov_b32_e32 v104, v2
	v_mov_b32_e32 v105, v2
	v_mov_b32_e32 v138, v2
	v_mov_b32_e32 v139, v2
	v_mov_b32_e32 v140, v2
	v_mov_b32_e32 v141, v2
	v_mov_b32_e32 v142, v2
	v_mov_b32_e32 v143, v2
	v_mov_b32_e32 v144, v2
	v_mov_b32_e32 v145, v2
	v_mov_b32_e32 v146, v2
	v_mov_b32_e32 v147, v2
	v_mov_b32_e32 v148, v2
	v_mov_b32_e32 v149, v2
	v_mov_b32_e32 v150, v2
	v_mov_b32_e32 v151, v2
	v_mov_b32_e32 v152, v2
	v_mov_b32_e32 v153, v2
	v_mov_b32_e32 v154, v2
	v_mov_b32_e32 v155, v2
	v_mov_b32_e32 v156, v2
	v_mov_b32_e32 v157, v2
	v_mov_b32_e32 v158, v2
	v_mov_b32_e32 v159, v2
	v_mov_b32_e32 v160, v2
	v_mov_b32_e32 v161, v2
	s_waitcnt lgkmcnt(0)
	s_barrier
.LBB0_466:
	s_bitcmp1_b32 s4, 0
	s_cselect_b32 s21, 0x12000, 0
	v_or_b32_e32 v184, s21, v206
	v_add_u32_e32 v185, v184, v0
	v_add_u32_e32 v184, v184, v167
	ds_read_b128 v[210:213], v185
	ds_read_b128 v[214:217], v185 offset:2048
	ds_read_b128 v[218:221], v185 offset:4096
	ds_read_b128 v[222:225], v185 offset:6144
	ds_read_b128 v[226:229], v184 offset:32768
	ds_read_b128 v[230:233], v184 offset:34816
	ds_read_b128 v[234:237], v184 offset:36864
	ds_read_b128 v[238:241], v184 offset:38912
	ds_read_b128 v[242:245], v184 offset:40960
	ds_read_b128 v[246:249], v184 offset:43008
	ds_read_b128 v[198:201], v184 offset:45056
	ds_read_b128 v[184:187], v184 offset:47104
	s_add_i32 s10, s4, 1
	s_bitcmp1_b32 s10, 0
	s_cselect_b32 s23, 0x12000, 0
	v_add_u32_e32 v171, s23, v166
	v_xor_b32_e32 v169, 64, v206
	v_add3_u32 v169, s21, v167, v169
	s_waitcnt lgkmcnt(7)
	v_mfma_f32_16x16x32_bf16 v[158:161], v[226:229], v[210:213], v[158:161]
	v_mfma_f32_16x16x32_bf16 v[94:97], v[226:229], v[214:217], v[94:97]
	v_mfma_f32_16x16x32_bf16 v[62:65], v[226:229], v[218:221], v[62:65]
	v_mfma_f32_16x16x32_bf16 v[30:33], v[226:229], v[222:225], v[30:33]
	ds_read_b128 v[226:229], v169 offset:32768
	s_waitcnt lgkmcnt(7)
	v_mfma_f32_16x16x32_bf16 v[154:157], v[230:233], v[210:213], v[154:157]
	v_mfma_f32_16x16x32_bf16 v[90:93], v[230:233], v[214:217], v[90:93]
	v_mfma_f32_16x16x32_bf16 v[58:61], v[230:233], v[218:221], v[58:61]
	v_mfma_f32_16x16x32_bf16 v[26:29], v[230:233], v[222:225], v[26:29]
	ds_read_b128 v[230:233], v169 offset:34816
	s_waitcnt lgkmcnt(7)
	v_mfma_f32_16x16x32_bf16 v[150:153], v[234:237], v[210:213], v[150:153]
	v_mfma_f32_16x16x32_bf16 v[86:89], v[234:237], v[214:217], v[86:89]
	v_mfma_f32_16x16x32_bf16 v[54:57], v[234:237], v[218:221], v[54:57]
	v_mfma_f32_16x16x32_bf16 v[22:25], v[234:237], v[222:225], v[22:25]
	ds_read_b128 v[234:237], v169 offset:36864
	s_waitcnt lgkmcnt(7)
	v_mfma_f32_16x16x32_bf16 v[146:149], v[238:241], v[210:213], v[146:149]
	v_mfma_f32_16x16x32_bf16 v[82:85], v[238:241], v[214:217], v[82:85]
	v_mfma_f32_16x16x32_bf16 v[50:53], v[238:241], v[218:221], v[50:53]
	v_mfma_f32_16x16x32_bf16 v[18:21], v[238:241], v[222:225], v[18:21]
	ds_read_b128 v[238:241], v169 offset:38912
	s_waitcnt lgkmcnt(7)
	v_mfma_f32_16x16x32_bf16 v[142:145], v[242:245], v[210:213], v[142:145]
	v_mfma_f32_16x16x32_bf16 v[78:81], v[242:245], v[214:217], v[78:81]
	v_mfma_f32_16x16x32_bf16 v[46:49], v[242:245], v[218:221], v[46:49]
	v_mfma_f32_16x16x32_bf16 v[14:17], v[242:245], v[222:225], v[14:17]
	ds_read_b128 v[242:245], v169 offset:40960
	s_waitcnt lgkmcnt(7)
	v_mfma_f32_16x16x32_bf16 v[138:141], v[246:249], v[210:213], v[138:141]
	v_mfma_f32_16x16x32_bf16 v[74:77], v[246:249], v[214:217], v[74:77]
	v_mfma_f32_16x16x32_bf16 v[42:45], v[246:249], v[218:221], v[42:45]
	v_mfma_f32_16x16x32_bf16 v[10:13], v[246:249], v[222:225], v[10:13]
	ds_read_b128 v[246:249], v169 offset:43008
	s_waitcnt lgkmcnt(7)
	v_mfma_f32_16x16x32_bf16 v[102:105], v[198:201], v[210:213], v[102:105]
	v_mfma_f32_16x16x32_bf16 v[70:73], v[198:201], v[214:217], v[70:73]
	v_mfma_f32_16x16x32_bf16 v[38:41], v[198:201], v[218:221], v[38:41]
	v_mfma_f32_16x16x32_bf16 v[6:9], v[198:201], v[222:225], v[6:9]
	ds_read_b128 v[198:201], v169 offset:45056
	s_waitcnt lgkmcnt(7)
	v_mfma_f32_16x16x32_bf16 v[98:101], v[184:187], v[210:213], v[98:101]
	v_mfma_f32_16x16x32_bf16 v[66:69], v[184:187], v[214:217], v[66:69]
	v_xor_b32_e32 v169, 64, v206
	v_add3_u32 v169, s21, v0, v169
	ds_read_b128 v[210:213], v169
	ds_read_b128 v[214:217], v169 offset:2048
	v_mfma_f32_16x16x32_bf16 v[34:37], v[184:187], v[218:221], v[34:37]
	ds_read_b128 v[218:221], v169 offset:4096
	v_mfma_f32_16x16x32_bf16 v[2:5], v[184:187], v[222:225], v[2:5]
	ds_read_b128 v[222:225], v169 offset:6144
	v_xor_b32_e32 v169, 64, v206
	v_add3_u32 v169, s21, v167, v169
	ds_read_b128 v[184:187], v169 offset:47104
	s_waitcnt lgkmcnt(1)
	v_mfma_f32_16x16x32_bf16 v[158:161], v[226:229], v[210:213], v[158:161]
	v_mfma_f32_16x16x32_bf16 v[94:97], v[226:229], v[214:217], v[94:97]
	v_mfma_f32_16x16x32_bf16 v[62:65], v[226:229], v[218:221], v[62:65]
	v_mfma_f32_16x16x32_bf16 v[30:33], v[226:229], v[222:225], v[30:33]
	s_waitcnt vmcnt(7)
	ds_write_b128 v171, v[114:117]
	v_mfma_f32_16x16x32_bf16 v[154:157], v[230:233], v[210:213], v[154:157]
	v_mfma_f32_16x16x32_bf16 v[90:93], v[230:233], v[214:217], v[90:93]
	global_load_dwordx4 v[114:117], v168, vcc offset:256
	v_mfma_f32_16x16x32_bf16 v[58:61], v[230:233], v[218:221], v[58:61]
	v_mfma_f32_16x16x32_bf16 v[26:29], v[230:233], v[222:225], v[26:29]
	s_waitcnt vmcnt(7)
	ds_write_b128 v171, v[106:109] offset:8192
	v_mfma_f32_16x16x32_bf16 v[150:153], v[234:237], v[210:213], v[150:153]
	v_mfma_f32_16x16x32_bf16 v[86:89], v[234:237], v[214:217], v[86:89]
	v_add_u32_e32 v106, s34, v168
	global_load_dwordx4 v[106:109], v106, vcc offset:256
	v_mfma_f32_16x16x32_bf16 v[54:57], v[234:237], v[218:221], v[54:57]
	v_mfma_f32_16x16x32_bf16 v[22:25], v[234:237], v[222:225], v[22:25]
	s_waitcnt vmcnt(7)
	ds_write_b128 v171, v[110:113] offset:16384
	v_mfma_f32_16x16x32_bf16 v[146:149], v[238:241], v[210:213], v[146:149]
	v_mfma_f32_16x16x32_bf16 v[82:85], v[238:241], v[214:217], v[82:85]
	v_add_u32_e32 v110, s35, v168
	global_load_dwordx4 v[110:113], v110, vcc offset:256
	v_mfma_f32_16x16x32_bf16 v[50:53], v[238:241], v[218:221], v[50:53]
	v_mfma_f32_16x16x32_bf16 v[18:21], v[238:241], v[222:225], v[18:21]
	s_waitcnt vmcnt(7)
	ds_write_b128 v171, v[126:129] offset:24576
	v_mfma_f32_16x16x32_bf16 v[142:145], v[242:245], v[210:213], v[142:145]
	v_mfma_f32_16x16x32_bf16 v[78:81], v[242:245], v[214:217], v[78:81]
	v_add_u32_e32 v126, s36, v168
	global_load_dwordx4 v[126:129], v126, vcc offset:256
	v_mfma_f32_16x16x32_bf16 v[46:49], v[242:245], v[218:221], v[46:49]
	v_mfma_f32_16x16x32_bf16 v[14:17], v[242:245], v[222:225], v[14:17]
	s_waitcnt vmcnt(7)
	ds_write_b128 v171, v[122:125] offset:32768
	v_mfma_f32_16x16x32_bf16 v[138:141], v[246:249], v[210:213], v[138:141]
	v_mfma_f32_16x16x32_bf16 v[74:77], v[246:249], v[214:217], v[74:77]
	global_load_dwordx4 v[122:125], v170, s[100:101] offset:256
	v_mfma_f32_16x16x32_bf16 v[42:45], v[246:249], v[218:221], v[42:45]
	v_mfma_f32_16x16x32_bf16 v[10:13], v[246:249], v[222:225], v[10:13]
	s_waitcnt vmcnt(7)
	ds_write_b128 v171, v[118:121] offset:40960
	v_mfma_f32_16x16x32_bf16 v[102:105], v[198:201], v[210:213], v[102:105]
	v_mfma_f32_16x16x32_bf16 v[70:73], v[198:201], v[214:217], v[70:73]
	v_add_u32_e32 v118, s34, v170
	global_load_dwordx4 v[118:121], v118, s[100:101] offset:256
	v_mfma_f32_16x16x32_bf16 v[38:41], v[198:201], v[218:221], v[38:41]
	v_mfma_f32_16x16x32_bf16 v[6:9], v[198:201], v[222:225], v[6:9]
	s_waitcnt vmcnt(7)
	ds_write_b128 v171, v[134:137] offset:49152
	s_waitcnt lgkmcnt(7)
	v_mfma_f32_16x16x32_bf16 v[98:101], v[184:187], v[210:213], v[98:101]
	v_mfma_f32_16x16x32_bf16 v[66:69], v[184:187], v[214:217], v[66:69]
	v_add_u32_e32 v134, s35, v170
	global_load_dwordx4 v[134:137], v134, s[100:101] offset:256
	v_mfma_f32_16x16x32_bf16 v[34:37], v[184:187], v[218:221], v[34:37]
	v_mfma_f32_16x16x32_bf16 v[2:5], v[184:187], v[222:225], v[2:5]
	s_waitcnt vmcnt(7)
	ds_write_b128 v171, v[130:133] offset:57344
	v_add_u32_e32 v130, s36, v170
	global_load_dwordx4 v[130:133], v130, s[100:101] offset:256
	v_add_u32_e32 v168, 0x80, v168
	v_add_u32_e32 v170, 0x80, v170
	s_waitcnt lgkmcnt(0)
	s_barrier
	s_cmp_eq_u32 s10, 16
	s_mov_b32 s4, s10
	s_cbranch_scc0 .LBB0_466
	s_waitcnt vmcnt(6)
	v_mul_f32_e32 v109, 0xbfb8aa3b, v158
	v_exp_f32_e32 v109, v109
	s_waitcnt vmcnt(5)
	v_mul_f32_e32 v111, 0xbfb8aa3b, v159
	v_exp_f32_e32 v111, v111
	v_mul_f32_e32 v115, 0xbfb8aa3b, v161
	v_add_f32_e32 v109, 1.0, v109
	v_rcp_f32_e32 v114, v109
	v_add_f32_e32 v109, 1.0, v111
	v_mul_f32_e32 v111, 0xbfb8aa3b, v160
	v_exp_f32_e32 v111, v111
	v_exp_f32_e32 v117, v115
	v_rcp_f32_e32 v116, v109
	s_waitcnt vmcnt(2)
	v_mov_b32_e32 v118, v158
	v_add_f32_e32 v109, 1.0, v111
	v_rcp_f32_e32 v115, v109
	v_add_f32_e32 v109, 1.0, v117
	v_rcp_f32_e32 v117, v109
	v_mov_b32_e32 v119, v160
	v_pk_mul_f32 v[114:115], v[118:119], v[114:115]
	v_mov_b32_e32 v118, v154
	v_mov_b32_e32 v119, v156
	v_mov_b32_e32 v160, v159
	v_pk_mul_f32 v[114:115], v[118:119], v[114:115]
	v_pk_mul_f32 v[116:117], v[160:161], v[116:117]
	v_mov_b32_e32 v156, v155
	v_pk_mul_f32 v[116:117], v[156:157], v[116:117]
	v_and_b32_sdwa v111, v115, v177 dst_sel:DWORD dst_unused:UNUSED_PAD src0_sel:WORD_1 src1_sel:DWORD
	v_and_b32_sdwa v118, v114, v177 dst_sel:DWORD dst_unused:UNUSED_PAD src0_sel:WORD_1 src1_sel:DWORD
	v_add3_u32 v111, v115, v111, s28
	v_and_b32_sdwa v115, v117, v177 dst_sel:DWORD dst_unused:UNUSED_PAD src0_sel:WORD_1 src1_sel:DWORD
	v_add3_u32 v114, v114, v118, s28
	v_and_b32_sdwa v118, v116, v177 dst_sel:DWORD dst_unused:UNUSED_PAD src0_sel:WORD_1 src1_sel:DWORD
	v_add3_u32 v115, v117, v115, s28
	v_or_b32_e32 v106, s7, v207
	v_add3_u32 v116, v116, v118, s28
	v_and_b32_e32 v115, 0xffff0000, v115
	v_ashrrev_i32_e32 v106, 1, v106
	v_and_b32_e32 v116, 0xffff0000, v116
	v_or_b32_sdwa v115, v115, v111 dst_sel:DWORD dst_unused:UNUSED_PAD src0_sel:DWORD src1_sel:WORD_1
	v_mul_f32_e32 v111, 0xbfb8aa3b, v150
	v_or_b32_e32 v108, v106, v208
	v_or_b32_sdwa v114, v116, v114 dst_sel:DWORD dst_unused:UNUSED_PAD src0_sel:DWORD src1_sel:WORD_1
	v_exp_f32_e32 v111, v111
	v_mul_f32_e32 v116, 0xbfb8aa3b, v151
	v_add_u32_e32 v110, s6, v205
	v_mov_b64_e32 v[106:107], s[14:15]
	v_ashrrev_i32_e32 v109, 31, v108
	v_exp_f32_e32 v116, v116
	v_mad_i64_i32 v[112:113], s[6:7], v110, s52, v[106:107]
	v_lshlrev_b64 v[108:109], 1, v[108:109]
	v_lshl_add_u64 v[112:113], v[112:113], 0, v[108:109]
	s_waitcnt vmcnt(0)
	global_store_dwordx2 v[112:113], v[114:115], off
	v_add_f32_e32 v111, 1.0, v111
	v_mul_f32_e32 v115, 0xbfb8aa3b, v152
	v_rcp_f32_e32 v114, v111
	v_add_f32_e32 v111, 1.0, v116
	v_exp_f32_e32 v115, v115
	v_mul_f32_e32 v116, 0xbfb8aa3b, v153
	v_exp_f32_e32 v117, v116
	v_rcp_f32_e32 v116, v111
	v_add_f32_e32 v111, 1.0, v115
	v_rcp_f32_e32 v115, v111
	v_add_f32_e32 v111, 1.0, v117
	v_rcp_f32_e32 v117, v111
	v_mov_b32_e32 v118, v150
	v_mov_b32_e32 v119, v152
	v_pk_mul_f32 v[114:115], v[118:119], v[114:115]
	v_mov_b32_e32 v118, v146
	v_mov_b32_e32 v119, v148
	v_mov_b32_e32 v152, v151
	v_pk_mul_f32 v[114:115], v[118:119], v[114:115]
	v_pk_mul_f32 v[116:117], v[152:153], v[116:117]
	v_mov_b32_e32 v148, v147
	v_pk_mul_f32 v[116:117], v[148:149], v[116:117]
	v_and_b32_sdwa v111, v115, v177 dst_sel:DWORD dst_unused:UNUSED_PAD src0_sel:WORD_1 src1_sel:DWORD
	v_and_b32_sdwa v118, v114, v177 dst_sel:DWORD dst_unused:UNUSED_PAD src0_sel:WORD_1 src1_sel:DWORD
	v_add3_u32 v111, v115, v111, s28
	v_and_b32_sdwa v115, v117, v177 dst_sel:DWORD dst_unused:UNUSED_PAD src0_sel:WORD_1 src1_sel:DWORD
	v_add3_u32 v114, v114, v118, s28
	v_and_b32_sdwa v118, v116, v177 dst_sel:DWORD dst_unused:UNUSED_PAD src0_sel:WORD_1 src1_sel:DWORD
	v_add3_u32 v115, v117, v115, s28
	v_add3_u32 v116, v116, v118, s28
	v_and_b32_e32 v115, 0xffff0000, v115
	v_and_b32_e32 v116, 0xffff0000, v116
	v_or_b32_sdwa v115, v115, v111 dst_sel:DWORD dst_unused:UNUSED_PAD src0_sel:DWORD src1_sel:WORD_1
	v_mul_f32_e32 v111, 0xbfb8aa3b, v142
	v_or_b32_sdwa v114, v116, v114 dst_sel:DWORD dst_unused:UNUSED_PAD src0_sel:DWORD src1_sel:WORD_1
	v_exp_f32_e32 v111, v111
	v_mul_f32_e32 v116, 0xbfb8aa3b, v143
	v_exp_f32_e32 v116, v116
	global_store_dwordx2 v[112:113], v[114:115], off offset:32
	v_add_f32_e32 v111, 1.0, v111
	v_mul_f32_e32 v115, 0xbfb8aa3b, v144
	v_rcp_f32_e32 v114, v111
	v_add_f32_e32 v111, 1.0, v116
	v_exp_f32_e32 v115, v115
	v_mul_f32_e32 v116, 0xbfb8aa3b, v145
	v_exp_f32_e32 v117, v116
	v_rcp_f32_e32 v116, v111
	v_add_f32_e32 v111, 1.0, v115
	v_rcp_f32_e32 v115, v111
	v_add_f32_e32 v111, 1.0, v117
	v_rcp_f32_e32 v117, v111
	v_mov_b32_e32 v118, v142
	v_mov_b32_e32 v119, v144
	v_pk_mul_f32 v[114:115], v[118:119], v[114:115]
	v_mov_b32_e32 v118, v138
	v_mov_b32_e32 v119, v140
	v_mov_b32_e32 v144, v143
	v_pk_mul_f32 v[114:115], v[118:119], v[114:115]
	v_pk_mul_f32 v[116:117], v[144:145], v[116:117]
	v_mov_b32_e32 v140, v139
	v_pk_mul_f32 v[116:117], v[140:141], v[116:117]
	v_and_b32_sdwa v111, v115, v177 dst_sel:DWORD dst_unused:UNUSED_PAD src0_sel:WORD_1 src1_sel:DWORD
	v_and_b32_sdwa v118, v114, v177 dst_sel:DWORD dst_unused:UNUSED_PAD src0_sel:WORD_1 src1_sel:DWORD
	v_add3_u32 v111, v115, v111, s28
	v_and_b32_sdwa v115, v117, v177 dst_sel:DWORD dst_unused:UNUSED_PAD src0_sel:WORD_1 src1_sel:DWORD
	v_add3_u32 v114, v114, v118, s28
	v_and_b32_sdwa v118, v116, v177 dst_sel:DWORD dst_unused:UNUSED_PAD src0_sel:WORD_1 src1_sel:DWORD
	v_add3_u32 v115, v117, v115, s28
	v_add3_u32 v116, v116, v118, s28
	v_and_b32_e32 v115, 0xffff0000, v115
	v_and_b32_e32 v116, 0xffff0000, v116
	v_or_b32_sdwa v115, v115, v111 dst_sel:DWORD dst_unused:UNUSED_PAD src0_sel:DWORD src1_sel:WORD_1
	v_mul_f32_e32 v111, 0xbfb8aa3b, v102
	v_or_b32_sdwa v114, v116, v114 dst_sel:DWORD dst_unused:UNUSED_PAD src0_sel:DWORD src1_sel:WORD_1
	v_exp_f32_e32 v111, v111
	v_mul_f32_e32 v116, 0xbfb8aa3b, v103
	v_exp_f32_e32 v116, v116
	global_store_dwordx2 v[112:113], v[114:115], off offset:64
	v_add_f32_e32 v111, 1.0, v111
	v_mul_f32_e32 v115, 0xbfb8aa3b, v104
	v_rcp_f32_e32 v114, v111
	v_add_f32_e32 v111, 1.0, v116
	v_exp_f32_e32 v115, v115
	v_mul_f32_e32 v116, 0xbfb8aa3b, v105
	v_exp_f32_e32 v117, v116
	v_rcp_f32_e32 v116, v111
	v_add_f32_e32 v111, 1.0, v115
	v_rcp_f32_e32 v115, v111
	v_add_f32_e32 v111, 1.0, v117
	v_rcp_f32_e32 v117, v111
	v_mov_b32_e32 v118, v102
	v_mov_b32_e32 v119, v104
	v_mov_b32_e32 v104, v103
	v_pk_mul_f32 v[114:115], v[118:119], v[114:115]
	v_mov_b32_e32 v119, v100
	v_pk_mul_f32 v[102:103], v[104:105], v[116:117]
	v_mov_b32_e32 v100, v99
	v_mov_b32_e32 v118, v98
	v_pk_mul_f32 v[98:99], v[100:101], v[102:103]
	v_pk_mul_f32 v[114:115], v[118:119], v[114:115]
	v_and_b32_sdwa v102, v99, v177 dst_sel:DWORD dst_unused:UNUSED_PAD src0_sel:WORD_1 src1_sel:DWORD
	v_and_b32_sdwa v103, v98, v177 dst_sel:DWORD dst_unused:UNUSED_PAD src0_sel:WORD_1 src1_sel:DWORD
	v_and_b32_sdwa v100, v115, v177 dst_sel:DWORD dst_unused:UNUSED_PAD src0_sel:WORD_1 src1_sel:DWORD
	v_and_b32_sdwa v101, v114, v177 dst_sel:DWORD dst_unused:UNUSED_PAD src0_sel:WORD_1 src1_sel:DWORD
	v_add3_u32 v99, v99, v102, s28
	v_add3_u32 v98, v98, v103, s28
	v_add3_u32 v101, v114, v101, s28
	v_add3_u32 v100, v115, v100, s28
	v_and_b32_e32 v99, 0xffff0000, v99
	v_and_b32_e32 v98, 0xffff0000, v98
	v_or_b32_sdwa v99, v99, v100 dst_sel:DWORD dst_unused:UNUSED_PAD src0_sel:DWORD src1_sel:WORD_1
	v_or_b32_sdwa v98, v98, v101 dst_sel:DWORD dst_unused:UNUSED_PAD src0_sel:DWORD src1_sel:WORD_1
	global_store_dwordx2 v[112:113], v[98:99], off offset:96
	v_mul_f32_e32 v99, 0xbfb8aa3b, v94
	v_exp_f32_e32 v100, v99
	v_mul_f32_e32 v99, 0xbfb8aa3b, v95
	v_mul_f32_e32 v102, 0xbfb8aa3b, v96
	v_exp_f32_e32 v101, v99
	v_exp_f32_e32 v103, v102
	v_mul_f32_e32 v102, 0xbfb8aa3b, v97
	v_exp_f32_e32 v104, v102
	v_add_f32_e32 v101, 1.0, v101
	v_add_f32_e32 v100, 1.0, v100
	v_rcp_f32_e32 v102, v101
	v_add_f32_e32 v101, 1.0, v103
	v_add_f32_e32 v103, 1.0, v104
	v_rcp_f32_e32 v100, v100
	v_rcp_f32_e32 v101, v101
	v_rcp_f32_e32 v103, v103
	v_mov_b32_e32 v104, v94
	v_mov_b32_e32 v105, v96
	v_mov_b32_e32 v96, v95
	v_pk_mul_f32 v[100:101], v[104:105], v[100:101]
	v_mov_b32_e32 v105, v92
	v_pk_mul_f32 v[94:95], v[96:97], v[102:103]
	v_mov_b32_e32 v92, v91
	v_mov_b32_e32 v104, v90
	v_pk_mul_f32 v[90:91], v[92:93], v[94:95]
	v_pk_mul_f32 v[100:101], v[104:105], v[100:101]
	v_and_b32_sdwa v94, v91, v177 dst_sel:DWORD dst_unused:UNUSED_PAD src0_sel:WORD_1 src1_sel:DWORD
	v_and_b32_sdwa v92, v101, v177 dst_sel:DWORD dst_unused:UNUSED_PAD src0_sel:WORD_1 src1_sel:DWORD
	v_and_b32_sdwa v95, v90, v177 dst_sel:DWORD dst_unused:UNUSED_PAD src0_sel:WORD_1 src1_sel:DWORD
	v_add3_u32 v91, v91, v94, s28
	v_and_b32_sdwa v93, v100, v177 dst_sel:DWORD dst_unused:UNUSED_PAD src0_sel:WORD_1 src1_sel:DWORD
	v_add3_u32 v92, v101, v92, s28
	v_add3_u32 v90, v90, v95, s28
	v_and_b32_e32 v91, 0xffff0000, v91
	v_add3_u32 v93, v100, v93, s28
	v_and_b32_e32 v90, 0xffff0000, v90
	v_or_b32_sdwa v91, v91, v92 dst_sel:DWORD dst_unused:UNUSED_PAD src0_sel:DWORD src1_sel:WORD_1
	v_mul_f32_e32 v92, 0xbfb8aa3b, v86
	v_or_b32_sdwa v90, v90, v93 dst_sel:DWORD dst_unused:UNUSED_PAD src0_sel:DWORD src1_sel:WORD_1
	v_exp_f32_e32 v92, v92
	v_mul_f32_e32 v93, 0xbfb8aa3b, v87
	v_or_b32_e32 v98, 16, v110
	v_exp_f32_e32 v93, v93
	v_mad_i64_i32 v[98:99], s[6:7], v98, s52, v[106:107]
	v_lshl_add_u64 v[98:99], v[98:99], 0, v[108:109]
	global_store_dwordx2 v[98:99], v[90:91], off
	v_add_f32_e32 v90, 1.0, v92
	v_mul_f32_e32 v92, 0xbfb8aa3b, v88
	v_add_f32_e32 v91, 1.0, v93
	v_exp_f32_e32 v93, v92
	v_mul_f32_e32 v92, 0xbfb8aa3b, v89
	v_exp_f32_e32 v94, v92
	v_rcp_f32_e32 v92, v91
	v_add_f32_e32 v91, 1.0, v93
	v_rcp_f32_e32 v90, v90
	v_add_f32_e32 v93, 1.0, v94
	v_rcp_f32_e32 v91, v91
	v_rcp_f32_e32 v93, v93
	v_mov_b32_e32 v94, v86
	v_mov_b32_e32 v95, v88
	v_mov_b32_e32 v88, v87
	v_pk_mul_f32 v[90:91], v[94:95], v[90:91]
	v_mov_b32_e32 v95, v84
	v_pk_mul_f32 v[86:87], v[88:89], v[92:93]
	v_mov_b32_e32 v84, v83
	v_mov_b32_e32 v94, v82
	v_pk_mul_f32 v[82:83], v[84:85], v[86:87]
	v_pk_mul_f32 v[90:91], v[94:95], v[90:91]
	v_and_b32_sdwa v86, v83, v177 dst_sel:DWORD dst_unused:UNUSED_PAD src0_sel:WORD_1 src1_sel:DWORD
	v_and_b32_sdwa v84, v91, v177 dst_sel:DWORD dst_unused:UNUSED_PAD src0_sel:WORD_1 src1_sel:DWORD
	v_and_b32_sdwa v87, v82, v177 dst_sel:DWORD dst_unused:UNUSED_PAD src0_sel:WORD_1 src1_sel:DWORD
	v_add3_u32 v83, v83, v86, s28
	v_and_b32_sdwa v85, v90, v177 dst_sel:DWORD dst_unused:UNUSED_PAD src0_sel:WORD_1 src1_sel:DWORD
	v_add3_u32 v84, v91, v84, s28
	v_add3_u32 v82, v82, v87, s28
	v_and_b32_e32 v83, 0xffff0000, v83
	v_add3_u32 v85, v90, v85, s28
	v_and_b32_e32 v82, 0xffff0000, v82
	v_or_b32_sdwa v83, v83, v84 dst_sel:DWORD dst_unused:UNUSED_PAD src0_sel:DWORD src1_sel:WORD_1
	v_mul_f32_e32 v84, 0xbfb8aa3b, v78
	v_or_b32_sdwa v82, v82, v85 dst_sel:DWORD dst_unused:UNUSED_PAD src0_sel:DWORD src1_sel:WORD_1
	v_exp_f32_e32 v84, v84
	v_mul_f32_e32 v85, 0xbfb8aa3b, v79
	v_exp_f32_e32 v85, v85
	global_store_dwordx2 v[98:99], v[82:83], off offset:32
	v_add_f32_e32 v82, 1.0, v84
	v_mul_f32_e32 v84, 0xbfb8aa3b, v80
	v_add_f32_e32 v83, 1.0, v85
	v_exp_f32_e32 v85, v84
	v_mul_f32_e32 v84, 0xbfb8aa3b, v81
	v_exp_f32_e32 v86, v84
	v_rcp_f32_e32 v84, v83
	v_add_f32_e32 v83, 1.0, v85
	v_rcp_f32_e32 v82, v82
	v_add_f32_e32 v85, 1.0, v86
	v_rcp_f32_e32 v83, v83
	v_rcp_f32_e32 v85, v85
	v_mov_b32_e32 v86, v78
	v_mov_b32_e32 v87, v80
	v_mov_b32_e32 v80, v79
	v_pk_mul_f32 v[82:83], v[86:87], v[82:83]
	v_mov_b32_e32 v87, v76
	v_pk_mul_f32 v[78:79], v[80:81], v[84:85]
	v_mov_b32_e32 v76, v75
	v_mov_b32_e32 v86, v74
	v_pk_mul_f32 v[74:75], v[76:77], v[78:79]
	v_pk_mul_f32 v[82:83], v[86:87], v[82:83]
	v_and_b32_sdwa v78, v75, v177 dst_sel:DWORD dst_unused:UNUSED_PAD src0_sel:WORD_1 src1_sel:DWORD
	v_and_b32_sdwa v76, v83, v177 dst_sel:DWORD dst_unused:UNUSED_PAD src0_sel:WORD_1 src1_sel:DWORD
	v_and_b32_sdwa v79, v74, v177 dst_sel:DWORD dst_unused:UNUSED_PAD src0_sel:WORD_1 src1_sel:DWORD
	v_add3_u32 v75, v75, v78, s28
	v_and_b32_sdwa v77, v82, v177 dst_sel:DWORD dst_unused:UNUSED_PAD src0_sel:WORD_1 src1_sel:DWORD
	v_add3_u32 v76, v83, v76, s28
	v_add3_u32 v74, v74, v79, s28
	v_and_b32_e32 v75, 0xffff0000, v75
	v_add3_u32 v77, v82, v77, s28
	v_and_b32_e32 v74, 0xffff0000, v74
	v_or_b32_sdwa v75, v75, v76 dst_sel:DWORD dst_unused:UNUSED_PAD src0_sel:DWORD src1_sel:WORD_1
	v_mul_f32_e32 v76, 0xbfb8aa3b, v70
	v_or_b32_sdwa v74, v74, v77 dst_sel:DWORD dst_unused:UNUSED_PAD src0_sel:DWORD src1_sel:WORD_1
	v_exp_f32_e32 v76, v76
	v_mul_f32_e32 v77, 0xbfb8aa3b, v71
	v_exp_f32_e32 v77, v77
	global_store_dwordx2 v[98:99], v[74:75], off offset:64
	v_add_f32_e32 v74, 1.0, v76
	v_mul_f32_e32 v76, 0xbfb8aa3b, v72
	v_add_f32_e32 v75, 1.0, v77
	v_exp_f32_e32 v77, v76
	v_mul_f32_e32 v76, 0xbfb8aa3b, v73
	v_exp_f32_e32 v78, v76
	v_rcp_f32_e32 v76, v75
	v_add_f32_e32 v75, 1.0, v77
	v_rcp_f32_e32 v74, v74
	v_add_f32_e32 v77, 1.0, v78
	v_rcp_f32_e32 v75, v75
	v_rcp_f32_e32 v77, v77
	v_mov_b32_e32 v78, v70
	v_mov_b32_e32 v79, v72
	v_mov_b32_e32 v72, v71
	v_pk_mul_f32 v[74:75], v[78:79], v[74:75]
	v_mov_b32_e32 v79, v68
	v_pk_mul_f32 v[70:71], v[72:73], v[76:77]
	v_mov_b32_e32 v68, v67
	v_mov_b32_e32 v78, v66
	v_pk_mul_f32 v[66:67], v[68:69], v[70:71]
	v_pk_mul_f32 v[74:75], v[78:79], v[74:75]
	v_and_b32_sdwa v70, v67, v177 dst_sel:DWORD dst_unused:UNUSED_PAD src0_sel:WORD_1 src1_sel:DWORD
	v_and_b32_sdwa v71, v66, v177 dst_sel:DWORD dst_unused:UNUSED_PAD src0_sel:WORD_1 src1_sel:DWORD
	v_and_b32_sdwa v68, v75, v177 dst_sel:DWORD dst_unused:UNUSED_PAD src0_sel:WORD_1 src1_sel:DWORD
	v_and_b32_sdwa v69, v74, v177 dst_sel:DWORD dst_unused:UNUSED_PAD src0_sel:WORD_1 src1_sel:DWORD
	v_add3_u32 v67, v67, v70, s28
	v_add3_u32 v66, v66, v71, s28
	v_add3_u32 v69, v74, v69, s28
	v_add3_u32 v68, v75, v68, s28
	v_and_b32_e32 v67, 0xffff0000, v67
	v_and_b32_e32 v66, 0xffff0000, v66
	v_or_b32_sdwa v67, v67, v68 dst_sel:DWORD dst_unused:UNUSED_PAD src0_sel:DWORD src1_sel:WORD_1
	v_or_b32_sdwa v66, v66, v69 dst_sel:DWORD dst_unused:UNUSED_PAD src0_sel:DWORD src1_sel:WORD_1
	global_store_dwordx2 v[98:99], v[66:67], off offset:96
	v_mul_f32_e32 v67, 0xbfb8aa3b, v62
	v_exp_f32_e32 v68, v67
	v_mul_f32_e32 v67, 0xbfb8aa3b, v63
	v_mul_f32_e32 v70, 0xbfb8aa3b, v64
	v_exp_f32_e32 v69, v67
	v_exp_f32_e32 v71, v70
	v_mul_f32_e32 v70, 0xbfb8aa3b, v65
	v_exp_f32_e32 v72, v70
	v_add_f32_e32 v69, 1.0, v69
	v_add_f32_e32 v68, 1.0, v68
	v_rcp_f32_e32 v70, v69
	v_add_f32_e32 v69, 1.0, v71
	v_add_f32_e32 v71, 1.0, v72
	v_rcp_f32_e32 v68, v68
	v_rcp_f32_e32 v69, v69
	v_rcp_f32_e32 v71, v71
	v_mov_b32_e32 v72, v62
	v_mov_b32_e32 v73, v64
	v_mov_b32_e32 v64, v63
	v_pk_mul_f32 v[68:69], v[72:73], v[68:69]
	v_mov_b32_e32 v73, v60
	v_pk_mul_f32 v[62:63], v[64:65], v[70:71]
	v_mov_b32_e32 v60, v59
	v_mov_b32_e32 v72, v58
	v_pk_mul_f32 v[58:59], v[60:61], v[62:63]
	v_pk_mul_f32 v[68:69], v[72:73], v[68:69]
	v_and_b32_sdwa v62, v59, v177 dst_sel:DWORD dst_unused:UNUSED_PAD src0_sel:WORD_1 src1_sel:DWORD
	v_and_b32_sdwa v60, v69, v177 dst_sel:DWORD dst_unused:UNUSED_PAD src0_sel:WORD_1 src1_sel:DWORD
	v_and_b32_sdwa v63, v58, v177 dst_sel:DWORD dst_unused:UNUSED_PAD src0_sel:WORD_1 src1_sel:DWORD
	v_add3_u32 v59, v59, v62, s28
	v_and_b32_sdwa v61, v68, v177 dst_sel:DWORD dst_unused:UNUSED_PAD src0_sel:WORD_1 src1_sel:DWORD
	v_add3_u32 v60, v69, v60, s28
	v_add3_u32 v58, v58, v63, s28
	v_and_b32_e32 v59, 0xffff0000, v59
	v_add3_u32 v61, v68, v61, s28
	v_and_b32_e32 v58, 0xffff0000, v58
	v_or_b32_sdwa v59, v59, v60 dst_sel:DWORD dst_unused:UNUSED_PAD src0_sel:DWORD src1_sel:WORD_1
	v_mul_f32_e32 v60, 0xbfb8aa3b, v54
	v_or_b32_sdwa v58, v58, v61 dst_sel:DWORD dst_unused:UNUSED_PAD src0_sel:DWORD src1_sel:WORD_1
	v_exp_f32_e32 v60, v60
	v_mul_f32_e32 v61, 0xbfb8aa3b, v55
	v_or_b32_e32 v66, 32, v110
	v_exp_f32_e32 v61, v61
	v_mad_i64_i32 v[66:67], s[6:7], v66, s52, v[106:107]
	v_lshl_add_u64 v[66:67], v[66:67], 0, v[108:109]
	global_store_dwordx2 v[66:67], v[58:59], off
	v_add_f32_e32 v58, 1.0, v60
	v_mul_f32_e32 v60, 0xbfb8aa3b, v56
	v_add_f32_e32 v59, 1.0, v61
	v_exp_f32_e32 v61, v60
	v_mul_f32_e32 v60, 0xbfb8aa3b, v57
	v_exp_f32_e32 v62, v60
	v_rcp_f32_e32 v60, v59
	v_add_f32_e32 v59, 1.0, v61
	v_rcp_f32_e32 v58, v58
	v_add_f32_e32 v61, 1.0, v62
	v_rcp_f32_e32 v59, v59
	v_rcp_f32_e32 v61, v61
	v_mov_b32_e32 v62, v54
	v_mov_b32_e32 v63, v56
	v_mov_b32_e32 v56, v55
	v_pk_mul_f32 v[58:59], v[62:63], v[58:59]
	v_mov_b32_e32 v63, v52
	v_pk_mul_f32 v[54:55], v[56:57], v[60:61]
	v_mov_b32_e32 v52, v51
	v_mov_b32_e32 v62, v50
	v_pk_mul_f32 v[50:51], v[52:53], v[54:55]
	v_pk_mul_f32 v[58:59], v[62:63], v[58:59]
	v_and_b32_sdwa v54, v51, v177 dst_sel:DWORD dst_unused:UNUSED_PAD src0_sel:WORD_1 src1_sel:DWORD
	v_and_b32_sdwa v52, v59, v177 dst_sel:DWORD dst_unused:UNUSED_PAD src0_sel:WORD_1 src1_sel:DWORD
	v_and_b32_sdwa v55, v50, v177 dst_sel:DWORD dst_unused:UNUSED_PAD src0_sel:WORD_1 src1_sel:DWORD
	v_add3_u32 v51, v51, v54, s28
	v_and_b32_sdwa v53, v58, v177 dst_sel:DWORD dst_unused:UNUSED_PAD src0_sel:WORD_1 src1_sel:DWORD
	v_add3_u32 v52, v59, v52, s28
	v_add3_u32 v50, v50, v55, s28
	v_and_b32_e32 v51, 0xffff0000, v51
	v_add3_u32 v53, v58, v53, s28
	v_and_b32_e32 v50, 0xffff0000, v50
	v_or_b32_sdwa v51, v51, v52 dst_sel:DWORD dst_unused:UNUSED_PAD src0_sel:DWORD src1_sel:WORD_1
	v_mul_f32_e32 v52, 0xbfb8aa3b, v46
	v_or_b32_sdwa v50, v50, v53 dst_sel:DWORD dst_unused:UNUSED_PAD src0_sel:DWORD src1_sel:WORD_1
	v_exp_f32_e32 v52, v52
	v_mul_f32_e32 v53, 0xbfb8aa3b, v47
	v_exp_f32_e32 v53, v53
	global_store_dwordx2 v[66:67], v[50:51], off offset:32
	v_add_f32_e32 v50, 1.0, v52
	v_mul_f32_e32 v52, 0xbfb8aa3b, v48
	v_add_f32_e32 v51, 1.0, v53
	v_exp_f32_e32 v53, v52
	v_mul_f32_e32 v52, 0xbfb8aa3b, v49
	v_exp_f32_e32 v54, v52
	v_rcp_f32_e32 v52, v51
	v_add_f32_e32 v51, 1.0, v53
	v_rcp_f32_e32 v50, v50
	v_add_f32_e32 v53, 1.0, v54
	v_rcp_f32_e32 v51, v51
	v_rcp_f32_e32 v53, v53
	v_mov_b32_e32 v54, v46
	v_mov_b32_e32 v55, v48
	v_mov_b32_e32 v48, v47
	v_pk_mul_f32 v[50:51], v[54:55], v[50:51]
	v_mov_b32_e32 v55, v44
	v_pk_mul_f32 v[46:47], v[48:49], v[52:53]
	v_mov_b32_e32 v44, v43
	v_mov_b32_e32 v54, v42
	v_pk_mul_f32 v[42:43], v[44:45], v[46:47]
	v_pk_mul_f32 v[50:51], v[54:55], v[50:51]
	v_and_b32_sdwa v46, v43, v177 dst_sel:DWORD dst_unused:UNUSED_PAD src0_sel:WORD_1 src1_sel:DWORD
	v_and_b32_sdwa v44, v51, v177 dst_sel:DWORD dst_unused:UNUSED_PAD src0_sel:WORD_1 src1_sel:DWORD
	v_and_b32_sdwa v47, v42, v177 dst_sel:DWORD dst_unused:UNUSED_PAD src0_sel:WORD_1 src1_sel:DWORD
	v_add3_u32 v43, v43, v46, s28
	v_and_b32_sdwa v45, v50, v177 dst_sel:DWORD dst_unused:UNUSED_PAD src0_sel:WORD_1 src1_sel:DWORD
	v_add3_u32 v44, v51, v44, s28
	v_add3_u32 v42, v42, v47, s28
	v_and_b32_e32 v43, 0xffff0000, v43
	v_add3_u32 v45, v50, v45, s28
	v_and_b32_e32 v42, 0xffff0000, v42
	v_or_b32_sdwa v43, v43, v44 dst_sel:DWORD dst_unused:UNUSED_PAD src0_sel:DWORD src1_sel:WORD_1
	v_mul_f32_e32 v44, 0xbfb8aa3b, v38
	v_or_b32_sdwa v42, v42, v45 dst_sel:DWORD dst_unused:UNUSED_PAD src0_sel:DWORD src1_sel:WORD_1
	v_exp_f32_e32 v44, v44
	v_mul_f32_e32 v45, 0xbfb8aa3b, v39
	v_exp_f32_e32 v45, v45
	global_store_dwordx2 v[66:67], v[42:43], off offset:64
	v_add_f32_e32 v42, 1.0, v44
	v_mul_f32_e32 v44, 0xbfb8aa3b, v40
	v_add_f32_e32 v43, 1.0, v45
	v_exp_f32_e32 v45, v44
	v_mul_f32_e32 v44, 0xbfb8aa3b, v41
	v_exp_f32_e32 v46, v44
	v_rcp_f32_e32 v44, v43
	v_add_f32_e32 v43, 1.0, v45
	v_rcp_f32_e32 v42, v42
	v_add_f32_e32 v45, 1.0, v46
	v_rcp_f32_e32 v43, v43
	v_rcp_f32_e32 v45, v45
	v_mov_b32_e32 v46, v38
	v_mov_b32_e32 v47, v40
	v_mov_b32_e32 v40, v39
	v_pk_mul_f32 v[42:43], v[46:47], v[42:43]
	v_mov_b32_e32 v47, v36
	v_pk_mul_f32 v[38:39], v[40:41], v[44:45]
	v_mov_b32_e32 v36, v35
	v_mov_b32_e32 v46, v34
	v_pk_mul_f32 v[34:35], v[36:37], v[38:39]
	v_pk_mul_f32 v[42:43], v[46:47], v[42:43]
	v_and_b32_sdwa v38, v35, v177 dst_sel:DWORD dst_unused:UNUSED_PAD src0_sel:WORD_1 src1_sel:DWORD
	v_and_b32_sdwa v39, v34, v177 dst_sel:DWORD dst_unused:UNUSED_PAD src0_sel:WORD_1 src1_sel:DWORD
	v_and_b32_sdwa v36, v43, v177 dst_sel:DWORD dst_unused:UNUSED_PAD src0_sel:WORD_1 src1_sel:DWORD
	v_and_b32_sdwa v37, v42, v177 dst_sel:DWORD dst_unused:UNUSED_PAD src0_sel:WORD_1 src1_sel:DWORD
	v_add3_u32 v35, v35, v38, s28
	v_add3_u32 v34, v34, v39, s28
	v_add3_u32 v37, v42, v37, s28
	v_add3_u32 v36, v43, v36, s28
	v_and_b32_e32 v35, 0xffff0000, v35
	v_and_b32_e32 v34, 0xffff0000, v34
	v_or_b32_sdwa v35, v35, v36 dst_sel:DWORD dst_unused:UNUSED_PAD src0_sel:DWORD src1_sel:WORD_1
	v_or_b32_sdwa v34, v34, v37 dst_sel:DWORD dst_unused:UNUSED_PAD src0_sel:DWORD src1_sel:WORD_1
	global_store_dwordx2 v[66:67], v[34:35], off offset:96
	v_mul_f32_e32 v35, 0xbfb8aa3b, v30
	v_exp_f32_e32 v36, v35
	v_mul_f32_e32 v35, 0xbfb8aa3b, v31
	v_mul_f32_e32 v38, 0xbfb8aa3b, v32
	v_exp_f32_e32 v37, v35
	v_exp_f32_e32 v39, v38
	v_mul_f32_e32 v38, 0xbfb8aa3b, v33
	v_exp_f32_e32 v40, v38
	v_add_f32_e32 v37, 1.0, v37
	v_add_f32_e32 v36, 1.0, v36
	v_rcp_f32_e32 v38, v37
	v_add_f32_e32 v37, 1.0, v39
	v_add_f32_e32 v39, 1.0, v40
	v_rcp_f32_e32 v36, v36
	v_rcp_f32_e32 v37, v37
	v_rcp_f32_e32 v39, v39
	v_mov_b32_e32 v40, v30
	v_mov_b32_e32 v41, v32
	v_mov_b32_e32 v32, v31
	v_pk_mul_f32 v[36:37], v[40:41], v[36:37]
	v_mov_b32_e32 v41, v28
	v_pk_mul_f32 v[30:31], v[32:33], v[38:39]
	v_mov_b32_e32 v28, v27
	v_mov_b32_e32 v40, v26
	v_pk_mul_f32 v[26:27], v[28:29], v[30:31]
	v_pk_mul_f32 v[36:37], v[40:41], v[36:37]
	v_and_b32_sdwa v30, v27, v177 dst_sel:DWORD dst_unused:UNUSED_PAD src0_sel:WORD_1 src1_sel:DWORD
	v_and_b32_sdwa v28, v37, v177 dst_sel:DWORD dst_unused:UNUSED_PAD src0_sel:WORD_1 src1_sel:DWORD
	v_and_b32_sdwa v31, v26, v177 dst_sel:DWORD dst_unused:UNUSED_PAD src0_sel:WORD_1 src1_sel:DWORD
	v_add3_u32 v27, v27, v30, s28
	v_and_b32_sdwa v29, v36, v177 dst_sel:DWORD dst_unused:UNUSED_PAD src0_sel:WORD_1 src1_sel:DWORD
	v_add3_u32 v28, v37, v28, s28
	v_add3_u32 v26, v26, v31, s28
	v_and_b32_e32 v27, 0xffff0000, v27
	v_add3_u32 v29, v36, v29, s28
	v_and_b32_e32 v26, 0xffff0000, v26
	v_or_b32_sdwa v27, v27, v28 dst_sel:DWORD dst_unused:UNUSED_PAD src0_sel:DWORD src1_sel:WORD_1
	v_mul_f32_e32 v28, 0xbfb8aa3b, v22
	v_or_b32_sdwa v26, v26, v29 dst_sel:DWORD dst_unused:UNUSED_PAD src0_sel:DWORD src1_sel:WORD_1
	v_exp_f32_e32 v28, v28
	v_mul_f32_e32 v29, 0xbfb8aa3b, v23
	v_or_b32_e32 v34, 48, v110
	v_exp_f32_e32 v29, v29
	v_mad_i64_i32 v[34:35], s[6:7], v34, s52, v[106:107]
	v_lshl_add_u64 v[34:35], v[34:35], 0, v[108:109]
	global_store_dwordx2 v[34:35], v[26:27], off
	v_add_f32_e32 v26, 1.0, v28
	v_mul_f32_e32 v28, 0xbfb8aa3b, v24
	v_add_f32_e32 v27, 1.0, v29
	v_exp_f32_e32 v29, v28
	v_mul_f32_e32 v28, 0xbfb8aa3b, v25
	v_exp_f32_e32 v30, v28
	v_rcp_f32_e32 v28, v27
	v_add_f32_e32 v27, 1.0, v29
	v_rcp_f32_e32 v26, v26
	v_add_f32_e32 v29, 1.0, v30
	v_rcp_f32_e32 v27, v27
	v_rcp_f32_e32 v29, v29
	v_mov_b32_e32 v30, v22
	v_mov_b32_e32 v31, v24
	v_mov_b32_e32 v24, v23
	v_pk_mul_f32 v[26:27], v[30:31], v[26:27]
	v_mov_b32_e32 v31, v20
	v_pk_mul_f32 v[22:23], v[24:25], v[28:29]
	v_mov_b32_e32 v20, v19
	v_mov_b32_e32 v30, v18
	v_pk_mul_f32 v[18:19], v[20:21], v[22:23]
	v_pk_mul_f32 v[26:27], v[30:31], v[26:27]
	v_and_b32_sdwa v22, v19, v177 dst_sel:DWORD dst_unused:UNUSED_PAD src0_sel:WORD_1 src1_sel:DWORD
	v_and_b32_sdwa v20, v27, v177 dst_sel:DWORD dst_unused:UNUSED_PAD src0_sel:WORD_1 src1_sel:DWORD
	v_and_b32_sdwa v23, v18, v177 dst_sel:DWORD dst_unused:UNUSED_PAD src0_sel:WORD_1 src1_sel:DWORD
	v_add3_u32 v19, v19, v22, s28
	v_and_b32_sdwa v21, v26, v177 dst_sel:DWORD dst_unused:UNUSED_PAD src0_sel:WORD_1 src1_sel:DWORD
	v_add3_u32 v20, v27, v20, s28
	v_add3_u32 v18, v18, v23, s28
	v_and_b32_e32 v19, 0xffff0000, v19
	v_add3_u32 v21, v26, v21, s28
	v_and_b32_e32 v18, 0xffff0000, v18
	v_or_b32_sdwa v19, v19, v20 dst_sel:DWORD dst_unused:UNUSED_PAD src0_sel:DWORD src1_sel:WORD_1
	v_mul_f32_e32 v20, 0xbfb8aa3b, v14
	v_or_b32_sdwa v18, v18, v21 dst_sel:DWORD dst_unused:UNUSED_PAD src0_sel:DWORD src1_sel:WORD_1
	v_exp_f32_e32 v20, v20
	v_mul_f32_e32 v21, 0xbfb8aa3b, v15
	v_exp_f32_e32 v21, v21
	global_store_dwordx2 v[34:35], v[18:19], off offset:32
	v_add_f32_e32 v18, 1.0, v20
	v_mul_f32_e32 v20, 0xbfb8aa3b, v16
	v_add_f32_e32 v19, 1.0, v21
	v_exp_f32_e32 v21, v20
	v_mul_f32_e32 v20, 0xbfb8aa3b, v17
	v_exp_f32_e32 v22, v20
	v_rcp_f32_e32 v20, v19
	v_add_f32_e32 v19, 1.0, v21
	v_rcp_f32_e32 v18, v18
	v_add_f32_e32 v21, 1.0, v22
	v_rcp_f32_e32 v19, v19
	v_rcp_f32_e32 v21, v21
	v_mov_b32_e32 v22, v14
	v_mov_b32_e32 v23, v16
	v_mov_b32_e32 v16, v15
	v_pk_mul_f32 v[18:19], v[22:23], v[18:19]
	v_mov_b32_e32 v23, v12
	v_pk_mul_f32 v[14:15], v[16:17], v[20:21]
	v_mov_b32_e32 v12, v11
	v_mov_b32_e32 v22, v10
	v_pk_mul_f32 v[10:11], v[12:13], v[14:15]
	v_pk_mul_f32 v[18:19], v[22:23], v[18:19]
	v_and_b32_sdwa v14, v11, v177 dst_sel:DWORD dst_unused:UNUSED_PAD src0_sel:WORD_1 src1_sel:DWORD
	v_and_b32_sdwa v12, v19, v177 dst_sel:DWORD dst_unused:UNUSED_PAD src0_sel:WORD_1 src1_sel:DWORD
	v_and_b32_sdwa v15, v10, v177 dst_sel:DWORD dst_unused:UNUSED_PAD src0_sel:WORD_1 src1_sel:DWORD
	v_add3_u32 v11, v11, v14, s28
	v_and_b32_sdwa v13, v18, v177 dst_sel:DWORD dst_unused:UNUSED_PAD src0_sel:WORD_1 src1_sel:DWORD
	v_add3_u32 v12, v19, v12, s28
	v_add3_u32 v10, v10, v15, s28
	v_and_b32_e32 v11, 0xffff0000, v11
	v_add3_u32 v13, v18, v13, s28
	v_and_b32_e32 v10, 0xffff0000, v10
	v_or_b32_sdwa v11, v11, v12 dst_sel:DWORD dst_unused:UNUSED_PAD src0_sel:DWORD src1_sel:WORD_1
	v_mul_f32_e32 v12, 0xbfb8aa3b, v6
	v_or_b32_sdwa v10, v10, v13 dst_sel:DWORD dst_unused:UNUSED_PAD src0_sel:DWORD src1_sel:WORD_1
	v_exp_f32_e32 v12, v12
	v_mul_f32_e32 v13, 0xbfb8aa3b, v7
	v_exp_f32_e32 v13, v13
	global_store_dwordx2 v[34:35], v[10:11], off offset:64
	v_add_f32_e32 v10, 1.0, v12
	v_mul_f32_e32 v12, 0xbfb8aa3b, v8
	v_add_f32_e32 v11, 1.0, v13
	v_exp_f32_e32 v13, v12
	v_mul_f32_e32 v12, 0xbfb8aa3b, v9
	v_exp_f32_e32 v14, v12
	v_rcp_f32_e32 v12, v11
	v_add_f32_e32 v11, 1.0, v13
	v_rcp_f32_e32 v10, v10
	v_add_f32_e32 v13, 1.0, v14
	v_rcp_f32_e32 v11, v11
	v_rcp_f32_e32 v13, v13
	v_mov_b32_e32 v14, v6
	v_mov_b32_e32 v15, v8
	v_mov_b32_e32 v8, v7
	v_pk_mul_f32 v[10:11], v[14:15], v[10:11]
	v_mov_b32_e32 v15, v4
	v_pk_mul_f32 v[6:7], v[8:9], v[12:13]
	v_mov_b32_e32 v4, v3
	v_mov_b32_e32 v14, v2
	v_pk_mul_f32 v[2:3], v[4:5], v[6:7]
	v_pk_mul_f32 v[10:11], v[14:15], v[10:11]
	v_and_b32_sdwa v6, v3, v177 dst_sel:DWORD dst_unused:UNUSED_PAD src0_sel:WORD_1 src1_sel:DWORD
	v_and_b32_sdwa v7, v2, v177 dst_sel:DWORD dst_unused:UNUSED_PAD src0_sel:WORD_1 src1_sel:DWORD
	v_and_b32_sdwa v4, v11, v177 dst_sel:DWORD dst_unused:UNUSED_PAD src0_sel:WORD_1 src1_sel:DWORD
	v_and_b32_sdwa v5, v10, v177 dst_sel:DWORD dst_unused:UNUSED_PAD src0_sel:WORD_1 src1_sel:DWORD
	v_add3_u32 v3, v3, v6, s28
	v_add3_u32 v2, v2, v7, s28
	v_add3_u32 v5, v10, v5, s28
	v_add3_u32 v4, v11, v4, s28
	v_and_b32_e32 v3, 0xffff0000, v3
	v_and_b32_e32 v2, 0xffff0000, v2
	s_add_i32 s20, s20, s11
	v_or_b32_sdwa v3, v3, v4 dst_sel:DWORD dst_unused:UNUSED_PAD src0_sel:DWORD src1_sel:WORD_1
	v_or_b32_sdwa v2, v2, v5 dst_sel:DWORD dst_unused:UNUSED_PAD src0_sel:DWORD src1_sel:WORD_1
	s_cmpk_gt_i32 s20, 0x5ff
	global_store_dwordx2 v[34:35], v[2:3], off offset:96
	s_cbranch_scc0 .LBB0_465
	s_setprio 0

.LBB0_531:
	s_lshl_b64 s[2:3], s[12:13], 2
	s_add_u32 s4, s14, s2
	v_writelane_b32 v255, s2, 48
	s_addc_u32 s6, s15, s3
	s_add_u32 s12, s4, 0x5602000
	s_addc_u32 s13, s6, 0
	s_load_dwordx2 s[48:49], s[18:19], 0x128
	s_add_u32 s18, s14, 0x6035800
	s_addc_u32 s19, s15, 0
	s_add_u32 s50, s14, 0x1600000
	s_addc_u32 s51, s15, 0
	v_mov_b32_e32 v2, v172
	s_mov_b32 s10, s42
	s_mov_b32 s11, s94
	v_writelane_b32 v255, s3, 49
	s_cmpk_gt_i32 s11, 0xff
	s_cbranch_scc1 .LBB0_536
	v_ashrrev_i32_e32 v204, 3, v2
	v_and_b32_e32 v205, 15, v2
	v_bfe_u32 v3, v2, 4, 2
	v_lshlrev_b32_e32 v0, 4, v2
	v_ashrrev_i32_e32 v4, 1, v2
	v_lshlrev_b32_e32 v2, 1, v2
	v_and_b32_e32 v0, 0x70, v0
	v_and_b32_e32 v206, 0xffffffc0, v4
	v_and_b32_e32 v2, 0x80, v2
	s_movk_i32 s2, 0x90
	v_or_b32_e32 v4, v206, v205
	v_or_b32_e32 v5, v2, v205
	v_and_b32_e32 v100, 7, v204
	v_lshlrev_b32_e32 v100, 4, v100
	v_xor_b32_e32 v100, v100, v0
	v_lshl_add_u32 v166, v204, 7, v100
	v_lshl_add_u64 v[162:163], s[18:19], 0, v[0:1]
	v_lshl_add_u64 v[164:165], s[50:51], 0, v[0:1]
	v_and_b32_e32 v100, 7, v205
	v_xor_b32_e32 v100, v100, v3
	v_lshlrev_b32_e32 v207, 4, v100
	v_lshl_or_b32 v208, v3, 2, v2
	v_lshlrev_b32_e32 v0, 7, v4
	v_lshlrev_b32_e32 v167, 7, v5
	v_readfirstlane_b32 s100, v172
	s_nop 0
	s_cmpk_ge_u32 s100, 0x100
	s_cbranch_scc0 .Lprio_skip_P3
	s_setprio 1
.Lprio_skip_P3:
.LBB0_533:
	s_ashr_i32 s4, s11, 31
	s_lshr_b32 s4, s4, 26
	s_add_i32 s4, s11, s4
	s_and_b32 s6, s4, 0xffffc0
	s_sub_i32 s6, s11, s6
	s_lshl_b32 s7, s6, 8
	v_add_u32_e32 v2, s7, v204
	v_mad_i64_i32 v[168:169], s[20:21], v2, s52, v[162:163]
	v_add_co_u32_e32 v56, vcc, 0x58000, v168
	s_lshl_b32 s4, s4, 2
	s_nop 0
	v_addc_co_u32_e32 v57, vcc, 0, v169, vcc
	v_add_co_u32_e32 v58, vcc, 0xb0000, v168
	s_and_b32 s6, s4, 0xffffff00
	s_nop 0
	v_addc_co_u32_e32 v59, vcc, 0, v169, vcc
	v_add_u32_e32 v2, s6, v204
	v_add_co_u32_e32 v60, vcc, 0x108000, v168
	v_mad_i64_i32 v[170:171], s[20:21], v2, s52, v[164:165]
	s_nop 0
	v_addc_co_u32_e32 v61, vcc, 0, v169, vcc
	v_add_co_u32_e32 v62, vcc, s92, v170
	global_load_dwordx4 v[24:27], v[56:57], off
	global_load_dwordx4 v[28:31], v[58:59], off
	v_addc_co_u32_e32 v63, vcc, 0, v171, vcc
	v_add_co_u32_e32 v64, vcc, s53, v170
	global_load_dwordx4 v[32:35], v[168:169], off
	global_load_dwordx4 v[36:39], v[170:171], off
	v_addc_co_u32_e32 v65, vcc, 0, v171, vcc
	v_add_co_u32_e32 v66, vcc, s8, v170
	global_load_dwordx4 v[40:43], v[60:61], off
	global_load_dwordx4 v[44:47], v[62:63], off
	v_addc_co_u32_e32 v67, vcc, 0, v171, vcc
	global_load_dwordx4 v[48:51], v[64:65], off
	global_load_dwordx4 v[52:55], v[66:67], off
	s_waitcnt lgkmcnt(0)
	s_barrier
	global_load_dwordx4 v[110:113], v[168:169], off offset:128
	global_load_dwordx4 v[102:105], v[56:57], off offset:128
	global_load_dwordx4 v[106:109], v[58:59], off offset:128
	global_load_dwordx4 v[122:125], v[60:61], off offset:128
	global_load_dwordx4 v[118:121], v[170:171], off offset:128
	global_load_dwordx4 v[114:117], v[62:63], off offset:128
	global_load_dwordx4 v[130:133], v[64:65], off offset:128
	global_load_dwordx4 v[126:129], v[66:67], off offset:128
	v_readfirstlane_b32 vcc_lo, v168
	v_readfirstlane_b32 vcc_hi, v169
	v_readfirstlane_b32 s100, v170
	v_readfirstlane_b32 s101, v171
	s_nop 1
	v_subrev_u32_e32 v168, vcc_lo, v168
	v_subrev_u32_e32 v170, s100, v170
	v_mov_b32_e32 v2, 0
	s_mov_b32 s4, 0
	v_mov_b32_e32 v3, v2
	v_mov_b32_e32 v4, v2
	v_mov_b32_e32 v5, v2
	v_mov_b32_e32 v6, v2
	v_mov_b32_e32 v7, v2
	v_mov_b32_e32 v8, v2
	v_mov_b32_e32 v9, v2
	v_mov_b32_e32 v10, v2
	v_mov_b32_e32 v11, v2
	v_mov_b32_e32 v12, v2
	v_mov_b32_e32 v13, v2
	v_mov_b32_e32 v14, v2
	v_mov_b32_e32 v15, v2
	v_mov_b32_e32 v16, v2
	v_mov_b32_e32 v17, v2
	v_mov_b32_e32 v18, v2
	v_mov_b32_e32 v19, v2
	v_mov_b32_e32 v20, v2
	v_mov_b32_e32 v21, v2
	v_mov_b32_e32 v22, v2
	v_mov_b32_e32 v23, v2
	v_mov_b32_e32 v56, v2
	v_mov_b32_e32 v57, v2
	v_mov_b32_e32 v58, v2
	v_mov_b32_e32 v59, v2
	v_mov_b32_e32 v60, v2
	v_mov_b32_e32 v61, v2
	v_mov_b32_e32 v62, v2
	v_mov_b32_e32 v63, v2
	v_mov_b32_e32 v64, v2
	v_mov_b32_e32 v65, v2
	v_mov_b32_e32 v66, v2
	v_mov_b32_e32 v67, v2
	v_mov_b32_e32 v68, v2
	v_mov_b32_e32 v69, v2
	v_mov_b32_e32 v70, v2
	v_mov_b32_e32 v71, v2
	v_mov_b32_e32 v72, v2
	v_mov_b32_e32 v73, v2
	v_mov_b32_e32 v74, v2
	v_mov_b32_e32 v75, v2
	v_mov_b32_e32 v76, v2
	v_mov_b32_e32 v77, v2
	v_mov_b32_e32 v78, v2
	v_mov_b32_e32 v79, v2
	v_mov_b32_e32 v80, v2
	v_mov_b32_e32 v81, v2
	v_mov_b32_e32 v82, v2
	v_mov_b32_e32 v83, v2
	v_mov_b32_e32 v84, v2
	v_mov_b32_e32 v85, v2
	s_waitcnt vmcnt(13)
	ds_write_b128 v166, v[32:35]
	s_waitcnt vmcnt(12)
	ds_write_b128 v166, v[36:39] offset:32768
	ds_write_b128 v166, v[24:27] offset:8192
	ds_write_b128 v166, v[28:31] offset:16384
	s_waitcnt vmcnt(11)
	ds_write_b128 v166, v[40:43] offset:24576
	s_waitcnt vmcnt(10)
	ds_write_b128 v166, v[44:47] offset:40960
	s_waitcnt vmcnt(9)
	ds_write_b128 v166, v[48:51] offset:49152
	s_waitcnt vmcnt(8)
	ds_write_b128 v166, v[52:55] offset:57344
	v_mov_b32_e32 v24, v2
	v_mov_b32_e32 v25, v2
	v_mov_b32_e32 v26, v2
	v_mov_b32_e32 v27, v2
	v_mov_b32_e32 v28, v2
	v_mov_b32_e32 v29, v2
	v_mov_b32_e32 v30, v2
	v_mov_b32_e32 v31, v2
	v_mov_b32_e32 v32, v2
	v_mov_b32_e32 v33, v2
	v_mov_b32_e32 v34, v2
	v_mov_b32_e32 v35, v2
	v_mov_b32_e32 v36, v2
	v_mov_b32_e32 v37, v2
	v_mov_b32_e32 v38, v2
	v_mov_b32_e32 v39, v2
	v_mov_b32_e32 v40, v2
	v_mov_b32_e32 v41, v2
	v_mov_b32_e32 v42, v2
	v_mov_b32_e32 v43, v2
	v_mov_b32_e32 v44, v2
	v_mov_b32_e32 v45, v2
	v_mov_b32_e32 v46, v2
	v_mov_b32_e32 v47, v2
	v_mov_b32_e32 v48, v2
	v_mov_b32_e32 v49, v2
	v_mov_b32_e32 v50, v2
	v_mov_b32_e32 v51, v2
	v_mov_b32_e32 v52, v2
	v_mov_b32_e32 v53, v2
	v_mov_b32_e32 v54, v2
	v_mov_b32_e32 v55, v2
	v_mov_b32_e32 v86, v2
	v_mov_b32_e32 v87, v2
	v_mov_b32_e32 v88, v2
	v_mov_b32_e32 v89, v2
	v_mov_b32_e32 v90, v2
	v_mov_b32_e32 v91, v2
	v_mov_b32_e32 v92, v2
	v_mov_b32_e32 v93, v2
	v_mov_b32_e32 v94, v2
	v_mov_b32_e32 v95, v2
	v_mov_b32_e32 v96, v2
	v_mov_b32_e32 v97, v2
	v_mov_b32_e32 v98, v2
	v_mov_b32_e32 v99, v2
	v_mov_b32_e32 v100, v2
	v_mov_b32_e32 v101, v2
	v_mov_b32_e32 v134, v2
	v_mov_b32_e32 v135, v2
	v_mov_b32_e32 v136, v2
	v_mov_b32_e32 v137, v2
	v_mov_b32_e32 v138, v2
	v_mov_b32_e32 v139, v2
	v_mov_b32_e32 v140, v2
	v_mov_b32_e32 v141, v2
	v_mov_b32_e32 v142, v2
	v_mov_b32_e32 v143, v2
	v_mov_b32_e32 v144, v2
	v_mov_b32_e32 v145, v2
	v_mov_b32_e32 v146, v2
	v_mov_b32_e32 v147, v2
	v_mov_b32_e32 v148, v2
	v_mov_b32_e32 v149, v2
	v_mov_b32_e32 v150, v2
	v_mov_b32_e32 v151, v2
	v_mov_b32_e32 v152, v2
	v_mov_b32_e32 v153, v2
	v_mov_b32_e32 v154, v2
	v_mov_b32_e32 v155, v2
	v_mov_b32_e32 v156, v2
	v_mov_b32_e32 v157, v2
	v_mov_b32_e32 v158, v2
	v_mov_b32_e32 v159, v2
	v_mov_b32_e32 v160, v2
	v_mov_b32_e32 v161, v2
	s_waitcnt lgkmcnt(0)
	s_barrier
.LBB0_534:
	s_bitcmp1_b32 s4, 0
	s_cselect_b32 s21, 0x12000, 0
	v_or_b32_e32 v218, s21, v207
	v_add_u32_e32 v214, v218, v0
	v_add_u32_e32 v246, v218, v167
	ds_read_b128 v[184:187], v214
	ds_read_b128 v[198:201], v214 offset:2048
	ds_read_b128 v[210:213], v214 offset:4096
	ds_read_b128 v[214:217], v214 offset:6144
	ds_read_b128 v[218:221], v246 offset:32768
	ds_read_b128 v[222:225], v246 offset:34816
	ds_read_b128 v[226:229], v246 offset:36864
	ds_read_b128 v[230:233], v246 offset:38912
	ds_read_b128 v[234:237], v246 offset:40960
	ds_read_b128 v[238:241], v246 offset:43008
	ds_read_b128 v[242:245], v246 offset:45056
	ds_read_b128 v[246:249], v246 offset:47104
	s_add_i32 s20, s4, 1
	s_bitcmp1_b32 s20, 0
	s_cselect_b32 s23, 0x12000, 0
	v_add_u32_e32 v171, s23, v166
	v_xor_b32_e32 v169, 64, v207
	v_add3_u32 v169, s21, v167, v169
	s_waitcnt lgkmcnt(7)
	v_mfma_f32_16x16x32_bf16 v[158:161], v[218:221], v[184:187], v[158:161]
	v_mfma_f32_16x16x32_bf16 v[94:97], v[218:221], v[198:201], v[94:97]
	v_mfma_f32_16x16x32_bf16 v[62:65], v[218:221], v[210:213], v[62:65]
	v_mfma_f32_16x16x32_bf16 v[30:33], v[218:221], v[214:217], v[30:33]
	ds_read_b128 v[218:221], v169 offset:32768
	s_waitcnt lgkmcnt(7)
	v_mfma_f32_16x16x32_bf16 v[154:157], v[222:225], v[184:187], v[154:157]
	v_mfma_f32_16x16x32_bf16 v[90:93], v[222:225], v[198:201], v[90:93]
	v_mfma_f32_16x16x32_bf16 v[58:61], v[222:225], v[210:213], v[58:61]
	v_mfma_f32_16x16x32_bf16 v[26:29], v[222:225], v[214:217], v[26:29]
	ds_read_b128 v[222:225], v169 offset:34816
	s_waitcnt lgkmcnt(7)
	v_mfma_f32_16x16x32_bf16 v[150:153], v[226:229], v[184:187], v[150:153]
	v_mfma_f32_16x16x32_bf16 v[86:89], v[226:229], v[198:201], v[86:89]
	v_mfma_f32_16x16x32_bf16 v[54:57], v[226:229], v[210:213], v[54:57]
	v_mfma_f32_16x16x32_bf16 v[22:25], v[226:229], v[214:217], v[22:25]
	ds_read_b128 v[226:229], v169 offset:36864
	s_waitcnt lgkmcnt(7)
	v_mfma_f32_16x16x32_bf16 v[146:149], v[230:233], v[184:187], v[146:149]
	v_mfma_f32_16x16x32_bf16 v[82:85], v[230:233], v[198:201], v[82:85]
	v_mfma_f32_16x16x32_bf16 v[50:53], v[230:233], v[210:213], v[50:53]
	v_mfma_f32_16x16x32_bf16 v[18:21], v[230:233], v[214:217], v[18:21]
	ds_read_b128 v[230:233], v169 offset:38912
	s_waitcnt lgkmcnt(7)
	v_mfma_f32_16x16x32_bf16 v[142:145], v[234:237], v[184:187], v[142:145]
	v_mfma_f32_16x16x32_bf16 v[78:81], v[234:237], v[198:201], v[78:81]
	v_mfma_f32_16x16x32_bf16 v[46:49], v[234:237], v[210:213], v[46:49]
	v_mfma_f32_16x16x32_bf16 v[14:17], v[234:237], v[214:217], v[14:17]
	ds_read_b128 v[234:237], v169 offset:40960
	s_waitcnt lgkmcnt(7)
	v_mfma_f32_16x16x32_bf16 v[138:141], v[238:241], v[184:187], v[138:141]
	v_mfma_f32_16x16x32_bf16 v[74:77], v[238:241], v[198:201], v[74:77]
	v_mfma_f32_16x16x32_bf16 v[42:45], v[238:241], v[210:213], v[42:45]
	v_mfma_f32_16x16x32_bf16 v[10:13], v[238:241], v[214:217], v[10:13]
	ds_read_b128 v[238:241], v169 offset:43008
	s_waitcnt lgkmcnt(7)
	v_mfma_f32_16x16x32_bf16 v[134:137], v[242:245], v[184:187], v[134:137]
	v_mfma_f32_16x16x32_bf16 v[70:73], v[242:245], v[198:201], v[70:73]
	v_mfma_f32_16x16x32_bf16 v[38:41], v[242:245], v[210:213], v[38:41]
	v_mfma_f32_16x16x32_bf16 v[6:9], v[242:245], v[214:217], v[6:9]
	ds_read_b128 v[242:245], v169 offset:45056
	s_waitcnt lgkmcnt(7)
	v_mfma_f32_16x16x32_bf16 v[98:101], v[246:249], v[184:187], v[98:101]
	v_mfma_f32_16x16x32_bf16 v[66:69], v[246:249], v[198:201], v[66:69]
	v_xor_b32_e32 v169, 64, v207
	v_add3_u32 v169, s21, v0, v169
	ds_read_b128 v[184:187], v169
	ds_read_b128 v[198:201], v169 offset:2048
	v_mfma_f32_16x16x32_bf16 v[34:37], v[246:249], v[210:213], v[34:37]
	ds_read_b128 v[210:213], v169 offset:4096
	v_mfma_f32_16x16x32_bf16 v[2:5], v[246:249], v[214:217], v[2:5]
	ds_read_b128 v[214:217], v169 offset:6144
	v_xor_b32_e32 v169, 64, v207
	v_add3_u32 v169, s21, v167, v169
	ds_read_b128 v[246:249], v169 offset:47104
	s_waitcnt lgkmcnt(1)
	v_mfma_f32_16x16x32_bf16 v[158:161], v[218:221], v[184:187], v[158:161]
	v_mfma_f32_16x16x32_bf16 v[94:97], v[218:221], v[198:201], v[94:97]
	v_mfma_f32_16x16x32_bf16 v[62:65], v[218:221], v[210:213], v[62:65]
	v_mfma_f32_16x16x32_bf16 v[30:33], v[218:221], v[214:217], v[30:33]
	s_waitcnt vmcnt(7)
	ds_write_b128 v171, v[110:113]
	v_mfma_f32_16x16x32_bf16 v[154:157], v[222:225], v[184:187], v[154:157]
	v_mfma_f32_16x16x32_bf16 v[90:93], v[222:225], v[198:201], v[90:93]
	global_load_dwordx4 v[110:113], v168, vcc offset:256
	v_mfma_f32_16x16x32_bf16 v[58:61], v[222:225], v[210:213], v[58:61]
	v_mfma_f32_16x16x32_bf16 v[26:29], v[222:225], v[214:217], v[26:29]
	s_waitcnt vmcnt(7)
	ds_write_b128 v171, v[102:105] offset:8192
	v_mfma_f32_16x16x32_bf16 v[150:153], v[226:229], v[184:187], v[150:153]
	v_mfma_f32_16x16x32_bf16 v[86:89], v[226:229], v[198:201], v[86:89]
	v_add_u32_e32 v102, 0x58000, v168
	global_load_dwordx4 v[102:105], v102, vcc offset:256
	v_mfma_f32_16x16x32_bf16 v[54:57], v[226:229], v[210:213], v[54:57]
	v_mfma_f32_16x16x32_bf16 v[22:25], v[226:229], v[214:217], v[22:25]
	s_waitcnt vmcnt(7)
	ds_write_b128 v171, v[106:109] offset:16384
	v_mfma_f32_16x16x32_bf16 v[146:149], v[230:233], v[184:187], v[146:149]
	v_mfma_f32_16x16x32_bf16 v[82:85], v[230:233], v[198:201], v[82:85]
	v_add_u32_e32 v106, 0xb0000, v168
	global_load_dwordx4 v[106:109], v106, vcc offset:256
	v_mfma_f32_16x16x32_bf16 v[50:53], v[230:233], v[210:213], v[50:53]
	v_mfma_f32_16x16x32_bf16 v[18:21], v[230:233], v[214:217], v[18:21]
	s_waitcnt vmcnt(7)
	ds_write_b128 v171, v[122:125] offset:24576
	v_mfma_f32_16x16x32_bf16 v[142:145], v[234:237], v[184:187], v[142:145]
	v_mfma_f32_16x16x32_bf16 v[78:81], v[234:237], v[198:201], v[78:81]
	v_add_u32_e32 v122, 0x108000, v168
	global_load_dwordx4 v[122:125], v122, vcc offset:256
	v_mfma_f32_16x16x32_bf16 v[46:49], v[234:237], v[210:213], v[46:49]
	v_mfma_f32_16x16x32_bf16 v[14:17], v[234:237], v[214:217], v[14:17]
	s_waitcnt vmcnt(7)
	ds_write_b128 v171, v[118:121] offset:32768
	v_mfma_f32_16x16x32_bf16 v[138:141], v[238:241], v[184:187], v[138:141]
	v_mfma_f32_16x16x32_bf16 v[74:77], v[238:241], v[198:201], v[74:77]
	global_load_dwordx4 v[118:121], v170, s[100:101] offset:256
	v_mfma_f32_16x16x32_bf16 v[42:45], v[238:241], v[210:213], v[42:45]
	v_mfma_f32_16x16x32_bf16 v[10:13], v[238:241], v[214:217], v[10:13]
	s_waitcnt vmcnt(7)
	ds_write_b128 v171, v[114:117] offset:40960
	v_mfma_f32_16x16x32_bf16 v[134:137], v[242:245], v[184:187], v[134:137]
	v_mfma_f32_16x16x32_bf16 v[70:73], v[242:245], v[198:201], v[70:73]
	v_add_u32_e32 v114, 0x58000, v170
	global_load_dwordx4 v[114:117], v114, s[100:101] offset:256
	v_mfma_f32_16x16x32_bf16 v[38:41], v[242:245], v[210:213], v[38:41]
	v_mfma_f32_16x16x32_bf16 v[6:9], v[242:245], v[214:217], v[6:9]
	s_waitcnt vmcnt(7)
	ds_write_b128 v171, v[130:133] offset:49152
	s_waitcnt lgkmcnt(7)
	v_mfma_f32_16x16x32_bf16 v[98:101], v[246:249], v[184:187], v[98:101]
	v_mfma_f32_16x16x32_bf16 v[66:69], v[246:249], v[198:201], v[66:69]
	v_add_u32_e32 v130, 0xb0000, v170
	global_load_dwordx4 v[130:133], v130, s[100:101] offset:256
	v_mfma_f32_16x16x32_bf16 v[34:37], v[246:249], v[210:213], v[34:37]
	v_mfma_f32_16x16x32_bf16 v[2:5], v[246:249], v[214:217], v[2:5]
	s_waitcnt vmcnt(7)
	ds_write_b128 v171, v[126:129] offset:57344
	v_add_u32_e32 v126, 0x108000, v170
	global_load_dwordx4 v[126:129], v126, s[100:101] offset:256
	v_add_u32_e32 v168, 0x80, v168
	v_add_u32_e32 v170, 0x80, v170
	s_waitcnt lgkmcnt(0)
	s_barrier
	s_cmp_eq_u32 s20, 44
	s_mov_b32 s4, s20
	s_cbranch_scc0 .LBB0_534
	s_waitcnt vmcnt(4)
	v_add_u32_e32 v102, s7, v206
	v_or_b32_e32 v104, v102, v205
	v_cmp_lt_i32_e32 vcc, s97, v104
	s_waitcnt vmcnt(3)
	v_ashrrev_i32_e32 v106, 31, v104
	v_add_u32_e32 v107, 0xffffc000, v104
	v_ashrrev_i32_e32 v105, 11, v102
	v_cndmask_b32_e64 v111, v106, 0, vcc
	v_cndmask_b32_e32 v110, v104, v107, vcc
	v_mov_b32_e32 v106, s45
	v_mov_b32_e32 v107, s47
	v_mov_b32_e32 v108, s44
	v_mov_b32_e32 v109, s46
	v_or_b32_e32 v102, s6, v208
	s_waitcnt vmcnt(2)
	v_cndmask_b32_e64 v114, v105, 8, vcc
	v_cndmask_b32_e32 v113, v106, v107, vcc
	v_cndmask_b32_e32 v112, v108, v109, vcc
	v_lshlrev_b64 v[122:123], 12, v[110:111]
	v_ashrrev_i32_e32 v103, 31, v102
	v_lshl_add_u64 v[110:111], v[112:113], 0, v[122:123]
	v_mul_hi_i32_i24_e32 v113, 0x9000, v114
	v_mul_i32_i24_e32 v112, 0x9000, v114
	v_lshl_add_u64 v[112:113], s[12:13], 0, v[112:113]
	v_lshlrev_b64 v[102:103], 2, v[102:103]
	s_waitcnt vmcnt(0)
	v_lshl_add_u64 v[124:125], v[112:113], 0, v[102:103]
	global_load_dwordx4 v[114:117], v[124:125], off
	s_waitcnt vmcnt(1)
	v_lshl_add_u64 v[126:127], v[110:111], 0, v[102:103]
	global_load_dwordx4 v[118:121], v[126:127], off
	v_mov_b32_e32 v110, s49
	v_mov_b32_e32 v111, s17
	v_mov_b32_e32 v112, s48
	v_mov_b32_e32 v113, s16
	v_cndmask_b32_e32 v129, v110, v111, vcc
	v_cndmask_b32_e32 v128, v112, v113, vcc
	v_lshl_add_u64 v[122:123], v[128:129], 0, v[122:123]
	v_lshl_add_u64 v[122:123], v[122:123], 0, v[102:103]
	s_waitcnt vmcnt(1)
	v_pk_mul_f32 v[114:115], v[114:115], 0.5 op_sel_hi:[1,0]
	v_pk_mul_f32 v[116:117], v[116:117], 0.5 op_sel_hi:[1,0]
	s_waitcnt vmcnt(0)
	v_pk_fma_f32 v[114:115], v[158:159], v[114:115], v[118:119]
	v_pk_fma_f32 v[116:117], v[160:161], v[116:117], v[120:121]
	global_store_dwordx4 v[122:123], v[114:117], off
	global_load_dwordx4 v[114:117], v[124:125], off offset:64
	s_nop 0
	global_load_dwordx4 v[118:121], v[126:127], off offset:64
	s_waitcnt vmcnt(1)
	v_pk_mul_f32 v[114:115], v[114:115], 0.5 op_sel_hi:[1,0]
	v_pk_mul_f32 v[116:117], v[116:117], 0.5 op_sel_hi:[1,0]
	s_waitcnt vmcnt(0)
	v_pk_fma_f32 v[114:115], v[154:155], v[114:115], v[118:119]
	v_pk_fma_f32 v[116:117], v[156:157], v[116:117], v[120:121]
	global_store_dwordx4 v[122:123], v[114:117], off offset:64
	global_load_dwordx4 v[114:117], v[124:125], off offset:128
	s_nop 0
	global_load_dwordx4 v[118:121], v[126:127], off offset:128
	s_waitcnt vmcnt(1)
	v_pk_mul_f32 v[114:115], v[114:115], 0.5 op_sel_hi:[1,0]
	v_pk_mul_f32 v[116:117], v[116:117], 0.5 op_sel_hi:[1,0]
	s_waitcnt vmcnt(0)
	v_pk_fma_f32 v[114:115], v[150:151], v[114:115], v[118:119]
	v_pk_fma_f32 v[116:117], v[152:153], v[116:117], v[120:121]
	global_store_dwordx4 v[122:123], v[114:117], off offset:128
	global_load_dwordx4 v[114:117], v[124:125], off offset:192
	s_nop 0
	global_load_dwordx4 v[118:121], v[126:127], off offset:192
	s_waitcnt vmcnt(1)
	v_pk_mul_f32 v[114:115], v[114:115], 0.5 op_sel_hi:[1,0]
	v_pk_mul_f32 v[116:117], v[116:117], 0.5 op_sel_hi:[1,0]
	s_waitcnt vmcnt(0)
	v_pk_fma_f32 v[114:115], v[146:147], v[114:115], v[118:119]
	v_pk_fma_f32 v[116:117], v[148:149], v[116:117], v[120:121]
	global_store_dwordx4 v[122:123], v[114:117], off offset:192
	global_load_dwordx4 v[114:117], v[124:125], off offset:256
	s_nop 0
	global_load_dwordx4 v[118:121], v[126:127], off offset:256
	s_waitcnt vmcnt(1)
	v_pk_mul_f32 v[114:115], v[114:115], 0.5 op_sel_hi:[1,0]
	v_pk_mul_f32 v[116:117], v[116:117], 0.5 op_sel_hi:[1,0]
	s_waitcnt vmcnt(0)
	v_pk_fma_f32 v[114:115], v[142:143], v[114:115], v[118:119]
	v_pk_fma_f32 v[116:117], v[144:145], v[116:117], v[120:121]
	global_store_dwordx4 v[122:123], v[114:117], off offset:256
	global_load_dwordx4 v[114:117], v[124:125], off offset:320
	s_nop 0
	global_load_dwordx4 v[118:121], v[126:127], off offset:320
	s_waitcnt vmcnt(1)
	v_pk_mul_f32 v[114:115], v[114:115], 0.5 op_sel_hi:[1,0]
	v_pk_mul_f32 v[116:117], v[116:117], 0.5 op_sel_hi:[1,0]
	s_waitcnt vmcnt(0)
	v_pk_fma_f32 v[114:115], v[138:139], v[114:115], v[118:119]
	v_pk_fma_f32 v[116:117], v[140:141], v[116:117], v[120:121]
	global_store_dwordx4 v[122:123], v[114:117], off offset:320
	global_load_dwordx4 v[114:117], v[124:125], off offset:384
	s_nop 0
	global_load_dwordx4 v[118:121], v[126:127], off offset:384
	s_waitcnt vmcnt(1)
	v_pk_mul_f32 v[114:115], v[114:115], 0.5 op_sel_hi:[1,0]
	v_pk_mul_f32 v[116:117], v[116:117], 0.5 op_sel_hi:[1,0]
	s_waitcnt vmcnt(0)
	v_pk_fma_f32 v[114:115], v[134:135], v[114:115], v[118:119]
	v_pk_fma_f32 v[116:117], v[136:137], v[116:117], v[120:121]
	global_store_dwordx4 v[122:123], v[114:117], off offset:384
	global_load_dwordx4 v[114:117], v[124:125], off offset:448
	s_nop 0
	global_load_dwordx4 v[118:121], v[126:127], off offset:448
	s_waitcnt vmcnt(1)
	v_pk_mul_f32 v[114:115], v[114:115], 0.5 op_sel_hi:[1,0]
	v_pk_mul_f32 v[116:117], v[116:117], 0.5 op_sel_hi:[1,0]
	s_waitcnt vmcnt(0)
	v_pk_fma_f32 v[98:99], v[98:99], v[114:115], v[118:119]
	v_pk_fma_f32 v[100:101], v[100:101], v[116:117], v[120:121]
	global_store_dwordx4 v[122:123], v[98:101], off offset:448
	s_nop 1
	v_or_b32_e32 v98, 16, v104
	v_cmp_lt_i32_e32 vcc, s97, v98
	v_add_u32_e32 v100, 0xffffc010, v104
	v_ashrrev_i32_e32 v99, 31, v98
	v_cndmask_b32_e64 v116, v105, 8, vcc
	v_cndmask_b32_e64 v99, v99, 0, vcc
	v_cndmask_b32_e32 v98, v98, v100, vcc
	v_lshlrev_b64 v[118:119], 12, v[98:99]
	v_mul_hi_i32_i24_e32 v99, 0x9000, v116
	v_mul_i32_i24_e32 v98, 0x9000, v116
	v_cndmask_b32_e32 v101, v106, v107, vcc
	v_cndmask_b32_e32 v100, v108, v109, vcc
	v_lshl_add_u64 v[98:99], s[12:13], 0, v[98:99]
	v_lshl_add_u64 v[114:115], v[100:101], 0, v[118:119]
	v_lshl_add_u64 v[120:121], v[98:99], 0, v[102:103]
	global_load_dwordx4 v[98:101], v[120:121], off
	v_lshl_add_u64 v[122:123], v[114:115], 0, v[102:103]
	global_load_dwordx4 v[114:117], v[122:123], off
	v_cndmask_b32_e32 v125, v110, v111, vcc
	v_cndmask_b32_e32 v124, v112, v113, vcc
	v_lshl_add_u64 v[118:119], v[124:125], 0, v[118:119]
	v_lshl_add_u64 v[118:119], v[118:119], 0, v[102:103]
	s_waitcnt vmcnt(1)
	v_pk_mul_f32 v[98:99], v[98:99], 0.5 op_sel_hi:[1,0]
	v_pk_mul_f32 v[100:101], v[100:101], 0.5 op_sel_hi:[1,0]
	s_waitcnt vmcnt(0)
	v_pk_fma_f32 v[94:95], v[94:95], v[98:99], v[114:115]
	v_pk_fma_f32 v[96:97], v[96:97], v[100:101], v[116:117]
	global_store_dwordx4 v[118:119], v[94:97], off
	global_load_dwordx4 v[94:97], v[120:121], off offset:64
	s_nop 0
	global_load_dwordx4 v[98:101], v[122:123], off offset:64
	s_waitcnt vmcnt(1)
	v_pk_mul_f32 v[94:95], v[94:95], 0.5 op_sel_hi:[1,0]
	v_pk_mul_f32 v[96:97], v[96:97], 0.5 op_sel_hi:[1,0]
	s_waitcnt vmcnt(0)
	v_pk_fma_f32 v[90:91], v[90:91], v[94:95], v[98:99]
	v_pk_fma_f32 v[92:93], v[92:93], v[96:97], v[100:101]
	global_store_dwordx4 v[118:119], v[90:93], off offset:64
	global_load_dwordx4 v[90:93], v[120:121], off offset:128
	s_nop 0
	global_load_dwordx4 v[94:97], v[122:123], off offset:128
	s_waitcnt vmcnt(1)
	v_pk_mul_f32 v[90:91], v[90:91], 0.5 op_sel_hi:[1,0]
	v_pk_mul_f32 v[92:93], v[92:93], 0.5 op_sel_hi:[1,0]
	s_waitcnt vmcnt(0)
	v_pk_fma_f32 v[86:87], v[86:87], v[90:91], v[94:95]
	v_pk_fma_f32 v[88:89], v[88:89], v[92:93], v[96:97]
	global_store_dwordx4 v[118:119], v[86:89], off offset:128
	global_load_dwordx4 v[86:89], v[120:121], off offset:192
	s_nop 0
	global_load_dwordx4 v[90:93], v[122:123], off offset:192
	s_waitcnt vmcnt(1)
	v_pk_mul_f32 v[86:87], v[86:87], 0.5 op_sel_hi:[1,0]
	v_pk_mul_f32 v[88:89], v[88:89], 0.5 op_sel_hi:[1,0]
	s_waitcnt vmcnt(0)
	v_pk_fma_f32 v[82:83], v[82:83], v[86:87], v[90:91]
	v_pk_fma_f32 v[84:85], v[84:85], v[88:89], v[92:93]
	global_store_dwordx4 v[118:119], v[82:85], off offset:192
	global_load_dwordx4 v[82:85], v[120:121], off offset:256
	s_nop 0
	global_load_dwordx4 v[86:89], v[122:123], off offset:256
	s_waitcnt vmcnt(1)
	v_pk_mul_f32 v[82:83], v[82:83], 0.5 op_sel_hi:[1,0]
	v_pk_mul_f32 v[84:85], v[84:85], 0.5 op_sel_hi:[1,0]
	s_waitcnt vmcnt(0)
	v_pk_fma_f32 v[78:79], v[78:79], v[82:83], v[86:87]
	v_pk_fma_f32 v[80:81], v[80:81], v[84:85], v[88:89]
	global_store_dwordx4 v[118:119], v[78:81], off offset:256
	global_load_dwordx4 v[78:81], v[120:121], off offset:320
	s_nop 0
	global_load_dwordx4 v[82:85], v[122:123], off offset:320
	s_waitcnt vmcnt(1)
	v_pk_mul_f32 v[78:79], v[78:79], 0.5 op_sel_hi:[1,0]
	v_pk_mul_f32 v[80:81], v[80:81], 0.5 op_sel_hi:[1,0]
	s_waitcnt vmcnt(0)
	v_pk_fma_f32 v[74:75], v[74:75], v[78:79], v[82:83]
	v_pk_fma_f32 v[76:77], v[76:77], v[80:81], v[84:85]
	global_store_dwordx4 v[118:119], v[74:77], off offset:320
	global_load_dwordx4 v[74:77], v[120:121], off offset:384
	s_nop 0
	global_load_dwordx4 v[78:81], v[122:123], off offset:384
	s_waitcnt vmcnt(1)
	v_pk_mul_f32 v[74:75], v[74:75], 0.5 op_sel_hi:[1,0]
	v_pk_mul_f32 v[76:77], v[76:77], 0.5 op_sel_hi:[1,0]
	s_waitcnt vmcnt(0)
	v_pk_fma_f32 v[70:71], v[70:71], v[74:75], v[78:79]
	v_pk_fma_f32 v[72:73], v[72:73], v[76:77], v[80:81]
	global_store_dwordx4 v[118:119], v[70:73], off offset:384
	global_load_dwordx4 v[70:73], v[120:121], off offset:448
	s_nop 0
	global_load_dwordx4 v[74:77], v[122:123], off offset:448
	s_waitcnt vmcnt(1)
	v_pk_mul_f32 v[70:71], v[70:71], 0.5 op_sel_hi:[1,0]
	v_pk_mul_f32 v[72:73], v[72:73], 0.5 op_sel_hi:[1,0]
	s_waitcnt vmcnt(0)
	v_pk_fma_f32 v[66:67], v[66:67], v[70:71], v[74:75]
	v_pk_fma_f32 v[68:69], v[68:69], v[72:73], v[76:77]
	global_store_dwordx4 v[118:119], v[66:69], off offset:448
	s_nop 1
	v_or_b32_e32 v66, 32, v104
	v_cmp_lt_i32_e32 vcc, s97, v66
	v_add_u32_e32 v68, 0xffffc020, v104
	v_ashrrev_i32_e32 v67, 31, v66
	v_cndmask_b32_e64 v72, v105, 8, vcc
	v_cndmask_b32_e64 v67, v67, 0, vcc
	v_cndmask_b32_e32 v66, v66, v68, vcc
	v_lshlrev_b64 v[74:75], 12, v[66:67]
	v_mul_hi_i32_i24_e32 v67, 0x9000, v72
	v_mul_i32_i24_e32 v66, 0x9000, v72
	v_cndmask_b32_e32 v69, v106, v107, vcc
	v_cndmask_b32_e32 v68, v108, v109, vcc
	v_lshl_add_u64 v[66:67], s[12:13], 0, v[66:67]
	v_lshl_add_u64 v[70:71], v[68:69], 0, v[74:75]
	v_lshl_add_u64 v[76:77], v[66:67], 0, v[102:103]
	global_load_dwordx4 v[66:69], v[76:77], off
	v_lshl_add_u64 v[78:79], v[70:71], 0, v[102:103]
	global_load_dwordx4 v[70:73], v[78:79], off
	v_cndmask_b32_e32 v81, v110, v111, vcc
	v_cndmask_b32_e32 v80, v112, v113, vcc
	v_lshl_add_u64 v[74:75], v[80:81], 0, v[74:75]
	v_lshl_add_u64 v[74:75], v[74:75], 0, v[102:103]
	s_waitcnt vmcnt(1)
	v_pk_mul_f32 v[66:67], v[66:67], 0.5 op_sel_hi:[1,0]
	v_pk_mul_f32 v[68:69], v[68:69], 0.5 op_sel_hi:[1,0]
	s_waitcnt vmcnt(0)
	v_pk_fma_f32 v[62:63], v[62:63], v[66:67], v[70:71]
	v_pk_fma_f32 v[64:65], v[64:65], v[68:69], v[72:73]
	global_store_dwordx4 v[74:75], v[62:65], off
	global_load_dwordx4 v[62:65], v[76:77], off offset:64
	s_nop 0
	global_load_dwordx4 v[66:69], v[78:79], off offset:64
	s_waitcnt vmcnt(1)
	v_pk_mul_f32 v[62:63], v[62:63], 0.5 op_sel_hi:[1,0]
	v_pk_mul_f32 v[64:65], v[64:65], 0.5 op_sel_hi:[1,0]
	s_waitcnt vmcnt(0)
	v_pk_fma_f32 v[58:59], v[58:59], v[62:63], v[66:67]
	v_pk_fma_f32 v[60:61], v[60:61], v[64:65], v[68:69]
	global_store_dwordx4 v[74:75], v[58:61], off offset:64
	global_load_dwordx4 v[58:61], v[76:77], off offset:128
	s_nop 0
	global_load_dwordx4 v[62:65], v[78:79], off offset:128
	s_waitcnt vmcnt(1)
	v_pk_mul_f32 v[58:59], v[58:59], 0.5 op_sel_hi:[1,0]
	v_pk_mul_f32 v[60:61], v[60:61], 0.5 op_sel_hi:[1,0]
	s_waitcnt vmcnt(0)
	v_pk_fma_f32 v[54:55], v[54:55], v[58:59], v[62:63]
	v_pk_fma_f32 v[56:57], v[56:57], v[60:61], v[64:65]
	global_store_dwordx4 v[74:75], v[54:57], off offset:128
	global_load_dwordx4 v[54:57], v[76:77], off offset:192
	s_nop 0
	global_load_dwordx4 v[58:61], v[78:79], off offset:192
	s_waitcnt vmcnt(1)
	v_pk_mul_f32 v[54:55], v[54:55], 0.5 op_sel_hi:[1,0]
	v_pk_mul_f32 v[56:57], v[56:57], 0.5 op_sel_hi:[1,0]
	s_waitcnt vmcnt(0)
	v_pk_fma_f32 v[50:51], v[50:51], v[54:55], v[58:59]
	v_pk_fma_f32 v[52:53], v[52:53], v[56:57], v[60:61]
	global_store_dwordx4 v[74:75], v[50:53], off offset:192
	global_load_dwordx4 v[50:53], v[76:77], off offset:256
	s_nop 0
	global_load_dwordx4 v[54:57], v[78:79], off offset:256
	s_waitcnt vmcnt(1)
	v_pk_mul_f32 v[50:51], v[50:51], 0.5 op_sel_hi:[1,0]
	v_pk_mul_f32 v[52:53], v[52:53], 0.5 op_sel_hi:[1,0]
	s_waitcnt vmcnt(0)
	v_pk_fma_f32 v[46:47], v[46:47], v[50:51], v[54:55]
	v_pk_fma_f32 v[48:49], v[48:49], v[52:53], v[56:57]
	global_store_dwordx4 v[74:75], v[46:49], off offset:256
	global_load_dwordx4 v[46:49], v[76:77], off offset:320
	s_nop 0
	global_load_dwordx4 v[50:53], v[78:79], off offset:320
	s_waitcnt vmcnt(1)
	v_pk_mul_f32 v[46:47], v[46:47], 0.5 op_sel_hi:[1,0]
	v_pk_mul_f32 v[48:49], v[48:49], 0.5 op_sel_hi:[1,0]
	s_waitcnt vmcnt(0)
	v_pk_fma_f32 v[42:43], v[42:43], v[46:47], v[50:51]
	v_pk_fma_f32 v[44:45], v[44:45], v[48:49], v[52:53]
	global_store_dwordx4 v[74:75], v[42:45], off offset:320
	global_load_dwordx4 v[42:45], v[76:77], off offset:384
	s_nop 0
	global_load_dwordx4 v[46:49], v[78:79], off offset:384
	s_waitcnt vmcnt(1)
	v_pk_mul_f32 v[42:43], v[42:43], 0.5 op_sel_hi:[1,0]
	v_pk_mul_f32 v[44:45], v[44:45], 0.5 op_sel_hi:[1,0]
	s_waitcnt vmcnt(0)
	v_pk_fma_f32 v[38:39], v[38:39], v[42:43], v[46:47]
	v_pk_fma_f32 v[40:41], v[40:41], v[44:45], v[48:49]
	global_store_dwordx4 v[74:75], v[38:41], off offset:384
	global_load_dwordx4 v[38:41], v[76:77], off offset:448
	s_nop 0
	global_load_dwordx4 v[42:45], v[78:79], off offset:448
	s_waitcnt vmcnt(1)
	v_pk_mul_f32 v[38:39], v[38:39], 0.5 op_sel_hi:[1,0]
	v_pk_mul_f32 v[40:41], v[40:41], 0.5 op_sel_hi:[1,0]
	s_waitcnt vmcnt(0)
	v_pk_fma_f32 v[34:35], v[34:35], v[38:39], v[42:43]
	v_pk_fma_f32 v[36:37], v[36:37], v[40:41], v[44:45]
	global_store_dwordx4 v[74:75], v[34:37], off offset:448
	s_nop 1
	v_or_b32_e32 v34, 48, v104
	v_cmp_lt_i32_e32 vcc, s97, v34
	v_add_u32_e32 v36, 0xffffc030, v104
	v_ashrrev_i32_e32 v35, 31, v34
	v_cndmask_b32_e64 v35, v35, 0, vcc
	v_cndmask_b32_e32 v34, v34, v36, vcc
	v_cndmask_b32_e64 v40, v105, 8, vcc
	v_cndmask_b32_e32 v37, v106, v107, vcc
	v_cndmask_b32_e32 v36, v108, v109, vcc
	v_lshlrev_b64 v[34:35], 12, v[34:35]
	v_cndmask_b32_e32 v39, v110, v111, vcc
	v_cndmask_b32_e32 v38, v112, v113, vcc
	v_lshl_add_u64 v[36:37], v[36:37], 0, v[34:35]
	v_lshl_add_u64 v[34:35], v[38:39], 0, v[34:35]
	v_mul_hi_i32_i24_e32 v39, 0x9000, v40
	v_mul_i32_i24_e32 v38, 0x9000, v40
	v_lshl_add_u64 v[38:39], s[12:13], 0, v[38:39]
	v_lshl_add_u64 v[42:43], v[38:39], 0, v[102:103]
	v_lshl_add_u64 v[44:45], v[36:37], 0, v[102:103]
	v_lshl_add_u64 v[46:47], v[34:35], 0, v[102:103]
	global_load_dwordx4 v[34:37], v[42:43], off
	global_load_dwordx4 v[38:41], v[44:45], off
	s_waitcnt vmcnt(1)
	v_pk_mul_f32 v[34:35], v[34:35], 0.5 op_sel_hi:[1,0]
	s_waitcnt vmcnt(0)
	v_pk_fma_f32 v[30:31], v[30:31], v[34:35], v[38:39]
	v_pk_mul_f32 v[34:35], v[36:37], 0.5 op_sel_hi:[1,0]
	s_nop 0
	v_pk_fma_f32 v[32:33], v[32:33], v[34:35], v[40:41]
	global_store_dwordx4 v[46:47], v[30:33], off
	global_load_dwordx4 v[30:33], v[42:43], off offset:64
	s_nop 0
	global_load_dwordx4 v[34:37], v[44:45], off offset:64
	s_waitcnt vmcnt(1)
	v_pk_mul_f32 v[30:31], v[30:31], 0.5 op_sel_hi:[1,0]
	s_waitcnt vmcnt(0)
	v_pk_fma_f32 v[26:27], v[26:27], v[30:31], v[34:35]
	v_pk_mul_f32 v[30:31], v[32:33], 0.5 op_sel_hi:[1,0]
	s_nop 0
	v_pk_fma_f32 v[28:29], v[28:29], v[30:31], v[36:37]
	global_store_dwordx4 v[46:47], v[26:29], off offset:64
	global_load_dwordx4 v[26:29], v[42:43], off offset:128
	s_nop 0
	global_load_dwordx4 v[30:33], v[44:45], off offset:128
	s_waitcnt vmcnt(1)
	v_pk_mul_f32 v[26:27], v[26:27], 0.5 op_sel_hi:[1,0]
	s_waitcnt vmcnt(0)
	v_pk_fma_f32 v[22:23], v[22:23], v[26:27], v[30:31]
	v_pk_mul_f32 v[26:27], v[28:29], 0.5 op_sel_hi:[1,0]
	s_nop 0
	v_pk_fma_f32 v[24:25], v[24:25], v[26:27], v[32:33]
	global_store_dwordx4 v[46:47], v[22:25], off offset:128
	global_load_dwordx4 v[22:25], v[42:43], off offset:192
	s_nop 0
	global_load_dwordx4 v[26:29], v[44:45], off offset:192
	s_waitcnt vmcnt(1)
	v_pk_mul_f32 v[22:23], v[22:23], 0.5 op_sel_hi:[1,0]
	s_waitcnt vmcnt(0)
	v_pk_fma_f32 v[18:19], v[18:19], v[22:23], v[26:27]
	v_pk_mul_f32 v[22:23], v[24:25], 0.5 op_sel_hi:[1,0]
	s_nop 0
	v_pk_fma_f32 v[20:21], v[20:21], v[22:23], v[28:29]
	global_store_dwordx4 v[46:47], v[18:21], off offset:192
	global_load_dwordx4 v[18:21], v[42:43], off offset:256
	s_nop 0
	global_load_dwordx4 v[22:25], v[44:45], off offset:256
	s_waitcnt vmcnt(1)
	v_pk_mul_f32 v[18:19], v[18:19], 0.5 op_sel_hi:[1,0]
	s_waitcnt vmcnt(0)
	v_pk_fma_f32 v[14:15], v[14:15], v[18:19], v[22:23]
	v_pk_mul_f32 v[18:19], v[20:21], 0.5 op_sel_hi:[1,0]
	s_nop 0
	v_pk_fma_f32 v[16:17], v[16:17], v[18:19], v[24:25]
	global_store_dwordx4 v[46:47], v[14:17], off offset:256
	global_load_dwordx4 v[14:17], v[42:43], off offset:320
	s_nop 0
	global_load_dwordx4 v[18:21], v[44:45], off offset:320
	s_waitcnt vmcnt(1)
	v_pk_mul_f32 v[14:15], v[14:15], 0.5 op_sel_hi:[1,0]
	s_waitcnt vmcnt(0)
	v_pk_fma_f32 v[10:11], v[10:11], v[14:15], v[18:19]
	v_pk_mul_f32 v[14:15], v[16:17], 0.5 op_sel_hi:[1,0]
	s_nop 0
	v_pk_fma_f32 v[12:13], v[12:13], v[14:15], v[20:21]
	global_store_dwordx4 v[46:47], v[10:13], off offset:320
	global_load_dwordx4 v[10:13], v[42:43], off offset:384
	s_nop 0
	global_load_dwordx4 v[14:17], v[44:45], off offset:384
	s_waitcnt vmcnt(1)
	v_pk_mul_f32 v[10:11], v[10:11], 0.5 op_sel_hi:[1,0]
	s_waitcnt vmcnt(0)
	v_pk_fma_f32 v[6:7], v[6:7], v[10:11], v[14:15]
	v_pk_mul_f32 v[10:11], v[12:13], 0.5 op_sel_hi:[1,0]
	s_nop 0
	v_pk_fma_f32 v[8:9], v[8:9], v[10:11], v[16:17]
	global_store_dwordx4 v[46:47], v[6:9], off offset:384
	global_load_dwordx4 v[6:9], v[42:43], off offset:448
	s_nop 0
	global_load_dwordx4 v[10:13], v[44:45], off offset:448
	s_waitcnt vmcnt(1)
	v_pk_mul_f32 v[6:7], v[6:7], 0.5 op_sel_hi:[1,0]
	s_waitcnt vmcnt(0)
	v_pk_fma_f32 v[2:3], v[2:3], v[6:7], v[10:11]
	v_pk_mul_f32 v[6:7], v[8:9], 0.5 op_sel_hi:[1,0]
	s_nop 0
	v_pk_fma_f32 v[4:5], v[4:5], v[6:7], v[12:13]
	global_store_dwordx4 v[46:47], v[2:5], off offset:448
	s_add_i32 s11, s11, s10
	s_cmpk_gt_i32 s11, 0xff
	s_cbranch_scc0 .LBB0_533
	s_setprio 0

.LBB0_662:
	s_or_b64 exec, exec, s[12:13]
	s_mov_b64 s[12:13], s[60:61]
	s_waitcnt lgkmcnt(0)
	v_mov_b32_e32 v2, v172
	s_mov_b32 s10, s42
	s_mov_b32 s11, s94
	s_barrier
	s_cmpk_lt_i32 s11, 0x3f0
	s_mov_b32 s42, 0xffff0000
	s_mov_b32 s94, 0x3f200000
	s_cbranch_scc0 .LBB0_667
	s_load_dwordx2 s[6:7], s[12:13], 0x130
	v_lshlrev_b32_e32 v0, 4, v2
	v_and_b32_e32 v0, 0x70, v0
	s_mov_b64 s[2:3], 0x3200000
	v_ashrrev_i32_e32 v204, 3, v2
	s_waitcnt lgkmcnt(0)
	s_add_u32 s12, s6, 0x6035800
	s_addc_u32 s13, s7, 0
	v_lshl_add_u64 v[4:5], s[6:7], 0, v[0:1]
	s_mov_b64 s[6:7], 0x2100000
	v_bfe_u32 v3, v2, 4, 2
	v_and_b32_e32 v6, 15, v2
	v_lshl_add_u64 v[162:163], v[4:5], 0, s[2:3]
	v_lshl_add_u64 v[164:165], v[4:5], 0, s[6:7]
	v_ashrrev_i32_e32 v4, 1, v2
	s_movk_i32 s2, 0xffc0
	v_lshlrev_b32_e32 v2, 1, v2
	v_and_or_b32 v205, v4, s2, v6
	v_and_b32_e32 v2, 0x80, v2
	s_movk_i32 s2, 0x90
	v_or_b32_e32 v4, v2, v6
	v_and_b32_e32 v100, 7, v204
	v_lshlrev_b32_e32 v100, 4, v100
	v_xor_b32_e32 v100, v100, v0
	v_lshl_add_u32 v166, v204, 7, v100
	v_and_b32_e32 v100, 7, v6
	v_xor_b32_e32 v100, v100, v3
	v_lshlrev_b32_e32 v206, 4, v100
	v_lshl_or_b32 v207, v3, 2, v2
	v_lshlrev_b32_e32 v0, 7, v205
	v_lshlrev_b32_e32 v167, 7, v4
	v_readfirstlane_b32 s100, v172
	s_nop 0
	s_cmpk_ge_u32 s100, 0x100
	s_cbranch_scc0 .Lprio_skip_P5
	s_setprio 1
.Lprio_skip_P5:
.LBB0_664:
	s_mul_hi_i32 s4, s11, 0x38e38e39
	s_lshr_b32 s6, s4, 31
	s_ashr_i32 s4, s4, 4
	s_add_i32 s4, s4, s6
	s_mul_i32 s6, s4, 0x48
	s_sub_i32 s6, s11, s6
	s_lshl_b32 s6, s6, 8
	v_add_u32_e32 v2, s6, v204
	v_ashrrev_i32_e32 v3, 31, v2
	v_lshlrev_b64 v[2:3], 11, v[2:3]
	v_lshl_add_u64 v[168:169], v[162:163], 0, v[2:3]
	v_add_co_u32_e32 v56, vcc, s34, v168
	s_lshl_b32 s7, s4, 8
	s_nop 0
	v_addc_co_u32_e32 v57, vcc, 0, v169, vcc
	v_add_u32_e32 v2, s7, v204
	v_add_co_u32_e32 v58, vcc, s35, v168
	v_ashrrev_i32_e32 v3, 31, v2
	s_nop 0
	v_addc_co_u32_e32 v59, vcc, 0, v169, vcc
	v_lshlrev_b64 v[2:3], 11, v[2:3]
	v_add_co_u32_e32 v60, vcc, s36, v168
	v_lshl_add_u64 v[170:171], v[164:165], 0, v[2:3]
	s_nop 0
	v_addc_co_u32_e32 v61, vcc, 0, v169, vcc
	v_add_co_u32_e32 v62, vcc, s35, v170
	global_load_dwordx4 v[24:27], v[56:57], off
	global_load_dwordx4 v[28:31], v[58:59], off
	v_addc_co_u32_e32 v63, vcc, 0, v171, vcc
	v_add_co_u32_e32 v64, vcc, s36, v170
	global_load_dwordx4 v[32:35], v[168:169], off
	global_load_dwordx4 v[36:39], v[170:171], off
	v_addc_co_u32_e32 v65, vcc, 0, v171, vcc
	v_add_co_u32_e32 v66, vcc, s34, v170
	global_load_dwordx4 v[40:43], v[62:63], off
	global_load_dwordx4 v[44:47], v[64:65], off
	v_addc_co_u32_e32 v67, vcc, 0, v171, vcc
	global_load_dwordx4 v[48:51], v[60:61], off
	global_load_dwordx4 v[52:55], v[66:67], off
	s_barrier
	global_load_dwordx4 v[94:97], v[168:169], off offset:128
	global_load_dwordx4 v[86:89], v[56:57], off offset:128
	global_load_dwordx4 v[90:93], v[58:59], off offset:128
	global_load_dwordx4 v[106:109], v[60:61], off offset:128
	global_load_dwordx4 v[102:105], v[170:171], off offset:128
	global_load_dwordx4 v[98:101], v[66:67], off offset:128
	global_load_dwordx4 v[118:121], v[62:63], off offset:128
	global_load_dwordx4 v[110:113], v[64:65], off offset:128
	v_readfirstlane_b32 vcc_lo, v168
	v_readfirstlane_b32 vcc_hi, v169
	v_readfirstlane_b32 s100, v170
	v_readfirstlane_b32 s101, v171
	s_nop 1
	v_subrev_u32_e32 v168, vcc_lo, v168
	v_subrev_u32_e32 v170, s100, v170
	v_mov_b32_e32 v2, 0
	s_mov_b32 s4, 0
	v_mov_b32_e32 v3, v2
	v_mov_b32_e32 v4, v2
	v_mov_b32_e32 v5, v2
	v_mov_b32_e32 v6, v2
	v_mov_b32_e32 v7, v2
	v_mov_b32_e32 v8, v2
	v_mov_b32_e32 v9, v2
	v_mov_b32_e32 v10, v2
	v_mov_b32_e32 v11, v2
	v_mov_b32_e32 v12, v2
	v_mov_b32_e32 v13, v2
	v_mov_b32_e32 v14, v2
	v_mov_b32_e32 v15, v2
	v_mov_b32_e32 v16, v2
	v_mov_b32_e32 v17, v2
	v_mov_b32_e32 v18, v2
	v_mov_b32_e32 v19, v2
	v_mov_b32_e32 v20, v2
	v_mov_b32_e32 v21, v2
	v_mov_b32_e32 v22, v2
	v_mov_b32_e32 v23, v2
	v_mov_b32_e32 v56, v2
	v_mov_b32_e32 v57, v2
	v_mov_b32_e32 v58, v2
	v_mov_b32_e32 v59, v2
	v_mov_b32_e32 v60, v2
	v_mov_b32_e32 v61, v2
	v_mov_b32_e32 v66, v2
	v_mov_b32_e32 v67, v2
	v_mov_b32_e32 v68, v2
	v_mov_b32_e32 v69, v2
	v_mov_b32_e32 v62, v2
	v_mov_b32_e32 v63, v2
	v_mov_b32_e32 v64, v2
	v_mov_b32_e32 v65, v2
	v_mov_b32_e32 v70, v2
	v_mov_b32_e32 v71, v2
	v_mov_b32_e32 v72, v2
	v_mov_b32_e32 v73, v2
	v_mov_b32_e32 v74, v2
	v_mov_b32_e32 v75, v2
	v_mov_b32_e32 v76, v2
	v_mov_b32_e32 v77, v2
	v_mov_b32_e32 v78, v2
	v_mov_b32_e32 v79, v2
	v_mov_b32_e32 v80, v2
	v_mov_b32_e32 v81, v2
	v_mov_b32_e32 v82, v2
	v_mov_b32_e32 v83, v2
	v_mov_b32_e32 v84, v2
	v_mov_b32_e32 v85, v2
	s_waitcnt vmcnt(11)
	ds_write_b128 v166, v[40:43] offset:49152
	s_waitcnt vmcnt(10)
	ds_write_b128 v166, v[44:47] offset:57344
	ds_write_b128 v166, v[32:35]
	ds_write_b128 v166, v[36:39] offset:32768
	ds_write_b128 v166, v[24:27] offset:8192
	ds_write_b128 v166, v[28:31] offset:16384
	s_waitcnt vmcnt(9)
	ds_write_b128 v166, v[48:51] offset:24576
	s_waitcnt vmcnt(8)
	ds_write_b128 v166, v[52:55] offset:40960
	v_mov_b32_e32 v24, v2
	v_mov_b32_e32 v25, v2
	v_mov_b32_e32 v26, v2
	v_mov_b32_e32 v27, v2
	v_mov_b32_e32 v28, v2
	v_mov_b32_e32 v29, v2
	v_mov_b32_e32 v34, v2
	v_mov_b32_e32 v35, v2
	v_mov_b32_e32 v36, v2
	v_mov_b32_e32 v37, v2
	v_mov_b32_e32 v30, v2
	v_mov_b32_e32 v31, v2
	v_mov_b32_e32 v32, v2
	v_mov_b32_e32 v33, v2
	v_mov_b32_e32 v38, v2
	v_mov_b32_e32 v39, v2
	v_mov_b32_e32 v40, v2
	v_mov_b32_e32 v41, v2
	v_mov_b32_e32 v42, v2
	v_mov_b32_e32 v43, v2
	v_mov_b32_e32 v44, v2
	v_mov_b32_e32 v45, v2
	v_mov_b32_e32 v46, v2
	v_mov_b32_e32 v47, v2
	v_mov_b32_e32 v48, v2
	v_mov_b32_e32 v49, v2
	v_mov_b32_e32 v50, v2
	v_mov_b32_e32 v51, v2
	v_mov_b32_e32 v52, v2
	v_mov_b32_e32 v53, v2
	v_mov_b32_e32 v54, v2
	v_mov_b32_e32 v55, v2
	v_mov_b32_e32 v114, v2
	v_mov_b32_e32 v115, v2
	v_mov_b32_e32 v116, v2
	v_mov_b32_e32 v117, v2
	v_mov_b32_e32 v122, v2
	v_mov_b32_e32 v123, v2
	v_mov_b32_e32 v124, v2
	v_mov_b32_e32 v125, v2
	v_mov_b32_e32 v130, v2
	v_mov_b32_e32 v131, v2
	v_mov_b32_e32 v132, v2
	v_mov_b32_e32 v133, v2
	v_mov_b32_e32 v126, v2
	v_mov_b32_e32 v127, v2
	v_mov_b32_e32 v128, v2
	v_mov_b32_e32 v129, v2
	v_mov_b32_e32 v134, v2
	v_mov_b32_e32 v135, v2
	v_mov_b32_e32 v136, v2
	v_mov_b32_e32 v137, v2
	v_mov_b32_e32 v138, v2
	v_mov_b32_e32 v139, v2
	v_mov_b32_e32 v140, v2
	v_mov_b32_e32 v141, v2
	v_mov_b32_e32 v142, v2
	v_mov_b32_e32 v143, v2
	v_mov_b32_e32 v144, v2
	v_mov_b32_e32 v145, v2
	v_mov_b32_e32 v146, v2
	v_mov_b32_e32 v147, v2
	v_mov_b32_e32 v148, v2
	v_mov_b32_e32 v149, v2
	v_mov_b32_e32 v150, v2
	v_mov_b32_e32 v151, v2
	v_mov_b32_e32 v152, v2
	v_mov_b32_e32 v153, v2
	v_mov_b32_e32 v154, v2
	v_mov_b32_e32 v155, v2
	v_mov_b32_e32 v156, v2
	v_mov_b32_e32 v157, v2
	v_mov_b32_e32 v158, v2
	v_mov_b32_e32 v159, v2
	v_mov_b32_e32 v160, v2
	v_mov_b32_e32 v161, v2
	s_waitcnt lgkmcnt(0)
	s_barrier
.LBB0_665:
	s_bitcmp1_b32 s4, 0
	s_cselect_b32 s15, 0x12000, 0
	v_or_b32_e32 v208, s15, v206
	v_add_u32_e32 v214, v208, v0
	v_add_u32_e32 v208, v208, v167
	ds_read_b128 v[184:187], v214
	ds_read_b128 v[198:201], v214 offset:2048
	ds_read_b128 v[210:213], v214 offset:4096
	ds_read_b128 v[214:217], v214 offset:6144
	ds_read_b128 v[218:221], v208 offset:32768
	ds_read_b128 v[222:225], v208 offset:34816
	ds_read_b128 v[226:229], v208 offset:36864
	ds_read_b128 v[230:233], v208 offset:38912
	ds_read_b128 v[234:237], v208 offset:40960
	ds_read_b128 v[238:241], v208 offset:43008
	ds_read_b128 v[242:245], v208 offset:45056
	ds_read_b128 v[246:249], v208 offset:47104
	s_add_i32 s14, s4, 1
	s_bitcmp1_b32 s14, 0
	s_cselect_b32 s16, 0x12000, 0
	v_add_u32_e32 v208, s16, v166
	v_add_u32_e32 v171, s16, v166
	v_xor_b32_e32 v169, 64, v206
	v_add3_u32 v169, s15, v167, v169
	s_waitcnt lgkmcnt(7)
	v_mfma_f32_16x16x32_bf16 v[158:161], v[218:221], v[184:187], v[158:161]
	v_mfma_f32_16x16x32_bf16 v[130:133], v[218:221], v[198:201], v[130:133]
	v_mfma_f32_16x16x32_bf16 v[66:69], v[218:221], v[210:213], v[66:69]
	v_mfma_f32_16x16x32_bf16 v[34:37], v[218:221], v[214:217], v[34:37]
	ds_read_b128 v[218:221], v169 offset:32768
	s_waitcnt lgkmcnt(7)
	v_mfma_f32_16x16x32_bf16 v[154:157], v[222:225], v[184:187], v[154:157]
	v_mfma_f32_16x16x32_bf16 v[122:125], v[222:225], v[198:201], v[122:125]
	v_mfma_f32_16x16x32_bf16 v[58:61], v[222:225], v[210:213], v[58:61]
	v_mfma_f32_16x16x32_bf16 v[26:29], v[222:225], v[214:217], v[26:29]
	ds_read_b128 v[222:225], v169 offset:34816
	s_waitcnt lgkmcnt(7)
	v_mfma_f32_16x16x32_bf16 v[150:153], v[226:229], v[184:187], v[150:153]
	v_mfma_f32_16x16x32_bf16 v[114:117], v[226:229], v[198:201], v[114:117]
	v_mfma_f32_16x16x32_bf16 v[54:57], v[226:229], v[210:213], v[54:57]
	v_mfma_f32_16x16x32_bf16 v[22:25], v[226:229], v[214:217], v[22:25]
	ds_read_b128 v[226:229], v169 offset:36864
	s_waitcnt lgkmcnt(7)
	v_mfma_f32_16x16x32_bf16 v[146:149], v[230:233], v[184:187], v[146:149]
	v_mfma_f32_16x16x32_bf16 v[82:85], v[230:233], v[198:201], v[82:85]
	v_mfma_f32_16x16x32_bf16 v[50:53], v[230:233], v[210:213], v[50:53]
	v_mfma_f32_16x16x32_bf16 v[18:21], v[230:233], v[214:217], v[18:21]
	ds_read_b128 v[230:233], v169 offset:38912
	s_waitcnt lgkmcnt(7)
	v_mfma_f32_16x16x32_bf16 v[142:145], v[234:237], v[184:187], v[142:145]
	v_mfma_f32_16x16x32_bf16 v[78:81], v[234:237], v[198:201], v[78:81]
	v_mfma_f32_16x16x32_bf16 v[46:49], v[234:237], v[210:213], v[46:49]
	v_mfma_f32_16x16x32_bf16 v[14:17], v[234:237], v[214:217], v[14:17]
	ds_read_b128 v[234:237], v169 offset:40960
	s_waitcnt lgkmcnt(7)
	v_mfma_f32_16x16x32_bf16 v[138:141], v[238:241], v[184:187], v[138:141]
	v_mfma_f32_16x16x32_bf16 v[74:77], v[238:241], v[198:201], v[74:77]
	v_mfma_f32_16x16x32_bf16 v[42:45], v[238:241], v[210:213], v[42:45]
	v_mfma_f32_16x16x32_bf16 v[10:13], v[238:241], v[214:217], v[10:13]
	ds_read_b128 v[238:241], v169 offset:43008
	s_waitcnt lgkmcnt(7)
	v_mfma_f32_16x16x32_bf16 v[134:137], v[242:245], v[184:187], v[134:137]
	v_mfma_f32_16x16x32_bf16 v[70:73], v[242:245], v[198:201], v[70:73]
	v_mfma_f32_16x16x32_bf16 v[38:41], v[242:245], v[210:213], v[38:41]
	v_mfma_f32_16x16x32_bf16 v[6:9], v[242:245], v[214:217], v[6:9]
	ds_read_b128 v[242:245], v169 offset:45056
	s_waitcnt lgkmcnt(7)
	v_mfma_f32_16x16x32_bf16 v[126:129], v[246:249], v[184:187], v[126:129]
	v_mfma_f32_16x16x32_bf16 v[62:65], v[246:249], v[198:201], v[62:65]
	v_xor_b32_e32 v169, 64, v206
	v_add3_u32 v169, s15, v0, v169
	ds_read_b128 v[184:187], v169
	ds_read_b128 v[198:201], v169 offset:2048
	v_mfma_f32_16x16x32_bf16 v[30:33], v[246:249], v[210:213], v[30:33]
	ds_read_b128 v[210:213], v169 offset:4096
	v_mfma_f32_16x16x32_bf16 v[2:5], v[246:249], v[214:217], v[2:5]
	ds_read_b128 v[214:217], v169 offset:6144
	v_xor_b32_e32 v169, 64, v206
	v_add3_u32 v169, s15, v167, v169
	ds_read_b128 v[246:249], v169 offset:47104
	s_waitcnt lgkmcnt(1)
	v_mfma_f32_16x16x32_bf16 v[158:161], v[218:221], v[184:187], v[158:161]
	v_mfma_f32_16x16x32_bf16 v[130:133], v[218:221], v[198:201], v[130:133]
	v_mfma_f32_16x16x32_bf16 v[66:69], v[218:221], v[210:213], v[66:69]
	v_mfma_f32_16x16x32_bf16 v[34:37], v[218:221], v[214:217], v[34:37]
	s_waitcnt vmcnt(7)
	ds_write_b128 v171, v[94:97]
	v_mfma_f32_16x16x32_bf16 v[154:157], v[222:225], v[184:187], v[154:157]
	v_mfma_f32_16x16x32_bf16 v[122:125], v[222:225], v[198:201], v[122:125]
	global_load_dwordx4 v[94:97], v168, vcc offset:256
	v_mfma_f32_16x16x32_bf16 v[58:61], v[222:225], v[210:213], v[58:61]
	v_mfma_f32_16x16x32_bf16 v[26:29], v[222:225], v[214:217], v[26:29]
	s_waitcnt vmcnt(7)
	ds_write_b128 v171, v[86:89] offset:8192
	v_mfma_f32_16x16x32_bf16 v[150:153], v[226:229], v[184:187], v[150:153]
	v_mfma_f32_16x16x32_bf16 v[114:117], v[226:229], v[198:201], v[114:117]
	v_add_u32_e32 v86, s34, v168
	global_load_dwordx4 v[86:89], v86, vcc offset:256
	v_mfma_f32_16x16x32_bf16 v[54:57], v[226:229], v[210:213], v[54:57]
	v_mfma_f32_16x16x32_bf16 v[22:25], v[226:229], v[214:217], v[22:25]
	s_waitcnt vmcnt(7)
	ds_write_b128 v171, v[90:93] offset:16384
	v_mfma_f32_16x16x32_bf16 v[146:149], v[230:233], v[184:187], v[146:149]
	v_mfma_f32_16x16x32_bf16 v[82:85], v[230:233], v[198:201], v[82:85]
	v_add_u32_e32 v90, s35, v168
	global_load_dwordx4 v[90:93], v90, vcc offset:256
	v_mfma_f32_16x16x32_bf16 v[50:53], v[230:233], v[210:213], v[50:53]
	v_mfma_f32_16x16x32_bf16 v[18:21], v[230:233], v[214:217], v[18:21]
	s_waitcnt vmcnt(7)
	ds_write_b128 v171, v[106:109] offset:24576
	v_mfma_f32_16x16x32_bf16 v[142:145], v[234:237], v[184:187], v[142:145]
	v_mfma_f32_16x16x32_bf16 v[78:81], v[234:237], v[198:201], v[78:81]
	v_add_u32_e32 v106, s36, v168
	global_load_dwordx4 v[106:109], v106, vcc offset:256
	v_mfma_f32_16x16x32_bf16 v[46:49], v[234:237], v[210:213], v[46:49]
	v_mfma_f32_16x16x32_bf16 v[14:17], v[234:237], v[214:217], v[14:17]
	s_waitcnt vmcnt(7)
	ds_write_b128 v171, v[102:105] offset:32768
	v_mfma_f32_16x16x32_bf16 v[138:141], v[238:241], v[184:187], v[138:141]
	v_mfma_f32_16x16x32_bf16 v[74:77], v[238:241], v[198:201], v[74:77]
	global_load_dwordx4 v[102:105], v170, s[100:101] offset:256
	v_mfma_f32_16x16x32_bf16 v[42:45], v[238:241], v[210:213], v[42:45]
	v_mfma_f32_16x16x32_bf16 v[10:13], v[238:241], v[214:217], v[10:13]
	s_waitcnt vmcnt(7)
	ds_write_b128 v171, v[98:101] offset:40960
	v_mfma_f32_16x16x32_bf16 v[134:137], v[242:245], v[184:187], v[134:137]
	v_mfma_f32_16x16x32_bf16 v[70:73], v[242:245], v[198:201], v[70:73]
	v_add_u32_e32 v98, s34, v170
	global_load_dwordx4 v[98:101], v98, s[100:101] offset:256
	v_mfma_f32_16x16x32_bf16 v[38:41], v[242:245], v[210:213], v[38:41]
	v_mfma_f32_16x16x32_bf16 v[6:9], v[242:245], v[214:217], v[6:9]
	s_waitcnt vmcnt(7)
	ds_write_b128 v171, v[118:121] offset:49152
	s_waitcnt lgkmcnt(7)
	v_mfma_f32_16x16x32_bf16 v[126:129], v[246:249], v[184:187], v[126:129]
	v_mfma_f32_16x16x32_bf16 v[62:65], v[246:249], v[198:201], v[62:65]
	v_add_u32_e32 v118, s35, v170
	global_load_dwordx4 v[118:121], v118, s[100:101] offset:256
	v_mfma_f32_16x16x32_bf16 v[30:33], v[246:249], v[210:213], v[30:33]
	v_mfma_f32_16x16x32_bf16 v[2:5], v[246:249], v[214:217], v[2:5]
	s_waitcnt vmcnt(7)
	ds_write_b128 v171, v[110:113] offset:57344
	v_add_u32_e32 v110, s36, v170
	global_load_dwordx4 v[110:113], v110, s[100:101] offset:256
	v_add_u32_e32 v168, 0x80, v168
	v_add_u32_e32 v170, 0x80, v170
	s_waitcnt lgkmcnt(0)
	s_barrier
	s_cmp_eq_u32 s14, 16
	s_mov_b32 s4, s14
	s_cbranch_scc0 .LBB0_665
	s_waitcnt vmcnt(3)
	v_and_b32_sdwa v93, v158, v177 dst_sel:DWORD dst_unused:UNUSED_PAD src0_sel:WORD_1 src1_sel:DWORD
	v_or_b32_e32 v88, s7, v207
	v_add3_u32 v95, v158, v93, s28
	v_and_b32_sdwa v93, v161, v177 dst_sel:DWORD dst_unused:UNUSED_PAD src0_sel:WORD_1 src1_sel:DWORD
	v_and_b32_sdwa v96, v159, v177 dst_sel:DWORD dst_unused:UNUSED_PAD src0_sel:WORD_1 src1_sel:DWORD
	v_add_u32_e32 v94, s6, v205
	v_mov_b64_e32 v[86:87], s[12:13]
	v_ashrrev_i32_e32 v89, 31, v88
	v_and_b32_sdwa v92, v160, v177 dst_sel:DWORD dst_unused:UNUSED_PAD src0_sel:WORD_1 src1_sel:DWORD
	v_add3_u32 v93, v161, v93, s28
	v_add3_u32 v96, v159, v96, s28
	v_mad_i64_i32 v[90:91], s[6:7], v94, s8, v[86:87]
	v_lshlrev_b64 v[88:89], 1, v[88:89]
	v_add3_u32 v92, v160, v92, s28
	v_and_b32_e32 v93, 0xffff0000, v93
	v_and_b32_e32 v96, 0xffff0000, v96
	v_lshl_add_u64 v[90:91], v[90:91], 0, v[88:89]
	v_or_b32_sdwa v93, v93, v92 dst_sel:DWORD dst_unused:UNUSED_PAD src0_sel:DWORD src1_sel:WORD_1
	v_or_b32_sdwa v92, v96, v95 dst_sel:DWORD dst_unused:UNUSED_PAD src0_sel:DWORD src1_sel:WORD_1
	s_waitcnt vmcnt(0)
	global_store_dwordx2 v[90:91], v[92:93], off
	v_and_b32_sdwa v93, v154, v177 dst_sel:DWORD dst_unused:UNUSED_PAD src0_sel:WORD_1 src1_sel:DWORD
	v_add3_u32 v95, v154, v93, s28
	v_and_b32_sdwa v93, v157, v177 dst_sel:DWORD dst_unused:UNUSED_PAD src0_sel:WORD_1 src1_sel:DWORD
	v_and_b32_sdwa v96, v155, v177 dst_sel:DWORD dst_unused:UNUSED_PAD src0_sel:WORD_1 src1_sel:DWORD
	v_and_b32_sdwa v92, v156, v177 dst_sel:DWORD dst_unused:UNUSED_PAD src0_sel:WORD_1 src1_sel:DWORD
	v_add3_u32 v93, v157, v93, s28
	v_add3_u32 v96, v155, v96, s28
	v_add3_u32 v92, v156, v92, s28
	v_and_b32_e32 v93, 0xffff0000, v93
	v_and_b32_e32 v96, 0xffff0000, v96
	v_or_b32_sdwa v93, v93, v92 dst_sel:DWORD dst_unused:UNUSED_PAD src0_sel:DWORD src1_sel:WORD_1
	v_or_b32_sdwa v92, v96, v95 dst_sel:DWORD dst_unused:UNUSED_PAD src0_sel:DWORD src1_sel:WORD_1
	global_store_dwordx2 v[90:91], v[92:93], off offset:32
	v_and_b32_sdwa v93, v150, v177 dst_sel:DWORD dst_unused:UNUSED_PAD src0_sel:WORD_1 src1_sel:DWORD
	v_add3_u32 v95, v150, v93, s28
	v_and_b32_sdwa v93, v153, v177 dst_sel:DWORD dst_unused:UNUSED_PAD src0_sel:WORD_1 src1_sel:DWORD
	v_and_b32_sdwa v96, v151, v177 dst_sel:DWORD dst_unused:UNUSED_PAD src0_sel:WORD_1 src1_sel:DWORD
	v_and_b32_sdwa v92, v152, v177 dst_sel:DWORD dst_unused:UNUSED_PAD src0_sel:WORD_1 src1_sel:DWORD
	v_add3_u32 v93, v153, v93, s28
	v_add3_u32 v96, v151, v96, s28
	v_add3_u32 v92, v152, v92, s28
	v_and_b32_e32 v93, 0xffff0000, v93
	v_and_b32_e32 v96, 0xffff0000, v96
	v_or_b32_sdwa v93, v93, v92 dst_sel:DWORD dst_unused:UNUSED_PAD src0_sel:DWORD src1_sel:WORD_1
	v_or_b32_sdwa v92, v96, v95 dst_sel:DWORD dst_unused:UNUSED_PAD src0_sel:DWORD src1_sel:WORD_1
	global_store_dwordx2 v[90:91], v[92:93], off offset:64
	v_and_b32_sdwa v93, v146, v177 dst_sel:DWORD dst_unused:UNUSED_PAD src0_sel:WORD_1 src1_sel:DWORD
	v_add3_u32 v95, v146, v93, s28
	v_and_b32_sdwa v93, v149, v177 dst_sel:DWORD dst_unused:UNUSED_PAD src0_sel:WORD_1 src1_sel:DWORD
	v_and_b32_sdwa v96, v147, v177 dst_sel:DWORD dst_unused:UNUSED_PAD src0_sel:WORD_1 src1_sel:DWORD
	v_and_b32_sdwa v92, v148, v177 dst_sel:DWORD dst_unused:UNUSED_PAD src0_sel:WORD_1 src1_sel:DWORD
	v_add3_u32 v93, v149, v93, s28
	v_add3_u32 v96, v147, v96, s28
	v_add3_u32 v92, v148, v92, s28
	v_and_b32_e32 v93, 0xffff0000, v93
	v_and_b32_e32 v96, 0xffff0000, v96
	v_or_b32_sdwa v93, v93, v92 dst_sel:DWORD dst_unused:UNUSED_PAD src0_sel:DWORD src1_sel:WORD_1
	v_or_b32_sdwa v92, v96, v95 dst_sel:DWORD dst_unused:UNUSED_PAD src0_sel:DWORD src1_sel:WORD_1
	global_store_dwordx2 v[90:91], v[92:93], off offset:96
	v_and_b32_sdwa v93, v142, v177 dst_sel:DWORD dst_unused:UNUSED_PAD src0_sel:WORD_1 src1_sel:DWORD
	v_add3_u32 v95, v142, v93, s28
	v_and_b32_sdwa v93, v145, v177 dst_sel:DWORD dst_unused:UNUSED_PAD src0_sel:WORD_1 src1_sel:DWORD
	v_and_b32_sdwa v96, v143, v177 dst_sel:DWORD dst_unused:UNUSED_PAD src0_sel:WORD_1 src1_sel:DWORD
	v_and_b32_sdwa v92, v144, v177 dst_sel:DWORD dst_unused:UNUSED_PAD src0_sel:WORD_1 src1_sel:DWORD
	v_add3_u32 v93, v145, v93, s28
	v_add3_u32 v96, v143, v96, s28
	v_add3_u32 v92, v144, v92, s28
	v_and_b32_e32 v93, 0xffff0000, v93
	v_and_b32_e32 v96, 0xffff0000, v96
	v_or_b32_sdwa v93, v93, v92 dst_sel:DWORD dst_unused:UNUSED_PAD src0_sel:DWORD src1_sel:WORD_1
	v_or_b32_sdwa v92, v96, v95 dst_sel:DWORD dst_unused:UNUSED_PAD src0_sel:DWORD src1_sel:WORD_1
	global_store_dwordx2 v[90:91], v[92:93], off offset:128
	v_and_b32_sdwa v93, v138, v177 dst_sel:DWORD dst_unused:UNUSED_PAD src0_sel:WORD_1 src1_sel:DWORD
	v_add3_u32 v95, v138, v93, s28
	v_and_b32_sdwa v93, v141, v177 dst_sel:DWORD dst_unused:UNUSED_PAD src0_sel:WORD_1 src1_sel:DWORD
	v_and_b32_sdwa v96, v139, v177 dst_sel:DWORD dst_unused:UNUSED_PAD src0_sel:WORD_1 src1_sel:DWORD
	v_and_b32_sdwa v92, v140, v177 dst_sel:DWORD dst_unused:UNUSED_PAD src0_sel:WORD_1 src1_sel:DWORD
	v_add3_u32 v93, v141, v93, s28
	v_add3_u32 v96, v139, v96, s28
	v_add3_u32 v92, v140, v92, s28
	v_and_b32_e32 v93, 0xffff0000, v93
	v_and_b32_e32 v96, 0xffff0000, v96
	v_or_b32_sdwa v93, v93, v92 dst_sel:DWORD dst_unused:UNUSED_PAD src0_sel:DWORD src1_sel:WORD_1
	v_or_b32_sdwa v92, v96, v95 dst_sel:DWORD dst_unused:UNUSED_PAD src0_sel:DWORD src1_sel:WORD_1
	global_store_dwordx2 v[90:91], v[92:93], off offset:160
	v_and_b32_sdwa v93, v134, v177 dst_sel:DWORD dst_unused:UNUSED_PAD src0_sel:WORD_1 src1_sel:DWORD
	v_add3_u32 v95, v134, v93, s28
	v_and_b32_sdwa v93, v137, v177 dst_sel:DWORD dst_unused:UNUSED_PAD src0_sel:WORD_1 src1_sel:DWORD
	v_and_b32_sdwa v96, v135, v177 dst_sel:DWORD dst_unused:UNUSED_PAD src0_sel:WORD_1 src1_sel:DWORD
	v_and_b32_sdwa v92, v136, v177 dst_sel:DWORD dst_unused:UNUSED_PAD src0_sel:WORD_1 src1_sel:DWORD
	v_add3_u32 v93, v137, v93, s28
	v_add3_u32 v96, v135, v96, s28
	v_add3_u32 v92, v136, v92, s28
	v_and_b32_e32 v93, 0xffff0000, v93
	v_and_b32_e32 v96, 0xffff0000, v96
	v_or_b32_sdwa v93, v93, v92 dst_sel:DWORD dst_unused:UNUSED_PAD src0_sel:DWORD src1_sel:WORD_1
	v_or_b32_sdwa v92, v96, v95 dst_sel:DWORD dst_unused:UNUSED_PAD src0_sel:DWORD src1_sel:WORD_1
	global_store_dwordx2 v[90:91], v[92:93], off offset:192
	v_and_b32_sdwa v93, v126, v177 dst_sel:DWORD dst_unused:UNUSED_PAD src0_sel:WORD_1 src1_sel:DWORD
	v_add3_u32 v95, v126, v93, s28
	v_and_b32_sdwa v93, v129, v177 dst_sel:DWORD dst_unused:UNUSED_PAD src0_sel:WORD_1 src1_sel:DWORD
	v_and_b32_sdwa v96, v127, v177 dst_sel:DWORD dst_unused:UNUSED_PAD src0_sel:WORD_1 src1_sel:DWORD
	v_and_b32_sdwa v92, v128, v177 dst_sel:DWORD dst_unused:UNUSED_PAD src0_sel:WORD_1 src1_sel:DWORD
	v_add3_u32 v93, v129, v93, s28
	v_add3_u32 v96, v127, v96, s28
	v_add3_u32 v92, v128, v92, s28
	v_and_b32_e32 v93, 0xffff0000, v93
	v_and_b32_e32 v96, 0xffff0000, v96
	v_or_b32_sdwa v93, v93, v92 dst_sel:DWORD dst_unused:UNUSED_PAD src0_sel:DWORD src1_sel:WORD_1
	v_or_b32_sdwa v92, v96, v95 dst_sel:DWORD dst_unused:UNUSED_PAD src0_sel:DWORD src1_sel:WORD_1
	global_store_dwordx2 v[90:91], v[92:93], off offset:224
	v_and_b32_sdwa v93, v130, v177 dst_sel:DWORD dst_unused:UNUSED_PAD src0_sel:WORD_1 src1_sel:DWORD
	v_add3_u32 v95, v130, v93, s28
	v_and_b32_sdwa v93, v133, v177 dst_sel:DWORD dst_unused:UNUSED_PAD src0_sel:WORD_1 src1_sel:DWORD
	v_and_b32_sdwa v96, v131, v177 dst_sel:DWORD dst_unused:UNUSED_PAD src0_sel:WORD_1 src1_sel:DWORD
	v_or_b32_e32 v90, 16, v94
	v_and_b32_sdwa v92, v132, v177 dst_sel:DWORD dst_unused:UNUSED_PAD src0_sel:WORD_1 src1_sel:DWORD
	v_add3_u32 v93, v133, v93, s28
	v_add3_u32 v96, v131, v96, s28
	v_mad_i64_i32 v[90:91], s[6:7], v90, s8, v[86:87]
	v_add3_u32 v92, v132, v92, s28
	v_and_b32_e32 v93, 0xffff0000, v93
	v_and_b32_e32 v96, 0xffff0000, v96
	v_lshl_add_u64 v[90:91], v[90:91], 0, v[88:89]
	v_or_b32_sdwa v93, v93, v92 dst_sel:DWORD dst_unused:UNUSED_PAD src0_sel:DWORD src1_sel:WORD_1
	v_or_b32_sdwa v92, v96, v95 dst_sel:DWORD dst_unused:UNUSED_PAD src0_sel:DWORD src1_sel:WORD_1
	global_store_dwordx2 v[90:91], v[92:93], off
	v_and_b32_sdwa v93, v122, v177 dst_sel:DWORD dst_unused:UNUSED_PAD src0_sel:WORD_1 src1_sel:DWORD
	v_add3_u32 v95, v122, v93, s28
	v_and_b32_sdwa v93, v125, v177 dst_sel:DWORD dst_unused:UNUSED_PAD src0_sel:WORD_1 src1_sel:DWORD
	v_and_b32_sdwa v96, v123, v177 dst_sel:DWORD dst_unused:UNUSED_PAD src0_sel:WORD_1 src1_sel:DWORD
	v_and_b32_sdwa v92, v124, v177 dst_sel:DWORD dst_unused:UNUSED_PAD src0_sel:WORD_1 src1_sel:DWORD
	v_add3_u32 v93, v125, v93, s28
	v_add3_u32 v96, v123, v96, s28
	v_add3_u32 v92, v124, v92, s28
	v_and_b32_e32 v93, 0xffff0000, v93
	v_and_b32_e32 v96, 0xffff0000, v96
	v_or_b32_sdwa v93, v93, v92 dst_sel:DWORD dst_unused:UNUSED_PAD src0_sel:DWORD src1_sel:WORD_1
	v_or_b32_sdwa v92, v96, v95 dst_sel:DWORD dst_unused:UNUSED_PAD src0_sel:DWORD src1_sel:WORD_1
	global_store_dwordx2 v[90:91], v[92:93], off offset:32
	v_and_b32_sdwa v93, v114, v177 dst_sel:DWORD dst_unused:UNUSED_PAD src0_sel:WORD_1 src1_sel:DWORD
	v_add3_u32 v95, v114, v93, s28
	v_and_b32_sdwa v93, v117, v177 dst_sel:DWORD dst_unused:UNUSED_PAD src0_sel:WORD_1 src1_sel:DWORD
	v_and_b32_sdwa v96, v115, v177 dst_sel:DWORD dst_unused:UNUSED_PAD src0_sel:WORD_1 src1_sel:DWORD
	v_and_b32_sdwa v92, v116, v177 dst_sel:DWORD dst_unused:UNUSED_PAD src0_sel:WORD_1 src1_sel:DWORD
	v_add3_u32 v93, v117, v93, s28
	v_add3_u32 v96, v115, v96, s28
	v_add3_u32 v92, v116, v92, s28
	v_and_b32_e32 v93, 0xffff0000, v93
	v_and_b32_e32 v96, 0xffff0000, v96
	v_or_b32_sdwa v93, v93, v92 dst_sel:DWORD dst_unused:UNUSED_PAD src0_sel:DWORD src1_sel:WORD_1
	v_or_b32_sdwa v92, v96, v95 dst_sel:DWORD dst_unused:UNUSED_PAD src0_sel:DWORD src1_sel:WORD_1
	global_store_dwordx2 v[90:91], v[92:93], off offset:64
	v_and_b32_sdwa v92, v84, v177 dst_sel:DWORD dst_unused:UNUSED_PAD src0_sel:WORD_1 src1_sel:DWORD
	v_and_b32_sdwa v93, v82, v177 dst_sel:DWORD dst_unused:UNUSED_PAD src0_sel:WORD_1 src1_sel:DWORD
	v_add3_u32 v82, v82, v93, s28
	v_add3_u32 v84, v84, v92, s28
	v_and_b32_sdwa v92, v85, v177 dst_sel:DWORD dst_unused:UNUSED_PAD src0_sel:WORD_1 src1_sel:DWORD
	v_and_b32_sdwa v93, v83, v177 dst_sel:DWORD dst_unused:UNUSED_PAD src0_sel:WORD_1 src1_sel:DWORD
	v_add3_u32 v85, v85, v92, s28
	v_add3_u32 v83, v83, v93, s28
	v_and_b32_e32 v85, 0xffff0000, v85
	v_and_b32_e32 v92, 0xffff0000, v83
	v_or_b32_sdwa v83, v85, v84 dst_sel:DWORD dst_unused:UNUSED_PAD src0_sel:DWORD src1_sel:WORD_1
	v_or_b32_sdwa v82, v92, v82 dst_sel:DWORD dst_unused:UNUSED_PAD src0_sel:DWORD src1_sel:WORD_1
	global_store_dwordx2 v[90:91], v[82:83], off offset:96
	v_and_b32_sdwa v82, v80, v177 dst_sel:DWORD dst_unused:UNUSED_PAD src0_sel:WORD_1 src1_sel:DWORD
	v_and_b32_sdwa v83, v78, v177 dst_sel:DWORD dst_unused:UNUSED_PAD src0_sel:WORD_1 src1_sel:DWORD
	v_add3_u32 v78, v78, v83, s28
	v_add3_u32 v80, v80, v82, s28
	v_and_b32_sdwa v82, v81, v177 dst_sel:DWORD dst_unused:UNUSED_PAD src0_sel:WORD_1 src1_sel:DWORD
	v_and_b32_sdwa v83, v79, v177 dst_sel:DWORD dst_unused:UNUSED_PAD src0_sel:WORD_1 src1_sel:DWORD
	v_add3_u32 v81, v81, v82, s28
	v_add3_u32 v79, v79, v83, s28
	v_and_b32_e32 v81, 0xffff0000, v81
	v_and_b32_e32 v82, 0xffff0000, v79
	v_or_b32_sdwa v79, v81, v80 dst_sel:DWORD dst_unused:UNUSED_PAD src0_sel:DWORD src1_sel:WORD_1
	v_or_b32_sdwa v78, v82, v78 dst_sel:DWORD dst_unused:UNUSED_PAD src0_sel:DWORD src1_sel:WORD_1
	global_store_dwordx2 v[90:91], v[78:79], off offset:128
	v_and_b32_sdwa v78, v76, v177 dst_sel:DWORD dst_unused:UNUSED_PAD src0_sel:WORD_1 src1_sel:DWORD
	v_and_b32_sdwa v79, v74, v177 dst_sel:DWORD dst_unused:UNUSED_PAD src0_sel:WORD_1 src1_sel:DWORD
	v_add3_u32 v74, v74, v79, s28
	v_add3_u32 v76, v76, v78, s28
	v_and_b32_sdwa v78, v77, v177 dst_sel:DWORD dst_unused:UNUSED_PAD src0_sel:WORD_1 src1_sel:DWORD
	v_and_b32_sdwa v79, v75, v177 dst_sel:DWORD dst_unused:UNUSED_PAD src0_sel:WORD_1 src1_sel:DWORD
	v_add3_u32 v77, v77, v78, s28
	v_add3_u32 v75, v75, v79, s28
	v_and_b32_e32 v77, 0xffff0000, v77
	v_and_b32_e32 v78, 0xffff0000, v75
	v_or_b32_sdwa v75, v77, v76 dst_sel:DWORD dst_unused:UNUSED_PAD src0_sel:DWORD src1_sel:WORD_1
	v_or_b32_sdwa v74, v78, v74 dst_sel:DWORD dst_unused:UNUSED_PAD src0_sel:DWORD src1_sel:WORD_1
	global_store_dwordx2 v[90:91], v[74:75], off offset:160
	v_and_b32_sdwa v74, v72, v177 dst_sel:DWORD dst_unused:UNUSED_PAD src0_sel:WORD_1 src1_sel:DWORD
	v_and_b32_sdwa v75, v70, v177 dst_sel:DWORD dst_unused:UNUSED_PAD src0_sel:WORD_1 src1_sel:DWORD
	v_add3_u32 v70, v70, v75, s28
	v_add3_u32 v72, v72, v74, s28
	v_and_b32_sdwa v74, v73, v177 dst_sel:DWORD dst_unused:UNUSED_PAD src0_sel:WORD_1 src1_sel:DWORD
	v_and_b32_sdwa v75, v71, v177 dst_sel:DWORD dst_unused:UNUSED_PAD src0_sel:WORD_1 src1_sel:DWORD
	v_add3_u32 v73, v73, v74, s28
	v_add3_u32 v71, v71, v75, s28
	v_and_b32_e32 v73, 0xffff0000, v73
	v_and_b32_e32 v74, 0xffff0000, v71
	v_or_b32_sdwa v71, v73, v72 dst_sel:DWORD dst_unused:UNUSED_PAD src0_sel:DWORD src1_sel:WORD_1
	v_or_b32_sdwa v70, v74, v70 dst_sel:DWORD dst_unused:UNUSED_PAD src0_sel:DWORD src1_sel:WORD_1
	global_store_dwordx2 v[90:91], v[70:71], off offset:192
	v_and_b32_sdwa v70, v64, v177 dst_sel:DWORD dst_unused:UNUSED_PAD src0_sel:WORD_1 src1_sel:DWORD
	v_and_b32_sdwa v71, v62, v177 dst_sel:DWORD dst_unused:UNUSED_PAD src0_sel:WORD_1 src1_sel:DWORD
	v_add3_u32 v64, v64, v70, s28
	v_and_b32_sdwa v70, v65, v177 dst_sel:DWORD dst_unused:UNUSED_PAD src0_sel:WORD_1 src1_sel:DWORD
	v_add3_u32 v62, v62, v71, s28
	v_and_b32_sdwa v71, v63, v177 dst_sel:DWORD dst_unused:UNUSED_PAD src0_sel:WORD_1 src1_sel:DWORD
	v_add3_u32 v65, v65, v70, s28
	v_add3_u32 v63, v63, v71, s28
	v_and_b32_e32 v65, 0xffff0000, v65
	v_and_b32_e32 v70, 0xffff0000, v63
	v_or_b32_sdwa v63, v65, v64 dst_sel:DWORD dst_unused:UNUSED_PAD src0_sel:DWORD src1_sel:WORD_1
	v_and_b32_sdwa v64, v68, v177 dst_sel:DWORD dst_unused:UNUSED_PAD src0_sel:WORD_1 src1_sel:DWORD
	v_and_b32_sdwa v65, v66, v177 dst_sel:DWORD dst_unused:UNUSED_PAD src0_sel:WORD_1 src1_sel:DWORD
	v_or_b32_sdwa v62, v70, v62 dst_sel:DWORD dst_unused:UNUSED_PAD src0_sel:DWORD src1_sel:WORD_1
	v_add3_u32 v66, v66, v65, s28
	v_add3_u32 v64, v68, v64, s28
	v_and_b32_sdwa v65, v69, v177 dst_sel:DWORD dst_unused:UNUSED_PAD src0_sel:WORD_1 src1_sel:DWORD
	v_and_b32_sdwa v68, v67, v177 dst_sel:DWORD dst_unused:UNUSED_PAD src0_sel:WORD_1 src1_sel:DWORD
	global_store_dwordx2 v[90:91], v[62:63], off offset:224
	v_or_b32_e32 v62, 32, v94
	v_add3_u32 v65, v69, v65, s28
	v_add3_u32 v67, v67, v68, s28
	v_mad_i64_i32 v[62:63], s[6:7], v62, s8, v[86:87]
	v_and_b32_e32 v65, 0xffff0000, v65
	v_and_b32_e32 v67, 0xffff0000, v67
	v_lshl_add_u64 v[62:63], v[62:63], 0, v[88:89]
	v_or_b32_sdwa v65, v65, v64 dst_sel:DWORD dst_unused:UNUSED_PAD src0_sel:DWORD src1_sel:WORD_1
	v_or_b32_sdwa v64, v67, v66 dst_sel:DWORD dst_unused:UNUSED_PAD src0_sel:DWORD src1_sel:WORD_1
	global_store_dwordx2 v[62:63], v[64:65], off
	v_and_b32_sdwa v64, v60, v177 dst_sel:DWORD dst_unused:UNUSED_PAD src0_sel:WORD_1 src1_sel:DWORD
	v_and_b32_sdwa v65, v58, v177 dst_sel:DWORD dst_unused:UNUSED_PAD src0_sel:WORD_1 src1_sel:DWORD
	v_add3_u32 v58, v58, v65, s28
	v_add3_u32 v60, v60, v64, s28
	v_and_b32_sdwa v64, v61, v177 dst_sel:DWORD dst_unused:UNUSED_PAD src0_sel:WORD_1 src1_sel:DWORD
	v_and_b32_sdwa v65, v59, v177 dst_sel:DWORD dst_unused:UNUSED_PAD src0_sel:WORD_1 src1_sel:DWORD
	v_add3_u32 v61, v61, v64, s28
	v_add3_u32 v59, v59, v65, s28
	v_and_b32_e32 v61, 0xffff0000, v61
	v_and_b32_e32 v64, 0xffff0000, v59
	v_or_b32_sdwa v59, v61, v60 dst_sel:DWORD dst_unused:UNUSED_PAD src0_sel:DWORD src1_sel:WORD_1
	v_or_b32_sdwa v58, v64, v58 dst_sel:DWORD dst_unused:UNUSED_PAD src0_sel:DWORD src1_sel:WORD_1
	global_store_dwordx2 v[62:63], v[58:59], off offset:32
	v_and_b32_sdwa v58, v56, v177 dst_sel:DWORD dst_unused:UNUSED_PAD src0_sel:WORD_1 src1_sel:DWORD
	v_and_b32_sdwa v59, v54, v177 dst_sel:DWORD dst_unused:UNUSED_PAD src0_sel:WORD_1 src1_sel:DWORD
	v_add3_u32 v54, v54, v59, s28
	v_add3_u32 v56, v56, v58, s28
	v_and_b32_sdwa v58, v57, v177 dst_sel:DWORD dst_unused:UNUSED_PAD src0_sel:WORD_1 src1_sel:DWORD
	v_and_b32_sdwa v59, v55, v177 dst_sel:DWORD dst_unused:UNUSED_PAD src0_sel:WORD_1 src1_sel:DWORD
	v_add3_u32 v57, v57, v58, s28
	v_add3_u32 v55, v55, v59, s28
	v_and_b32_e32 v57, 0xffff0000, v57
	v_and_b32_e32 v58, 0xffff0000, v55
	v_or_b32_sdwa v55, v57, v56 dst_sel:DWORD dst_unused:UNUSED_PAD src0_sel:DWORD src1_sel:WORD_1
	v_or_b32_sdwa v54, v58, v54 dst_sel:DWORD dst_unused:UNUSED_PAD src0_sel:DWORD src1_sel:WORD_1
	global_store_dwordx2 v[62:63], v[54:55], off offset:64
	v_and_b32_sdwa v54, v52, v177 dst_sel:DWORD dst_unused:UNUSED_PAD src0_sel:WORD_1 src1_sel:DWORD
	v_and_b32_sdwa v55, v50, v177 dst_sel:DWORD dst_unused:UNUSED_PAD src0_sel:WORD_1 src1_sel:DWORD
	v_add3_u32 v50, v50, v55, s28
	v_add3_u32 v52, v52, v54, s28
	v_and_b32_sdwa v54, v53, v177 dst_sel:DWORD dst_unused:UNUSED_PAD src0_sel:WORD_1 src1_sel:DWORD
	v_and_b32_sdwa v55, v51, v177 dst_sel:DWORD dst_unused:UNUSED_PAD src0_sel:WORD_1 src1_sel:DWORD
	v_add3_u32 v53, v53, v54, s28
	v_add3_u32 v51, v51, v55, s28
	v_and_b32_e32 v53, 0xffff0000, v53
	v_and_b32_e32 v54, 0xffff0000, v51
	v_or_b32_sdwa v51, v53, v52 dst_sel:DWORD dst_unused:UNUSED_PAD src0_sel:DWORD src1_sel:WORD_1
	v_or_b32_sdwa v50, v54, v50 dst_sel:DWORD dst_unused:UNUSED_PAD src0_sel:DWORD src1_sel:WORD_1
	global_store_dwordx2 v[62:63], v[50:51], off offset:96
	v_and_b32_sdwa v50, v48, v177 dst_sel:DWORD dst_unused:UNUSED_PAD src0_sel:WORD_1 src1_sel:DWORD
	v_and_b32_sdwa v51, v46, v177 dst_sel:DWORD dst_unused:UNUSED_PAD src0_sel:WORD_1 src1_sel:DWORD
	v_add3_u32 v46, v46, v51, s28
	v_add3_u32 v48, v48, v50, s28
	v_and_b32_sdwa v50, v49, v177 dst_sel:DWORD dst_unused:UNUSED_PAD src0_sel:WORD_1 src1_sel:DWORD
	v_and_b32_sdwa v51, v47, v177 dst_sel:DWORD dst_unused:UNUSED_PAD src0_sel:WORD_1 src1_sel:DWORD
	v_add3_u32 v49, v49, v50, s28
	v_add3_u32 v47, v47, v51, s28
	v_and_b32_e32 v49, 0xffff0000, v49
	v_and_b32_e32 v50, 0xffff0000, v47
	v_or_b32_sdwa v47, v49, v48 dst_sel:DWORD dst_unused:UNUSED_PAD src0_sel:DWORD src1_sel:WORD_1
	v_or_b32_sdwa v46, v50, v46 dst_sel:DWORD dst_unused:UNUSED_PAD src0_sel:DWORD src1_sel:WORD_1
	global_store_dwordx2 v[62:63], v[46:47], off offset:128
	v_and_b32_sdwa v46, v44, v177 dst_sel:DWORD dst_unused:UNUSED_PAD src0_sel:WORD_1 src1_sel:DWORD
	v_and_b32_sdwa v47, v42, v177 dst_sel:DWORD dst_unused:UNUSED_PAD src0_sel:WORD_1 src1_sel:DWORD
	v_add3_u32 v42, v42, v47, s28
	v_add3_u32 v44, v44, v46, s28
	v_and_b32_sdwa v46, v45, v177 dst_sel:DWORD dst_unused:UNUSED_PAD src0_sel:WORD_1 src1_sel:DWORD
	v_and_b32_sdwa v47, v43, v177 dst_sel:DWORD dst_unused:UNUSED_PAD src0_sel:WORD_1 src1_sel:DWORD
	v_add3_u32 v45, v45, v46, s28
	v_add3_u32 v43, v43, v47, s28
	v_and_b32_e32 v45, 0xffff0000, v45
	v_and_b32_e32 v46, 0xffff0000, v43
	v_or_b32_sdwa v43, v45, v44 dst_sel:DWORD dst_unused:UNUSED_PAD src0_sel:DWORD src1_sel:WORD_1
	v_or_b32_sdwa v42, v46, v42 dst_sel:DWORD dst_unused:UNUSED_PAD src0_sel:DWORD src1_sel:WORD_1
	global_store_dwordx2 v[62:63], v[42:43], off offset:160
	v_and_b32_sdwa v42, v40, v177 dst_sel:DWORD dst_unused:UNUSED_PAD src0_sel:WORD_1 src1_sel:DWORD
	v_and_b32_sdwa v43, v38, v177 dst_sel:DWORD dst_unused:UNUSED_PAD src0_sel:WORD_1 src1_sel:DWORD
	v_add3_u32 v38, v38, v43, s28
	v_add3_u32 v40, v40, v42, s28
	v_and_b32_sdwa v42, v41, v177 dst_sel:DWORD dst_unused:UNUSED_PAD src0_sel:WORD_1 src1_sel:DWORD
	v_and_b32_sdwa v43, v39, v177 dst_sel:DWORD dst_unused:UNUSED_PAD src0_sel:WORD_1 src1_sel:DWORD
	v_add3_u32 v41, v41, v42, s28
	v_add3_u32 v39, v39, v43, s28
	v_and_b32_e32 v41, 0xffff0000, v41
	v_and_b32_e32 v42, 0xffff0000, v39
	v_or_b32_sdwa v39, v41, v40 dst_sel:DWORD dst_unused:UNUSED_PAD src0_sel:DWORD src1_sel:WORD_1
	v_or_b32_sdwa v38, v42, v38 dst_sel:DWORD dst_unused:UNUSED_PAD src0_sel:DWORD src1_sel:WORD_1
	global_store_dwordx2 v[62:63], v[38:39], off offset:192
	v_and_b32_sdwa v38, v32, v177 dst_sel:DWORD dst_unused:UNUSED_PAD src0_sel:WORD_1 src1_sel:DWORD
	v_and_b32_sdwa v39, v30, v177 dst_sel:DWORD dst_unused:UNUSED_PAD src0_sel:WORD_1 src1_sel:DWORD
	v_add3_u32 v32, v32, v38, s28
	v_and_b32_sdwa v38, v33, v177 dst_sel:DWORD dst_unused:UNUSED_PAD src0_sel:WORD_1 src1_sel:DWORD
	v_add3_u32 v30, v30, v39, s28
	v_and_b32_sdwa v39, v31, v177 dst_sel:DWORD dst_unused:UNUSED_PAD src0_sel:WORD_1 src1_sel:DWORD
	v_add3_u32 v33, v33, v38, s28
	v_add3_u32 v31, v31, v39, s28
	v_and_b32_e32 v33, 0xffff0000, v33
	v_and_b32_e32 v38, 0xffff0000, v31
	v_or_b32_sdwa v31, v33, v32 dst_sel:DWORD dst_unused:UNUSED_PAD src0_sel:DWORD src1_sel:WORD_1
	v_and_b32_sdwa v32, v36, v177 dst_sel:DWORD dst_unused:UNUSED_PAD src0_sel:WORD_1 src1_sel:DWORD
	v_and_b32_sdwa v33, v34, v177 dst_sel:DWORD dst_unused:UNUSED_PAD src0_sel:WORD_1 src1_sel:DWORD
	v_or_b32_sdwa v30, v38, v30 dst_sel:DWORD dst_unused:UNUSED_PAD src0_sel:DWORD src1_sel:WORD_1
	v_add3_u32 v34, v34, v33, s28
	v_add3_u32 v32, v36, v32, s28
	v_and_b32_sdwa v33, v37, v177 dst_sel:DWORD dst_unused:UNUSED_PAD src0_sel:WORD_1 src1_sel:DWORD
	v_and_b32_sdwa v36, v35, v177 dst_sel:DWORD dst_unused:UNUSED_PAD src0_sel:WORD_1 src1_sel:DWORD
	global_store_dwordx2 v[62:63], v[30:31], off offset:224
	v_or_b32_e32 v30, 48, v94
	v_add3_u32 v33, v37, v33, s28
	v_add3_u32 v35, v35, v36, s28
	v_mad_i64_i32 v[30:31], s[6:7], v30, s8, v[86:87]
	v_and_b32_e32 v33, 0xffff0000, v33
	v_and_b32_e32 v35, 0xffff0000, v35
	v_lshl_add_u64 v[30:31], v[30:31], 0, v[88:89]
	v_or_b32_sdwa v33, v33, v32 dst_sel:DWORD dst_unused:UNUSED_PAD src0_sel:DWORD src1_sel:WORD_1
	v_or_b32_sdwa v32, v35, v34 dst_sel:DWORD dst_unused:UNUSED_PAD src0_sel:DWORD src1_sel:WORD_1
	global_store_dwordx2 v[30:31], v[32:33], off
	v_and_b32_sdwa v32, v28, v177 dst_sel:DWORD dst_unused:UNUSED_PAD src0_sel:WORD_1 src1_sel:DWORD
	v_and_b32_sdwa v33, v26, v177 dst_sel:DWORD dst_unused:UNUSED_PAD src0_sel:WORD_1 src1_sel:DWORD
	v_add3_u32 v26, v26, v33, s28
	v_add3_u32 v28, v28, v32, s28
	v_and_b32_sdwa v32, v29, v177 dst_sel:DWORD dst_unused:UNUSED_PAD src0_sel:WORD_1 src1_sel:DWORD
	v_and_b32_sdwa v33, v27, v177 dst_sel:DWORD dst_unused:UNUSED_PAD src0_sel:WORD_1 src1_sel:DWORD
	v_add3_u32 v29, v29, v32, s28
	v_add3_u32 v27, v27, v33, s28
	v_and_b32_e32 v29, 0xffff0000, v29
	v_and_b32_e32 v32, 0xffff0000, v27
	v_or_b32_sdwa v27, v29, v28 dst_sel:DWORD dst_unused:UNUSED_PAD src0_sel:DWORD src1_sel:WORD_1
	v_or_b32_sdwa v26, v32, v26 dst_sel:DWORD dst_unused:UNUSED_PAD src0_sel:DWORD src1_sel:WORD_1
	global_store_dwordx2 v[30:31], v[26:27], off offset:32
	v_and_b32_sdwa v26, v24, v177 dst_sel:DWORD dst_unused:UNUSED_PAD src0_sel:WORD_1 src1_sel:DWORD
	v_and_b32_sdwa v27, v22, v177 dst_sel:DWORD dst_unused:UNUSED_PAD src0_sel:WORD_1 src1_sel:DWORD
	v_add3_u32 v22, v22, v27, s28
	v_add3_u32 v24, v24, v26, s28
	v_and_b32_sdwa v26, v25, v177 dst_sel:DWORD dst_unused:UNUSED_PAD src0_sel:WORD_1 src1_sel:DWORD
	v_and_b32_sdwa v27, v23, v177 dst_sel:DWORD dst_unused:UNUSED_PAD src0_sel:WORD_1 src1_sel:DWORD
	v_add3_u32 v25, v25, v26, s28
	v_add3_u32 v23, v23, v27, s28
	v_and_b32_e32 v25, 0xffff0000, v25
	v_and_b32_e32 v26, 0xffff0000, v23
	v_or_b32_sdwa v23, v25, v24 dst_sel:DWORD dst_unused:UNUSED_PAD src0_sel:DWORD src1_sel:WORD_1
	v_or_b32_sdwa v22, v26, v22 dst_sel:DWORD dst_unused:UNUSED_PAD src0_sel:DWORD src1_sel:WORD_1
	global_store_dwordx2 v[30:31], v[22:23], off offset:64
	v_and_b32_sdwa v22, v20, v177 dst_sel:DWORD dst_unused:UNUSED_PAD src0_sel:WORD_1 src1_sel:DWORD
	v_and_b32_sdwa v23, v18, v177 dst_sel:DWORD dst_unused:UNUSED_PAD src0_sel:WORD_1 src1_sel:DWORD
	v_add3_u32 v18, v18, v23, s28
	v_add3_u32 v20, v20, v22, s28
	v_and_b32_sdwa v22, v21, v177 dst_sel:DWORD dst_unused:UNUSED_PAD src0_sel:WORD_1 src1_sel:DWORD
	v_and_b32_sdwa v23, v19, v177 dst_sel:DWORD dst_unused:UNUSED_PAD src0_sel:WORD_1 src1_sel:DWORD
	v_add3_u32 v21, v21, v22, s28
	v_add3_u32 v19, v19, v23, s28
	v_and_b32_e32 v21, 0xffff0000, v21
	v_and_b32_e32 v22, 0xffff0000, v19
	v_or_b32_sdwa v19, v21, v20 dst_sel:DWORD dst_unused:UNUSED_PAD src0_sel:DWORD src1_sel:WORD_1
	v_or_b32_sdwa v18, v22, v18 dst_sel:DWORD dst_unused:UNUSED_PAD src0_sel:DWORD src1_sel:WORD_1
	global_store_dwordx2 v[30:31], v[18:19], off offset:96
	v_and_b32_sdwa v18, v16, v177 dst_sel:DWORD dst_unused:UNUSED_PAD src0_sel:WORD_1 src1_sel:DWORD
	v_and_b32_sdwa v19, v14, v177 dst_sel:DWORD dst_unused:UNUSED_PAD src0_sel:WORD_1 src1_sel:DWORD
	v_add3_u32 v14, v14, v19, s28
	v_add3_u32 v16, v16, v18, s28
	v_and_b32_sdwa v18, v17, v177 dst_sel:DWORD dst_unused:UNUSED_PAD src0_sel:WORD_1 src1_sel:DWORD
	v_and_b32_sdwa v19, v15, v177 dst_sel:DWORD dst_unused:UNUSED_PAD src0_sel:WORD_1 src1_sel:DWORD
	v_add3_u32 v17, v17, v18, s28
	v_add3_u32 v15, v15, v19, s28
	v_and_b32_e32 v17, 0xffff0000, v17
	v_and_b32_e32 v18, 0xffff0000, v15
	v_or_b32_sdwa v15, v17, v16 dst_sel:DWORD dst_unused:UNUSED_PAD src0_sel:DWORD src1_sel:WORD_1
	v_or_b32_sdwa v14, v18, v14 dst_sel:DWORD dst_unused:UNUSED_PAD src0_sel:DWORD src1_sel:WORD_1
	global_store_dwordx2 v[30:31], v[14:15], off offset:128
	v_and_b32_sdwa v14, v12, v177 dst_sel:DWORD dst_unused:UNUSED_PAD src0_sel:WORD_1 src1_sel:DWORD
	v_and_b32_sdwa v15, v10, v177 dst_sel:DWORD dst_unused:UNUSED_PAD src0_sel:WORD_1 src1_sel:DWORD
	v_add3_u32 v10, v10, v15, s28
	v_add3_u32 v12, v12, v14, s28
	v_and_b32_sdwa v14, v13, v177 dst_sel:DWORD dst_unused:UNUSED_PAD src0_sel:WORD_1 src1_sel:DWORD
	v_and_b32_sdwa v15, v11, v177 dst_sel:DWORD dst_unused:UNUSED_PAD src0_sel:WORD_1 src1_sel:DWORD
	v_add3_u32 v13, v13, v14, s28
	v_add3_u32 v11, v11, v15, s28
	v_and_b32_e32 v13, 0xffff0000, v13
	v_and_b32_e32 v14, 0xffff0000, v11
	v_or_b32_sdwa v11, v13, v12 dst_sel:DWORD dst_unused:UNUSED_PAD src0_sel:DWORD src1_sel:WORD_1
	v_or_b32_sdwa v10, v14, v10 dst_sel:DWORD dst_unused:UNUSED_PAD src0_sel:DWORD src1_sel:WORD_1
	global_store_dwordx2 v[30:31], v[10:11], off offset:160
	v_and_b32_sdwa v10, v8, v177 dst_sel:DWORD dst_unused:UNUSED_PAD src0_sel:WORD_1 src1_sel:DWORD
	v_and_b32_sdwa v11, v6, v177 dst_sel:DWORD dst_unused:UNUSED_PAD src0_sel:WORD_1 src1_sel:DWORD
	v_add3_u32 v6, v6, v11, s28
	v_add3_u32 v8, v8, v10, s28
	v_and_b32_sdwa v10, v9, v177 dst_sel:DWORD dst_unused:UNUSED_PAD src0_sel:WORD_1 src1_sel:DWORD
	v_and_b32_sdwa v11, v7, v177 dst_sel:DWORD dst_unused:UNUSED_PAD src0_sel:WORD_1 src1_sel:DWORD
	v_add3_u32 v9, v9, v10, s28
	v_add3_u32 v7, v7, v11, s28
	v_and_b32_e32 v9, 0xffff0000, v9
	v_and_b32_e32 v10, 0xffff0000, v7
	v_or_b32_sdwa v7, v9, v8 dst_sel:DWORD dst_unused:UNUSED_PAD src0_sel:DWORD src1_sel:WORD_1
	v_or_b32_sdwa v6, v10, v6 dst_sel:DWORD dst_unused:UNUSED_PAD src0_sel:DWORD src1_sel:WORD_1
	global_store_dwordx2 v[30:31], v[6:7], off offset:192
	v_and_b32_sdwa v6, v4, v177 dst_sel:DWORD dst_unused:UNUSED_PAD src0_sel:WORD_1 src1_sel:DWORD
	v_and_b32_sdwa v7, v2, v177 dst_sel:DWORD dst_unused:UNUSED_PAD src0_sel:WORD_1 src1_sel:DWORD
	v_add3_u32 v2, v2, v7, s28
	v_add3_u32 v4, v4, v6, s28
	v_and_b32_sdwa v6, v5, v177 dst_sel:DWORD dst_unused:UNUSED_PAD src0_sel:WORD_1 src1_sel:DWORD
	v_and_b32_sdwa v7, v3, v177 dst_sel:DWORD dst_unused:UNUSED_PAD src0_sel:WORD_1 src1_sel:DWORD
	v_add3_u32 v5, v5, v6, s28
	v_add3_u32 v3, v3, v7, s28
	v_and_b32_e32 v5, 0xffff0000, v5
	v_and_b32_e32 v6, 0xffff0000, v3
	s_add_i32 s11, s11, s10
	v_or_b32_sdwa v3, v5, v4 dst_sel:DWORD dst_unused:UNUSED_PAD src0_sel:DWORD src1_sel:WORD_1
	v_or_b32_sdwa v2, v6, v2 dst_sel:DWORD dst_unused:UNUSED_PAD src0_sel:DWORD src1_sel:WORD_1
	s_cmpk_gt_i32 s11, 0x3ef
	global_store_dwordx2 v[30:31], v[2:3], off offset:224
	s_cbranch_scc0 .LBB0_664
	s_setprio 0

.LBB0_1305:
	s_or_b64 exec, exec, s[12:13]
	s_mov_b64 s[6:7], s[60:61]
	s_waitcnt lgkmcnt(0)
	s_barrier
	s_load_dwordx4 s[44:47], s[6:7], 0x128
	v_readlane_b32 s2, v255, 48
	v_readlane_b32 s3, v255, 49
	v_mov_b32_e32 v2, v172
	s_mov_b32 s18, s42
	s_waitcnt lgkmcnt(0)
	s_add_u32 s12, s46, 0x2a00000
	s_addc_u32 s13, s47, 0
	s_add_u32 s2, s46, s2
	s_addc_u32 s3, s47, s3
	s_add_u32 s14, s2, 0x5605000
	s_addc_u32 s15, s3, 0
	s_add_u32 s16, s46, 0x3200000
	s_addc_u32 s17, s47, 0
	s_add_u32 s48, s46, 0x2800000
	s_addc_u32 s49, s47, 0
	s_mov_b32 s19, s94
	s_cmpk_gt_i32 s19, 0xff
	s_cbranch_scc1 .LBB0_1310
	v_ashrrev_i32_e32 v204, 3, v2
	v_and_b32_e32 v205, 15, v2
	v_bfe_u32 v3, v2, 4, 2
	v_lshlrev_b32_e32 v0, 4, v2
	v_ashrrev_i32_e32 v4, 1, v2
	v_lshlrev_b32_e32 v2, 1, v2
	v_and_b32_e32 v0, 0x70, v0
	v_and_b32_e32 v206, 0xffffffc0, v4
	v_and_b32_e32 v2, 0x80, v2
	s_movk_i32 s2, 0x90
	v_or_b32_e32 v4, v206, v205
	v_or_b32_e32 v5, v2, v205
	v_and_b32_e32 v100, 7, v204
	v_lshlrev_b32_e32 v100, 4, v100
	v_xor_b32_e32 v100, v100, v0
	v_lshl_add_u32 v166, v204, 7, v100
	v_lshl_add_u64 v[162:163], s[16:17], 0, v[0:1]
	v_lshl_add_u64 v[164:165], s[48:49], 0, v[0:1]
	v_and_b32_e32 v100, 7, v205
	v_xor_b32_e32 v100, v100, v3
	v_lshlrev_b32_e32 v207, 4, v100
	v_lshl_or_b32 v208, v3, 2, v2
	v_lshlrev_b32_e32 v0, 7, v4
	v_lshlrev_b32_e32 v167, 7, v5
	v_readfirstlane_b32 s100, v172
	s_nop 0
	s_cmpk_ge_u32 s100, 0x100
	s_cbranch_scc0 .Lprio_skip_P9
	s_setprio 1
.Lprio_skip_P9:
.LBB0_1307:
	s_ashr_i32 s2, s19, 31
	s_lshr_b32 s2, s2, 26
	s_add_i32 s2, s19, s2
	s_and_b32 s3, s2, 0xffffc0
	s_sub_i32 s3, s19, s3
	s_lshl_b32 s7, s3, 8
	v_add_u32_e32 v2, s7, v204
	v_ashrrev_i32_e32 v3, 31, v2
	v_lshlrev_b64 v[2:3], 11, v[2:3]
	v_lshl_add_u64 v[168:169], v[162:163], 0, v[2:3]
	s_lshl_b32 s2, s2, 2
	v_add_co_u32_e32 v56, vcc, s34, v168
	s_and_b32 s6, s2, 0xffffff00
	s_nop 0
	v_addc_co_u32_e32 v57, vcc, 0, v169, vcc
	v_add_u32_e32 v2, s6, v204
	v_add_co_u32_e32 v58, vcc, s35, v168
	v_ashrrev_i32_e32 v3, 31, v2
	s_nop 0
	v_addc_co_u32_e32 v59, vcc, 0, v169, vcc
	v_add_co_u32_e32 v60, vcc, s36, v168
	v_lshlrev_b64 v[2:3], 11, v[2:3]
	s_nop 0
	v_addc_co_u32_e32 v61, vcc, 0, v169, vcc
	v_lshl_add_u64 v[170:171], v[164:165], 0, v[2:3]
	v_add_co_u32_e32 v62, vcc, s35, v170
	global_load_dwordx4 v[24:27], v[56:57], off
	global_load_dwordx4 v[28:31], v[58:59], off
	v_addc_co_u32_e32 v63, vcc, 0, v171, vcc
	v_add_co_u32_e32 v64, vcc, s36, v170
	global_load_dwordx4 v[32:35], v[168:169], off
	global_load_dwordx4 v[36:39], v[170:171], off
	v_addc_co_u32_e32 v65, vcc, 0, v171, vcc
	v_add_co_u32_e32 v66, vcc, s34, v170
	global_load_dwordx4 v[40:43], v[62:63], off
	global_load_dwordx4 v[44:47], v[64:65], off
	v_addc_co_u32_e32 v67, vcc, 0, v171, vcc
	global_load_dwordx4 v[48:51], v[60:61], off
	global_load_dwordx4 v[52:55], v[66:67], off
	s_barrier
	global_load_dwordx4 v[118:121], v[168:169], off offset:128
	global_load_dwordx4 v[110:113], v[56:57], off offset:128
	global_load_dwordx4 v[114:117], v[58:59], off offset:128
	global_load_dwordx4 v[130:133], v[60:61], off offset:128
	global_load_dwordx4 v[126:129], v[170:171], off offset:128
	global_load_dwordx4 v[122:125], v[66:67], off offset:128
	global_load_dwordx4 v[138:141], v[62:63], off offset:128
	global_load_dwordx4 v[134:137], v[64:65], off offset:128
	v_readfirstlane_b32 vcc_lo, v168
	v_readfirstlane_b32 vcc_hi, v169
	v_readfirstlane_b32 s100, v170
	v_readfirstlane_b32 s101, v171
	s_nop 1
	v_subrev_u32_e32 v168, vcc_lo, v168
	v_subrev_u32_e32 v170, s100, v170
	v_mov_b32_e32 v2, 0
	s_mov_b32 s4, 0
	v_mov_b32_e32 v3, v2
	v_mov_b32_e32 v4, v2
	v_mov_b32_e32 v5, v2
	v_mov_b32_e32 v6, v2
	v_mov_b32_e32 v7, v2
	v_mov_b32_e32 v8, v2
	v_mov_b32_e32 v9, v2
	v_mov_b32_e32 v10, v2
	v_mov_b32_e32 v11, v2
	v_mov_b32_e32 v12, v2
	v_mov_b32_e32 v13, v2
	v_mov_b32_e32 v14, v2
	v_mov_b32_e32 v15, v2
	v_mov_b32_e32 v16, v2
	v_mov_b32_e32 v17, v2
	v_mov_b32_e32 v18, v2
	v_mov_b32_e32 v19, v2
	v_mov_b32_e32 v20, v2
	v_mov_b32_e32 v21, v2
	v_mov_b32_e32 v22, v2
	v_mov_b32_e32 v23, v2
	v_mov_b32_e32 v56, v2
	v_mov_b32_e32 v57, v2
	v_mov_b32_e32 v58, v2
	v_mov_b32_e32 v59, v2
	v_mov_b32_e32 v60, v2
	v_mov_b32_e32 v61, v2
	v_mov_b32_e32 v66, v2
	v_mov_b32_e32 v67, v2
	v_mov_b32_e32 v68, v2
	v_mov_b32_e32 v69, v2
	v_mov_b32_e32 v62, v2
	v_mov_b32_e32 v63, v2
	v_mov_b32_e32 v64, v2
	v_mov_b32_e32 v65, v2
	v_mov_b32_e32 v70, v2
	v_mov_b32_e32 v71, v2
	v_mov_b32_e32 v72, v2
	v_mov_b32_e32 v73, v2
	v_mov_b32_e32 v74, v2
	v_mov_b32_e32 v75, v2
	v_mov_b32_e32 v76, v2
	v_mov_b32_e32 v77, v2
	v_mov_b32_e32 v78, v2
	v_mov_b32_e32 v79, v2
	v_mov_b32_e32 v80, v2
	v_mov_b32_e32 v81, v2
	v_mov_b32_e32 v82, v2
	v_mov_b32_e32 v83, v2
	v_mov_b32_e32 v84, v2
	v_mov_b32_e32 v85, v2
	s_waitcnt vmcnt(13)
	ds_write_b128 v166, v[32:35]
	s_waitcnt vmcnt(12)
	ds_write_b128 v166, v[36:39] offset:32768
	s_waitcnt vmcnt(11)
	ds_write_b128 v166, v[40:43] offset:49152
	s_waitcnt vmcnt(10)
	ds_write_b128 v166, v[44:47] offset:57344
	ds_write_b128 v166, v[24:27] offset:8192
	ds_write_b128 v166, v[28:31] offset:16384
	s_waitcnt vmcnt(9)
	ds_write_b128 v166, v[48:51] offset:24576
	s_waitcnt vmcnt(8)
	ds_write_b128 v166, v[52:55] offset:40960
	v_mov_b32_e32 v24, v2
	v_mov_b32_e32 v25, v2
	v_mov_b32_e32 v26, v2
	v_mov_b32_e32 v27, v2
	v_mov_b32_e32 v28, v2
	v_mov_b32_e32 v29, v2
	v_mov_b32_e32 v34, v2
	v_mov_b32_e32 v35, v2
	v_mov_b32_e32 v36, v2
	v_mov_b32_e32 v37, v2
	v_mov_b32_e32 v30, v2
	v_mov_b32_e32 v31, v2
	v_mov_b32_e32 v32, v2
	v_mov_b32_e32 v33, v2
	v_mov_b32_e32 v38, v2
	v_mov_b32_e32 v39, v2
	v_mov_b32_e32 v40, v2
	v_mov_b32_e32 v41, v2
	v_mov_b32_e32 v42, v2
	v_mov_b32_e32 v43, v2
	v_mov_b32_e32 v44, v2
	v_mov_b32_e32 v45, v2
	v_mov_b32_e32 v46, v2
	v_mov_b32_e32 v47, v2
	v_mov_b32_e32 v48, v2
	v_mov_b32_e32 v49, v2
	v_mov_b32_e32 v50, v2
	v_mov_b32_e32 v51, v2
	v_mov_b32_e32 v52, v2
	v_mov_b32_e32 v53, v2
	v_mov_b32_e32 v54, v2
	v_mov_b32_e32 v55, v2
	v_mov_b32_e32 v86, v2
	v_mov_b32_e32 v87, v2
	v_mov_b32_e32 v88, v2
	v_mov_b32_e32 v89, v2
	v_mov_b32_e32 v90, v2
	v_mov_b32_e32 v91, v2
	v_mov_b32_e32 v92, v2
	v_mov_b32_e32 v93, v2
	v_mov_b32_e32 v98, v2
	v_mov_b32_e32 v99, v2
	v_mov_b32_e32 v100, v2
	v_mov_b32_e32 v101, v2
	v_mov_b32_e32 v94, v2
	v_mov_b32_e32 v95, v2
	v_mov_b32_e32 v96, v2
	v_mov_b32_e32 v97, v2
	v_mov_b32_e32 v102, v2
	v_mov_b32_e32 v103, v2
	v_mov_b32_e32 v104, v2
	v_mov_b32_e32 v105, v2
	v_mov_b32_e32 v106, v2
	v_mov_b32_e32 v107, v2
	v_mov_b32_e32 v108, v2
	v_mov_b32_e32 v109, v2
	v_mov_b32_e32 v142, v2
	v_mov_b32_e32 v143, v2
	v_mov_b32_e32 v144, v2
	v_mov_b32_e32 v145, v2
	v_mov_b32_e32 v146, v2
	v_mov_b32_e32 v147, v2
	v_mov_b32_e32 v148, v2
	v_mov_b32_e32 v149, v2
	v_mov_b32_e32 v150, v2
	v_mov_b32_e32 v151, v2
	v_mov_b32_e32 v152, v2
	v_mov_b32_e32 v153, v2
	v_mov_b32_e32 v154, v2
	v_mov_b32_e32 v155, v2
	v_mov_b32_e32 v156, v2
	v_mov_b32_e32 v157, v2
	v_mov_b32_e32 v158, v2
	v_mov_b32_e32 v159, v2
	v_mov_b32_e32 v160, v2
	v_mov_b32_e32 v161, v2
	s_waitcnt lgkmcnt(0)
	s_barrier
.LBB0_1308:
	s_bitcmp1_b32 s4, 0
	s_cselect_b32 s2, 0x12000, 0
	v_or_b32_e32 v218, s2, v207
	v_add_u32_e32 v214, v218, v0
	v_add_u32_e32 v246, v218, v167
	ds_read_b128 v[184:187], v214
	ds_read_b128 v[198:201], v214 offset:2048
	ds_read_b128 v[210:213], v214 offset:4096
	ds_read_b128 v[214:217], v214 offset:6144
	ds_read_b128 v[218:221], v246 offset:32768
	ds_read_b128 v[222:225], v246 offset:34816
	ds_read_b128 v[226:229], v246 offset:36864
	ds_read_b128 v[230:233], v246 offset:38912
	ds_read_b128 v[234:237], v246 offset:40960
	ds_read_b128 v[238:241], v246 offset:43008
	ds_read_b128 v[242:245], v246 offset:45056
	ds_read_b128 v[246:249], v246 offset:47104
	s_add_i32 s10, s4, 1
	s_bitcmp1_b32 s10, 0
	s_cselect_b32 s3, 0x12000, 0
	v_add_u32_e32 v171, s3, v166
	v_xor_b32_e32 v169, 64, v207
	v_add3_u32 v169, s2, v167, v169
	s_waitcnt lgkmcnt(7)
	v_mfma_f32_16x16x32_bf16 v[158:161], v[218:221], v[184:187], v[158:161]
	v_mfma_f32_16x16x32_bf16 v[98:101], v[218:221], v[198:201], v[98:101]
	v_mfma_f32_16x16x32_bf16 v[66:69], v[218:221], v[210:213], v[66:69]
	v_mfma_f32_16x16x32_bf16 v[34:37], v[218:221], v[214:217], v[34:37]
	ds_read_b128 v[218:221], v169 offset:32768
	s_waitcnt lgkmcnt(7)
	v_mfma_f32_16x16x32_bf16 v[154:157], v[222:225], v[184:187], v[154:157]
	v_mfma_f32_16x16x32_bf16 v[90:93], v[222:225], v[198:201], v[90:93]
	v_mfma_f32_16x16x32_bf16 v[58:61], v[222:225], v[210:213], v[58:61]
	v_mfma_f32_16x16x32_bf16 v[26:29], v[222:225], v[214:217], v[26:29]
	ds_read_b128 v[222:225], v169 offset:34816
	s_waitcnt lgkmcnt(7)
	v_mfma_f32_16x16x32_bf16 v[150:153], v[226:229], v[184:187], v[150:153]
	v_mfma_f32_16x16x32_bf16 v[86:89], v[226:229], v[198:201], v[86:89]
	v_mfma_f32_16x16x32_bf16 v[54:57], v[226:229], v[210:213], v[54:57]
	v_mfma_f32_16x16x32_bf16 v[22:25], v[226:229], v[214:217], v[22:25]
	ds_read_b128 v[226:229], v169 offset:36864
	s_waitcnt lgkmcnt(7)
	v_mfma_f32_16x16x32_bf16 v[146:149], v[230:233], v[184:187], v[146:149]
	v_mfma_f32_16x16x32_bf16 v[82:85], v[230:233], v[198:201], v[82:85]
	v_mfma_f32_16x16x32_bf16 v[50:53], v[230:233], v[210:213], v[50:53]
	v_mfma_f32_16x16x32_bf16 v[18:21], v[230:233], v[214:217], v[18:21]
	ds_read_b128 v[230:233], v169 offset:38912
	s_waitcnt lgkmcnt(7)
	v_mfma_f32_16x16x32_bf16 v[142:145], v[234:237], v[184:187], v[142:145]
	v_mfma_f32_16x16x32_bf16 v[78:81], v[234:237], v[198:201], v[78:81]
	v_mfma_f32_16x16x32_bf16 v[46:49], v[234:237], v[210:213], v[46:49]
	v_mfma_f32_16x16x32_bf16 v[14:17], v[234:237], v[214:217], v[14:17]
	ds_read_b128 v[234:237], v169 offset:40960
	s_waitcnt lgkmcnt(7)
	v_mfma_f32_16x16x32_bf16 v[106:109], v[238:241], v[184:187], v[106:109]
	v_mfma_f32_16x16x32_bf16 v[74:77], v[238:241], v[198:201], v[74:77]
	v_mfma_f32_16x16x32_bf16 v[42:45], v[238:241], v[210:213], v[42:45]
	v_mfma_f32_16x16x32_bf16 v[10:13], v[238:241], v[214:217], v[10:13]
	ds_read_b128 v[238:241], v169 offset:43008
	s_waitcnt lgkmcnt(7)
	v_mfma_f32_16x16x32_bf16 v[102:105], v[242:245], v[184:187], v[102:105]
	v_mfma_f32_16x16x32_bf16 v[70:73], v[242:245], v[198:201], v[70:73]
	v_mfma_f32_16x16x32_bf16 v[38:41], v[242:245], v[210:213], v[38:41]
	v_mfma_f32_16x16x32_bf16 v[6:9], v[242:245], v[214:217], v[6:9]
	ds_read_b128 v[242:245], v169 offset:45056
	s_waitcnt lgkmcnt(7)
	v_mfma_f32_16x16x32_bf16 v[94:97], v[246:249], v[184:187], v[94:97]
	v_mfma_f32_16x16x32_bf16 v[62:65], v[246:249], v[198:201], v[62:65]
	v_xor_b32_e32 v169, 64, v207
	v_add3_u32 v169, s2, v0, v169
	ds_read_b128 v[184:187], v169
	ds_read_b128 v[198:201], v169 offset:2048
	v_mfma_f32_16x16x32_bf16 v[30:33], v[246:249], v[210:213], v[30:33]
	ds_read_b128 v[210:213], v169 offset:4096
	v_mfma_f32_16x16x32_bf16 v[2:5], v[246:249], v[214:217], v[2:5]
	ds_read_b128 v[214:217], v169 offset:6144
	v_xor_b32_e32 v169, 64, v207
	v_add3_u32 v169, s2, v167, v169
	ds_read_b128 v[246:249], v169 offset:47104
	s_waitcnt lgkmcnt(1)
	v_mfma_f32_16x16x32_bf16 v[158:161], v[218:221], v[184:187], v[158:161]
	v_mfma_f32_16x16x32_bf16 v[98:101], v[218:221], v[198:201], v[98:101]
	v_mfma_f32_16x16x32_bf16 v[66:69], v[218:221], v[210:213], v[66:69]
	v_mfma_f32_16x16x32_bf16 v[34:37], v[218:221], v[214:217], v[34:37]
	s_waitcnt vmcnt(7)
	ds_write_b128 v171, v[118:121]
	v_mfma_f32_16x16x32_bf16 v[154:157], v[222:225], v[184:187], v[154:157]
	v_mfma_f32_16x16x32_bf16 v[90:93], v[222:225], v[198:201], v[90:93]
	global_load_dwordx4 v[118:121], v168, vcc offset:256
	v_mfma_f32_16x16x32_bf16 v[58:61], v[222:225], v[210:213], v[58:61]
	v_mfma_f32_16x16x32_bf16 v[26:29], v[222:225], v[214:217], v[26:29]
	s_waitcnt vmcnt(7)
	ds_write_b128 v171, v[110:113] offset:8192
	v_mfma_f32_16x16x32_bf16 v[150:153], v[226:229], v[184:187], v[150:153]
	v_mfma_f32_16x16x32_bf16 v[86:89], v[226:229], v[198:201], v[86:89]
	v_add_u32_e32 v110, s34, v168
	global_load_dwordx4 v[110:113], v110, vcc offset:256
	v_mfma_f32_16x16x32_bf16 v[54:57], v[226:229], v[210:213], v[54:57]
	v_mfma_f32_16x16x32_bf16 v[22:25], v[226:229], v[214:217], v[22:25]
	s_waitcnt vmcnt(7)
	ds_write_b128 v171, v[114:117] offset:16384
	v_mfma_f32_16x16x32_bf16 v[146:149], v[230:233], v[184:187], v[146:149]
	v_mfma_f32_16x16x32_bf16 v[82:85], v[230:233], v[198:201], v[82:85]
	v_add_u32_e32 v114, s35, v168
	global_load_dwordx4 v[114:117], v114, vcc offset:256
	v_mfma_f32_16x16x32_bf16 v[50:53], v[230:233], v[210:213], v[50:53]
	v_mfma_f32_16x16x32_bf16 v[18:21], v[230:233], v[214:217], v[18:21]
	s_waitcnt vmcnt(7)
	ds_write_b128 v171, v[130:133] offset:24576
	v_mfma_f32_16x16x32_bf16 v[142:145], v[234:237], v[184:187], v[142:145]
	v_mfma_f32_16x16x32_bf16 v[78:81], v[234:237], v[198:201], v[78:81]
	v_add_u32_e32 v130, s36, v168
	global_load_dwordx4 v[130:133], v130, vcc offset:256
	v_mfma_f32_16x16x32_bf16 v[46:49], v[234:237], v[210:213], v[46:49]
	v_mfma_f32_16x16x32_bf16 v[14:17], v[234:237], v[214:217], v[14:17]
	s_waitcnt vmcnt(7)
	ds_write_b128 v171, v[126:129] offset:32768
	v_mfma_f32_16x16x32_bf16 v[106:109], v[238:241], v[184:187], v[106:109]
	v_mfma_f32_16x16x32_bf16 v[74:77], v[238:241], v[198:201], v[74:77]
	global_load_dwordx4 v[126:129], v170, s[100:101] offset:256
	v_mfma_f32_16x16x32_bf16 v[42:45], v[238:241], v[210:213], v[42:45]
	v_mfma_f32_16x16x32_bf16 v[10:13], v[238:241], v[214:217], v[10:13]
	s_waitcnt vmcnt(7)
	ds_write_b128 v171, v[122:125] offset:40960
	v_mfma_f32_16x16x32_bf16 v[102:105], v[242:245], v[184:187], v[102:105]
	v_mfma_f32_16x16x32_bf16 v[70:73], v[242:245], v[198:201], v[70:73]
	v_add_u32_e32 v122, s34, v170
	global_load_dwordx4 v[122:125], v122, s[100:101] offset:256
	v_mfma_f32_16x16x32_bf16 v[38:41], v[242:245], v[210:213], v[38:41]
	v_mfma_f32_16x16x32_bf16 v[6:9], v[242:245], v[214:217], v[6:9]
	s_waitcnt vmcnt(7)
	ds_write_b128 v171, v[138:141] offset:49152
	s_waitcnt lgkmcnt(7)
	v_mfma_f32_16x16x32_bf16 v[94:97], v[246:249], v[184:187], v[94:97]
	v_mfma_f32_16x16x32_bf16 v[62:65], v[246:249], v[198:201], v[62:65]
	v_add_u32_e32 v138, s35, v170
	global_load_dwordx4 v[138:141], v138, s[100:101] offset:256
	v_mfma_f32_16x16x32_bf16 v[30:33], v[246:249], v[210:213], v[30:33]
	v_mfma_f32_16x16x32_bf16 v[2:5], v[246:249], v[214:217], v[2:5]
	s_waitcnt vmcnt(7)
	ds_write_b128 v171, v[134:137] offset:57344
	v_add_u32_e32 v134, s36, v170
	global_load_dwordx4 v[134:137], v134, s[100:101] offset:256
	v_add_u32_e32 v168, 0x80, v168
	v_add_u32_e32 v170, 0x80, v170
	s_waitcnt lgkmcnt(0)
	s_barrier
	s_cmp_eq_u32 s10, 16
	s_mov_b32 s4, s10
	s_cbranch_scc0 .LBB0_1308
	s_waitcnt vmcnt(4)
	v_add_u32_e32 v110, s7, v206
	s_waitcnt vmcnt(3)
	v_or_b32_e32 v114, v110, v205
	v_cmp_lt_i32_e32 vcc, s97, v114
	v_ashrrev_i32_e32 v112, 31, v114
	v_add_u32_e32 v116, 0xffffc000, v114
	v_ashrrev_i32_e32 v115, 11, v110
	v_cndmask_b32_e64 v113, v112, 0, vcc
	v_cndmask_b32_e32 v112, v114, v116, vcc
	v_mov_b32_e32 v116, s45
	v_mov_b32_e32 v117, s13
	v_mov_b32_e32 v118, s44
	v_mov_b32_e32 v119, s12
	v_or_b32_e32 v110, s6, v208
	s_waitcnt vmcnt(2)
	v_cndmask_b32_e64 v122, v115, 8, vcc
	v_cndmask_b32_e32 v121, v116, v117, vcc
	v_cndmask_b32_e32 v120, v118, v119, vcc
	v_lshlrev_b64 v[112:113], 12, v[112:113]
	v_ashrrev_i32_e32 v111, 31, v110
	v_lshl_add_u64 v[112:113], v[120:121], 0, v[112:113]
	v_mul_hi_i32_i24_e32 v121, 0x9000, v122
	v_mul_i32_i24_e32 v120, 0x9000, v122
	v_lshl_add_u64 v[120:121], s[14:15], 0, v[120:121]
	v_lshlrev_b64 v[110:111], 2, v[110:111]
	s_waitcnt vmcnt(0)
	v_lshl_add_u64 v[128:129], v[120:121], 0, v[110:111]
	v_lshl_add_u64 v[112:113], v[112:113], 0, v[110:111]
	global_load_dwordx4 v[120:123], v[128:129], off
	global_load_dwordx4 v[124:127], v[112:113], off
	s_waitcnt vmcnt(0)
	v_pk_fma_f32 v[120:121], v[158:159], v[120:121], v[124:125]
	v_pk_fma_f32 v[122:123], v[160:161], v[122:123], v[126:127]
	global_store_dwordx4 v[112:113], v[120:123], off
	global_load_dwordx4 v[120:123], v[128:129], off offset:64
	s_nop 0
	global_load_dwordx4 v[124:127], v[112:113], off offset:64
	s_waitcnt vmcnt(0)
	v_pk_fma_f32 v[120:121], v[154:155], v[120:121], v[124:125]
	v_pk_fma_f32 v[122:123], v[156:157], v[122:123], v[126:127]
	global_store_dwordx4 v[112:113], v[120:123], off offset:64
	global_load_dwordx4 v[120:123], v[128:129], off offset:128
	s_nop 0
	global_load_dwordx4 v[124:127], v[112:113], off offset:128
	s_waitcnt vmcnt(0)
	v_pk_fma_f32 v[120:121], v[150:151], v[120:121], v[124:125]
	v_pk_fma_f32 v[122:123], v[152:153], v[122:123], v[126:127]
	global_store_dwordx4 v[112:113], v[120:123], off offset:128
	global_load_dwordx4 v[120:123], v[128:129], off offset:192
	s_nop 0
	global_load_dwordx4 v[124:127], v[112:113], off offset:192
	s_waitcnt vmcnt(0)
	v_pk_fma_f32 v[120:121], v[146:147], v[120:121], v[124:125]
	v_pk_fma_f32 v[122:123], v[148:149], v[122:123], v[126:127]
	global_store_dwordx4 v[112:113], v[120:123], off offset:192
	global_load_dwordx4 v[120:123], v[128:129], off offset:256
	s_nop 0
	global_load_dwordx4 v[124:127], v[112:113], off offset:256
	s_waitcnt vmcnt(0)
	v_pk_fma_f32 v[120:121], v[142:143], v[120:121], v[124:125]
	v_pk_fma_f32 v[122:123], v[144:145], v[122:123], v[126:127]
	global_store_dwordx4 v[112:113], v[120:123], off offset:256
	global_load_dwordx4 v[120:123], v[128:129], off offset:320
	s_nop 0
	global_load_dwordx4 v[124:127], v[112:113], off offset:320
	s_waitcnt vmcnt(0)
	v_pk_fma_f32 v[106:107], v[106:107], v[120:121], v[124:125]
	v_pk_fma_f32 v[108:109], v[108:109], v[122:123], v[126:127]
	global_store_dwordx4 v[112:113], v[106:109], off offset:320
	global_load_dwordx4 v[106:109], v[128:129], off offset:384
	s_nop 0
	global_load_dwordx4 v[120:123], v[112:113], off offset:384
	s_waitcnt vmcnt(0)
	v_pk_fma_f32 v[102:103], v[102:103], v[106:107], v[120:121]
	v_pk_fma_f32 v[104:105], v[104:105], v[108:109], v[122:123]
	global_store_dwordx4 v[112:113], v[102:105], off offset:384
	global_load_dwordx4 v[102:105], v[128:129], off offset:448
	s_nop 0
	global_load_dwordx4 v[106:109], v[112:113], off offset:448
	s_waitcnt vmcnt(0)
	v_pk_fma_f32 v[94:95], v[94:95], v[102:103], v[106:107]
	v_pk_fma_f32 v[96:97], v[96:97], v[104:105], v[108:109]
	global_store_dwordx4 v[112:113], v[94:97], off offset:448
	s_nop 1
	v_or_b32_e32 v94, 16, v114
	v_cmp_lt_i32_e32 vcc, s97, v94
	v_add_u32_e32 v96, 0xffffc010, v114
	v_ashrrev_i32_e32 v95, 31, v94
	v_cndmask_b32_e64 v95, v95, 0, vcc
	v_cndmask_b32_e32 v94, v94, v96, vcc
	v_cndmask_b32_e64 v102, v115, 8, vcc
	v_cndmask_b32_e32 v97, v116, v117, vcc
	v_cndmask_b32_e32 v96, v118, v119, vcc
	v_lshlrev_b64 v[94:95], 12, v[94:95]
	v_lshl_add_u64 v[94:95], v[96:97], 0, v[94:95]
	v_mul_hi_i32_i24_e32 v97, 0x9000, v102
	v_mul_i32_i24_e32 v96, 0x9000, v102
	v_lshl_add_u64 v[96:97], s[14:15], 0, v[96:97]
	v_lshl_add_u64 v[112:113], v[96:97], 0, v[110:111]
	v_lshl_add_u64 v[94:95], v[94:95], 0, v[110:111]
	global_load_dwordx4 v[102:105], v[112:113], off
	global_load_dwordx4 v[106:109], v[94:95], off
	s_waitcnt vmcnt(0)
	v_pk_fma_f32 v[96:97], v[98:99], v[102:103], v[106:107]
	v_pk_fma_f32 v[98:99], v[100:101], v[104:105], v[108:109]
	global_store_dwordx4 v[94:95], v[96:99], off
	global_load_dwordx4 v[96:99], v[112:113], off offset:64
	s_nop 0
	global_load_dwordx4 v[100:103], v[94:95], off offset:64
	s_waitcnt vmcnt(0)
	v_pk_fma_f32 v[90:91], v[90:91], v[96:97], v[100:101]
	v_pk_fma_f32 v[92:93], v[92:93], v[98:99], v[102:103]
	global_store_dwordx4 v[94:95], v[90:93], off offset:64
	global_load_dwordx4 v[90:93], v[112:113], off offset:128
	s_nop 0
	global_load_dwordx4 v[96:99], v[94:95], off offset:128
	s_waitcnt vmcnt(0)
	v_pk_fma_f32 v[86:87], v[86:87], v[90:91], v[96:97]
	v_pk_fma_f32 v[88:89], v[88:89], v[92:93], v[98:99]
	global_store_dwordx4 v[94:95], v[86:89], off offset:128
	global_load_dwordx4 v[86:89], v[112:113], off offset:192
	s_nop 0
	global_load_dwordx4 v[90:93], v[94:95], off offset:192
	s_waitcnt vmcnt(0)
	v_pk_fma_f32 v[82:83], v[82:83], v[86:87], v[90:91]
	v_pk_fma_f32 v[84:85], v[84:85], v[88:89], v[92:93]
	global_store_dwordx4 v[94:95], v[82:85], off offset:192
	global_load_dwordx4 v[82:85], v[112:113], off offset:256
	s_nop 0
	global_load_dwordx4 v[86:89], v[94:95], off offset:256
	s_waitcnt vmcnt(0)
	v_pk_fma_f32 v[78:79], v[78:79], v[82:83], v[86:87]
	v_pk_fma_f32 v[80:81], v[80:81], v[84:85], v[88:89]
	global_store_dwordx4 v[94:95], v[78:81], off offset:256
	global_load_dwordx4 v[78:81], v[112:113], off offset:320
	s_nop 0
	global_load_dwordx4 v[82:85], v[94:95], off offset:320
	s_waitcnt vmcnt(0)
	v_pk_fma_f32 v[74:75], v[74:75], v[78:79], v[82:83]
	v_pk_fma_f32 v[76:77], v[76:77], v[80:81], v[84:85]
	global_store_dwordx4 v[94:95], v[74:77], off offset:320
	global_load_dwordx4 v[74:77], v[112:113], off offset:384
	s_nop 0
	global_load_dwordx4 v[78:81], v[94:95], off offset:384
	s_waitcnt vmcnt(0)
	v_pk_fma_f32 v[70:71], v[70:71], v[74:75], v[78:79]
	v_pk_fma_f32 v[72:73], v[72:73], v[76:77], v[80:81]
	global_store_dwordx4 v[94:95], v[70:73], off offset:384
	global_load_dwordx4 v[70:73], v[112:113], off offset:448
	s_nop 0
	global_load_dwordx4 v[74:77], v[94:95], off offset:448
	s_waitcnt vmcnt(0)
	v_pk_fma_f32 v[62:63], v[62:63], v[70:71], v[74:75]
	v_pk_fma_f32 v[64:65], v[64:65], v[72:73], v[76:77]
	global_store_dwordx4 v[94:95], v[62:65], off offset:448
	s_nop 1
	v_or_b32_e32 v62, 32, v114
	v_cmp_lt_i32_e32 vcc, s97, v62
	v_add_u32_e32 v64, 0xffffc020, v114
	v_ashrrev_i32_e32 v63, 31, v62
	v_cndmask_b32_e64 v63, v63, 0, vcc
	v_cndmask_b32_e32 v62, v62, v64, vcc
	v_cndmask_b32_e64 v70, v115, 8, vcc
	v_cndmask_b32_e32 v65, v116, v117, vcc
	v_cndmask_b32_e32 v64, v118, v119, vcc
	v_lshlrev_b64 v[62:63], 12, v[62:63]
	v_lshl_add_u64 v[62:63], v[64:65], 0, v[62:63]
	v_mul_hi_i32_i24_e32 v65, 0x9000, v70
	v_mul_i32_i24_e32 v64, 0x9000, v70
	v_lshl_add_u64 v[64:65], s[14:15], 0, v[64:65]
	v_lshl_add_u64 v[78:79], v[64:65], 0, v[110:111]
	v_lshl_add_u64 v[62:63], v[62:63], 0, v[110:111]
	global_load_dwordx4 v[70:73], v[78:79], off
	global_load_dwordx4 v[74:77], v[62:63], off
	s_waitcnt vmcnt(0)
	v_pk_fma_f32 v[64:65], v[66:67], v[70:71], v[74:75]
	v_pk_fma_f32 v[66:67], v[68:69], v[72:73], v[76:77]
	global_store_dwordx4 v[62:63], v[64:67], off
	global_load_dwordx4 v[64:67], v[78:79], off offset:64
	s_nop 0
	global_load_dwordx4 v[68:71], v[62:63], off offset:64
	s_waitcnt vmcnt(0)
	v_pk_fma_f32 v[58:59], v[58:59], v[64:65], v[68:69]
	v_pk_fma_f32 v[60:61], v[60:61], v[66:67], v[70:71]
	global_store_dwordx4 v[62:63], v[58:61], off offset:64
	global_load_dwordx4 v[58:61], v[78:79], off offset:128
	s_nop 0
	global_load_dwordx4 v[64:67], v[62:63], off offset:128
	s_waitcnt vmcnt(0)
	v_pk_fma_f32 v[54:55], v[54:55], v[58:59], v[64:65]
	v_pk_fma_f32 v[56:57], v[56:57], v[60:61], v[66:67]
	global_store_dwordx4 v[62:63], v[54:57], off offset:128
	global_load_dwordx4 v[54:57], v[78:79], off offset:192
	s_nop 0
	global_load_dwordx4 v[58:61], v[62:63], off offset:192
	s_waitcnt vmcnt(0)
	v_pk_fma_f32 v[50:51], v[50:51], v[54:55], v[58:59]
	v_pk_fma_f32 v[52:53], v[52:53], v[56:57], v[60:61]
	global_store_dwordx4 v[62:63], v[50:53], off offset:192
	global_load_dwordx4 v[50:53], v[78:79], off offset:256
	s_nop 0
	global_load_dwordx4 v[54:57], v[62:63], off offset:256
	s_waitcnt vmcnt(0)
	v_pk_fma_f32 v[46:47], v[46:47], v[50:51], v[54:55]
	v_pk_fma_f32 v[48:49], v[48:49], v[52:53], v[56:57]
	global_store_dwordx4 v[62:63], v[46:49], off offset:256
	global_load_dwordx4 v[46:49], v[78:79], off offset:320
	s_nop 0
	global_load_dwordx4 v[50:53], v[62:63], off offset:320
	s_waitcnt vmcnt(0)
	v_pk_fma_f32 v[42:43], v[42:43], v[46:47], v[50:51]
	v_pk_fma_f32 v[44:45], v[44:45], v[48:49], v[52:53]
	global_store_dwordx4 v[62:63], v[42:45], off offset:320
	global_load_dwordx4 v[42:45], v[78:79], off offset:384
	s_nop 0
	global_load_dwordx4 v[46:49], v[62:63], off offset:384
	s_waitcnt vmcnt(0)
	v_pk_fma_f32 v[38:39], v[38:39], v[42:43], v[46:47]
	v_pk_fma_f32 v[40:41], v[40:41], v[44:45], v[48:49]
	global_store_dwordx4 v[62:63], v[38:41], off offset:384
	global_load_dwordx4 v[38:41], v[78:79], off offset:448
	s_nop 0
	global_load_dwordx4 v[42:45], v[62:63], off offset:448
	s_waitcnt vmcnt(0)
	v_pk_fma_f32 v[30:31], v[30:31], v[38:39], v[42:43]
	v_pk_fma_f32 v[32:33], v[32:33], v[40:41], v[44:45]
	global_store_dwordx4 v[62:63], v[30:33], off offset:448
	s_nop 1
	v_or_b32_e32 v30, 48, v114
	v_cmp_lt_i32_e32 vcc, s97, v30
	v_add_u32_e32 v32, 0xffffc030, v114
	v_ashrrev_i32_e32 v31, 31, v30
	v_cndmask_b32_e64 v31, v31, 0, vcc
	v_cndmask_b32_e32 v30, v30, v32, vcc
	v_cndmask_b32_e64 v38, v115, 8, vcc
	v_cndmask_b32_e32 v33, v116, v117, vcc
	v_cndmask_b32_e32 v32, v118, v119, vcc
	v_lshlrev_b64 v[30:31], 12, v[30:31]
	v_lshl_add_u64 v[30:31], v[32:33], 0, v[30:31]
	v_mul_hi_i32_i24_e32 v33, 0x9000, v38
	v_mul_i32_i24_e32 v32, 0x9000, v38
	v_lshl_add_u64 v[32:33], s[14:15], 0, v[32:33]
	v_lshl_add_u64 v[46:47], v[32:33], 0, v[110:111]
	v_lshl_add_u64 v[30:31], v[30:31], 0, v[110:111]
	global_load_dwordx4 v[38:41], v[46:47], off
	global_load_dwordx4 v[42:45], v[30:31], off
	s_waitcnt vmcnt(0)
	v_pk_fma_f32 v[32:33], v[34:35], v[38:39], v[42:43]
	v_pk_fma_f32 v[34:35], v[36:37], v[40:41], v[44:45]
	global_store_dwordx4 v[30:31], v[32:35], off
	global_load_dwordx4 v[32:35], v[46:47], off offset:64
	s_nop 0
	global_load_dwordx4 v[36:39], v[30:31], off offset:64
	s_waitcnt vmcnt(0)
	v_pk_fma_f32 v[26:27], v[26:27], v[32:33], v[36:37]
	v_pk_fma_f32 v[28:29], v[28:29], v[34:35], v[38:39]
	global_store_dwordx4 v[30:31], v[26:29], off offset:64
	global_load_dwordx4 v[26:29], v[46:47], off offset:128
	s_nop 0
	global_load_dwordx4 v[32:35], v[30:31], off offset:128
	s_waitcnt vmcnt(0)
	v_pk_fma_f32 v[22:23], v[22:23], v[26:27], v[32:33]
	v_pk_fma_f32 v[24:25], v[24:25], v[28:29], v[34:35]
	global_store_dwordx4 v[30:31], v[22:25], off offset:128
	global_load_dwordx4 v[22:25], v[46:47], off offset:192
	s_nop 0
	global_load_dwordx4 v[26:29], v[30:31], off offset:192
	s_waitcnt vmcnt(0)
	v_pk_fma_f32 v[18:19], v[18:19], v[22:23], v[26:27]
	v_pk_fma_f32 v[20:21], v[20:21], v[24:25], v[28:29]
	global_store_dwordx4 v[30:31], v[18:21], off offset:192
	global_load_dwordx4 v[18:21], v[46:47], off offset:256
	s_nop 0
	global_load_dwordx4 v[22:25], v[30:31], off offset:256
	s_waitcnt vmcnt(0)
	v_pk_fma_f32 v[14:15], v[14:15], v[18:19], v[22:23]
	v_pk_fma_f32 v[16:17], v[16:17], v[20:21], v[24:25]
	global_store_dwordx4 v[30:31], v[14:17], off offset:256
	global_load_dwordx4 v[14:17], v[46:47], off offset:320
	s_nop 0
	global_load_dwordx4 v[18:21], v[30:31], off offset:320
	s_waitcnt vmcnt(0)
	v_pk_fma_f32 v[10:11], v[10:11], v[14:15], v[18:19]
	v_pk_fma_f32 v[12:13], v[12:13], v[16:17], v[20:21]
	global_store_dwordx4 v[30:31], v[10:13], off offset:320
	global_load_dwordx4 v[10:13], v[46:47], off offset:384
	s_nop 0
	global_load_dwordx4 v[14:17], v[30:31], off offset:384
	s_waitcnt vmcnt(0)
	v_pk_fma_f32 v[6:7], v[6:7], v[10:11], v[14:15]
	v_pk_fma_f32 v[8:9], v[8:9], v[12:13], v[16:17]
	global_store_dwordx4 v[30:31], v[6:9], off offset:384
	global_load_dwordx4 v[6:9], v[46:47], off offset:448
	s_nop 0
	global_load_dwordx4 v[10:13], v[30:31], off offset:448
	s_waitcnt vmcnt(0)
	v_pk_fma_f32 v[2:3], v[2:3], v[6:7], v[10:11]
	v_pk_fma_f32 v[4:5], v[4:5], v[8:9], v[12:13]
	global_store_dwordx4 v[30:31], v[2:5], off offset:448
	s_add_i32 s19, s19, s18
	s_cmpk_gt_i32 s19, 0xff
	s_cbranch_scc0 .LBB0_1307
	s_setprio 0

.LBB0_1437:
	s_or_b64 exec, exec, s[12:13]
	s_mov_b64 s[6:7], s[60:61]
	s_waitcnt lgkmcnt(0)
	s_barrier
	s_load_dwordx2 s[6:7], s[6:7], 0x130
	v_readlane_b32 s2, v255, 44
	v_readlane_b32 s3, v255, 45
	s_mov_b64 s[14:15], -1
	s_waitcnt lgkmcnt(0)
	s_add_u32 s12, s6, 0x6035800
	s_addc_u32 s13, s7, 0
	s_add_u32 s44, s6, 0xb00000
	s_addc_u32 s45, s7, 0
	s_add_u32 s46, s6, 0x3200000
	s_addc_u32 s47, s7, 0
	s_and_b64 vcc, exec, s[2:3]
	s_cbranch_vccz .LBB0_1458
	v_mov_b32_e32 v2, v172
	s_mov_b32 s11, s42
	s_mov_b32 s14, s94
	s_cmpk_gt_i32 s14, 0x4ff
	s_cbranch_scc1 .LBB0_1443
	v_ashrrev_i32_e32 v204, 3, v2
	v_bfe_u32 v3, v2, 4, 2
	v_and_b32_e32 v4, 15, v2
	v_lshlrev_b32_e32 v0, 4, v2
	v_ashrrev_i32_e32 v5, 1, v2
	s_movk_i32 s2, 0xffc0
	v_lshlrev_b32_e32 v2, 1, v2
	v_and_b32_e32 v0, 0x70, v0
	v_and_or_b32 v205, v5, s2, v4
	v_and_b32_e32 v207, 0x80, v2
	s_movk_i32 s2, 0x90
	v_or_b32_e32 v2, v207, v4
	v_and_b32_e32 v100, 7, v204
	v_lshlrev_b32_e32 v100, 4, v100
	v_xor_b32_e32 v100, v100, v0
	v_lshl_add_u32 v166, v204, 7, v100
	v_lshl_add_u64 v[162:163], s[46:47], 0, v[0:1]
	v_lshl_add_u64 v[164:165], s[44:45], 0, v[0:1]
	v_and_b32_e32 v100, 7, v4
	v_xor_b32_e32 v100, v100, v3
	v_lshlrev_b32_e32 v206, 4, v100
	v_lshlrev_b32_e32 v208, 2, v3
	v_lshlrev_b32_e32 v0, 7, v205
	v_lshlrev_b32_e32 v167, 7, v2
	v_readfirstlane_b32 s100, v172
	s_nop 0
	s_cmpk_ge_u32 s100, 0x100
	s_cbranch_scc0 .Lprio_skip_P11A
	s_setprio 1
.Lprio_skip_P11A:
.LBB0_1440:
	s_ashr_i32 s2, s14, 31
	s_lshr_b32 s2, s2, 26
	s_add_i32 s2, s14, s2
	s_and_b32 s3, s2, 0xffffc0
	s_sub_i32 s3, s14, s3
	s_lshl_b32 s6, s3, 8
	v_add_u32_e32 v2, s6, v204
	v_ashrrev_i32_e32 v3, 31, v2
	v_lshlrev_b64 v[2:3], 11, v[2:3]
	v_lshl_add_u64 v[168:169], v[162:163], 0, v[2:3]
	s_lshl_b32 s2, s2, 2
	v_add_co_u32_e32 v56, vcc, s34, v168
	s_and_b32 s7, s2, 0xffffff00
	s_nop 0
	v_addc_co_u32_e32 v57, vcc, 0, v169, vcc
	v_add_u32_e32 v2, s7, v204
	v_add_co_u32_e32 v58, vcc, s35, v168
	v_ashrrev_i32_e32 v3, 31, v2
	s_nop 0
	v_addc_co_u32_e32 v59, vcc, 0, v169, vcc
	v_lshlrev_b64 v[2:3], 11, v[2:3]
	v_add_co_u32_e32 v60, vcc, s36, v168
	v_lshl_add_u64 v[170:171], v[164:165], 0, v[2:3]
	s_nop 0
	v_addc_co_u32_e32 v61, vcc, 0, v169, vcc
	v_add_co_u32_e32 v62, vcc, s35, v170
	global_load_dwordx4 v[24:27], v[56:57], off
	global_load_dwordx4 v[28:31], v[58:59], off
	v_addc_co_u32_e32 v63, vcc, 0, v171, vcc
	v_add_co_u32_e32 v64, vcc, s36, v170
	global_load_dwordx4 v[32:35], v[168:169], off
	global_load_dwordx4 v[36:39], v[170:171], off
	v_addc_co_u32_e32 v65, vcc, 0, v171, vcc
	v_add_co_u32_e32 v66, vcc, s34, v170
	global_load_dwordx4 v[40:43], v[62:63], off
	global_load_dwordx4 v[44:47], v[64:65], off
	v_addc_co_u32_e32 v67, vcc, 0, v171, vcc
	global_load_dwordx4 v[48:51], v[60:61], off
	global_load_dwordx4 v[52:55], v[66:67], off
	s_barrier
	global_load_dwordx4 v[114:117], v[168:169], off offset:128
	global_load_dwordx4 v[106:109], v[56:57], off offset:128
	global_load_dwordx4 v[110:113], v[58:59], off offset:128
	global_load_dwordx4 v[126:129], v[60:61], off offset:128
	global_load_dwordx4 v[122:125], v[170:171], off offset:128
	global_load_dwordx4 v[118:121], v[66:67], off offset:128
	global_load_dwordx4 v[134:137], v[62:63], off offset:128
	global_load_dwordx4 v[130:133], v[64:65], off offset:128
	v_readfirstlane_b32 vcc_lo, v168
	v_readfirstlane_b32 vcc_hi, v169
	v_readfirstlane_b32 s100, v170
	v_readfirstlane_b32 s101, v171
	s_nop 1
	v_subrev_u32_e32 v168, vcc_lo, v168
	v_subrev_u32_e32 v170, s100, v170
	v_mov_b32_e32 v2, 0
	s_mov_b32 s4, 0
	v_mov_b32_e32 v3, v2
	v_mov_b32_e32 v4, v2
	v_mov_b32_e32 v5, v2
	v_mov_b32_e32 v6, v2
	v_mov_b32_e32 v7, v2
	v_mov_b32_e32 v8, v2
	v_mov_b32_e32 v9, v2
	v_mov_b32_e32 v10, v2
	v_mov_b32_e32 v11, v2
	v_mov_b32_e32 v12, v2
	v_mov_b32_e32 v13, v2
	v_mov_b32_e32 v14, v2
	v_mov_b32_e32 v15, v2
	v_mov_b32_e32 v16, v2
	v_mov_b32_e32 v17, v2
	v_mov_b32_e32 v18, v2
	v_mov_b32_e32 v19, v2
	v_mov_b32_e32 v20, v2
	v_mov_b32_e32 v21, v2
	v_mov_b32_e32 v22, v2
	v_mov_b32_e32 v23, v2
	v_mov_b32_e32 v56, v2
	v_mov_b32_e32 v57, v2
	v_mov_b32_e32 v58, v2
	v_mov_b32_e32 v59, v2
	v_mov_b32_e32 v60, v2
	v_mov_b32_e32 v61, v2
	v_mov_b32_e32 v62, v2
	v_mov_b32_e32 v63, v2
	v_mov_b32_e32 v64, v2
	v_mov_b32_e32 v65, v2
	v_mov_b32_e32 v66, v2
	v_mov_b32_e32 v67, v2
	v_mov_b32_e32 v68, v2
	v_mov_b32_e32 v69, v2
	v_mov_b32_e32 v70, v2
	v_mov_b32_e32 v71, v2
	v_mov_b32_e32 v72, v2
	v_mov_b32_e32 v73, v2
	v_mov_b32_e32 v74, v2
	v_mov_b32_e32 v75, v2
	v_mov_b32_e32 v76, v2
	v_mov_b32_e32 v77, v2
	v_mov_b32_e32 v78, v2
	v_mov_b32_e32 v79, v2
	v_mov_b32_e32 v80, v2
	v_mov_b32_e32 v81, v2
	v_mov_b32_e32 v82, v2
	v_mov_b32_e32 v83, v2
	v_mov_b32_e32 v84, v2
	v_mov_b32_e32 v85, v2
	s_waitcnt vmcnt(13)
	ds_write_b128 v166, v[32:35]
	s_waitcnt vmcnt(12)
	ds_write_b128 v166, v[36:39] offset:32768
	s_waitcnt vmcnt(11)
	ds_write_b128 v166, v[40:43] offset:49152
	s_waitcnt vmcnt(10)
	ds_write_b128 v166, v[44:47] offset:57344
	ds_write_b128 v166, v[24:27] offset:8192
	ds_write_b128 v166, v[28:31] offset:16384
	s_waitcnt vmcnt(9)
	ds_write_b128 v166, v[48:51] offset:24576
	s_waitcnt vmcnt(8)
	ds_write_b128 v166, v[52:55] offset:40960
	v_mov_b32_e32 v24, v2
	v_mov_b32_e32 v25, v2
	v_mov_b32_e32 v26, v2
	v_mov_b32_e32 v27, v2
	v_mov_b32_e32 v28, v2
	v_mov_b32_e32 v29, v2
	v_mov_b32_e32 v30, v2
	v_mov_b32_e32 v31, v2
	v_mov_b32_e32 v32, v2
	v_mov_b32_e32 v33, v2
	v_mov_b32_e32 v34, v2
	v_mov_b32_e32 v35, v2
	v_mov_b32_e32 v36, v2
	v_mov_b32_e32 v37, v2
	v_mov_b32_e32 v38, v2
	v_mov_b32_e32 v39, v2
	v_mov_b32_e32 v40, v2
	v_mov_b32_e32 v41, v2
	v_mov_b32_e32 v42, v2
	v_mov_b32_e32 v43, v2
	v_mov_b32_e32 v44, v2
	v_mov_b32_e32 v45, v2
	v_mov_b32_e32 v46, v2
	v_mov_b32_e32 v47, v2
	v_mov_b32_e32 v48, v2
	v_mov_b32_e32 v49, v2
	v_mov_b32_e32 v50, v2
	v_mov_b32_e32 v51, v2
	v_mov_b32_e32 v52, v2
	v_mov_b32_e32 v53, v2
	v_mov_b32_e32 v54, v2
	v_mov_b32_e32 v55, v2
	v_mov_b32_e32 v86, v2
	v_mov_b32_e32 v87, v2
	v_mov_b32_e32 v88, v2
	v_mov_b32_e32 v89, v2
	v_mov_b32_e32 v90, v2
	v_mov_b32_e32 v91, v2
	v_mov_b32_e32 v92, v2
	v_mov_b32_e32 v93, v2
	v_mov_b32_e32 v94, v2
	v_mov_b32_e32 v95, v2
	v_mov_b32_e32 v96, v2
	v_mov_b32_e32 v97, v2
	v_mov_b32_e32 v98, v2
	v_mov_b32_e32 v99, v2
	v_mov_b32_e32 v100, v2
	v_mov_b32_e32 v101, v2
	v_mov_b32_e32 v102, v2
	v_mov_b32_e32 v103, v2
	v_mov_b32_e32 v104, v2
	v_mov_b32_e32 v105, v2
	v_mov_b32_e32 v138, v2
	v_mov_b32_e32 v139, v2
	v_mov_b32_e32 v140, v2
	v_mov_b32_e32 v141, v2
	v_mov_b32_e32 v142, v2
	v_mov_b32_e32 v143, v2
	v_mov_b32_e32 v144, v2
	v_mov_b32_e32 v145, v2
	v_mov_b32_e32 v146, v2
	v_mov_b32_e32 v147, v2
	v_mov_b32_e32 v148, v2
	v_mov_b32_e32 v149, v2
	v_mov_b32_e32 v150, v2
	v_mov_b32_e32 v151, v2
	v_mov_b32_e32 v152, v2
	v_mov_b32_e32 v153, v2
	v_mov_b32_e32 v154, v2
	v_mov_b32_e32 v155, v2
	v_mov_b32_e32 v156, v2
	v_mov_b32_e32 v157, v2
	v_mov_b32_e32 v158, v2
	v_mov_b32_e32 v159, v2
	v_mov_b32_e32 v160, v2
	v_mov_b32_e32 v161, v2
	s_waitcnt lgkmcnt(0)
	s_barrier
.LBB0_1441:
	s_bitcmp1_b32 s4, 0
	s_cselect_b32 s2, 0x12000, 0
	v_or_b32_e32 v218, s2, v206
	v_add_u32_e32 v214, v218, v0
	v_add_u32_e32 v246, v218, v167
	ds_read_b128 v[184:187], v214
	ds_read_b128 v[198:201], v214 offset:2048
	ds_read_b128 v[210:213], v214 offset:4096
	ds_read_b128 v[214:217], v214 offset:6144
	ds_read_b128 v[218:221], v246 offset:32768
	ds_read_b128 v[222:225], v246 offset:34816
	ds_read_b128 v[226:229], v246 offset:36864
	ds_read_b128 v[230:233], v246 offset:38912
	ds_read_b128 v[234:237], v246 offset:40960
	ds_read_b128 v[238:241], v246 offset:43008
	ds_read_b128 v[242:245], v246 offset:45056
	ds_read_b128 v[246:249], v246 offset:47104
	s_add_i32 s10, s4, 1
	s_bitcmp1_b32 s10, 0
	s_cselect_b32 s3, 0x12000, 0
	v_add_u32_e32 v171, s3, v166
	v_xor_b32_e32 v169, 64, v206
	v_add3_u32 v169, s2, v167, v169
	s_waitcnt lgkmcnt(7)
	v_mfma_f32_16x16x32_bf16 v[158:161], v[218:221], v[184:187], v[158:161]
	v_mfma_f32_16x16x32_bf16 v[94:97], v[218:221], v[198:201], v[94:97]
	v_mfma_f32_16x16x32_bf16 v[62:65], v[218:221], v[210:213], v[62:65]
	v_mfma_f32_16x16x32_bf16 v[30:33], v[218:221], v[214:217], v[30:33]
	ds_read_b128 v[218:221], v169 offset:32768
	s_waitcnt lgkmcnt(7)
	v_mfma_f32_16x16x32_bf16 v[154:157], v[222:225], v[184:187], v[154:157]
	v_mfma_f32_16x16x32_bf16 v[90:93], v[222:225], v[198:201], v[90:93]
	v_mfma_f32_16x16x32_bf16 v[58:61], v[222:225], v[210:213], v[58:61]
	v_mfma_f32_16x16x32_bf16 v[26:29], v[222:225], v[214:217], v[26:29]
	ds_read_b128 v[222:225], v169 offset:34816
	s_waitcnt lgkmcnt(7)
	v_mfma_f32_16x16x32_bf16 v[150:153], v[226:229], v[184:187], v[150:153]
	v_mfma_f32_16x16x32_bf16 v[86:89], v[226:229], v[198:201], v[86:89]
	v_mfma_f32_16x16x32_bf16 v[54:57], v[226:229], v[210:213], v[54:57]
	v_mfma_f32_16x16x32_bf16 v[22:25], v[226:229], v[214:217], v[22:25]
	ds_read_b128 v[226:229], v169 offset:36864
	s_waitcnt lgkmcnt(7)
	v_mfma_f32_16x16x32_bf16 v[146:149], v[230:233], v[184:187], v[146:149]
	v_mfma_f32_16x16x32_bf16 v[82:85], v[230:233], v[198:201], v[82:85]
	v_mfma_f32_16x16x32_bf16 v[50:53], v[230:233], v[210:213], v[50:53]
	v_mfma_f32_16x16x32_bf16 v[18:21], v[230:233], v[214:217], v[18:21]
	ds_read_b128 v[230:233], v169 offset:38912
	s_waitcnt lgkmcnt(7)
	v_mfma_f32_16x16x32_bf16 v[142:145], v[234:237], v[184:187], v[142:145]
	v_mfma_f32_16x16x32_bf16 v[78:81], v[234:237], v[198:201], v[78:81]
	v_mfma_f32_16x16x32_bf16 v[46:49], v[234:237], v[210:213], v[46:49]
	v_mfma_f32_16x16x32_bf16 v[14:17], v[234:237], v[214:217], v[14:17]
	ds_read_b128 v[234:237], v169 offset:40960
	s_waitcnt lgkmcnt(7)
	v_mfma_f32_16x16x32_bf16 v[138:141], v[238:241], v[184:187], v[138:141]
	v_mfma_f32_16x16x32_bf16 v[74:77], v[238:241], v[198:201], v[74:77]
	v_mfma_f32_16x16x32_bf16 v[42:45], v[238:241], v[210:213], v[42:45]
	v_mfma_f32_16x16x32_bf16 v[10:13], v[238:241], v[214:217], v[10:13]
	ds_read_b128 v[238:241], v169 offset:43008
	s_waitcnt lgkmcnt(7)
	v_mfma_f32_16x16x32_bf16 v[102:105], v[242:245], v[184:187], v[102:105]
	v_mfma_f32_16x16x32_bf16 v[70:73], v[242:245], v[198:201], v[70:73]
	v_mfma_f32_16x16x32_bf16 v[38:41], v[242:245], v[210:213], v[38:41]
	v_mfma_f32_16x16x32_bf16 v[6:9], v[242:245], v[214:217], v[6:9]
	ds_read_b128 v[242:245], v169 offset:45056
	s_waitcnt lgkmcnt(7)
	v_mfma_f32_16x16x32_bf16 v[98:101], v[246:249], v[184:187], v[98:101]
	v_mfma_f32_16x16x32_bf16 v[66:69], v[246:249], v[198:201], v[66:69]
	v_xor_b32_e32 v169, 64, v206
	v_add3_u32 v169, s2, v0, v169
	ds_read_b128 v[184:187], v169
	ds_read_b128 v[198:201], v169 offset:2048
	v_mfma_f32_16x16x32_bf16 v[34:37], v[246:249], v[210:213], v[34:37]
	ds_read_b128 v[210:213], v169 offset:4096
	v_mfma_f32_16x16x32_bf16 v[2:5], v[246:249], v[214:217], v[2:5]
	ds_read_b128 v[214:217], v169 offset:6144
	v_xor_b32_e32 v169, 64, v206
	v_add3_u32 v169, s2, v167, v169
	ds_read_b128 v[246:249], v169 offset:47104
	s_waitcnt lgkmcnt(1)
	v_mfma_f32_16x16x32_bf16 v[158:161], v[218:221], v[184:187], v[158:161]
	v_mfma_f32_16x16x32_bf16 v[94:97], v[218:221], v[198:201], v[94:97]
	v_mfma_f32_16x16x32_bf16 v[62:65], v[218:221], v[210:213], v[62:65]
	v_mfma_f32_16x16x32_bf16 v[30:33], v[218:221], v[214:217], v[30:33]
	s_waitcnt vmcnt(7)
	ds_write_b128 v171, v[114:117]
	v_mfma_f32_16x16x32_bf16 v[154:157], v[222:225], v[184:187], v[154:157]
	v_mfma_f32_16x16x32_bf16 v[90:93], v[222:225], v[198:201], v[90:93]
	global_load_dwordx4 v[114:117], v168, vcc offset:256
	v_mfma_f32_16x16x32_bf16 v[58:61], v[222:225], v[210:213], v[58:61]
	v_mfma_f32_16x16x32_bf16 v[26:29], v[222:225], v[214:217], v[26:29]
	s_waitcnt vmcnt(7)
	ds_write_b128 v171, v[106:109] offset:8192
	v_mfma_f32_16x16x32_bf16 v[150:153], v[226:229], v[184:187], v[150:153]
	v_mfma_f32_16x16x32_bf16 v[86:89], v[226:229], v[198:201], v[86:89]
	v_add_u32_e32 v106, s34, v168
	global_load_dwordx4 v[106:109], v106, vcc offset:256
	v_mfma_f32_16x16x32_bf16 v[54:57], v[226:229], v[210:213], v[54:57]
	v_mfma_f32_16x16x32_bf16 v[22:25], v[226:229], v[214:217], v[22:25]
	s_waitcnt vmcnt(7)
	ds_write_b128 v171, v[110:113] offset:16384
	v_mfma_f32_16x16x32_bf16 v[146:149], v[230:233], v[184:187], v[146:149]
	v_mfma_f32_16x16x32_bf16 v[82:85], v[230:233], v[198:201], v[82:85]
	v_add_u32_e32 v110, s35, v168
	global_load_dwordx4 v[110:113], v110, vcc offset:256
	v_mfma_f32_16x16x32_bf16 v[50:53], v[230:233], v[210:213], v[50:53]
	v_mfma_f32_16x16x32_bf16 v[18:21], v[230:233], v[214:217], v[18:21]
	s_waitcnt vmcnt(7)
	ds_write_b128 v171, v[126:129] offset:24576
	v_mfma_f32_16x16x32_bf16 v[142:145], v[234:237], v[184:187], v[142:145]
	v_mfma_f32_16x16x32_bf16 v[78:81], v[234:237], v[198:201], v[78:81]
	v_add_u32_e32 v126, s36, v168
	global_load_dwordx4 v[126:129], v126, vcc offset:256
	v_mfma_f32_16x16x32_bf16 v[46:49], v[234:237], v[210:213], v[46:49]
	v_mfma_f32_16x16x32_bf16 v[14:17], v[234:237], v[214:217], v[14:17]
	s_waitcnt vmcnt(7)
	ds_write_b128 v171, v[122:125] offset:32768
	v_mfma_f32_16x16x32_bf16 v[138:141], v[238:241], v[184:187], v[138:141]
	v_mfma_f32_16x16x32_bf16 v[74:77], v[238:241], v[198:201], v[74:77]
	global_load_dwordx4 v[122:125], v170, s[100:101] offset:256
	v_mfma_f32_16x16x32_bf16 v[42:45], v[238:241], v[210:213], v[42:45]
	v_mfma_f32_16x16x32_bf16 v[10:13], v[238:241], v[214:217], v[10:13]
	s_waitcnt vmcnt(7)
	ds_write_b128 v171, v[118:121] offset:40960
	v_mfma_f32_16x16x32_bf16 v[102:105], v[242:245], v[184:187], v[102:105]
	v_mfma_f32_16x16x32_bf16 v[70:73], v[242:245], v[198:201], v[70:73]
	v_add_u32_e32 v118, s34, v170
	global_load_dwordx4 v[118:121], v118, s[100:101] offset:256
	v_mfma_f32_16x16x32_bf16 v[38:41], v[242:245], v[210:213], v[38:41]
	v_mfma_f32_16x16x32_bf16 v[6:9], v[242:245], v[214:217], v[6:9]
	s_waitcnt vmcnt(7)
	ds_write_b128 v171, v[134:137] offset:49152
	s_waitcnt lgkmcnt(7)
	v_mfma_f32_16x16x32_bf16 v[98:101], v[246:249], v[184:187], v[98:101]
	v_mfma_f32_16x16x32_bf16 v[66:69], v[246:249], v[198:201], v[66:69]
	v_add_u32_e32 v134, s35, v170
	global_load_dwordx4 v[134:137], v134, s[100:101] offset:256
	v_mfma_f32_16x16x32_bf16 v[34:37], v[246:249], v[210:213], v[34:37]
	v_mfma_f32_16x16x32_bf16 v[2:5], v[246:249], v[214:217], v[2:5]
	s_waitcnt vmcnt(7)
	ds_write_b128 v171, v[130:133] offset:57344
	v_add_u32_e32 v130, s36, v170
	global_load_dwordx4 v[130:133], v130, s[100:101] offset:256
	v_add_u32_e32 v168, 0x80, v168
	v_add_u32_e32 v170, 0x80, v170
	s_waitcnt lgkmcnt(0)
	s_barrier
	s_cmp_eq_u32 s10, 16
	s_mov_b32 s4, s10
	s_cbranch_scc0 .LBB0_1441
	s_waitcnt vmcnt(4)
	v_mul_f32_e32 v109, 0xbfb8aa3b, v158
	v_exp_f32_e32 v109, v109
	s_waitcnt vmcnt(3)
	v_mul_f32_e32 v111, 0xbfb8aa3b, v159
	v_exp_f32_e32 v111, v111
	v_mul_f32_e32 v115, 0xbfb8aa3b, v161
	v_add_f32_e32 v109, 1.0, v109
	v_rcp_f32_e32 v114, v109
	v_add_f32_e32 v109, 1.0, v111
	v_mul_f32_e32 v111, 0xbfb8aa3b, v160
	v_exp_f32_e32 v111, v111
	v_exp_f32_e32 v117, v115
	v_rcp_f32_e32 v116, v109
	s_waitcnt vmcnt(2)
	v_mov_b32_e32 v118, v158
	v_add_f32_e32 v109, 1.0, v111
	v_rcp_f32_e32 v115, v109
	v_add_f32_e32 v109, 1.0, v117
	v_rcp_f32_e32 v117, v109
	v_mov_b32_e32 v119, v160
	v_pk_mul_f32 v[114:115], v[118:119], v[114:115]
	v_mov_b32_e32 v118, v154
	v_mov_b32_e32 v119, v156
	v_mov_b32_e32 v160, v159
	v_pk_mul_f32 v[114:115], v[118:119], v[114:115]
	v_pk_mul_f32 v[116:117], v[160:161], v[116:117]
	v_mov_b32_e32 v156, v155
	v_pk_mul_f32 v[116:117], v[156:157], v[116:117]
	v_and_b32_sdwa v111, v115, v177 dst_sel:DWORD dst_unused:UNUSED_PAD src0_sel:WORD_1 src1_sel:DWORD
	v_and_b32_sdwa v118, v114, v177 dst_sel:DWORD dst_unused:UNUSED_PAD src0_sel:WORD_1 src1_sel:DWORD
	v_add3_u32 v111, v115, v111, s28
	v_and_b32_sdwa v115, v117, v177 dst_sel:DWORD dst_unused:UNUSED_PAD src0_sel:WORD_1 src1_sel:DWORD
	v_add3_u32 v114, v114, v118, s28
	v_and_b32_sdwa v118, v116, v177 dst_sel:DWORD dst_unused:UNUSED_PAD src0_sel:WORD_1 src1_sel:DWORD
	v_add3_u32 v115, v117, v115, s28
	v_or_b32_e32 v106, s7, v207
	v_add3_u32 v116, v116, v118, s28
	v_and_b32_e32 v115, 0xffff0000, v115
	v_ashrrev_i32_e32 v106, 1, v106
	v_and_b32_e32 v116, 0xffff0000, v116
	v_or_b32_sdwa v115, v115, v111 dst_sel:DWORD dst_unused:UNUSED_PAD src0_sel:DWORD src1_sel:WORD_1
	v_mul_f32_e32 v111, 0xbfb8aa3b, v150
	v_or_b32_e32 v108, v106, v208
	v_or_b32_sdwa v114, v116, v114 dst_sel:DWORD dst_unused:UNUSED_PAD src0_sel:DWORD src1_sel:WORD_1
	v_exp_f32_e32 v111, v111
	v_mul_f32_e32 v116, 0xbfb8aa3b, v151
	v_add_u32_e32 v110, s6, v205
	v_mov_b64_e32 v[106:107], s[12:13]
	v_ashrrev_i32_e32 v109, 31, v108
	v_exp_f32_e32 v116, v116
	v_mad_i64_i32 v[112:113], s[6:7], v110, s52, v[106:107]
	v_lshlrev_b64 v[108:109], 1, v[108:109]
	v_lshl_add_u64 v[112:113], v[112:113], 0, v[108:109]
	s_waitcnt vmcnt(0)
	global_store_dwordx2 v[112:113], v[114:115], off
	v_add_f32_e32 v111, 1.0, v111
	v_mul_f32_e32 v115, 0xbfb8aa3b, v152
	v_rcp_f32_e32 v114, v111
	v_add_f32_e32 v111, 1.0, v116
	v_exp_f32_e32 v115, v115
	v_mul_f32_e32 v116, 0xbfb8aa3b, v153
	v_exp_f32_e32 v117, v116
	v_rcp_f32_e32 v116, v111
	v_add_f32_e32 v111, 1.0, v115
	v_rcp_f32_e32 v115, v111
	v_add_f32_e32 v111, 1.0, v117
	v_rcp_f32_e32 v117, v111
	v_mov_b32_e32 v118, v150
	v_mov_b32_e32 v119, v152
	v_pk_mul_f32 v[114:115], v[118:119], v[114:115]
	v_mov_b32_e32 v118, v146
	v_mov_b32_e32 v119, v148
	v_mov_b32_e32 v152, v151
	v_pk_mul_f32 v[114:115], v[118:119], v[114:115]
	v_pk_mul_f32 v[116:117], v[152:153], v[116:117]
	v_mov_b32_e32 v148, v147
	v_pk_mul_f32 v[116:117], v[148:149], v[116:117]
	v_and_b32_sdwa v111, v115, v177 dst_sel:DWORD dst_unused:UNUSED_PAD src0_sel:WORD_1 src1_sel:DWORD
	v_and_b32_sdwa v118, v114, v177 dst_sel:DWORD dst_unused:UNUSED_PAD src0_sel:WORD_1 src1_sel:DWORD
	v_add3_u32 v111, v115, v111, s28
	v_and_b32_sdwa v115, v117, v177 dst_sel:DWORD dst_unused:UNUSED_PAD src0_sel:WORD_1 src1_sel:DWORD
	v_add3_u32 v114, v114, v118, s28
	v_and_b32_sdwa v118, v116, v177 dst_sel:DWORD dst_unused:UNUSED_PAD src0_sel:WORD_1 src1_sel:DWORD
	v_add3_u32 v115, v117, v115, s28
	v_add3_u32 v116, v116, v118, s28
	v_and_b32_e32 v115, 0xffff0000, v115
	v_and_b32_e32 v116, 0xffff0000, v116
	v_or_b32_sdwa v115, v115, v111 dst_sel:DWORD dst_unused:UNUSED_PAD src0_sel:DWORD src1_sel:WORD_1
	v_mul_f32_e32 v111, 0xbfb8aa3b, v142
	v_or_b32_sdwa v114, v116, v114 dst_sel:DWORD dst_unused:UNUSED_PAD src0_sel:DWORD src1_sel:WORD_1
	v_exp_f32_e32 v111, v111
	v_mul_f32_e32 v116, 0xbfb8aa3b, v143
	v_exp_f32_e32 v116, v116
	global_store_dwordx2 v[112:113], v[114:115], off offset:32
	v_add_f32_e32 v111, 1.0, v111
	v_mul_f32_e32 v115, 0xbfb8aa3b, v144
	v_rcp_f32_e32 v114, v111
	v_add_f32_e32 v111, 1.0, v116
	v_exp_f32_e32 v115, v115
	v_mul_f32_e32 v116, 0xbfb8aa3b, v145
	v_exp_f32_e32 v117, v116
	v_rcp_f32_e32 v116, v111
	v_add_f32_e32 v111, 1.0, v115
	v_rcp_f32_e32 v115, v111
	v_add_f32_e32 v111, 1.0, v117
	v_rcp_f32_e32 v117, v111
	v_mov_b32_e32 v118, v142
	v_mov_b32_e32 v119, v144
	v_pk_mul_f32 v[114:115], v[118:119], v[114:115]
	v_mov_b32_e32 v118, v138
	v_mov_b32_e32 v119, v140
	v_mov_b32_e32 v144, v143
	v_pk_mul_f32 v[114:115], v[118:119], v[114:115]
	v_pk_mul_f32 v[116:117], v[144:145], v[116:117]
	v_mov_b32_e32 v140, v139
	v_pk_mul_f32 v[116:117], v[140:141], v[116:117]
	v_and_b32_sdwa v111, v115, v177 dst_sel:DWORD dst_unused:UNUSED_PAD src0_sel:WORD_1 src1_sel:DWORD
	v_and_b32_sdwa v118, v114, v177 dst_sel:DWORD dst_unused:UNUSED_PAD src0_sel:WORD_1 src1_sel:DWORD
	v_add3_u32 v111, v115, v111, s28
	v_and_b32_sdwa v115, v117, v177 dst_sel:DWORD dst_unused:UNUSED_PAD src0_sel:WORD_1 src1_sel:DWORD
	v_add3_u32 v114, v114, v118, s28
	v_and_b32_sdwa v118, v116, v177 dst_sel:DWORD dst_unused:UNUSED_PAD src0_sel:WORD_1 src1_sel:DWORD
	v_add3_u32 v115, v117, v115, s28
	v_add3_u32 v116, v116, v118, s28
	v_and_b32_e32 v115, 0xffff0000, v115
	v_and_b32_e32 v116, 0xffff0000, v116
	v_or_b32_sdwa v115, v115, v111 dst_sel:DWORD dst_unused:UNUSED_PAD src0_sel:DWORD src1_sel:WORD_1
	v_mul_f32_e32 v111, 0xbfb8aa3b, v102
	v_or_b32_sdwa v114, v116, v114 dst_sel:DWORD dst_unused:UNUSED_PAD src0_sel:DWORD src1_sel:WORD_1
	v_exp_f32_e32 v111, v111
	v_mul_f32_e32 v116, 0xbfb8aa3b, v103
	v_exp_f32_e32 v116, v116
	global_store_dwordx2 v[112:113], v[114:115], off offset:64
	v_add_f32_e32 v111, 1.0, v111
	v_mul_f32_e32 v115, 0xbfb8aa3b, v104
	v_rcp_f32_e32 v114, v111
	v_add_f32_e32 v111, 1.0, v116
	v_exp_f32_e32 v115, v115
	v_mul_f32_e32 v116, 0xbfb8aa3b, v105
	v_exp_f32_e32 v117, v116
	v_rcp_f32_e32 v116, v111
	v_add_f32_e32 v111, 1.0, v115
	v_rcp_f32_e32 v115, v111
	v_add_f32_e32 v111, 1.0, v117
	v_rcp_f32_e32 v117, v111
	v_mov_b32_e32 v118, v102
	v_mov_b32_e32 v119, v104
	v_mov_b32_e32 v104, v103
	v_pk_mul_f32 v[114:115], v[118:119], v[114:115]
	v_mov_b32_e32 v119, v100
	v_pk_mul_f32 v[102:103], v[104:105], v[116:117]
	v_mov_b32_e32 v100, v99
	v_mov_b32_e32 v118, v98
	v_pk_mul_f32 v[98:99], v[100:101], v[102:103]
	v_pk_mul_f32 v[114:115], v[118:119], v[114:115]
	v_and_b32_sdwa v102, v99, v177 dst_sel:DWORD dst_unused:UNUSED_PAD src0_sel:WORD_1 src1_sel:DWORD
	v_and_b32_sdwa v103, v98, v177 dst_sel:DWORD dst_unused:UNUSED_PAD src0_sel:WORD_1 src1_sel:DWORD
	v_and_b32_sdwa v100, v115, v177 dst_sel:DWORD dst_unused:UNUSED_PAD src0_sel:WORD_1 src1_sel:DWORD
	v_and_b32_sdwa v101, v114, v177 dst_sel:DWORD dst_unused:UNUSED_PAD src0_sel:WORD_1 src1_sel:DWORD
	v_add3_u32 v99, v99, v102, s28
	v_add3_u32 v98, v98, v103, s28
	v_add3_u32 v101, v114, v101, s28
	v_add3_u32 v100, v115, v100, s28
	v_and_b32_e32 v99, 0xffff0000, v99
	v_and_b32_e32 v98, 0xffff0000, v98
	v_or_b32_sdwa v99, v99, v100 dst_sel:DWORD dst_unused:UNUSED_PAD src0_sel:DWORD src1_sel:WORD_1
	v_or_b32_sdwa v98, v98, v101 dst_sel:DWORD dst_unused:UNUSED_PAD src0_sel:DWORD src1_sel:WORD_1
	global_store_dwordx2 v[112:113], v[98:99], off offset:96
	v_mul_f32_e32 v99, 0xbfb8aa3b, v94
	v_exp_f32_e32 v100, v99
	v_mul_f32_e32 v99, 0xbfb8aa3b, v95
	v_mul_f32_e32 v102, 0xbfb8aa3b, v96
	v_exp_f32_e32 v101, v99
	v_exp_f32_e32 v103, v102
	v_mul_f32_e32 v102, 0xbfb8aa3b, v97
	v_exp_f32_e32 v104, v102
	v_add_f32_e32 v101, 1.0, v101
	v_add_f32_e32 v100, 1.0, v100
	v_rcp_f32_e32 v102, v101
	v_add_f32_e32 v101, 1.0, v103
	v_add_f32_e32 v103, 1.0, v104
	v_rcp_f32_e32 v100, v100
	v_rcp_f32_e32 v101, v101
	v_rcp_f32_e32 v103, v103
	v_mov_b32_e32 v104, v94
	v_mov_b32_e32 v105, v96
	v_mov_b32_e32 v96, v95
	v_pk_mul_f32 v[100:101], v[104:105], v[100:101]
	v_mov_b32_e32 v105, v92
	v_pk_mul_f32 v[94:95], v[96:97], v[102:103]
	v_mov_b32_e32 v92, v91
	v_mov_b32_e32 v104, v90
	v_pk_mul_f32 v[90:91], v[92:93], v[94:95]
	v_pk_mul_f32 v[100:101], v[104:105], v[100:101]
	v_and_b32_sdwa v94, v91, v177 dst_sel:DWORD dst_unused:UNUSED_PAD src0_sel:WORD_1 src1_sel:DWORD
	v_and_b32_sdwa v92, v101, v177 dst_sel:DWORD dst_unused:UNUSED_PAD src0_sel:WORD_1 src1_sel:DWORD
	v_and_b32_sdwa v95, v90, v177 dst_sel:DWORD dst_unused:UNUSED_PAD src0_sel:WORD_1 src1_sel:DWORD
	v_add3_u32 v91, v91, v94, s28
	v_and_b32_sdwa v93, v100, v177 dst_sel:DWORD dst_unused:UNUSED_PAD src0_sel:WORD_1 src1_sel:DWORD
	v_add3_u32 v92, v101, v92, s28
	v_add3_u32 v90, v90, v95, s28
	v_and_b32_e32 v91, 0xffff0000, v91
	v_add3_u32 v93, v100, v93, s28
	v_and_b32_e32 v90, 0xffff0000, v90
	v_or_b32_sdwa v91, v91, v92 dst_sel:DWORD dst_unused:UNUSED_PAD src0_sel:DWORD src1_sel:WORD_1
	v_mul_f32_e32 v92, 0xbfb8aa3b, v86
	v_or_b32_sdwa v90, v90, v93 dst_sel:DWORD dst_unused:UNUSED_PAD src0_sel:DWORD src1_sel:WORD_1
	v_exp_f32_e32 v92, v92
	v_mul_f32_e32 v93, 0xbfb8aa3b, v87
	v_or_b32_e32 v98, 16, v110
	v_exp_f32_e32 v93, v93
	v_mad_i64_i32 v[98:99], s[6:7], v98, s52, v[106:107]
	v_lshl_add_u64 v[98:99], v[98:99], 0, v[108:109]
	global_store_dwordx2 v[98:99], v[90:91], off
	v_add_f32_e32 v90, 1.0, v92
	v_mul_f32_e32 v92, 0xbfb8aa3b, v88
	v_add_f32_e32 v91, 1.0, v93
	v_exp_f32_e32 v93, v92
	v_mul_f32_e32 v92, 0xbfb8aa3b, v89
	v_exp_f32_e32 v94, v92
	v_rcp_f32_e32 v92, v91
	v_add_f32_e32 v91, 1.0, v93
	v_rcp_f32_e32 v90, v90
	v_add_f32_e32 v93, 1.0, v94
	v_rcp_f32_e32 v91, v91
	v_rcp_f32_e32 v93, v93
	v_mov_b32_e32 v94, v86
	v_mov_b32_e32 v95, v88
	v_mov_b32_e32 v88, v87
	v_pk_mul_f32 v[90:91], v[94:95], v[90:91]
	v_mov_b32_e32 v95, v84
	v_pk_mul_f32 v[86:87], v[88:89], v[92:93]
	v_mov_b32_e32 v84, v83
	v_mov_b32_e32 v94, v82
	v_pk_mul_f32 v[82:83], v[84:85], v[86:87]
	v_pk_mul_f32 v[90:91], v[94:95], v[90:91]
	v_and_b32_sdwa v86, v83, v177 dst_sel:DWORD dst_unused:UNUSED_PAD src0_sel:WORD_1 src1_sel:DWORD
	v_and_b32_sdwa v84, v91, v177 dst_sel:DWORD dst_unused:UNUSED_PAD src0_sel:WORD_1 src1_sel:DWORD
	v_and_b32_sdwa v87, v82, v177 dst_sel:DWORD dst_unused:UNUSED_PAD src0_sel:WORD_1 src1_sel:DWORD
	v_add3_u32 v83, v83, v86, s28
	v_and_b32_sdwa v85, v90, v177 dst_sel:DWORD dst_unused:UNUSED_PAD src0_sel:WORD_1 src1_sel:DWORD
	v_add3_u32 v84, v91, v84, s28
	v_add3_u32 v82, v82, v87, s28
	v_and_b32_e32 v83, 0xffff0000, v83
	v_add3_u32 v85, v90, v85, s28
	v_and_b32_e32 v82, 0xffff0000, v82
	v_or_b32_sdwa v83, v83, v84 dst_sel:DWORD dst_unused:UNUSED_PAD src0_sel:DWORD src1_sel:WORD_1
	v_mul_f32_e32 v84, 0xbfb8aa3b, v78
	v_or_b32_sdwa v82, v82, v85 dst_sel:DWORD dst_unused:UNUSED_PAD src0_sel:DWORD src1_sel:WORD_1
	v_exp_f32_e32 v84, v84
	v_mul_f32_e32 v85, 0xbfb8aa3b, v79
	v_exp_f32_e32 v85, v85
	global_store_dwordx2 v[98:99], v[82:83], off offset:32
	v_add_f32_e32 v82, 1.0, v84
	v_mul_f32_e32 v84, 0xbfb8aa3b, v80
	v_add_f32_e32 v83, 1.0, v85
	v_exp_f32_e32 v85, v84
	v_mul_f32_e32 v84, 0xbfb8aa3b, v81
	v_exp_f32_e32 v86, v84
	v_rcp_f32_e32 v84, v83
	v_add_f32_e32 v83, 1.0, v85
	v_rcp_f32_e32 v82, v82
	v_add_f32_e32 v85, 1.0, v86
	v_rcp_f32_e32 v83, v83
	v_rcp_f32_e32 v85, v85
	v_mov_b32_e32 v86, v78
	v_mov_b32_e32 v87, v80
	v_mov_b32_e32 v80, v79
	v_pk_mul_f32 v[82:83], v[86:87], v[82:83]
	v_mov_b32_e32 v87, v76
	v_pk_mul_f32 v[78:79], v[80:81], v[84:85]
	v_mov_b32_e32 v76, v75
	v_mov_b32_e32 v86, v74
	v_pk_mul_f32 v[74:75], v[76:77], v[78:79]
	v_pk_mul_f32 v[82:83], v[86:87], v[82:83]
	v_and_b32_sdwa v78, v75, v177 dst_sel:DWORD dst_unused:UNUSED_PAD src0_sel:WORD_1 src1_sel:DWORD
	v_and_b32_sdwa v76, v83, v177 dst_sel:DWORD dst_unused:UNUSED_PAD src0_sel:WORD_1 src1_sel:DWORD
	v_and_b32_sdwa v79, v74, v177 dst_sel:DWORD dst_unused:UNUSED_PAD src0_sel:WORD_1 src1_sel:DWORD
	v_add3_u32 v75, v75, v78, s28
	v_and_b32_sdwa v77, v82, v177 dst_sel:DWORD dst_unused:UNUSED_PAD src0_sel:WORD_1 src1_sel:DWORD
	v_add3_u32 v76, v83, v76, s28
	v_add3_u32 v74, v74, v79, s28
	v_and_b32_e32 v75, 0xffff0000, v75
	v_add3_u32 v77, v82, v77, s28
	v_and_b32_e32 v74, 0xffff0000, v74
	v_or_b32_sdwa v75, v75, v76 dst_sel:DWORD dst_unused:UNUSED_PAD src0_sel:DWORD src1_sel:WORD_1
	v_mul_f32_e32 v76, 0xbfb8aa3b, v70
	v_or_b32_sdwa v74, v74, v77 dst_sel:DWORD dst_unused:UNUSED_PAD src0_sel:DWORD src1_sel:WORD_1
	v_exp_f32_e32 v76, v76
	v_mul_f32_e32 v77, 0xbfb8aa3b, v71
	v_exp_f32_e32 v77, v77
	global_store_dwordx2 v[98:99], v[74:75], off offset:64
	v_add_f32_e32 v74, 1.0, v76
	v_mul_f32_e32 v76, 0xbfb8aa3b, v72
	v_add_f32_e32 v75, 1.0, v77
	v_exp_f32_e32 v77, v76
	v_mul_f32_e32 v76, 0xbfb8aa3b, v73
	v_exp_f32_e32 v78, v76
	v_rcp_f32_e32 v76, v75
	v_add_f32_e32 v75, 1.0, v77
	v_rcp_f32_e32 v74, v74
	v_add_f32_e32 v77, 1.0, v78
	v_rcp_f32_e32 v75, v75
	v_rcp_f32_e32 v77, v77
	v_mov_b32_e32 v78, v70
	v_mov_b32_e32 v79, v72
	v_mov_b32_e32 v72, v71
	v_pk_mul_f32 v[74:75], v[78:79], v[74:75]
	v_mov_b32_e32 v79, v68
	v_pk_mul_f32 v[70:71], v[72:73], v[76:77]
	v_mov_b32_e32 v68, v67
	v_mov_b32_e32 v78, v66
	v_pk_mul_f32 v[66:67], v[68:69], v[70:71]
	v_pk_mul_f32 v[74:75], v[78:79], v[74:75]
	v_and_b32_sdwa v70, v67, v177 dst_sel:DWORD dst_unused:UNUSED_PAD src0_sel:WORD_1 src1_sel:DWORD
	v_and_b32_sdwa v71, v66, v177 dst_sel:DWORD dst_unused:UNUSED_PAD src0_sel:WORD_1 src1_sel:DWORD
	v_and_b32_sdwa v68, v75, v177 dst_sel:DWORD dst_unused:UNUSED_PAD src0_sel:WORD_1 src1_sel:DWORD
	v_and_b32_sdwa v69, v74, v177 dst_sel:DWORD dst_unused:UNUSED_PAD src0_sel:WORD_1 src1_sel:DWORD
	v_add3_u32 v67, v67, v70, s28
	v_add3_u32 v66, v66, v71, s28
	v_add3_u32 v69, v74, v69, s28
	v_add3_u32 v68, v75, v68, s28
	v_and_b32_e32 v67, 0xffff0000, v67
	v_and_b32_e32 v66, 0xffff0000, v66
	v_or_b32_sdwa v67, v67, v68 dst_sel:DWORD dst_unused:UNUSED_PAD src0_sel:DWORD src1_sel:WORD_1
	v_or_b32_sdwa v66, v66, v69 dst_sel:DWORD dst_unused:UNUSED_PAD src0_sel:DWORD src1_sel:WORD_1
	global_store_dwordx2 v[98:99], v[66:67], off offset:96
	v_mul_f32_e32 v67, 0xbfb8aa3b, v62
	v_exp_f32_e32 v68, v67
	v_mul_f32_e32 v67, 0xbfb8aa3b, v63
	v_mul_f32_e32 v70, 0xbfb8aa3b, v64
	v_exp_f32_e32 v69, v67
	v_exp_f32_e32 v71, v70
	v_mul_f32_e32 v70, 0xbfb8aa3b, v65
	v_exp_f32_e32 v72, v70
	v_add_f32_e32 v69, 1.0, v69
	v_add_f32_e32 v68, 1.0, v68
	v_rcp_f32_e32 v70, v69
	v_add_f32_e32 v69, 1.0, v71
	v_add_f32_e32 v71, 1.0, v72
	v_rcp_f32_e32 v68, v68
	v_rcp_f32_e32 v69, v69
	v_rcp_f32_e32 v71, v71
	v_mov_b32_e32 v72, v62
	v_mov_b32_e32 v73, v64
	v_mov_b32_e32 v64, v63
	v_pk_mul_f32 v[68:69], v[72:73], v[68:69]
	v_mov_b32_e32 v73, v60
	v_pk_mul_f32 v[62:63], v[64:65], v[70:71]
	v_mov_b32_e32 v60, v59
	v_mov_b32_e32 v72, v58
	v_pk_mul_f32 v[58:59], v[60:61], v[62:63]
	v_pk_mul_f32 v[68:69], v[72:73], v[68:69]
	v_and_b32_sdwa v62, v59, v177 dst_sel:DWORD dst_unused:UNUSED_PAD src0_sel:WORD_1 src1_sel:DWORD
	v_and_b32_sdwa v60, v69, v177 dst_sel:DWORD dst_unused:UNUSED_PAD src0_sel:WORD_1 src1_sel:DWORD
	v_and_b32_sdwa v63, v58, v177 dst_sel:DWORD dst_unused:UNUSED_PAD src0_sel:WORD_1 src1_sel:DWORD
	v_add3_u32 v59, v59, v62, s28
	v_and_b32_sdwa v61, v68, v177 dst_sel:DWORD dst_unused:UNUSED_PAD src0_sel:WORD_1 src1_sel:DWORD
	v_add3_u32 v60, v69, v60, s28
	v_add3_u32 v58, v58, v63, s28
	v_and_b32_e32 v59, 0xffff0000, v59
	v_add3_u32 v61, v68, v61, s28
	v_and_b32_e32 v58, 0xffff0000, v58
	v_or_b32_sdwa v59, v59, v60 dst_sel:DWORD dst_unused:UNUSED_PAD src0_sel:DWORD src1_sel:WORD_1
	v_mul_f32_e32 v60, 0xbfb8aa3b, v54
	v_or_b32_sdwa v58, v58, v61 dst_sel:DWORD dst_unused:UNUSED_PAD src0_sel:DWORD src1_sel:WORD_1
	v_exp_f32_e32 v60, v60
	v_mul_f32_e32 v61, 0xbfb8aa3b, v55
	v_or_b32_e32 v66, 32, v110
	v_exp_f32_e32 v61, v61
	v_mad_i64_i32 v[66:67], s[6:7], v66, s52, v[106:107]
	v_lshl_add_u64 v[66:67], v[66:67], 0, v[108:109]
	global_store_dwordx2 v[66:67], v[58:59], off
	v_add_f32_e32 v58, 1.0, v60
	v_mul_f32_e32 v60, 0xbfb8aa3b, v56
	v_add_f32_e32 v59, 1.0, v61
	v_exp_f32_e32 v61, v60
	v_mul_f32_e32 v60, 0xbfb8aa3b, v57
	v_exp_f32_e32 v62, v60
	v_rcp_f32_e32 v60, v59
	v_add_f32_e32 v59, 1.0, v61
	v_rcp_f32_e32 v58, v58
	v_add_f32_e32 v61, 1.0, v62
	v_rcp_f32_e32 v59, v59
	v_rcp_f32_e32 v61, v61
	v_mov_b32_e32 v62, v54
	v_mov_b32_e32 v63, v56
	v_mov_b32_e32 v56, v55
	v_pk_mul_f32 v[58:59], v[62:63], v[58:59]
	v_mov_b32_e32 v63, v52
	v_pk_mul_f32 v[54:55], v[56:57], v[60:61]
	v_mov_b32_e32 v52, v51
	v_mov_b32_e32 v62, v50
	v_pk_mul_f32 v[50:51], v[52:53], v[54:55]
	v_pk_mul_f32 v[58:59], v[62:63], v[58:59]
	v_and_b32_sdwa v54, v51, v177 dst_sel:DWORD dst_unused:UNUSED_PAD src0_sel:WORD_1 src1_sel:DWORD
	v_and_b32_sdwa v52, v59, v177 dst_sel:DWORD dst_unused:UNUSED_PAD src0_sel:WORD_1 src1_sel:DWORD
	v_and_b32_sdwa v55, v50, v177 dst_sel:DWORD dst_unused:UNUSED_PAD src0_sel:WORD_1 src1_sel:DWORD
	v_add3_u32 v51, v51, v54, s28
	v_and_b32_sdwa v53, v58, v177 dst_sel:DWORD dst_unused:UNUSED_PAD src0_sel:WORD_1 src1_sel:DWORD
	v_add3_u32 v52, v59, v52, s28
	v_add3_u32 v50, v50, v55, s28
	v_and_b32_e32 v51, 0xffff0000, v51
	v_add3_u32 v53, v58, v53, s28
	v_and_b32_e32 v50, 0xffff0000, v50
	v_or_b32_sdwa v51, v51, v52 dst_sel:DWORD dst_unused:UNUSED_PAD src0_sel:DWORD src1_sel:WORD_1
	v_mul_f32_e32 v52, 0xbfb8aa3b, v46
	v_or_b32_sdwa v50, v50, v53 dst_sel:DWORD dst_unused:UNUSED_PAD src0_sel:DWORD src1_sel:WORD_1
	v_exp_f32_e32 v52, v52
	v_mul_f32_e32 v53, 0xbfb8aa3b, v47
	v_exp_f32_e32 v53, v53
	global_store_dwordx2 v[66:67], v[50:51], off offset:32
	v_add_f32_e32 v50, 1.0, v52
	v_mul_f32_e32 v52, 0xbfb8aa3b, v48
	v_add_f32_e32 v51, 1.0, v53
	v_exp_f32_e32 v53, v52
	v_mul_f32_e32 v52, 0xbfb8aa3b, v49
	v_exp_f32_e32 v54, v52
	v_rcp_f32_e32 v52, v51
	v_add_f32_e32 v51, 1.0, v53
	v_rcp_f32_e32 v50, v50
	v_add_f32_e32 v53, 1.0, v54
	v_rcp_f32_e32 v51, v51
	v_rcp_f32_e32 v53, v53
	v_mov_b32_e32 v54, v46
	v_mov_b32_e32 v55, v48
	v_mov_b32_e32 v48, v47
	v_pk_mul_f32 v[50:51], v[54:55], v[50:51]
	v_mov_b32_e32 v55, v44
	v_pk_mul_f32 v[46:47], v[48:49], v[52:53]
	v_mov_b32_e32 v44, v43
	v_mov_b32_e32 v54, v42
	v_pk_mul_f32 v[42:43], v[44:45], v[46:47]
	v_pk_mul_f32 v[50:51], v[54:55], v[50:51]
	v_and_b32_sdwa v46, v43, v177 dst_sel:DWORD dst_unused:UNUSED_PAD src0_sel:WORD_1 src1_sel:DWORD
	v_and_b32_sdwa v44, v51, v177 dst_sel:DWORD dst_unused:UNUSED_PAD src0_sel:WORD_1 src1_sel:DWORD
	v_and_b32_sdwa v47, v42, v177 dst_sel:DWORD dst_unused:UNUSED_PAD src0_sel:WORD_1 src1_sel:DWORD
	v_add3_u32 v43, v43, v46, s28
	v_and_b32_sdwa v45, v50, v177 dst_sel:DWORD dst_unused:UNUSED_PAD src0_sel:WORD_1 src1_sel:DWORD
	v_add3_u32 v44, v51, v44, s28
	v_add3_u32 v42, v42, v47, s28
	v_and_b32_e32 v43, 0xffff0000, v43
	v_add3_u32 v45, v50, v45, s28
	v_and_b32_e32 v42, 0xffff0000, v42
	v_or_b32_sdwa v43, v43, v44 dst_sel:DWORD dst_unused:UNUSED_PAD src0_sel:DWORD src1_sel:WORD_1
	v_mul_f32_e32 v44, 0xbfb8aa3b, v38
	v_or_b32_sdwa v42, v42, v45 dst_sel:DWORD dst_unused:UNUSED_PAD src0_sel:DWORD src1_sel:WORD_1
	v_exp_f32_e32 v44, v44
	v_mul_f32_e32 v45, 0xbfb8aa3b, v39
	v_exp_f32_e32 v45, v45
	global_store_dwordx2 v[66:67], v[42:43], off offset:64
	v_add_f32_e32 v42, 1.0, v44
	v_mul_f32_e32 v44, 0xbfb8aa3b, v40
	v_add_f32_e32 v43, 1.0, v45
	v_exp_f32_e32 v45, v44
	v_mul_f32_e32 v44, 0xbfb8aa3b, v41
	v_exp_f32_e32 v46, v44
	v_rcp_f32_e32 v44, v43
	v_add_f32_e32 v43, 1.0, v45
	v_rcp_f32_e32 v42, v42
	v_add_f32_e32 v45, 1.0, v46
	v_rcp_f32_e32 v43, v43
	v_rcp_f32_e32 v45, v45
	v_mov_b32_e32 v46, v38
	v_mov_b32_e32 v47, v40
	v_mov_b32_e32 v40, v39
	v_pk_mul_f32 v[42:43], v[46:47], v[42:43]
	v_mov_b32_e32 v47, v36
	v_pk_mul_f32 v[38:39], v[40:41], v[44:45]
	v_mov_b32_e32 v36, v35
	v_mov_b32_e32 v46, v34
	v_pk_mul_f32 v[34:35], v[36:37], v[38:39]
	v_pk_mul_f32 v[42:43], v[46:47], v[42:43]
	v_and_b32_sdwa v38, v35, v177 dst_sel:DWORD dst_unused:UNUSED_PAD src0_sel:WORD_1 src1_sel:DWORD
	v_and_b32_sdwa v39, v34, v177 dst_sel:DWORD dst_unused:UNUSED_PAD src0_sel:WORD_1 src1_sel:DWORD
	v_and_b32_sdwa v36, v43, v177 dst_sel:DWORD dst_unused:UNUSED_PAD src0_sel:WORD_1 src1_sel:DWORD
	v_and_b32_sdwa v37, v42, v177 dst_sel:DWORD dst_unused:UNUSED_PAD src0_sel:WORD_1 src1_sel:DWORD
	v_add3_u32 v35, v35, v38, s28
	v_add3_u32 v34, v34, v39, s28
	v_add3_u32 v37, v42, v37, s28
	v_add3_u32 v36, v43, v36, s28
	v_and_b32_e32 v35, 0xffff0000, v35
	v_and_b32_e32 v34, 0xffff0000, v34
	v_or_b32_sdwa v35, v35, v36 dst_sel:DWORD dst_unused:UNUSED_PAD src0_sel:DWORD src1_sel:WORD_1
	v_or_b32_sdwa v34, v34, v37 dst_sel:DWORD dst_unused:UNUSED_PAD src0_sel:DWORD src1_sel:WORD_1
	global_store_dwordx2 v[66:67], v[34:35], off offset:96
	v_mul_f32_e32 v35, 0xbfb8aa3b, v30
	v_exp_f32_e32 v36, v35
	v_mul_f32_e32 v35, 0xbfb8aa3b, v31
	v_mul_f32_e32 v38, 0xbfb8aa3b, v32
	v_exp_f32_e32 v37, v35
	v_exp_f32_e32 v39, v38
	v_mul_f32_e32 v38, 0xbfb8aa3b, v33
	v_exp_f32_e32 v40, v38
	v_add_f32_e32 v37, 1.0, v37
	v_add_f32_e32 v36, 1.0, v36
	v_rcp_f32_e32 v38, v37
	v_add_f32_e32 v37, 1.0, v39
	v_add_f32_e32 v39, 1.0, v40
	v_rcp_f32_e32 v36, v36
	v_rcp_f32_e32 v37, v37
	v_rcp_f32_e32 v39, v39
	v_mov_b32_e32 v40, v30
	v_mov_b32_e32 v41, v32
	v_mov_b32_e32 v32, v31
	v_pk_mul_f32 v[36:37], v[40:41], v[36:37]
	v_mov_b32_e32 v41, v28
	v_pk_mul_f32 v[30:31], v[32:33], v[38:39]
	v_mov_b32_e32 v28, v27
	v_mov_b32_e32 v40, v26
	v_pk_mul_f32 v[26:27], v[28:29], v[30:31]
	v_pk_mul_f32 v[36:37], v[40:41], v[36:37]
	v_and_b32_sdwa v30, v27, v177 dst_sel:DWORD dst_unused:UNUSED_PAD src0_sel:WORD_1 src1_sel:DWORD
	v_and_b32_sdwa v28, v37, v177 dst_sel:DWORD dst_unused:UNUSED_PAD src0_sel:WORD_1 src1_sel:DWORD
	v_and_b32_sdwa v31, v26, v177 dst_sel:DWORD dst_unused:UNUSED_PAD src0_sel:WORD_1 src1_sel:DWORD
	v_add3_u32 v27, v27, v30, s28
	v_and_b32_sdwa v29, v36, v177 dst_sel:DWORD dst_unused:UNUSED_PAD src0_sel:WORD_1 src1_sel:DWORD
	v_add3_u32 v28, v37, v28, s28
	v_add3_u32 v26, v26, v31, s28
	v_and_b32_e32 v27, 0xffff0000, v27
	v_add3_u32 v29, v36, v29, s28
	v_and_b32_e32 v26, 0xffff0000, v26
	v_or_b32_sdwa v27, v27, v28 dst_sel:DWORD dst_unused:UNUSED_PAD src0_sel:DWORD src1_sel:WORD_1
	v_mul_f32_e32 v28, 0xbfb8aa3b, v22
	v_or_b32_sdwa v26, v26, v29 dst_sel:DWORD dst_unused:UNUSED_PAD src0_sel:DWORD src1_sel:WORD_1
	v_exp_f32_e32 v28, v28
	v_mul_f32_e32 v29, 0xbfb8aa3b, v23
	v_or_b32_e32 v34, 48, v110
	v_exp_f32_e32 v29, v29
	v_mad_i64_i32 v[34:35], s[6:7], v34, s52, v[106:107]
	v_lshl_add_u64 v[34:35], v[34:35], 0, v[108:109]
	global_store_dwordx2 v[34:35], v[26:27], off
	v_add_f32_e32 v26, 1.0, v28
	v_mul_f32_e32 v28, 0xbfb8aa3b, v24
	v_add_f32_e32 v27, 1.0, v29
	v_exp_f32_e32 v29, v28
	v_mul_f32_e32 v28, 0xbfb8aa3b, v25
	v_exp_f32_e32 v30, v28
	v_rcp_f32_e32 v28, v27
	v_add_f32_e32 v27, 1.0, v29
	v_rcp_f32_e32 v26, v26
	v_add_f32_e32 v29, 1.0, v30
	v_rcp_f32_e32 v27, v27
	v_rcp_f32_e32 v29, v29
	v_mov_b32_e32 v30, v22
	v_mov_b32_e32 v31, v24
	v_mov_b32_e32 v24, v23
	v_pk_mul_f32 v[26:27], v[30:31], v[26:27]
	v_mov_b32_e32 v31, v20
	v_pk_mul_f32 v[22:23], v[24:25], v[28:29]
	v_mov_b32_e32 v20, v19
	v_mov_b32_e32 v30, v18
	v_pk_mul_f32 v[18:19], v[20:21], v[22:23]
	v_pk_mul_f32 v[26:27], v[30:31], v[26:27]
	v_and_b32_sdwa v22, v19, v177 dst_sel:DWORD dst_unused:UNUSED_PAD src0_sel:WORD_1 src1_sel:DWORD
	v_and_b32_sdwa v20, v27, v177 dst_sel:DWORD dst_unused:UNUSED_PAD src0_sel:WORD_1 src1_sel:DWORD
	v_and_b32_sdwa v23, v18, v177 dst_sel:DWORD dst_unused:UNUSED_PAD src0_sel:WORD_1 src1_sel:DWORD
	v_add3_u32 v19, v19, v22, s28
	v_and_b32_sdwa v21, v26, v177 dst_sel:DWORD dst_unused:UNUSED_PAD src0_sel:WORD_1 src1_sel:DWORD
	v_add3_u32 v20, v27, v20, s28
	v_add3_u32 v18, v18, v23, s28
	v_and_b32_e32 v19, 0xffff0000, v19
	v_add3_u32 v21, v26, v21, s28
	v_and_b32_e32 v18, 0xffff0000, v18
	v_or_b32_sdwa v19, v19, v20 dst_sel:DWORD dst_unused:UNUSED_PAD src0_sel:DWORD src1_sel:WORD_1
	v_mul_f32_e32 v20, 0xbfb8aa3b, v14
	v_or_b32_sdwa v18, v18, v21 dst_sel:DWORD dst_unused:UNUSED_PAD src0_sel:DWORD src1_sel:WORD_1
	v_exp_f32_e32 v20, v20
	v_mul_f32_e32 v21, 0xbfb8aa3b, v15
	v_exp_f32_e32 v21, v21
	global_store_dwordx2 v[34:35], v[18:19], off offset:32
	v_add_f32_e32 v18, 1.0, v20
	v_mul_f32_e32 v20, 0xbfb8aa3b, v16
	v_add_f32_e32 v19, 1.0, v21
	v_exp_f32_e32 v21, v20
	v_mul_f32_e32 v20, 0xbfb8aa3b, v17
	v_exp_f32_e32 v22, v20
	v_rcp_f32_e32 v20, v19
	v_add_f32_e32 v19, 1.0, v21
	v_rcp_f32_e32 v18, v18
	v_add_f32_e32 v21, 1.0, v22
	v_rcp_f32_e32 v19, v19
	v_rcp_f32_e32 v21, v21
	v_mov_b32_e32 v22, v14
	v_mov_b32_e32 v23, v16
	v_mov_b32_e32 v16, v15
	v_pk_mul_f32 v[18:19], v[22:23], v[18:19]
	v_mov_b32_e32 v23, v12
	v_pk_mul_f32 v[14:15], v[16:17], v[20:21]
	v_mov_b32_e32 v12, v11
	v_mov_b32_e32 v22, v10
	v_pk_mul_f32 v[10:11], v[12:13], v[14:15]
	v_pk_mul_f32 v[18:19], v[22:23], v[18:19]
	v_and_b32_sdwa v14, v11, v177 dst_sel:DWORD dst_unused:UNUSED_PAD src0_sel:WORD_1 src1_sel:DWORD
	v_and_b32_sdwa v12, v19, v177 dst_sel:DWORD dst_unused:UNUSED_PAD src0_sel:WORD_1 src1_sel:DWORD
	v_and_b32_sdwa v15, v10, v177 dst_sel:DWORD dst_unused:UNUSED_PAD src0_sel:WORD_1 src1_sel:DWORD
	v_add3_u32 v11, v11, v14, s28
	v_and_b32_sdwa v13, v18, v177 dst_sel:DWORD dst_unused:UNUSED_PAD src0_sel:WORD_1 src1_sel:DWORD
	v_add3_u32 v12, v19, v12, s28
	v_add3_u32 v10, v10, v15, s28
	v_and_b32_e32 v11, 0xffff0000, v11
	v_add3_u32 v13, v18, v13, s28
	v_and_b32_e32 v10, 0xffff0000, v10
	v_or_b32_sdwa v11, v11, v12 dst_sel:DWORD dst_unused:UNUSED_PAD src0_sel:DWORD src1_sel:WORD_1
	v_mul_f32_e32 v12, 0xbfb8aa3b, v6
	v_or_b32_sdwa v10, v10, v13 dst_sel:DWORD dst_unused:UNUSED_PAD src0_sel:DWORD src1_sel:WORD_1
	v_exp_f32_e32 v12, v12
	v_mul_f32_e32 v13, 0xbfb8aa3b, v7
	v_exp_f32_e32 v13, v13
	global_store_dwordx2 v[34:35], v[10:11], off offset:64
	v_add_f32_e32 v10, 1.0, v12
	v_mul_f32_e32 v12, 0xbfb8aa3b, v8
	v_add_f32_e32 v11, 1.0, v13
	v_exp_f32_e32 v13, v12
	v_mul_f32_e32 v12, 0xbfb8aa3b, v9
	v_exp_f32_e32 v14, v12
	v_rcp_f32_e32 v12, v11
	v_add_f32_e32 v11, 1.0, v13
	v_rcp_f32_e32 v10, v10
	v_add_f32_e32 v13, 1.0, v14
	v_rcp_f32_e32 v11, v11
	v_rcp_f32_e32 v13, v13
	v_mov_b32_e32 v14, v6
	v_mov_b32_e32 v15, v8
	v_mov_b32_e32 v8, v7
	v_pk_mul_f32 v[10:11], v[14:15], v[10:11]
	v_mov_b32_e32 v15, v4
	v_pk_mul_f32 v[6:7], v[8:9], v[12:13]
	v_mov_b32_e32 v4, v3
	v_mov_b32_e32 v14, v2
	v_pk_mul_f32 v[2:3], v[4:5], v[6:7]
	v_pk_mul_f32 v[10:11], v[14:15], v[10:11]
	v_and_b32_sdwa v6, v3, v177 dst_sel:DWORD dst_unused:UNUSED_PAD src0_sel:WORD_1 src1_sel:DWORD
	v_and_b32_sdwa v7, v2, v177 dst_sel:DWORD dst_unused:UNUSED_PAD src0_sel:WORD_1 src1_sel:DWORD
	v_and_b32_sdwa v4, v11, v177 dst_sel:DWORD dst_unused:UNUSED_PAD src0_sel:WORD_1 src1_sel:DWORD
	v_and_b32_sdwa v5, v10, v177 dst_sel:DWORD dst_unused:UNUSED_PAD src0_sel:WORD_1 src1_sel:DWORD
	v_add3_u32 v3, v3, v6, s28
	v_add3_u32 v2, v2, v7, s28
	v_add3_u32 v5, v10, v5, s28
	v_add3_u32 v4, v11, v4, s28
	v_and_b32_e32 v3, 0xffff0000, v3
	v_and_b32_e32 v2, 0xffff0000, v2
	s_add_i32 s14, s14, s11
	v_or_b32_sdwa v3, v3, v4 dst_sel:DWORD dst_unused:UNUSED_PAD src0_sel:DWORD src1_sel:WORD_1
	v_or_b32_sdwa v2, v2, v5 dst_sel:DWORD dst_unused:UNUSED_PAD src0_sel:DWORD src1_sel:WORD_1
	s_cmpk_gt_i32 s14, 0x4ff
	global_store_dwordx2 v[34:35], v[2:3], off offset:96
	s_cbranch_scc0 .LBB0_1440
	s_setprio 0

.LBB0_1458:
	s_and_b64 vcc, exec, s[14:15]
	s_cbranch_vccz .LBB0_1472
	v_mov_b32_e32 v2, v172
	s_mov_b32 s11, s42
	s_mov_b32 s14, s94
	s_cmpk_gt_i32 s14, 0x5ff
	s_cbranch_scc1 .LBB0_1464
	v_ashrrev_i32_e32 v204, 3, v2
	v_bfe_u32 v3, v2, 4, 2
	v_and_b32_e32 v4, 15, v2
	v_lshlrev_b32_e32 v0, 4, v2
	v_ashrrev_i32_e32 v5, 1, v2
	s_movk_i32 s2, 0xffc0
	v_lshlrev_b32_e32 v2, 1, v2
	v_and_b32_e32 v0, 0x70, v0
	v_and_or_b32 v205, v5, s2, v4
	v_and_b32_e32 v207, 0x80, v2
	s_movk_i32 s2, 0x90
	v_or_b32_e32 v2, v207, v4
	v_and_b32_e32 v100, 7, v204
	v_lshlrev_b32_e32 v100, 4, v100
	v_xor_b32_e32 v100, v100, v0
	v_lshl_add_u32 v166, v204, 7, v100
	v_lshl_add_u64 v[162:163], s[46:47], 0, v[0:1]
	v_lshl_add_u64 v[164:165], s[44:45], 0, v[0:1]
	v_and_b32_e32 v100, 7, v4
	v_xor_b32_e32 v100, v100, v3
	v_lshlrev_b32_e32 v206, 4, v100
	v_lshlrev_b32_e32 v208, 2, v3
	v_lshlrev_b32_e32 v0, 7, v205
	v_lshlrev_b32_e32 v167, 7, v2
	v_readfirstlane_b32 s100, v172
	s_nop 0
	s_cmpk_ge_u32 s100, 0x100
	s_cbranch_scc0 .Lprio_skip_P11B
	s_setprio 1
.Lprio_skip_P11B:
.LBB0_1461:
	s_mul_hi_i32 s2, s14, 0x38e38e39
	s_lshr_b32 s3, s2, 31
	s_ashr_i32 s2, s2, 4
	s_add_i32 s2, s2, s3
	s_mul_i32 s3, s2, 0x48
	s_sub_i32 s3, s14, s3
	s_lshl_b32 s6, s3, 8
	v_add_u32_e32 v2, s6, v204
	v_ashrrev_i32_e32 v3, 31, v2
	v_lshlrev_b64 v[2:3], 11, v[2:3]
	v_lshl_add_u64 v[168:169], v[162:163], 0, v[2:3]
	v_add_co_u32_e32 v56, vcc, s34, v168
	s_lshl_b32 s7, s2, 8
	s_nop 0
	v_addc_co_u32_e32 v57, vcc, 0, v169, vcc
	v_add_u32_e32 v2, s7, v204
	s_waitcnt vmcnt(9)
	v_add_co_u32_e32 v58, vcc, s35, v168
	v_ashrrev_i32_e32 v3, 31, v2
	s_nop 0
	v_addc_co_u32_e32 v59, vcc, 0, v169, vcc
	v_lshlrev_b64 v[2:3], 11, v[2:3]
	v_add_co_u32_e32 v60, vcc, s36, v168
	v_lshl_add_u64 v[170:171], v[164:165], 0, v[2:3]
	s_nop 0
	v_addc_co_u32_e32 v61, vcc, 0, v169, vcc
	s_waitcnt vmcnt(8)
	v_add_co_u32_e32 v62, vcc, s35, v170
	global_load_dwordx4 v[24:27], v[56:57], off
	global_load_dwordx4 v[28:31], v[58:59], off
	v_addc_co_u32_e32 v63, vcc, 0, v171, vcc
	v_add_co_u32_e32 v64, vcc, s36, v170
	global_load_dwordx4 v[32:35], v[168:169], off
	global_load_dwordx4 v[36:39], v[170:171], off
	v_addc_co_u32_e32 v65, vcc, 0, v171, vcc
	v_add_co_u32_e32 v66, vcc, s34, v170
	global_load_dwordx4 v[40:43], v[62:63], off
	global_load_dwordx4 v[44:47], v[64:65], off
	v_addc_co_u32_e32 v67, vcc, 0, v171, vcc
	global_load_dwordx4 v[48:51], v[60:61], off
	global_load_dwordx4 v[52:55], v[66:67], off
	s_waitcnt lgkmcnt(0)
	s_barrier
	global_load_dwordx4 v[114:117], v[168:169], off offset:128
	global_load_dwordx4 v[106:109], v[56:57], off offset:128
	global_load_dwordx4 v[110:113], v[58:59], off offset:128
	global_load_dwordx4 v[126:129], v[60:61], off offset:128
	global_load_dwordx4 v[122:125], v[170:171], off offset:128
	global_load_dwordx4 v[118:121], v[66:67], off offset:128
	global_load_dwordx4 v[134:137], v[62:63], off offset:128
	global_load_dwordx4 v[130:133], v[64:65], off offset:128
	v_readfirstlane_b32 vcc_lo, v168
	v_readfirstlane_b32 vcc_hi, v169
	v_readfirstlane_b32 s100, v170
	v_readfirstlane_b32 s101, v171
	s_nop 1
	v_subrev_u32_e32 v168, vcc_lo, v168
	v_subrev_u32_e32 v170, s100, v170
	v_mov_b32_e32 v2, 0
	s_mov_b32 s4, 0
	v_mov_b32_e32 v3, v2
	v_mov_b32_e32 v4, v2
	v_mov_b32_e32 v5, v2
	v_mov_b32_e32 v6, v2
	v_mov_b32_e32 v7, v2
	v_mov_b32_e32 v8, v2
	v_mov_b32_e32 v9, v2
	v_mov_b32_e32 v10, v2
	v_mov_b32_e32 v11, v2
	v_mov_b32_e32 v12, v2
	v_mov_b32_e32 v13, v2
	v_mov_b32_e32 v14, v2
	v_mov_b32_e32 v15, v2
	v_mov_b32_e32 v16, v2
	v_mov_b32_e32 v17, v2
	v_mov_b32_e32 v18, v2
	v_mov_b32_e32 v19, v2
	v_mov_b32_e32 v20, v2
	v_mov_b32_e32 v21, v2
	v_mov_b32_e32 v22, v2
	v_mov_b32_e32 v23, v2
	v_mov_b32_e32 v56, v2
	v_mov_b32_e32 v57, v2
	v_mov_b32_e32 v58, v2
	v_mov_b32_e32 v59, v2
	v_mov_b32_e32 v60, v2
	v_mov_b32_e32 v61, v2
	v_mov_b32_e32 v62, v2
	v_mov_b32_e32 v63, v2
	v_mov_b32_e32 v64, v2
	v_mov_b32_e32 v65, v2
	v_mov_b32_e32 v66, v2
	v_mov_b32_e32 v67, v2
	v_mov_b32_e32 v68, v2
	v_mov_b32_e32 v69, v2
	v_mov_b32_e32 v70, v2
	v_mov_b32_e32 v71, v2
	v_mov_b32_e32 v72, v2
	v_mov_b32_e32 v73, v2
	v_mov_b32_e32 v74, v2
	v_mov_b32_e32 v75, v2
	v_mov_b32_e32 v76, v2
	v_mov_b32_e32 v77, v2
	v_mov_b32_e32 v78, v2
	v_mov_b32_e32 v79, v2
	v_mov_b32_e32 v80, v2
	v_mov_b32_e32 v81, v2
	v_mov_b32_e32 v82, v2
	v_mov_b32_e32 v83, v2
	v_mov_b32_e32 v84, v2
	v_mov_b32_e32 v85, v2
	s_waitcnt vmcnt(11)
	ds_write_b128 v166, v[40:43] offset:49152
	s_waitcnt vmcnt(10)
	ds_write_b128 v166, v[44:47] offset:57344
	ds_write_b128 v166, v[32:35]
	ds_write_b128 v166, v[36:39] offset:32768
	ds_write_b128 v166, v[24:27] offset:8192
	ds_write_b128 v166, v[28:31] offset:16384
	s_waitcnt vmcnt(9)
	ds_write_b128 v166, v[48:51] offset:24576
	s_waitcnt vmcnt(8)
	ds_write_b128 v166, v[52:55] offset:40960
	v_mov_b32_e32 v24, v2
	v_mov_b32_e32 v25, v2
	v_mov_b32_e32 v26, v2
	v_mov_b32_e32 v27, v2
	v_mov_b32_e32 v28, v2
	v_mov_b32_e32 v29, v2
	v_mov_b32_e32 v30, v2
	v_mov_b32_e32 v31, v2
	v_mov_b32_e32 v32, v2
	v_mov_b32_e32 v33, v2
	v_mov_b32_e32 v34, v2
	v_mov_b32_e32 v35, v2
	v_mov_b32_e32 v36, v2
	v_mov_b32_e32 v37, v2
	v_mov_b32_e32 v38, v2
	v_mov_b32_e32 v39, v2
	v_mov_b32_e32 v40, v2
	v_mov_b32_e32 v41, v2
	v_mov_b32_e32 v42, v2
	v_mov_b32_e32 v43, v2
	v_mov_b32_e32 v44, v2
	v_mov_b32_e32 v45, v2
	v_mov_b32_e32 v46, v2
	v_mov_b32_e32 v47, v2
	v_mov_b32_e32 v48, v2
	v_mov_b32_e32 v49, v2
	v_mov_b32_e32 v50, v2
	v_mov_b32_e32 v51, v2
	v_mov_b32_e32 v52, v2
	v_mov_b32_e32 v53, v2
	v_mov_b32_e32 v54, v2
	v_mov_b32_e32 v55, v2
	v_mov_b32_e32 v86, v2
	v_mov_b32_e32 v87, v2
	v_mov_b32_e32 v88, v2
	v_mov_b32_e32 v89, v2
	v_mov_b32_e32 v90, v2
	v_mov_b32_e32 v91, v2
	v_mov_b32_e32 v92, v2
	v_mov_b32_e32 v93, v2
	v_mov_b32_e32 v94, v2
	v_mov_b32_e32 v95, v2
	v_mov_b32_e32 v96, v2
	v_mov_b32_e32 v97, v2
	v_mov_b32_e32 v98, v2
	v_mov_b32_e32 v99, v2
	v_mov_b32_e32 v100, v2
	v_mov_b32_e32 v101, v2
	v_mov_b32_e32 v102, v2
	v_mov_b32_e32 v103, v2
	v_mov_b32_e32 v104, v2
	v_mov_b32_e32 v105, v2
	v_mov_b32_e32 v138, v2
	v_mov_b32_e32 v139, v2
	v_mov_b32_e32 v140, v2
	v_mov_b32_e32 v141, v2
	v_mov_b32_e32 v142, v2
	v_mov_b32_e32 v143, v2
	v_mov_b32_e32 v144, v2
	v_mov_b32_e32 v145, v2
	v_mov_b32_e32 v146, v2
	v_mov_b32_e32 v147, v2
	v_mov_b32_e32 v148, v2
	v_mov_b32_e32 v149, v2
	v_mov_b32_e32 v150, v2
	v_mov_b32_e32 v151, v2
	v_mov_b32_e32 v152, v2
	v_mov_b32_e32 v153, v2
	v_mov_b32_e32 v154, v2
	v_mov_b32_e32 v155, v2
	v_mov_b32_e32 v156, v2
	v_mov_b32_e32 v157, v2
	v_mov_b32_e32 v158, v2
	v_mov_b32_e32 v159, v2
	v_mov_b32_e32 v160, v2
	v_mov_b32_e32 v161, v2
	s_waitcnt lgkmcnt(0)
	s_barrier
.LBB0_1462:
	s_bitcmp1_b32 s4, 0
	s_cselect_b32 s2, 0x12000, 0
	v_or_b32_e32 v218, s2, v206
	v_add_u32_e32 v214, v218, v0
	v_add_u32_e32 v246, v218, v167
	ds_read_b128 v[184:187], v214
	ds_read_b128 v[198:201], v214 offset:2048
	ds_read_b128 v[210:213], v214 offset:4096
	ds_read_b128 v[214:217], v214 offset:6144
	ds_read_b128 v[218:221], v246 offset:32768
	ds_read_b128 v[222:225], v246 offset:34816
	ds_read_b128 v[226:229], v246 offset:36864
	ds_read_b128 v[230:233], v246 offset:38912
	ds_read_b128 v[234:237], v246 offset:40960
	ds_read_b128 v[238:241], v246 offset:43008
	ds_read_b128 v[242:245], v246 offset:45056
	ds_read_b128 v[246:249], v246 offset:47104
	s_add_i32 s10, s4, 1
	s_bitcmp1_b32 s10, 0
	s_cselect_b32 s3, 0x12000, 0
	v_add_u32_e32 v171, s3, v166
	v_xor_b32_e32 v169, 64, v206
	v_add3_u32 v169, s2, v167, v169
	s_waitcnt lgkmcnt(7)
	v_mfma_f32_16x16x32_bf16 v[158:161], v[218:221], v[184:187], v[158:161]
	v_mfma_f32_16x16x32_bf16 v[94:97], v[218:221], v[198:201], v[94:97]
	v_mfma_f32_16x16x32_bf16 v[62:65], v[218:221], v[210:213], v[62:65]
	v_mfma_f32_16x16x32_bf16 v[30:33], v[218:221], v[214:217], v[30:33]
	ds_read_b128 v[218:221], v169 offset:32768
	s_waitcnt lgkmcnt(7)
	v_mfma_f32_16x16x32_bf16 v[154:157], v[222:225], v[184:187], v[154:157]
	v_mfma_f32_16x16x32_bf16 v[90:93], v[222:225], v[198:201], v[90:93]
	v_mfma_f32_16x16x32_bf16 v[58:61], v[222:225], v[210:213], v[58:61]
	v_mfma_f32_16x16x32_bf16 v[26:29], v[222:225], v[214:217], v[26:29]
	ds_read_b128 v[222:225], v169 offset:34816
	s_waitcnt lgkmcnt(7)
	v_mfma_f32_16x16x32_bf16 v[150:153], v[226:229], v[184:187], v[150:153]
	v_mfma_f32_16x16x32_bf16 v[86:89], v[226:229], v[198:201], v[86:89]
	v_mfma_f32_16x16x32_bf16 v[54:57], v[226:229], v[210:213], v[54:57]
	v_mfma_f32_16x16x32_bf16 v[22:25], v[226:229], v[214:217], v[22:25]
	ds_read_b128 v[226:229], v169 offset:36864
	s_waitcnt lgkmcnt(7)
	v_mfma_f32_16x16x32_bf16 v[146:149], v[230:233], v[184:187], v[146:149]
	v_mfma_f32_16x16x32_bf16 v[82:85], v[230:233], v[198:201], v[82:85]
	v_mfma_f32_16x16x32_bf16 v[50:53], v[230:233], v[210:213], v[50:53]
	v_mfma_f32_16x16x32_bf16 v[18:21], v[230:233], v[214:217], v[18:21]
	ds_read_b128 v[230:233], v169 offset:38912
	s_waitcnt lgkmcnt(7)
	v_mfma_f32_16x16x32_bf16 v[142:145], v[234:237], v[184:187], v[142:145]
	v_mfma_f32_16x16x32_bf16 v[78:81], v[234:237], v[198:201], v[78:81]
	v_mfma_f32_16x16x32_bf16 v[46:49], v[234:237], v[210:213], v[46:49]
	v_mfma_f32_16x16x32_bf16 v[14:17], v[234:237], v[214:217], v[14:17]
	ds_read_b128 v[234:237], v169 offset:40960
	s_waitcnt lgkmcnt(7)
	v_mfma_f32_16x16x32_bf16 v[138:141], v[238:241], v[184:187], v[138:141]
	v_mfma_f32_16x16x32_bf16 v[74:77], v[238:241], v[198:201], v[74:77]
	v_mfma_f32_16x16x32_bf16 v[42:45], v[238:241], v[210:213], v[42:45]
	v_mfma_f32_16x16x32_bf16 v[10:13], v[238:241], v[214:217], v[10:13]
	ds_read_b128 v[238:241], v169 offset:43008
	s_waitcnt lgkmcnt(7)
	v_mfma_f32_16x16x32_bf16 v[102:105], v[242:245], v[184:187], v[102:105]
	v_mfma_f32_16x16x32_bf16 v[70:73], v[242:245], v[198:201], v[70:73]
	v_mfma_f32_16x16x32_bf16 v[38:41], v[242:245], v[210:213], v[38:41]
	v_mfma_f32_16x16x32_bf16 v[6:9], v[242:245], v[214:217], v[6:9]
	ds_read_b128 v[242:245], v169 offset:45056
	s_waitcnt lgkmcnt(7)
	v_mfma_f32_16x16x32_bf16 v[98:101], v[246:249], v[184:187], v[98:101]
	v_mfma_f32_16x16x32_bf16 v[66:69], v[246:249], v[198:201], v[66:69]
	v_xor_b32_e32 v169, 64, v206
	v_add3_u32 v169, s2, v0, v169
	ds_read_b128 v[184:187], v169
	ds_read_b128 v[198:201], v169 offset:2048
	v_mfma_f32_16x16x32_bf16 v[34:37], v[246:249], v[210:213], v[34:37]
	ds_read_b128 v[210:213], v169 offset:4096
	v_mfma_f32_16x16x32_bf16 v[2:5], v[246:249], v[214:217], v[2:5]
	ds_read_b128 v[214:217], v169 offset:6144
	v_xor_b32_e32 v169, 64, v206
	v_add3_u32 v169, s2, v167, v169
	ds_read_b128 v[246:249], v169 offset:47104
	s_waitcnt lgkmcnt(1)
	v_mfma_f32_16x16x32_bf16 v[158:161], v[218:221], v[184:187], v[158:161]
	v_mfma_f32_16x16x32_bf16 v[94:97], v[218:221], v[198:201], v[94:97]
	v_mfma_f32_16x16x32_bf16 v[62:65], v[218:221], v[210:213], v[62:65]
	v_mfma_f32_16x16x32_bf16 v[30:33], v[218:221], v[214:217], v[30:33]
	s_waitcnt vmcnt(7)
	ds_write_b128 v171, v[114:117]
	v_mfma_f32_16x16x32_bf16 v[154:157], v[222:225], v[184:187], v[154:157]
	v_mfma_f32_16x16x32_bf16 v[90:93], v[222:225], v[198:201], v[90:93]
	global_load_dwordx4 v[114:117], v168, vcc offset:256
	v_mfma_f32_16x16x32_bf16 v[58:61], v[222:225], v[210:213], v[58:61]
	v_mfma_f32_16x16x32_bf16 v[26:29], v[222:225], v[214:217], v[26:29]
	s_waitcnt vmcnt(7)
	ds_write_b128 v171, v[106:109] offset:8192
	v_mfma_f32_16x16x32_bf16 v[150:153], v[226:229], v[184:187], v[150:153]
	v_mfma_f32_16x16x32_bf16 v[86:89], v[226:229], v[198:201], v[86:89]
	v_add_u32_e32 v106, s34, v168
	global_load_dwordx4 v[106:109], v106, vcc offset:256
	v_mfma_f32_16x16x32_bf16 v[54:57], v[226:229], v[210:213], v[54:57]
	v_mfma_f32_16x16x32_bf16 v[22:25], v[226:229], v[214:217], v[22:25]
	s_waitcnt vmcnt(7)
	ds_write_b128 v171, v[110:113] offset:16384
	v_mfma_f32_16x16x32_bf16 v[146:149], v[230:233], v[184:187], v[146:149]
	v_mfma_f32_16x16x32_bf16 v[82:85], v[230:233], v[198:201], v[82:85]
	v_add_u32_e32 v110, s35, v168
	global_load_dwordx4 v[110:113], v110, vcc offset:256
	v_mfma_f32_16x16x32_bf16 v[50:53], v[230:233], v[210:213], v[50:53]
	v_mfma_f32_16x16x32_bf16 v[18:21], v[230:233], v[214:217], v[18:21]
	s_waitcnt vmcnt(7)
	ds_write_b128 v171, v[126:129] offset:24576
	v_mfma_f32_16x16x32_bf16 v[142:145], v[234:237], v[184:187], v[142:145]
	v_mfma_f32_16x16x32_bf16 v[78:81], v[234:237], v[198:201], v[78:81]
	v_add_u32_e32 v126, s36, v168
	global_load_dwordx4 v[126:129], v126, vcc offset:256
	v_mfma_f32_16x16x32_bf16 v[46:49], v[234:237], v[210:213], v[46:49]
	v_mfma_f32_16x16x32_bf16 v[14:17], v[234:237], v[214:217], v[14:17]
	s_waitcnt vmcnt(7)
	ds_write_b128 v171, v[122:125] offset:32768
	v_mfma_f32_16x16x32_bf16 v[138:141], v[238:241], v[184:187], v[138:141]
	v_mfma_f32_16x16x32_bf16 v[74:77], v[238:241], v[198:201], v[74:77]
	global_load_dwordx4 v[122:125], v170, s[100:101] offset:256
	v_mfma_f32_16x16x32_bf16 v[42:45], v[238:241], v[210:213], v[42:45]
	v_mfma_f32_16x16x32_bf16 v[10:13], v[238:241], v[214:217], v[10:13]
	s_waitcnt vmcnt(7)
	ds_write_b128 v171, v[118:121] offset:40960
	v_mfma_f32_16x16x32_bf16 v[102:105], v[242:245], v[184:187], v[102:105]
	v_mfma_f32_16x16x32_bf16 v[70:73], v[242:245], v[198:201], v[70:73]
	v_add_u32_e32 v118, s34, v170
	global_load_dwordx4 v[118:121], v118, s[100:101] offset:256
	v_mfma_f32_16x16x32_bf16 v[38:41], v[242:245], v[210:213], v[38:41]
	v_mfma_f32_16x16x32_bf16 v[6:9], v[242:245], v[214:217], v[6:9]
	s_waitcnt vmcnt(7)
	ds_write_b128 v171, v[134:137] offset:49152
	s_waitcnt lgkmcnt(7)
	v_mfma_f32_16x16x32_bf16 v[98:101], v[246:249], v[184:187], v[98:101]
	v_mfma_f32_16x16x32_bf16 v[66:69], v[246:249], v[198:201], v[66:69]
	v_add_u32_e32 v134, s35, v170
	global_load_dwordx4 v[134:137], v134, s[100:101] offset:256
	v_mfma_f32_16x16x32_bf16 v[34:37], v[246:249], v[210:213], v[34:37]
	v_mfma_f32_16x16x32_bf16 v[2:5], v[246:249], v[214:217], v[2:5]
	s_waitcnt vmcnt(7)
	ds_write_b128 v171, v[130:133] offset:57344
	v_add_u32_e32 v130, s36, v170
	global_load_dwordx4 v[130:133], v130, s[100:101] offset:256
	v_add_u32_e32 v168, 0x80, v168
	v_add_u32_e32 v170, 0x80, v170
	s_waitcnt lgkmcnt(0)
	s_barrier
	s_cmp_eq_u32 s10, 16
	s_mov_b32 s4, s10
	s_cbranch_scc0 .LBB0_1462
	s_waitcnt vmcnt(4)
	v_mul_f32_e32 v109, 0xbfb8aa3b, v158
	v_exp_f32_e32 v109, v109
	s_waitcnt vmcnt(3)
	v_mul_f32_e32 v111, 0xbfb8aa3b, v159
	v_exp_f32_e32 v111, v111
	v_mul_f32_e32 v115, 0xbfb8aa3b, v161
	v_add_f32_e32 v109, 1.0, v109
	v_rcp_f32_e32 v114, v109
	v_add_f32_e32 v109, 1.0, v111
	v_mul_f32_e32 v111, 0xbfb8aa3b, v160
	v_exp_f32_e32 v111, v111
	v_exp_f32_e32 v117, v115
	v_rcp_f32_e32 v116, v109
	s_waitcnt vmcnt(2)
	v_mov_b32_e32 v118, v158
	v_add_f32_e32 v109, 1.0, v111
	v_rcp_f32_e32 v115, v109
	v_add_f32_e32 v109, 1.0, v117
	v_rcp_f32_e32 v117, v109
	v_mov_b32_e32 v119, v160
	v_pk_mul_f32 v[114:115], v[118:119], v[114:115]
	v_mov_b32_e32 v118, v154
	v_mov_b32_e32 v119, v156
	v_mov_b32_e32 v160, v159
	v_pk_mul_f32 v[114:115], v[118:119], v[114:115]
	v_pk_mul_f32 v[116:117], v[160:161], v[116:117]
	v_mov_b32_e32 v156, v155
	v_pk_mul_f32 v[116:117], v[156:157], v[116:117]
	v_and_b32_sdwa v111, v115, v177 dst_sel:DWORD dst_unused:UNUSED_PAD src0_sel:WORD_1 src1_sel:DWORD
	v_and_b32_sdwa v118, v114, v177 dst_sel:DWORD dst_unused:UNUSED_PAD src0_sel:WORD_1 src1_sel:DWORD
	v_add3_u32 v111, v115, v111, s28
	v_and_b32_sdwa v115, v117, v177 dst_sel:DWORD dst_unused:UNUSED_PAD src0_sel:WORD_1 src1_sel:DWORD
	v_add3_u32 v114, v114, v118, s28
	v_and_b32_sdwa v118, v116, v177 dst_sel:DWORD dst_unused:UNUSED_PAD src0_sel:WORD_1 src1_sel:DWORD
	v_add3_u32 v115, v117, v115, s28
	v_or_b32_e32 v106, s7, v207
	v_add3_u32 v116, v116, v118, s28
	v_and_b32_e32 v115, 0xffff0000, v115
	v_ashrrev_i32_e32 v106, 1, v106
	v_and_b32_e32 v116, 0xffff0000, v116
	v_or_b32_sdwa v115, v115, v111 dst_sel:DWORD dst_unused:UNUSED_PAD src0_sel:DWORD src1_sel:WORD_1
	v_mul_f32_e32 v111, 0xbfb8aa3b, v150
	v_or_b32_e32 v108, v106, v208
	v_or_b32_sdwa v114, v116, v114 dst_sel:DWORD dst_unused:UNUSED_PAD src0_sel:DWORD src1_sel:WORD_1
	v_exp_f32_e32 v111, v111
	v_mul_f32_e32 v116, 0xbfb8aa3b, v151
	v_add_u32_e32 v110, s6, v205
	v_mov_b64_e32 v[106:107], s[12:13]
	v_ashrrev_i32_e32 v109, 31, v108
	v_exp_f32_e32 v116, v116
	v_mad_i64_i32 v[112:113], s[6:7], v110, s52, v[106:107]
	v_lshlrev_b64 v[108:109], 1, v[108:109]
	v_lshl_add_u64 v[112:113], v[112:113], 0, v[108:109]
	s_waitcnt vmcnt(0)
	global_store_dwordx2 v[112:113], v[114:115], off
	v_add_f32_e32 v111, 1.0, v111
	v_mul_f32_e32 v115, 0xbfb8aa3b, v152
	v_rcp_f32_e32 v114, v111
	v_add_f32_e32 v111, 1.0, v116
	v_exp_f32_e32 v115, v115
	v_mul_f32_e32 v116, 0xbfb8aa3b, v153
	v_exp_f32_e32 v117, v116
	v_rcp_f32_e32 v116, v111
	v_add_f32_e32 v111, 1.0, v115
	v_rcp_f32_e32 v115, v111
	v_add_f32_e32 v111, 1.0, v117
	v_rcp_f32_e32 v117, v111
	v_mov_b32_e32 v118, v150
	v_mov_b32_e32 v119, v152
	v_pk_mul_f32 v[114:115], v[118:119], v[114:115]
	v_mov_b32_e32 v118, v146
	v_mov_b32_e32 v119, v148
	v_mov_b32_e32 v152, v151
	v_pk_mul_f32 v[114:115], v[118:119], v[114:115]
	v_pk_mul_f32 v[116:117], v[152:153], v[116:117]
	v_mov_b32_e32 v148, v147
	v_pk_mul_f32 v[116:117], v[148:149], v[116:117]
	v_and_b32_sdwa v111, v115, v177 dst_sel:DWORD dst_unused:UNUSED_PAD src0_sel:WORD_1 src1_sel:DWORD
	v_and_b32_sdwa v118, v114, v177 dst_sel:DWORD dst_unused:UNUSED_PAD src0_sel:WORD_1 src1_sel:DWORD
	v_add3_u32 v111, v115, v111, s28
	v_and_b32_sdwa v115, v117, v177 dst_sel:DWORD dst_unused:UNUSED_PAD src0_sel:WORD_1 src1_sel:DWORD
	v_add3_u32 v114, v114, v118, s28
	v_and_b32_sdwa v118, v116, v177 dst_sel:DWORD dst_unused:UNUSED_PAD src0_sel:WORD_1 src1_sel:DWORD
	v_add3_u32 v115, v117, v115, s28
	v_add3_u32 v116, v116, v118, s28
	v_and_b32_e32 v115, 0xffff0000, v115
	v_and_b32_e32 v116, 0xffff0000, v116
	v_or_b32_sdwa v115, v115, v111 dst_sel:DWORD dst_unused:UNUSED_PAD src0_sel:DWORD src1_sel:WORD_1
	v_mul_f32_e32 v111, 0xbfb8aa3b, v142
	v_or_b32_sdwa v114, v116, v114 dst_sel:DWORD dst_unused:UNUSED_PAD src0_sel:DWORD src1_sel:WORD_1
	v_exp_f32_e32 v111, v111
	v_mul_f32_e32 v116, 0xbfb8aa3b, v143
	v_exp_f32_e32 v116, v116
	global_store_dwordx2 v[112:113], v[114:115], off offset:32
	v_add_f32_e32 v111, 1.0, v111
	v_mul_f32_e32 v115, 0xbfb8aa3b, v144
	v_rcp_f32_e32 v114, v111
	v_add_f32_e32 v111, 1.0, v116
	v_exp_f32_e32 v115, v115
	v_mul_f32_e32 v116, 0xbfb8aa3b, v145
	v_exp_f32_e32 v117, v116
	v_rcp_f32_e32 v116, v111
	v_add_f32_e32 v111, 1.0, v115
	v_rcp_f32_e32 v115, v111
	v_add_f32_e32 v111, 1.0, v117
	v_rcp_f32_e32 v117, v111
	v_mov_b32_e32 v118, v142
	v_mov_b32_e32 v119, v144
	v_pk_mul_f32 v[114:115], v[118:119], v[114:115]
	v_mov_b32_e32 v118, v138
	v_mov_b32_e32 v119, v140
	v_mov_b32_e32 v144, v143
	v_pk_mul_f32 v[114:115], v[118:119], v[114:115]
	v_pk_mul_f32 v[116:117], v[144:145], v[116:117]
	v_mov_b32_e32 v140, v139
	v_pk_mul_f32 v[116:117], v[140:141], v[116:117]
	v_and_b32_sdwa v111, v115, v177 dst_sel:DWORD dst_unused:UNUSED_PAD src0_sel:WORD_1 src1_sel:DWORD
	v_and_b32_sdwa v118, v114, v177 dst_sel:DWORD dst_unused:UNUSED_PAD src0_sel:WORD_1 src1_sel:DWORD
	v_add3_u32 v111, v115, v111, s28
	v_and_b32_sdwa v115, v117, v177 dst_sel:DWORD dst_unused:UNUSED_PAD src0_sel:WORD_1 src1_sel:DWORD
	v_add3_u32 v114, v114, v118, s28
	v_and_b32_sdwa v118, v116, v177 dst_sel:DWORD dst_unused:UNUSED_PAD src0_sel:WORD_1 src1_sel:DWORD
	v_add3_u32 v115, v117, v115, s28
	v_add3_u32 v116, v116, v118, s28
	v_and_b32_e32 v115, 0xffff0000, v115
	v_and_b32_e32 v116, 0xffff0000, v116
	v_or_b32_sdwa v115, v115, v111 dst_sel:DWORD dst_unused:UNUSED_PAD src0_sel:DWORD src1_sel:WORD_1
	v_mul_f32_e32 v111, 0xbfb8aa3b, v102
	v_or_b32_sdwa v114, v116, v114 dst_sel:DWORD dst_unused:UNUSED_PAD src0_sel:DWORD src1_sel:WORD_1
	v_exp_f32_e32 v111, v111
	v_mul_f32_e32 v116, 0xbfb8aa3b, v103
	v_exp_f32_e32 v116, v116
	global_store_dwordx2 v[112:113], v[114:115], off offset:64
	v_add_f32_e32 v111, 1.0, v111
	v_mul_f32_e32 v115, 0xbfb8aa3b, v104
	v_rcp_f32_e32 v114, v111
	v_add_f32_e32 v111, 1.0, v116
	v_exp_f32_e32 v115, v115
	v_mul_f32_e32 v116, 0xbfb8aa3b, v105
	v_exp_f32_e32 v117, v116
	v_rcp_f32_e32 v116, v111
	v_add_f32_e32 v111, 1.0, v115
	v_rcp_f32_e32 v115, v111
	v_add_f32_e32 v111, 1.0, v117
	v_rcp_f32_e32 v117, v111
	v_mov_b32_e32 v118, v102
	v_mov_b32_e32 v119, v104
	v_mov_b32_e32 v104, v103
	v_pk_mul_f32 v[114:115], v[118:119], v[114:115]
	v_mov_b32_e32 v119, v100
	v_pk_mul_f32 v[102:103], v[104:105], v[116:117]
	v_mov_b32_e32 v100, v99
	v_mov_b32_e32 v118, v98
	v_pk_mul_f32 v[98:99], v[100:101], v[102:103]
	v_pk_mul_f32 v[114:115], v[118:119], v[114:115]
	v_and_b32_sdwa v102, v99, v177 dst_sel:DWORD dst_unused:UNUSED_PAD src0_sel:WORD_1 src1_sel:DWORD
	v_and_b32_sdwa v103, v98, v177 dst_sel:DWORD dst_unused:UNUSED_PAD src0_sel:WORD_1 src1_sel:DWORD
	v_and_b32_sdwa v100, v115, v177 dst_sel:DWORD dst_unused:UNUSED_PAD src0_sel:WORD_1 src1_sel:DWORD
	v_and_b32_sdwa v101, v114, v177 dst_sel:DWORD dst_unused:UNUSED_PAD src0_sel:WORD_1 src1_sel:DWORD
	v_add3_u32 v99, v99, v102, s28
	v_add3_u32 v98, v98, v103, s28
	v_add3_u32 v101, v114, v101, s28
	v_add3_u32 v100, v115, v100, s28
	v_and_b32_e32 v99, 0xffff0000, v99
	v_and_b32_e32 v98, 0xffff0000, v98
	v_or_b32_sdwa v99, v99, v100 dst_sel:DWORD dst_unused:UNUSED_PAD src0_sel:DWORD src1_sel:WORD_1
	v_or_b32_sdwa v98, v98, v101 dst_sel:DWORD dst_unused:UNUSED_PAD src0_sel:DWORD src1_sel:WORD_1
	global_store_dwordx2 v[112:113], v[98:99], off offset:96
	v_mul_f32_e32 v99, 0xbfb8aa3b, v94
	v_exp_f32_e32 v100, v99
	v_mul_f32_e32 v99, 0xbfb8aa3b, v95
	v_mul_f32_e32 v102, 0xbfb8aa3b, v96
	v_exp_f32_e32 v101, v99
	v_exp_f32_e32 v103, v102
	v_mul_f32_e32 v102, 0xbfb8aa3b, v97
	v_exp_f32_e32 v104, v102
	v_add_f32_e32 v101, 1.0, v101
	v_add_f32_e32 v100, 1.0, v100
	v_rcp_f32_e32 v102, v101
	v_add_f32_e32 v101, 1.0, v103
	v_add_f32_e32 v103, 1.0, v104
	v_rcp_f32_e32 v100, v100
	v_rcp_f32_e32 v101, v101
	v_rcp_f32_e32 v103, v103
	v_mov_b32_e32 v104, v94
	v_mov_b32_e32 v105, v96
	v_mov_b32_e32 v96, v95
	v_pk_mul_f32 v[100:101], v[104:105], v[100:101]
	v_mov_b32_e32 v105, v92
	v_pk_mul_f32 v[94:95], v[96:97], v[102:103]
	v_mov_b32_e32 v92, v91
	v_mov_b32_e32 v104, v90
	v_pk_mul_f32 v[90:91], v[92:93], v[94:95]
	v_pk_mul_f32 v[100:101], v[104:105], v[100:101]
	v_and_b32_sdwa v94, v91, v177 dst_sel:DWORD dst_unused:UNUSED_PAD src0_sel:WORD_1 src1_sel:DWORD
	v_and_b32_sdwa v92, v101, v177 dst_sel:DWORD dst_unused:UNUSED_PAD src0_sel:WORD_1 src1_sel:DWORD
	v_and_b32_sdwa v95, v90, v177 dst_sel:DWORD dst_unused:UNUSED_PAD src0_sel:WORD_1 src1_sel:DWORD
	v_add3_u32 v91, v91, v94, s28
	v_and_b32_sdwa v93, v100, v177 dst_sel:DWORD dst_unused:UNUSED_PAD src0_sel:WORD_1 src1_sel:DWORD
	v_add3_u32 v92, v101, v92, s28
	v_add3_u32 v90, v90, v95, s28
	v_and_b32_e32 v91, 0xffff0000, v91
	v_add3_u32 v93, v100, v93, s28
	v_and_b32_e32 v90, 0xffff0000, v90
	v_or_b32_sdwa v91, v91, v92 dst_sel:DWORD dst_unused:UNUSED_PAD src0_sel:DWORD src1_sel:WORD_1
	v_mul_f32_e32 v92, 0xbfb8aa3b, v86
	v_or_b32_sdwa v90, v90, v93 dst_sel:DWORD dst_unused:UNUSED_PAD src0_sel:DWORD src1_sel:WORD_1
	v_exp_f32_e32 v92, v92
	v_mul_f32_e32 v93, 0xbfb8aa3b, v87
	v_or_b32_e32 v98, 16, v110
	v_exp_f32_e32 v93, v93
	v_mad_i64_i32 v[98:99], s[6:7], v98, s52, v[106:107]
	v_lshl_add_u64 v[98:99], v[98:99], 0, v[108:109]
	global_store_dwordx2 v[98:99], v[90:91], off
	v_add_f32_e32 v90, 1.0, v92
	v_mul_f32_e32 v92, 0xbfb8aa3b, v88
	v_add_f32_e32 v91, 1.0, v93
	v_exp_f32_e32 v93, v92
	v_mul_f32_e32 v92, 0xbfb8aa3b, v89
	v_exp_f32_e32 v94, v92
	v_rcp_f32_e32 v92, v91
	v_add_f32_e32 v91, 1.0, v93
	v_rcp_f32_e32 v90, v90
	v_add_f32_e32 v93, 1.0, v94
	v_rcp_f32_e32 v91, v91
	v_rcp_f32_e32 v93, v93
	v_mov_b32_e32 v94, v86
	v_mov_b32_e32 v95, v88
	v_mov_b32_e32 v88, v87
	v_pk_mul_f32 v[90:91], v[94:95], v[90:91]
	v_mov_b32_e32 v95, v84
	v_pk_mul_f32 v[86:87], v[88:89], v[92:93]
	v_mov_b32_e32 v84, v83
	v_mov_b32_e32 v94, v82
	v_pk_mul_f32 v[82:83], v[84:85], v[86:87]
	v_pk_mul_f32 v[90:91], v[94:95], v[90:91]
	v_and_b32_sdwa v86, v83, v177 dst_sel:DWORD dst_unused:UNUSED_PAD src0_sel:WORD_1 src1_sel:DWORD
	v_and_b32_sdwa v84, v91, v177 dst_sel:DWORD dst_unused:UNUSED_PAD src0_sel:WORD_1 src1_sel:DWORD
	v_and_b32_sdwa v87, v82, v177 dst_sel:DWORD dst_unused:UNUSED_PAD src0_sel:WORD_1 src1_sel:DWORD
	v_add3_u32 v83, v83, v86, s28
	v_and_b32_sdwa v85, v90, v177 dst_sel:DWORD dst_unused:UNUSED_PAD src0_sel:WORD_1 src1_sel:DWORD
	v_add3_u32 v84, v91, v84, s28
	v_add3_u32 v82, v82, v87, s28
	v_and_b32_e32 v83, 0xffff0000, v83
	v_add3_u32 v85, v90, v85, s28
	v_and_b32_e32 v82, 0xffff0000, v82
	v_or_b32_sdwa v83, v83, v84 dst_sel:DWORD dst_unused:UNUSED_PAD src0_sel:DWORD src1_sel:WORD_1
	v_mul_f32_e32 v84, 0xbfb8aa3b, v78
	v_or_b32_sdwa v82, v82, v85 dst_sel:DWORD dst_unused:UNUSED_PAD src0_sel:DWORD src1_sel:WORD_1
	v_exp_f32_e32 v84, v84
	v_mul_f32_e32 v85, 0xbfb8aa3b, v79
	v_exp_f32_e32 v85, v85
	global_store_dwordx2 v[98:99], v[82:83], off offset:32
	v_add_f32_e32 v82, 1.0, v84
	v_mul_f32_e32 v84, 0xbfb8aa3b, v80
	v_add_f32_e32 v83, 1.0, v85
	v_exp_f32_e32 v85, v84
	v_mul_f32_e32 v84, 0xbfb8aa3b, v81
	v_exp_f32_e32 v86, v84
	v_rcp_f32_e32 v84, v83
	v_add_f32_e32 v83, 1.0, v85
	v_rcp_f32_e32 v82, v82
	v_add_f32_e32 v85, 1.0, v86
	v_rcp_f32_e32 v83, v83
	v_rcp_f32_e32 v85, v85
	v_mov_b32_e32 v86, v78
	v_mov_b32_e32 v87, v80
	v_mov_b32_e32 v80, v79
	v_pk_mul_f32 v[82:83], v[86:87], v[82:83]
	v_mov_b32_e32 v87, v76
	v_pk_mul_f32 v[78:79], v[80:81], v[84:85]
	v_mov_b32_e32 v76, v75
	v_mov_b32_e32 v86, v74
	v_pk_mul_f32 v[74:75], v[76:77], v[78:79]
	v_pk_mul_f32 v[82:83], v[86:87], v[82:83]
	v_and_b32_sdwa v78, v75, v177 dst_sel:DWORD dst_unused:UNUSED_PAD src0_sel:WORD_1 src1_sel:DWORD
	v_and_b32_sdwa v76, v83, v177 dst_sel:DWORD dst_unused:UNUSED_PAD src0_sel:WORD_1 src1_sel:DWORD
	v_and_b32_sdwa v79, v74, v177 dst_sel:DWORD dst_unused:UNUSED_PAD src0_sel:WORD_1 src1_sel:DWORD
	v_add3_u32 v75, v75, v78, s28
	v_and_b32_sdwa v77, v82, v177 dst_sel:DWORD dst_unused:UNUSED_PAD src0_sel:WORD_1 src1_sel:DWORD
	v_add3_u32 v76, v83, v76, s28
	v_add3_u32 v74, v74, v79, s28
	v_and_b32_e32 v75, 0xffff0000, v75
	v_add3_u32 v77, v82, v77, s28
	v_and_b32_e32 v74, 0xffff0000, v74
	v_or_b32_sdwa v75, v75, v76 dst_sel:DWORD dst_unused:UNUSED_PAD src0_sel:DWORD src1_sel:WORD_1
	v_mul_f32_e32 v76, 0xbfb8aa3b, v70
	v_or_b32_sdwa v74, v74, v77 dst_sel:DWORD dst_unused:UNUSED_PAD src0_sel:DWORD src1_sel:WORD_1
	v_exp_f32_e32 v76, v76
	v_mul_f32_e32 v77, 0xbfb8aa3b, v71
	v_exp_f32_e32 v77, v77
	global_store_dwordx2 v[98:99], v[74:75], off offset:64
	v_add_f32_e32 v74, 1.0, v76
	v_mul_f32_e32 v76, 0xbfb8aa3b, v72
	v_add_f32_e32 v75, 1.0, v77
	v_exp_f32_e32 v77, v76
	v_mul_f32_e32 v76, 0xbfb8aa3b, v73
	v_exp_f32_e32 v78, v76
	v_rcp_f32_e32 v76, v75
	v_add_f32_e32 v75, 1.0, v77
	v_rcp_f32_e32 v74, v74
	v_add_f32_e32 v77, 1.0, v78
	v_rcp_f32_e32 v75, v75
	v_rcp_f32_e32 v77, v77
	v_mov_b32_e32 v78, v70
	v_mov_b32_e32 v79, v72
	v_mov_b32_e32 v72, v71
	v_pk_mul_f32 v[74:75], v[78:79], v[74:75]
	v_mov_b32_e32 v79, v68
	v_pk_mul_f32 v[70:71], v[72:73], v[76:77]
	v_mov_b32_e32 v68, v67
	v_mov_b32_e32 v78, v66
	v_pk_mul_f32 v[66:67], v[68:69], v[70:71]
	v_pk_mul_f32 v[74:75], v[78:79], v[74:75]
	v_and_b32_sdwa v70, v67, v177 dst_sel:DWORD dst_unused:UNUSED_PAD src0_sel:WORD_1 src1_sel:DWORD
	v_and_b32_sdwa v71, v66, v177 dst_sel:DWORD dst_unused:UNUSED_PAD src0_sel:WORD_1 src1_sel:DWORD
	v_and_b32_sdwa v68, v75, v177 dst_sel:DWORD dst_unused:UNUSED_PAD src0_sel:WORD_1 src1_sel:DWORD
	v_and_b32_sdwa v69, v74, v177 dst_sel:DWORD dst_unused:UNUSED_PAD src0_sel:WORD_1 src1_sel:DWORD
	v_add3_u32 v67, v67, v70, s28
	v_add3_u32 v66, v66, v71, s28
	v_add3_u32 v69, v74, v69, s28
	v_add3_u32 v68, v75, v68, s28
	v_and_b32_e32 v67, 0xffff0000, v67
	v_and_b32_e32 v66, 0xffff0000, v66
	v_or_b32_sdwa v67, v67, v68 dst_sel:DWORD dst_unused:UNUSED_PAD src0_sel:DWORD src1_sel:WORD_1
	v_or_b32_sdwa v66, v66, v69 dst_sel:DWORD dst_unused:UNUSED_PAD src0_sel:DWORD src1_sel:WORD_1
	global_store_dwordx2 v[98:99], v[66:67], off offset:96
	v_mul_f32_e32 v67, 0xbfb8aa3b, v62
	v_exp_f32_e32 v68, v67
	v_mul_f32_e32 v67, 0xbfb8aa3b, v63
	v_mul_f32_e32 v70, 0xbfb8aa3b, v64
	v_exp_f32_e32 v69, v67
	v_exp_f32_e32 v71, v70
	v_mul_f32_e32 v70, 0xbfb8aa3b, v65
	v_exp_f32_e32 v72, v70
	v_add_f32_e32 v69, 1.0, v69
	v_add_f32_e32 v68, 1.0, v68
	v_rcp_f32_e32 v70, v69
	v_add_f32_e32 v69, 1.0, v71
	v_add_f32_e32 v71, 1.0, v72
	v_rcp_f32_e32 v68, v68
	v_rcp_f32_e32 v69, v69
	v_rcp_f32_e32 v71, v71
	v_mov_b32_e32 v72, v62
	v_mov_b32_e32 v73, v64
	v_mov_b32_e32 v64, v63
	v_pk_mul_f32 v[68:69], v[72:73], v[68:69]
	v_mov_b32_e32 v73, v60
	v_pk_mul_f32 v[62:63], v[64:65], v[70:71]
	v_mov_b32_e32 v60, v59
	v_mov_b32_e32 v72, v58
	v_pk_mul_f32 v[58:59], v[60:61], v[62:63]
	v_pk_mul_f32 v[68:69], v[72:73], v[68:69]
	v_and_b32_sdwa v62, v59, v177 dst_sel:DWORD dst_unused:UNUSED_PAD src0_sel:WORD_1 src1_sel:DWORD
	v_and_b32_sdwa v60, v69, v177 dst_sel:DWORD dst_unused:UNUSED_PAD src0_sel:WORD_1 src1_sel:DWORD
	v_and_b32_sdwa v63, v58, v177 dst_sel:DWORD dst_unused:UNUSED_PAD src0_sel:WORD_1 src1_sel:DWORD
	v_add3_u32 v59, v59, v62, s28
	v_and_b32_sdwa v61, v68, v177 dst_sel:DWORD dst_unused:UNUSED_PAD src0_sel:WORD_1 src1_sel:DWORD
	v_add3_u32 v60, v69, v60, s28
	v_add3_u32 v58, v58, v63, s28
	v_and_b32_e32 v59, 0xffff0000, v59
	v_add3_u32 v61, v68, v61, s28
	v_and_b32_e32 v58, 0xffff0000, v58
	v_or_b32_sdwa v59, v59, v60 dst_sel:DWORD dst_unused:UNUSED_PAD src0_sel:DWORD src1_sel:WORD_1
	v_mul_f32_e32 v60, 0xbfb8aa3b, v54
	v_or_b32_sdwa v58, v58, v61 dst_sel:DWORD dst_unused:UNUSED_PAD src0_sel:DWORD src1_sel:WORD_1
	v_exp_f32_e32 v60, v60
	v_mul_f32_e32 v61, 0xbfb8aa3b, v55
	v_or_b32_e32 v66, 32, v110
	v_exp_f32_e32 v61, v61
	v_mad_i64_i32 v[66:67], s[6:7], v66, s52, v[106:107]
	v_lshl_add_u64 v[66:67], v[66:67], 0, v[108:109]
	global_store_dwordx2 v[66:67], v[58:59], off
	v_add_f32_e32 v58, 1.0, v60
	v_mul_f32_e32 v60, 0xbfb8aa3b, v56
	v_add_f32_e32 v59, 1.0, v61
	v_exp_f32_e32 v61, v60
	v_mul_f32_e32 v60, 0xbfb8aa3b, v57
	v_exp_f32_e32 v62, v60
	v_rcp_f32_e32 v60, v59
	v_add_f32_e32 v59, 1.0, v61
	v_rcp_f32_e32 v58, v58
	v_add_f32_e32 v61, 1.0, v62
	v_rcp_f32_e32 v59, v59
	v_rcp_f32_e32 v61, v61
	v_mov_b32_e32 v62, v54
	v_mov_b32_e32 v63, v56
	v_mov_b32_e32 v56, v55
	v_pk_mul_f32 v[58:59], v[62:63], v[58:59]
	v_mov_b32_e32 v63, v52
	v_pk_mul_f32 v[54:55], v[56:57], v[60:61]
	v_mov_b32_e32 v52, v51
	v_mov_b32_e32 v62, v50
	v_pk_mul_f32 v[50:51], v[52:53], v[54:55]
	v_pk_mul_f32 v[58:59], v[62:63], v[58:59]
	v_and_b32_sdwa v54, v51, v177 dst_sel:DWORD dst_unused:UNUSED_PAD src0_sel:WORD_1 src1_sel:DWORD
	v_and_b32_sdwa v52, v59, v177 dst_sel:DWORD dst_unused:UNUSED_PAD src0_sel:WORD_1 src1_sel:DWORD
	v_and_b32_sdwa v55, v50, v177 dst_sel:DWORD dst_unused:UNUSED_PAD src0_sel:WORD_1 src1_sel:DWORD
	v_add3_u32 v51, v51, v54, s28
	v_and_b32_sdwa v53, v58, v177 dst_sel:DWORD dst_unused:UNUSED_PAD src0_sel:WORD_1 src1_sel:DWORD
	v_add3_u32 v52, v59, v52, s28
	v_add3_u32 v50, v50, v55, s28
	v_and_b32_e32 v51, 0xffff0000, v51
	v_add3_u32 v53, v58, v53, s28
	v_and_b32_e32 v50, 0xffff0000, v50
	v_or_b32_sdwa v51, v51, v52 dst_sel:DWORD dst_unused:UNUSED_PAD src0_sel:DWORD src1_sel:WORD_1
	v_mul_f32_e32 v52, 0xbfb8aa3b, v46
	v_or_b32_sdwa v50, v50, v53 dst_sel:DWORD dst_unused:UNUSED_PAD src0_sel:DWORD src1_sel:WORD_1
	v_exp_f32_e32 v52, v52
	v_mul_f32_e32 v53, 0xbfb8aa3b, v47
	v_exp_f32_e32 v53, v53
	global_store_dwordx2 v[66:67], v[50:51], off offset:32
	v_add_f32_e32 v50, 1.0, v52
	v_mul_f32_e32 v52, 0xbfb8aa3b, v48
	v_add_f32_e32 v51, 1.0, v53
	v_exp_f32_e32 v53, v52
	v_mul_f32_e32 v52, 0xbfb8aa3b, v49
	v_exp_f32_e32 v54, v52
	v_rcp_f32_e32 v52, v51
	v_add_f32_e32 v51, 1.0, v53
	v_rcp_f32_e32 v50, v50
	v_add_f32_e32 v53, 1.0, v54
	v_rcp_f32_e32 v51, v51
	v_rcp_f32_e32 v53, v53
	v_mov_b32_e32 v54, v46
	v_mov_b32_e32 v55, v48
	v_mov_b32_e32 v48, v47
	v_pk_mul_f32 v[50:51], v[54:55], v[50:51]
	v_mov_b32_e32 v55, v44
	v_pk_mul_f32 v[46:47], v[48:49], v[52:53]
	v_mov_b32_e32 v44, v43
	v_mov_b32_e32 v54, v42
	v_pk_mul_f32 v[42:43], v[44:45], v[46:47]
	v_pk_mul_f32 v[50:51], v[54:55], v[50:51]
	v_and_b32_sdwa v46, v43, v177 dst_sel:DWORD dst_unused:UNUSED_PAD src0_sel:WORD_1 src1_sel:DWORD
	v_and_b32_sdwa v44, v51, v177 dst_sel:DWORD dst_unused:UNUSED_PAD src0_sel:WORD_1 src1_sel:DWORD
	v_and_b32_sdwa v47, v42, v177 dst_sel:DWORD dst_unused:UNUSED_PAD src0_sel:WORD_1 src1_sel:DWORD
	v_add3_u32 v43, v43, v46, s28
	v_and_b32_sdwa v45, v50, v177 dst_sel:DWORD dst_unused:UNUSED_PAD src0_sel:WORD_1 src1_sel:DWORD
	v_add3_u32 v44, v51, v44, s28
	v_add3_u32 v42, v42, v47, s28
	v_and_b32_e32 v43, 0xffff0000, v43
	v_add3_u32 v45, v50, v45, s28
	v_and_b32_e32 v42, 0xffff0000, v42
	v_or_b32_sdwa v43, v43, v44 dst_sel:DWORD dst_unused:UNUSED_PAD src0_sel:DWORD src1_sel:WORD_1
	v_mul_f32_e32 v44, 0xbfb8aa3b, v38
	v_or_b32_sdwa v42, v42, v45 dst_sel:DWORD dst_unused:UNUSED_PAD src0_sel:DWORD src1_sel:WORD_1
	v_exp_f32_e32 v44, v44
	v_mul_f32_e32 v45, 0xbfb8aa3b, v39
	v_exp_f32_e32 v45, v45
	global_store_dwordx2 v[66:67], v[42:43], off offset:64
	v_add_f32_e32 v42, 1.0, v44
	v_mul_f32_e32 v44, 0xbfb8aa3b, v40
	v_add_f32_e32 v43, 1.0, v45
	v_exp_f32_e32 v45, v44
	v_mul_f32_e32 v44, 0xbfb8aa3b, v41
	v_exp_f32_e32 v46, v44
	v_rcp_f32_e32 v44, v43
	v_add_f32_e32 v43, 1.0, v45
	v_rcp_f32_e32 v42, v42
	v_add_f32_e32 v45, 1.0, v46
	v_rcp_f32_e32 v43, v43
	v_rcp_f32_e32 v45, v45
	v_mov_b32_e32 v46, v38
	v_mov_b32_e32 v47, v40
	v_mov_b32_e32 v40, v39
	v_pk_mul_f32 v[42:43], v[46:47], v[42:43]
	v_mov_b32_e32 v47, v36
	v_pk_mul_f32 v[38:39], v[40:41], v[44:45]
	v_mov_b32_e32 v36, v35
	v_mov_b32_e32 v46, v34
	v_pk_mul_f32 v[34:35], v[36:37], v[38:39]
	v_pk_mul_f32 v[42:43], v[46:47], v[42:43]
	v_and_b32_sdwa v38, v35, v177 dst_sel:DWORD dst_unused:UNUSED_PAD src0_sel:WORD_1 src1_sel:DWORD
	v_and_b32_sdwa v39, v34, v177 dst_sel:DWORD dst_unused:UNUSED_PAD src0_sel:WORD_1 src1_sel:DWORD
	v_and_b32_sdwa v36, v43, v177 dst_sel:DWORD dst_unused:UNUSED_PAD src0_sel:WORD_1 src1_sel:DWORD
	v_and_b32_sdwa v37, v42, v177 dst_sel:DWORD dst_unused:UNUSED_PAD src0_sel:WORD_1 src1_sel:DWORD
	v_add3_u32 v35, v35, v38, s28
	v_add3_u32 v34, v34, v39, s28
	v_add3_u32 v37, v42, v37, s28
	v_add3_u32 v36, v43, v36, s28
	v_and_b32_e32 v35, 0xffff0000, v35
	v_and_b32_e32 v34, 0xffff0000, v34
	v_or_b32_sdwa v35, v35, v36 dst_sel:DWORD dst_unused:UNUSED_PAD src0_sel:DWORD src1_sel:WORD_1
	v_or_b32_sdwa v34, v34, v37 dst_sel:DWORD dst_unused:UNUSED_PAD src0_sel:DWORD src1_sel:WORD_1
	global_store_dwordx2 v[66:67], v[34:35], off offset:96
	v_mul_f32_e32 v35, 0xbfb8aa3b, v30
	v_exp_f32_e32 v36, v35
	v_mul_f32_e32 v35, 0xbfb8aa3b, v31
	v_mul_f32_e32 v38, 0xbfb8aa3b, v32
	v_exp_f32_e32 v37, v35
	v_exp_f32_e32 v39, v38
	v_mul_f32_e32 v38, 0xbfb8aa3b, v33
	v_exp_f32_e32 v40, v38
	v_add_f32_e32 v37, 1.0, v37
	v_add_f32_e32 v36, 1.0, v36
	v_rcp_f32_e32 v38, v37
	v_add_f32_e32 v37, 1.0, v39
	v_add_f32_e32 v39, 1.0, v40
	v_rcp_f32_e32 v36, v36
	v_rcp_f32_e32 v37, v37
	v_rcp_f32_e32 v39, v39
	v_mov_b32_e32 v40, v30
	v_mov_b32_e32 v41, v32
	v_mov_b32_e32 v32, v31
	v_pk_mul_f32 v[36:37], v[40:41], v[36:37]
	v_mov_b32_e32 v41, v28
	v_pk_mul_f32 v[30:31], v[32:33], v[38:39]
	v_mov_b32_e32 v28, v27
	v_mov_b32_e32 v40, v26
	v_pk_mul_f32 v[26:27], v[28:29], v[30:31]
	v_pk_mul_f32 v[36:37], v[40:41], v[36:37]
	v_and_b32_sdwa v30, v27, v177 dst_sel:DWORD dst_unused:UNUSED_PAD src0_sel:WORD_1 src1_sel:DWORD
	v_and_b32_sdwa v28, v37, v177 dst_sel:DWORD dst_unused:UNUSED_PAD src0_sel:WORD_1 src1_sel:DWORD
	v_and_b32_sdwa v31, v26, v177 dst_sel:DWORD dst_unused:UNUSED_PAD src0_sel:WORD_1 src1_sel:DWORD
	v_add3_u32 v27, v27, v30, s28
	v_and_b32_sdwa v29, v36, v177 dst_sel:DWORD dst_unused:UNUSED_PAD src0_sel:WORD_1 src1_sel:DWORD
	v_add3_u32 v28, v37, v28, s28
	v_add3_u32 v26, v26, v31, s28
	v_and_b32_e32 v27, 0xffff0000, v27
	v_add3_u32 v29, v36, v29, s28
	v_and_b32_e32 v26, 0xffff0000, v26
	v_or_b32_sdwa v27, v27, v28 dst_sel:DWORD dst_unused:UNUSED_PAD src0_sel:DWORD src1_sel:WORD_1
	v_mul_f32_e32 v28, 0xbfb8aa3b, v22
	v_or_b32_sdwa v26, v26, v29 dst_sel:DWORD dst_unused:UNUSED_PAD src0_sel:DWORD src1_sel:WORD_1
	v_exp_f32_e32 v28, v28
	v_mul_f32_e32 v29, 0xbfb8aa3b, v23
	v_or_b32_e32 v34, 48, v110
	v_exp_f32_e32 v29, v29
	v_mad_i64_i32 v[34:35], s[6:7], v34, s52, v[106:107]
	v_lshl_add_u64 v[34:35], v[34:35], 0, v[108:109]
	global_store_dwordx2 v[34:35], v[26:27], off
	v_add_f32_e32 v26, 1.0, v28
	v_mul_f32_e32 v28, 0xbfb8aa3b, v24
	v_add_f32_e32 v27, 1.0, v29
	v_exp_f32_e32 v29, v28
	v_mul_f32_e32 v28, 0xbfb8aa3b, v25
	v_exp_f32_e32 v30, v28
	v_rcp_f32_e32 v28, v27
	v_add_f32_e32 v27, 1.0, v29
	v_rcp_f32_e32 v26, v26
	v_add_f32_e32 v29, 1.0, v30
	v_rcp_f32_e32 v27, v27
	v_rcp_f32_e32 v29, v29
	v_mov_b32_e32 v30, v22
	v_mov_b32_e32 v31, v24
	v_mov_b32_e32 v24, v23
	v_pk_mul_f32 v[26:27], v[30:31], v[26:27]
	v_mov_b32_e32 v31, v20
	v_pk_mul_f32 v[22:23], v[24:25], v[28:29]
	v_mov_b32_e32 v20, v19
	v_mov_b32_e32 v30, v18
	v_pk_mul_f32 v[18:19], v[20:21], v[22:23]
	v_pk_mul_f32 v[26:27], v[30:31], v[26:27]
	v_and_b32_sdwa v22, v19, v177 dst_sel:DWORD dst_unused:UNUSED_PAD src0_sel:WORD_1 src1_sel:DWORD
	v_and_b32_sdwa v20, v27, v177 dst_sel:DWORD dst_unused:UNUSED_PAD src0_sel:WORD_1 src1_sel:DWORD
	v_and_b32_sdwa v23, v18, v177 dst_sel:DWORD dst_unused:UNUSED_PAD src0_sel:WORD_1 src1_sel:DWORD
	v_add3_u32 v19, v19, v22, s28
	v_and_b32_sdwa v21, v26, v177 dst_sel:DWORD dst_unused:UNUSED_PAD src0_sel:WORD_1 src1_sel:DWORD
	v_add3_u32 v20, v27, v20, s28
	v_add3_u32 v18, v18, v23, s28
	v_and_b32_e32 v19, 0xffff0000, v19
	v_add3_u32 v21, v26, v21, s28
	v_and_b32_e32 v18, 0xffff0000, v18
	v_or_b32_sdwa v19, v19, v20 dst_sel:DWORD dst_unused:UNUSED_PAD src0_sel:DWORD src1_sel:WORD_1
	v_mul_f32_e32 v20, 0xbfb8aa3b, v14
	v_or_b32_sdwa v18, v18, v21 dst_sel:DWORD dst_unused:UNUSED_PAD src0_sel:DWORD src1_sel:WORD_1
	v_exp_f32_e32 v20, v20
	v_mul_f32_e32 v21, 0xbfb8aa3b, v15
	v_exp_f32_e32 v21, v21
	global_store_dwordx2 v[34:35], v[18:19], off offset:32
	v_add_f32_e32 v18, 1.0, v20
	v_mul_f32_e32 v20, 0xbfb8aa3b, v16
	v_add_f32_e32 v19, 1.0, v21
	v_exp_f32_e32 v21, v20
	v_mul_f32_e32 v20, 0xbfb8aa3b, v17
	v_exp_f32_e32 v22, v20
	v_rcp_f32_e32 v20, v19
	v_add_f32_e32 v19, 1.0, v21
	v_rcp_f32_e32 v18, v18
	v_add_f32_e32 v21, 1.0, v22
	v_rcp_f32_e32 v19, v19
	v_rcp_f32_e32 v21, v21
	v_mov_b32_e32 v22, v14
	v_mov_b32_e32 v23, v16
	v_mov_b32_e32 v16, v15
	v_pk_mul_f32 v[18:19], v[22:23], v[18:19]
	v_mov_b32_e32 v23, v12
	v_pk_mul_f32 v[14:15], v[16:17], v[20:21]
	v_mov_b32_e32 v12, v11
	v_mov_b32_e32 v22, v10
	v_pk_mul_f32 v[10:11], v[12:13], v[14:15]
	v_pk_mul_f32 v[18:19], v[22:23], v[18:19]
	v_and_b32_sdwa v14, v11, v177 dst_sel:DWORD dst_unused:UNUSED_PAD src0_sel:WORD_1 src1_sel:DWORD
	v_and_b32_sdwa v12, v19, v177 dst_sel:DWORD dst_unused:UNUSED_PAD src0_sel:WORD_1 src1_sel:DWORD
	v_and_b32_sdwa v15, v10, v177 dst_sel:DWORD dst_unused:UNUSED_PAD src0_sel:WORD_1 src1_sel:DWORD
	v_add3_u32 v11, v11, v14, s28
	v_and_b32_sdwa v13, v18, v177 dst_sel:DWORD dst_unused:UNUSED_PAD src0_sel:WORD_1 src1_sel:DWORD
	v_add3_u32 v12, v19, v12, s28
	v_add3_u32 v10, v10, v15, s28
	v_and_b32_e32 v11, 0xffff0000, v11
	v_add3_u32 v13, v18, v13, s28
	v_and_b32_e32 v10, 0xffff0000, v10
	v_or_b32_sdwa v11, v11, v12 dst_sel:DWORD dst_unused:UNUSED_PAD src0_sel:DWORD src1_sel:WORD_1
	v_mul_f32_e32 v12, 0xbfb8aa3b, v6
	v_or_b32_sdwa v10, v10, v13 dst_sel:DWORD dst_unused:UNUSED_PAD src0_sel:DWORD src1_sel:WORD_1
	v_exp_f32_e32 v12, v12
	v_mul_f32_e32 v13, 0xbfb8aa3b, v7
	v_exp_f32_e32 v13, v13
	global_store_dwordx2 v[34:35], v[10:11], off offset:64
	v_add_f32_e32 v10, 1.0, v12
	v_mul_f32_e32 v12, 0xbfb8aa3b, v8
	v_add_f32_e32 v11, 1.0, v13
	v_exp_f32_e32 v13, v12
	v_mul_f32_e32 v12, 0xbfb8aa3b, v9
	v_exp_f32_e32 v14, v12
	v_rcp_f32_e32 v12, v11
	v_add_f32_e32 v11, 1.0, v13
	v_rcp_f32_e32 v10, v10
	v_add_f32_e32 v13, 1.0, v14
	v_rcp_f32_e32 v11, v11
	v_rcp_f32_e32 v13, v13
	v_mov_b32_e32 v14, v6
	v_mov_b32_e32 v15, v8
	v_mov_b32_e32 v8, v7
	v_pk_mul_f32 v[10:11], v[14:15], v[10:11]
	v_mov_b32_e32 v15, v4
	v_pk_mul_f32 v[6:7], v[8:9], v[12:13]
	v_mov_b32_e32 v4, v3
	v_mov_b32_e32 v14, v2
	v_pk_mul_f32 v[2:3], v[4:5], v[6:7]
	v_pk_mul_f32 v[10:11], v[14:15], v[10:11]
	v_and_b32_sdwa v6, v3, v177 dst_sel:DWORD dst_unused:UNUSED_PAD src0_sel:WORD_1 src1_sel:DWORD
	v_and_b32_sdwa v7, v2, v177 dst_sel:DWORD dst_unused:UNUSED_PAD src0_sel:WORD_1 src1_sel:DWORD
	v_and_b32_sdwa v4, v11, v177 dst_sel:DWORD dst_unused:UNUSED_PAD src0_sel:WORD_1 src1_sel:DWORD
	v_and_b32_sdwa v5, v10, v177 dst_sel:DWORD dst_unused:UNUSED_PAD src0_sel:WORD_1 src1_sel:DWORD
	v_add3_u32 v3, v3, v6, s28
	v_add3_u32 v2, v2, v7, s28
	v_add3_u32 v5, v10, v5, s28
	v_add3_u32 v4, v11, v4, s28
	v_and_b32_e32 v3, 0xffff0000, v3
	v_and_b32_e32 v2, 0xffff0000, v2
	s_add_i32 s14, s14, s11
	v_or_b32_sdwa v3, v3, v4 dst_sel:DWORD dst_unused:UNUSED_PAD src0_sel:DWORD src1_sel:WORD_1
	v_or_b32_sdwa v2, v2, v5 dst_sel:DWORD dst_unused:UNUSED_PAD src0_sel:DWORD src1_sel:WORD_1
	s_cmpk_gt_i32 s14, 0x5ff
	global_store_dwordx2 v[34:35], v[2:3], off offset:96
	s_cbranch_scc0 .LBB0_1461
	s_setprio 0

.LBB0_1525:
	s_or_b64 exec, exec, s[12:13]
	s_mov_b64 s[6:7], s[60:61]
	s_waitcnt lgkmcnt(0)
	s_barrier
	s_load_dwordx4 s[44:47], s[6:7], 0x128
	v_readlane_b32 s2, v255, 48
	v_readlane_b32 s3, v255, 49
	v_mov_b32_e32 v2, v172
	s_mov_b32 s11, s42
	s_waitcnt lgkmcnt(0)
	s_add_u32 s12, s46, 0x2a00000
	s_addc_u32 s13, s47, 0
	s_add_u32 s2, s46, s2
	s_addc_u32 s3, s47, s3
	s_add_u32 s14, s2, 0x5608000
	s_addc_u32 s15, s3, 0
	s_add_u32 s16, s46, 0x6035800
	s_addc_u32 s17, s47, 0
	s_add_u32 s48, s46, 0x1b80000
	s_addc_u32 s49, s47, 0
	s_mov_b32 s18, s94
	s_cmpk_gt_i32 s18, 0xff
	s_cbranch_scc1 .LBB0_1530
	v_ashrrev_i32_e32 v204, 3, v2
	v_and_b32_e32 v205, 15, v2
	v_bfe_u32 v3, v2, 4, 2
	v_lshlrev_b32_e32 v0, 4, v2
	v_ashrrev_i32_e32 v4, 1, v2
	v_lshlrev_b32_e32 v2, 1, v2
	v_and_b32_e32 v0, 0x70, v0
	v_and_b32_e32 v206, 0xffffffc0, v4
	v_and_b32_e32 v2, 0x80, v2
	s_movk_i32 s2, 0x90
	v_or_b32_e32 v4, v206, v205
	v_or_b32_e32 v5, v2, v205
	v_and_b32_e32 v100, 7, v204
	v_lshlrev_b32_e32 v100, 4, v100
	v_xor_b32_e32 v100, v100, v0
	v_lshl_add_u32 v166, v204, 7, v100
	v_lshl_add_u64 v[162:163], s[16:17], 0, v[0:1]
	v_lshl_add_u64 v[164:165], s[48:49], 0, v[0:1]
	v_and_b32_e32 v100, 7, v205
	v_xor_b32_e32 v100, v100, v3
	v_lshlrev_b32_e32 v207, 4, v100
	v_lshl_or_b32 v208, v3, 2, v2
	v_lshlrev_b32_e32 v0, 7, v4
	v_lshlrev_b32_e32 v167, 7, v5
	v_readfirstlane_b32 s100, v172
	s_nop 0
	s_cmpk_ge_u32 s100, 0x100
	s_cbranch_scc0 .Lprio_skip_P12
	s_setprio 1
.Lprio_skip_P12:
.LBB0_1527:
	s_ashr_i32 s2, s18, 31
	s_lshr_b32 s2, s2, 26
	s_add_i32 s2, s18, s2
	s_and_b32 s3, s2, 0xffffc0
	s_sub_i32 s3, s18, s3
	s_lshl_b32 s7, s3, 8
	v_add_u32_e32 v2, s7, v204
	v_mad_i64_i32 v[168:169], s[20:21], v2, s52, v[162:163]
	v_add_co_u32_e32 v56, vcc, 0x58000, v168
	s_lshl_b32 s2, s2, 2
	s_nop 0
	v_addc_co_u32_e32 v57, vcc, 0, v169, vcc
	s_waitcnt vmcnt(9)
	v_add_co_u32_e32 v58, vcc, 0xb0000, v168
	s_and_b32 s6, s2, 0xffffff00
	s_nop 0
	v_addc_co_u32_e32 v59, vcc, 0, v169, vcc
	v_add_u32_e32 v2, s6, v204
	v_add_co_u32_e32 v60, vcc, 0x108000, v168
	v_mad_i64_i32 v[170:171], s[20:21], v2, s52, v[164:165]
	s_nop 0
	v_addc_co_u32_e32 v61, vcc, 0, v169, vcc
	s_waitcnt vmcnt(8)
	v_add_co_u32_e32 v62, vcc, s92, v170
	s_mov_b32 s19, 0x108000
	s_nop 0
	v_addc_co_u32_e32 v63, vcc, 0, v171, vcc
	v_add_co_u32_e32 v64, vcc, s53, v170
	global_load_dwordx4 v[24:27], v[56:57], off
	global_load_dwordx4 v[28:31], v[58:59], off
	v_addc_co_u32_e32 v65, vcc, 0, v171, vcc
	v_add_co_u32_e32 v66, vcc, s19, v170
	global_load_dwordx4 v[32:35], v[168:169], off
	global_load_dwordx4 v[36:39], v[170:171], off
	global_load_dwordx4 v[40:43], v[60:61], off
	global_load_dwordx4 v[44:47], v[62:63], off
	v_addc_co_u32_e32 v67, vcc, 0, v171, vcc
	global_load_dwordx4 v[48:51], v[64:65], off
	global_load_dwordx4 v[52:55], v[66:67], off
	s_barrier
	global_load_dwordx4 v[118:121], v[168:169], off offset:128
	global_load_dwordx4 v[110:113], v[56:57], off offset:128
	global_load_dwordx4 v[114:117], v[58:59], off offset:128
	global_load_dwordx4 v[130:133], v[60:61], off offset:128
	global_load_dwordx4 v[126:129], v[170:171], off offset:128
	global_load_dwordx4 v[122:125], v[62:63], off offset:128
	global_load_dwordx4 v[142:145], v[64:65], off offset:128
	global_load_dwordx4 v[138:141], v[66:67], off offset:128
	v_readfirstlane_b32 vcc_lo, v168
	v_readfirstlane_b32 vcc_hi, v169
	v_readfirstlane_b32 s100, v170
	v_readfirstlane_b32 s101, v171
	s_nop 1
	v_subrev_u32_e32 v168, vcc_lo, v168
	v_subrev_u32_e32 v170, s100, v170
	v_mov_b32_e32 v2, 0
	s_mov_b32 s4, 0
	v_mov_b32_e32 v3, v2
	v_mov_b32_e32 v4, v2
	v_mov_b32_e32 v5, v2
	v_mov_b32_e32 v6, v2
	v_mov_b32_e32 v7, v2
	v_mov_b32_e32 v8, v2
	v_mov_b32_e32 v9, v2
	v_mov_b32_e32 v10, v2
	v_mov_b32_e32 v11, v2
	v_mov_b32_e32 v12, v2
	v_mov_b32_e32 v13, v2
	v_mov_b32_e32 v14, v2
	v_mov_b32_e32 v15, v2
	v_mov_b32_e32 v16, v2
	v_mov_b32_e32 v17, v2
	v_mov_b32_e32 v18, v2
	v_mov_b32_e32 v19, v2
	v_mov_b32_e32 v20, v2
	v_mov_b32_e32 v21, v2
	v_mov_b32_e32 v22, v2
	v_mov_b32_e32 v23, v2
	v_mov_b32_e32 v56, v2
	v_mov_b32_e32 v57, v2
	v_mov_b32_e32 v58, v2
	v_mov_b32_e32 v59, v2
	v_mov_b32_e32 v60, v2
	v_mov_b32_e32 v61, v2
	v_mov_b32_e32 v62, v2
	v_mov_b32_e32 v63, v2
	v_mov_b32_e32 v64, v2
	v_mov_b32_e32 v65, v2
	v_mov_b32_e32 v66, v2
	v_mov_b32_e32 v67, v2
	v_mov_b32_e32 v68, v2
	v_mov_b32_e32 v69, v2
	v_mov_b32_e32 v70, v2
	v_mov_b32_e32 v71, v2
	v_mov_b32_e32 v72, v2
	v_mov_b32_e32 v73, v2
	v_mov_b32_e32 v74, v2
	v_mov_b32_e32 v75, v2
	v_mov_b32_e32 v76, v2
	v_mov_b32_e32 v77, v2
	v_mov_b32_e32 v78, v2
	v_mov_b32_e32 v79, v2
	v_mov_b32_e32 v80, v2
	v_mov_b32_e32 v81, v2
	v_mov_b32_e32 v82, v2
	v_mov_b32_e32 v83, v2
	v_mov_b32_e32 v84, v2
	s_waitcnt vmcnt(13)
	ds_write_b128 v166, v[32:35]
	s_waitcnt vmcnt(12)
	ds_write_b128 v166, v[36:39] offset:32768
	ds_write_b128 v166, v[24:27] offset:8192
	ds_write_b128 v166, v[28:31] offset:16384
	s_waitcnt vmcnt(11)
	ds_write_b128 v166, v[40:43] offset:24576
	s_waitcnt vmcnt(10)
	ds_write_b128 v166, v[44:47] offset:40960
	s_waitcnt vmcnt(9)
	ds_write_b128 v166, v[48:51] offset:49152
	s_waitcnt vmcnt(8)
	ds_write_b128 v166, v[52:55] offset:57344
	v_mov_b32_e32 v24, v2
	v_mov_b32_e32 v25, v2
	v_mov_b32_e32 v26, v2
	v_mov_b32_e32 v27, v2
	v_mov_b32_e32 v28, v2
	v_mov_b32_e32 v29, v2
	v_mov_b32_e32 v30, v2
	v_mov_b32_e32 v31, v2
	v_mov_b32_e32 v32, v2
	v_mov_b32_e32 v33, v2
	v_mov_b32_e32 v34, v2
	v_mov_b32_e32 v35, v2
	v_mov_b32_e32 v36, v2
	v_mov_b32_e32 v37, v2
	v_mov_b32_e32 v38, v2
	v_mov_b32_e32 v39, v2
	v_mov_b32_e32 v40, v2
	v_mov_b32_e32 v41, v2
	v_mov_b32_e32 v42, v2
	v_mov_b32_e32 v43, v2
	v_mov_b32_e32 v44, v2
	v_mov_b32_e32 v45, v2
	v_mov_b32_e32 v46, v2
	v_mov_b32_e32 v47, v2
	v_mov_b32_e32 v48, v2
	v_mov_b32_e32 v49, v2
	v_mov_b32_e32 v50, v2
	v_mov_b32_e32 v51, v2
	v_mov_b32_e32 v52, v2
	v_mov_b32_e32 v53, v2
	v_mov_b32_e32 v54, v2
	v_mov_b32_e32 v55, v2
	v_mov_b32_e32 v85, v2
	v_mov_b32_e32 v86, v2
	v_mov_b32_e32 v87, v2
	v_mov_b32_e32 v88, v2
	v_mov_b32_e32 v89, v2
	v_mov_b32_e32 v90, v2
	v_mov_b32_e32 v91, v2
	v_mov_b32_e32 v92, v2
	v_mov_b32_e32 v93, v2
	v_mov_b32_e32 v94, v2
	v_mov_b32_e32 v95, v2
	v_mov_b32_e32 v96, v2
	v_mov_b32_e32 v97, v2
	v_mov_b32_e32 v98, v2
	v_mov_b32_e32 v99, v2
	v_mov_b32_e32 v100, v2
	v_mov_b32_e32 v101, v2
	v_mov_b32_e32 v102, v2
	v_mov_b32_e32 v103, v2
	v_mov_b32_e32 v104, v2
	v_mov_b32_e32 v105, v2
	v_mov_b32_e32 v106, v2
	v_mov_b32_e32 v107, v2
	v_mov_b32_e32 v108, v2
	v_mov_b32_e32 v109, v2
	v_mov_b32_e32 v134, v2
	v_mov_b32_e32 v135, v2
	v_mov_b32_e32 v136, v2
	v_mov_b32_e32 v137, v2
	v_mov_b32_e32 v146, v2
	v_mov_b32_e32 v147, v2
	v_mov_b32_e32 v148, v2
	v_mov_b32_e32 v149, v2
	v_mov_b32_e32 v150, v2
	v_mov_b32_e32 v151, v2
	v_mov_b32_e32 v152, v2
	v_mov_b32_e32 v153, v2
	v_mov_b32_e32 v154, v2
	v_mov_b32_e32 v155, v2
	v_mov_b32_e32 v156, v2
	v_mov_b32_e32 v157, v2
	v_mov_b32_e32 v158, v2
	v_mov_b32_e32 v159, v2
	v_mov_b32_e32 v160, v2
	v_mov_b32_e32 v161, v2
	s_waitcnt lgkmcnt(0)
	s_barrier
.LBB0_1528:
	s_bitcmp1_b32 s4, 0
	s_cselect_b32 s2, 0x12000, 0
	v_or_b32_e32 v218, s2, v207
	v_add_u32_e32 v214, v218, v0
	v_add_u32_e32 v246, v218, v167
	ds_read_b128 v[184:187], v214
	ds_read_b128 v[198:201], v214 offset:2048
	ds_read_b128 v[210:213], v214 offset:4096
	ds_read_b128 v[214:217], v214 offset:6144
	ds_read_b128 v[218:221], v246 offset:32768
	ds_read_b128 v[222:225], v246 offset:34816
	ds_read_b128 v[226:229], v246 offset:36864
	ds_read_b128 v[230:233], v246 offset:38912
	ds_read_b128 v[234:237], v246 offset:40960
	ds_read_b128 v[238:241], v246 offset:43008
	ds_read_b128 v[242:245], v246 offset:45056
	ds_read_b128 v[246:249], v246 offset:47104
	s_add_i32 s10, s4, 1
	s_bitcmp1_b32 s10, 0
	s_cselect_b32 s3, 0x12000, 0
	v_add_u32_e32 v171, s3, v166
	v_xor_b32_e32 v169, 64, v207
	v_add3_u32 v169, s2, v167, v169
	s_waitcnt lgkmcnt(7)
	v_mfma_f32_16x16x32_bf16 v[158:161], v[218:221], v[184:187], v[158:161]
	v_mfma_f32_16x16x32_bf16 v[94:97], v[218:221], v[198:201], v[94:97]
	v_mfma_f32_16x16x32_bf16 v[62:65], v[218:221], v[210:213], v[62:65]
	v_mfma_f32_16x16x32_bf16 v[30:33], v[218:221], v[214:217], v[30:33]
	ds_read_b128 v[218:221], v169 offset:32768
	s_waitcnt lgkmcnt(7)
	v_mfma_f32_16x16x32_bf16 v[154:157], v[222:225], v[184:187], v[154:157]
	v_mfma_f32_16x16x32_bf16 v[90:93], v[222:225], v[198:201], v[90:93]
	v_mfma_f32_16x16x32_bf16 v[58:61], v[222:225], v[210:213], v[58:61]
	v_mfma_f32_16x16x32_bf16 v[26:29], v[222:225], v[214:217], v[26:29]
	ds_read_b128 v[222:225], v169 offset:34816
	s_waitcnt lgkmcnt(7)
	v_mfma_f32_16x16x32_bf16 v[150:153], v[226:229], v[184:187], v[150:153]
	v_mfma_f32_16x16x32_bf16 v[86:89], v[226:229], v[198:201], v[86:89]
	v_mfma_f32_16x16x32_bf16 v[54:57], v[226:229], v[210:213], v[54:57]
	v_mfma_f32_16x16x32_bf16 v[22:25], v[226:229], v[214:217], v[22:25]
	ds_read_b128 v[226:229], v169 offset:36864
	s_waitcnt lgkmcnt(7)
	v_mfma_f32_16x16x32_bf16 v[146:149], v[230:233], v[184:187], v[146:149]
	v_mfma_f32_16x16x32_bf16 v[82:85], v[230:233], v[198:201], v[82:85]
	v_mfma_f32_16x16x32_bf16 v[50:53], v[230:233], v[210:213], v[50:53]
	v_mfma_f32_16x16x32_bf16 v[18:21], v[230:233], v[214:217], v[18:21]
	ds_read_b128 v[230:233], v169 offset:38912
	s_waitcnt lgkmcnt(7)
	v_mfma_f32_16x16x32_bf16 v[134:137], v[234:237], v[184:187], v[134:137]
	v_mfma_f32_16x16x32_bf16 v[78:81], v[234:237], v[198:201], v[78:81]
	v_mfma_f32_16x16x32_bf16 v[46:49], v[234:237], v[210:213], v[46:49]
	v_mfma_f32_16x16x32_bf16 v[14:17], v[234:237], v[214:217], v[14:17]
	ds_read_b128 v[234:237], v169 offset:40960
	s_waitcnt lgkmcnt(7)
	v_mfma_f32_16x16x32_bf16 v[106:109], v[238:241], v[184:187], v[106:109]
	v_mfma_f32_16x16x32_bf16 v[74:77], v[238:241], v[198:201], v[74:77]
	v_mfma_f32_16x16x32_bf16 v[42:45], v[238:241], v[210:213], v[42:45]
	v_mfma_f32_16x16x32_bf16 v[10:13], v[238:241], v[214:217], v[10:13]
	ds_read_b128 v[238:241], v169 offset:43008
	s_waitcnt lgkmcnt(7)
	v_mfma_f32_16x16x32_bf16 v[102:105], v[242:245], v[184:187], v[102:105]
	v_mfma_f32_16x16x32_bf16 v[70:73], v[242:245], v[198:201], v[70:73]
	v_mfma_f32_16x16x32_bf16 v[38:41], v[242:245], v[210:213], v[38:41]
	v_mfma_f32_16x16x32_bf16 v[6:9], v[242:245], v[214:217], v[6:9]
	ds_read_b128 v[242:245], v169 offset:45056
	s_waitcnt lgkmcnt(7)
	v_mfma_f32_16x16x32_bf16 v[98:101], v[246:249], v[184:187], v[98:101]
	v_mfma_f32_16x16x32_bf16 v[66:69], v[246:249], v[198:201], v[66:69]
	v_xor_b32_e32 v169, 64, v207
	v_add3_u32 v169, s2, v0, v169
	ds_read_b128 v[184:187], v169
	ds_read_b128 v[198:201], v169 offset:2048
	v_mfma_f32_16x16x32_bf16 v[34:37], v[246:249], v[210:213], v[34:37]
	ds_read_b128 v[210:213], v169 offset:4096
	v_mfma_f32_16x16x32_bf16 v[2:5], v[246:249], v[214:217], v[2:5]
	ds_read_b128 v[214:217], v169 offset:6144
	v_xor_b32_e32 v169, 64, v207
	v_add3_u32 v169, s2, v167, v169
	ds_read_b128 v[246:249], v169 offset:47104
	s_waitcnt lgkmcnt(1)
	v_mfma_f32_16x16x32_bf16 v[158:161], v[218:221], v[184:187], v[158:161]
	v_mfma_f32_16x16x32_bf16 v[94:97], v[218:221], v[198:201], v[94:97]
	v_mfma_f32_16x16x32_bf16 v[62:65], v[218:221], v[210:213], v[62:65]
	v_mfma_f32_16x16x32_bf16 v[30:33], v[218:221], v[214:217], v[30:33]
	s_waitcnt vmcnt(7)
	ds_write_b128 v171, v[118:121]
	v_mfma_f32_16x16x32_bf16 v[154:157], v[222:225], v[184:187], v[154:157]
	v_mfma_f32_16x16x32_bf16 v[90:93], v[222:225], v[198:201], v[90:93]
	global_load_dwordx4 v[118:121], v168, vcc offset:256
	v_mfma_f32_16x16x32_bf16 v[58:61], v[222:225], v[210:213], v[58:61]
	v_mfma_f32_16x16x32_bf16 v[26:29], v[222:225], v[214:217], v[26:29]
	s_waitcnt vmcnt(7)
	ds_write_b128 v171, v[110:113] offset:8192
	v_mfma_f32_16x16x32_bf16 v[150:153], v[226:229], v[184:187], v[150:153]
	v_mfma_f32_16x16x32_bf16 v[86:89], v[226:229], v[198:201], v[86:89]
	v_add_u32_e32 v110, 0x58000, v168
	global_load_dwordx4 v[110:113], v110, vcc offset:256
	v_mfma_f32_16x16x32_bf16 v[54:57], v[226:229], v[210:213], v[54:57]
	v_mfma_f32_16x16x32_bf16 v[22:25], v[226:229], v[214:217], v[22:25]
	s_waitcnt vmcnt(7)
	ds_write_b128 v171, v[114:117] offset:16384
	v_mfma_f32_16x16x32_bf16 v[146:149], v[230:233], v[184:187], v[146:149]
	v_mfma_f32_16x16x32_bf16 v[82:85], v[230:233], v[198:201], v[82:85]
	v_add_u32_e32 v114, 0xb0000, v168
	global_load_dwordx4 v[114:117], v114, vcc offset:256
	v_mfma_f32_16x16x32_bf16 v[50:53], v[230:233], v[210:213], v[50:53]
	v_mfma_f32_16x16x32_bf16 v[18:21], v[230:233], v[214:217], v[18:21]
	s_waitcnt vmcnt(7)
	ds_write_b128 v171, v[130:133] offset:24576
	v_mfma_f32_16x16x32_bf16 v[134:137], v[234:237], v[184:187], v[134:137]
	v_mfma_f32_16x16x32_bf16 v[78:81], v[234:237], v[198:201], v[78:81]
	v_add_u32_e32 v130, 0x108000, v168
	global_load_dwordx4 v[130:133], v130, vcc offset:256
	v_mfma_f32_16x16x32_bf16 v[46:49], v[234:237], v[210:213], v[46:49]
	v_mfma_f32_16x16x32_bf16 v[14:17], v[234:237], v[214:217], v[14:17]
	s_waitcnt vmcnt(7)
	ds_write_b128 v171, v[126:129] offset:32768
	v_mfma_f32_16x16x32_bf16 v[106:109], v[238:241], v[184:187], v[106:109]
	v_mfma_f32_16x16x32_bf16 v[74:77], v[238:241], v[198:201], v[74:77]
	global_load_dwordx4 v[126:129], v170, s[100:101] offset:256
	v_mfma_f32_16x16x32_bf16 v[42:45], v[238:241], v[210:213], v[42:45]
	v_mfma_f32_16x16x32_bf16 v[10:13], v[238:241], v[214:217], v[10:13]
	s_waitcnt vmcnt(7)
	ds_write_b128 v171, v[122:125] offset:40960
	v_mfma_f32_16x16x32_bf16 v[102:105], v[242:245], v[184:187], v[102:105]
	v_mfma_f32_16x16x32_bf16 v[70:73], v[242:245], v[198:201], v[70:73]
	v_add_u32_e32 v122, 0x58000, v170
	global_load_dwordx4 v[122:125], v122, s[100:101] offset:256
	v_mfma_f32_16x16x32_bf16 v[38:41], v[242:245], v[210:213], v[38:41]
	v_mfma_f32_16x16x32_bf16 v[6:9], v[242:245], v[214:217], v[6:9]
	s_waitcnt vmcnt(7)
	ds_write_b128 v171, v[142:145] offset:49152
	s_waitcnt lgkmcnt(7)
	v_mfma_f32_16x16x32_bf16 v[98:101], v[246:249], v[184:187], v[98:101]
	v_mfma_f32_16x16x32_bf16 v[66:69], v[246:249], v[198:201], v[66:69]
	v_add_u32_e32 v142, 0xb0000, v170
	global_load_dwordx4 v[142:145], v142, s[100:101] offset:256
	v_mfma_f32_16x16x32_bf16 v[34:37], v[246:249], v[210:213], v[34:37]
	v_mfma_f32_16x16x32_bf16 v[2:5], v[246:249], v[214:217], v[2:5]
	s_waitcnt vmcnt(7)
	ds_write_b128 v171, v[138:141] offset:57344
	v_add_u32_e32 v138, 0x108000, v170
	global_load_dwordx4 v[138:141], v138, s[100:101] offset:256
	v_add_u32_e32 v168, 0x80, v168
	v_add_u32_e32 v170, 0x80, v170
	s_waitcnt lgkmcnt(0)
	s_barrier
	s_cmp_eq_u32 s10, 44
	s_mov_b32 s4, s10
	s_cbranch_scc0 .LBB0_1528
	s_waitcnt vmcnt(4)
	v_add_u32_e32 v110, s7, v206
	s_waitcnt vmcnt(3)
	v_or_b32_e32 v114, v110, v205
	v_cmp_lt_i32_e32 vcc, s97, v114
	v_ashrrev_i32_e32 v112, 31, v114
	v_add_u32_e32 v116, 0xffffc000, v114
	v_ashrrev_i32_e32 v115, 11, v110
	v_cndmask_b32_e64 v113, v112, 0, vcc
	v_cndmask_b32_e32 v112, v114, v116, vcc
	v_mov_b32_e32 v116, s45
	v_mov_b32_e32 v117, s13
	v_mov_b32_e32 v118, s44
	v_mov_b32_e32 v119, s12
	v_or_b32_e32 v110, s6, v208
	s_waitcnt vmcnt(2)
	v_cndmask_b32_e64 v122, v115, 8, vcc
	v_cndmask_b32_e32 v121, v116, v117, vcc
	v_cndmask_b32_e32 v120, v118, v119, vcc
	v_lshlrev_b64 v[112:113], 12, v[112:113]
	v_ashrrev_i32_e32 v111, 31, v110
	v_lshl_add_u64 v[112:113], v[120:121], 0, v[112:113]
	v_mul_hi_i32_i24_e32 v121, 0x9000, v122
	v_mul_i32_i24_e32 v120, 0x9000, v122
	v_lshl_add_u64 v[120:121], s[14:15], 0, v[120:121]
	v_lshlrev_b64 v[110:111], 2, v[110:111]
	s_waitcnt vmcnt(0)
	v_lshl_add_u64 v[128:129], v[120:121], 0, v[110:111]
	global_load_dwordx4 v[120:123], v[128:129], off
	v_lshl_add_u64 v[112:113], v[112:113], 0, v[110:111]
	global_load_dwordx4 v[124:127], v[112:113], off
	s_waitcnt vmcnt(1)
	v_pk_mul_f32 v[120:121], v[120:121], 0.5 op_sel_hi:[1,0]
	v_pk_mul_f32 v[122:123], v[122:123], 0.5 op_sel_hi:[1,0]
	s_waitcnt vmcnt(0)
	v_pk_fma_f32 v[120:121], v[158:159], v[120:121], v[124:125]
	v_pk_fma_f32 v[122:123], v[160:161], v[122:123], v[126:127]
	global_store_dwordx4 v[112:113], v[120:123], off
	global_load_dwordx4 v[120:123], v[128:129], off offset:64
	s_nop 0
	global_load_dwordx4 v[124:127], v[112:113], off offset:64
	s_waitcnt vmcnt(1)
	v_pk_mul_f32 v[120:121], v[120:121], 0.5 op_sel_hi:[1,0]
	v_pk_mul_f32 v[122:123], v[122:123], 0.5 op_sel_hi:[1,0]
	s_waitcnt vmcnt(0)
	v_pk_fma_f32 v[120:121], v[154:155], v[120:121], v[124:125]
	v_pk_fma_f32 v[122:123], v[156:157], v[122:123], v[126:127]
	global_store_dwordx4 v[112:113], v[120:123], off offset:64
	global_load_dwordx4 v[120:123], v[128:129], off offset:128
	s_nop 0
	global_load_dwordx4 v[124:127], v[112:113], off offset:128
	s_waitcnt vmcnt(1)
	v_pk_mul_f32 v[120:121], v[120:121], 0.5 op_sel_hi:[1,0]
	v_pk_mul_f32 v[122:123], v[122:123], 0.5 op_sel_hi:[1,0]
	s_waitcnt vmcnt(0)
	v_pk_fma_f32 v[120:121], v[150:151], v[120:121], v[124:125]
	v_pk_fma_f32 v[122:123], v[152:153], v[122:123], v[126:127]
	global_store_dwordx4 v[112:113], v[120:123], off offset:128
	global_load_dwordx4 v[120:123], v[128:129], off offset:192
	s_nop 0
	global_load_dwordx4 v[124:127], v[112:113], off offset:192
	s_waitcnt vmcnt(1)
	v_pk_mul_f32 v[120:121], v[120:121], 0.5 op_sel_hi:[1,0]
	v_pk_mul_f32 v[122:123], v[122:123], 0.5 op_sel_hi:[1,0]
	s_waitcnt vmcnt(0)
	v_pk_fma_f32 v[120:121], v[146:147], v[120:121], v[124:125]
	v_pk_fma_f32 v[122:123], v[148:149], v[122:123], v[126:127]
	global_store_dwordx4 v[112:113], v[120:123], off offset:192
	global_load_dwordx4 v[120:123], v[128:129], off offset:256
	s_nop 0
	global_load_dwordx4 v[124:127], v[112:113], off offset:256
	s_waitcnt vmcnt(1)
	v_pk_mul_f32 v[120:121], v[120:121], 0.5 op_sel_hi:[1,0]
	v_pk_mul_f32 v[122:123], v[122:123], 0.5 op_sel_hi:[1,0]
	s_waitcnt vmcnt(0)
	v_pk_fma_f32 v[120:121], v[134:135], v[120:121], v[124:125]
	v_pk_fma_f32 v[122:123], v[136:137], v[122:123], v[126:127]
	global_store_dwordx4 v[112:113], v[120:123], off offset:256
	global_load_dwordx4 v[120:123], v[128:129], off offset:320
	s_nop 0
	global_load_dwordx4 v[124:127], v[112:113], off offset:320
	s_waitcnt vmcnt(1)
	v_pk_mul_f32 v[120:121], v[120:121], 0.5 op_sel_hi:[1,0]
	v_pk_mul_f32 v[122:123], v[122:123], 0.5 op_sel_hi:[1,0]
	s_waitcnt vmcnt(0)
	v_pk_fma_f32 v[106:107], v[106:107], v[120:121], v[124:125]
	v_pk_fma_f32 v[108:109], v[108:109], v[122:123], v[126:127]
	global_store_dwordx4 v[112:113], v[106:109], off offset:320
	global_load_dwordx4 v[106:109], v[128:129], off offset:384
	s_nop 0
	global_load_dwordx4 v[120:123], v[112:113], off offset:384
	s_waitcnt vmcnt(1)
	v_pk_mul_f32 v[106:107], v[106:107], 0.5 op_sel_hi:[1,0]
	v_pk_mul_f32 v[108:109], v[108:109], 0.5 op_sel_hi:[1,0]
	s_waitcnt vmcnt(0)
	v_pk_fma_f32 v[102:103], v[102:103], v[106:107], v[120:121]
	v_pk_fma_f32 v[104:105], v[104:105], v[108:109], v[122:123]
	global_store_dwordx4 v[112:113], v[102:105], off offset:384
	global_load_dwordx4 v[102:105], v[128:129], off offset:448
	s_nop 0
	global_load_dwordx4 v[106:109], v[112:113], off offset:448
	s_waitcnt vmcnt(1)
	v_pk_mul_f32 v[102:103], v[102:103], 0.5 op_sel_hi:[1,0]
	v_pk_mul_f32 v[104:105], v[104:105], 0.5 op_sel_hi:[1,0]
	s_waitcnt vmcnt(0)
	v_pk_fma_f32 v[98:99], v[98:99], v[102:103], v[106:107]
	v_pk_fma_f32 v[100:101], v[100:101], v[104:105], v[108:109]
	global_store_dwordx4 v[112:113], v[98:101], off offset:448
	s_nop 1
	v_or_b32_e32 v98, 16, v114
	v_cmp_lt_i32_e32 vcc, s97, v98
	v_add_u32_e32 v100, 0xffffc010, v114
	v_ashrrev_i32_e32 v99, 31, v98
	v_cndmask_b32_e64 v99, v99, 0, vcc
	v_cndmask_b32_e32 v98, v98, v100, vcc
	v_cndmask_b32_e64 v102, v115, 8, vcc
	v_cndmask_b32_e32 v101, v116, v117, vcc
	v_cndmask_b32_e32 v100, v118, v119, vcc
	v_lshlrev_b64 v[98:99], 12, v[98:99]
	v_lshl_add_u64 v[98:99], v[100:101], 0, v[98:99]
	v_mul_hi_i32_i24_e32 v101, 0x9000, v102
	v_mul_i32_i24_e32 v100, 0x9000, v102
	v_lshl_add_u64 v[100:101], s[14:15], 0, v[100:101]
	v_lshl_add_u64 v[108:109], v[100:101], 0, v[110:111]
	global_load_dwordx4 v[100:103], v[108:109], off
	v_lshl_add_u64 v[98:99], v[98:99], 0, v[110:111]
	global_load_dwordx4 v[104:107], v[98:99], off
	s_waitcnt vmcnt(1)
	v_pk_mul_f32 v[100:101], v[100:101], 0.5 op_sel_hi:[1,0]
	v_pk_mul_f32 v[102:103], v[102:103], 0.5 op_sel_hi:[1,0]
	s_waitcnt vmcnt(0)
	v_pk_fma_f32 v[94:95], v[94:95], v[100:101], v[104:105]
	v_pk_fma_f32 v[96:97], v[96:97], v[102:103], v[106:107]
	global_store_dwordx4 v[98:99], v[94:97], off
	global_load_dwordx4 v[94:97], v[108:109], off offset:64
	s_nop 0
	global_load_dwordx4 v[100:103], v[98:99], off offset:64
	s_waitcnt vmcnt(1)
	v_pk_mul_f32 v[94:95], v[94:95], 0.5 op_sel_hi:[1,0]
	v_pk_mul_f32 v[96:97], v[96:97], 0.5 op_sel_hi:[1,0]
	s_waitcnt vmcnt(0)
	v_pk_fma_f32 v[90:91], v[90:91], v[94:95], v[100:101]
	v_pk_fma_f32 v[92:93], v[92:93], v[96:97], v[102:103]
	global_store_dwordx4 v[98:99], v[90:93], off offset:64
	global_load_dwordx4 v[90:93], v[108:109], off offset:128
	s_nop 0
	global_load_dwordx4 v[94:97], v[98:99], off offset:128
	s_waitcnt vmcnt(1)
	v_pk_mul_f32 v[90:91], v[90:91], 0.5 op_sel_hi:[1,0]
	v_pk_mul_f32 v[92:93], v[92:93], 0.5 op_sel_hi:[1,0]
	s_waitcnt vmcnt(0)
	v_pk_fma_f32 v[86:87], v[86:87], v[90:91], v[94:95]
	v_pk_fma_f32 v[88:89], v[88:89], v[92:93], v[96:97]
	global_store_dwordx4 v[98:99], v[86:89], off offset:128
	global_load_dwordx4 v[86:89], v[108:109], off offset:192
	s_nop 0
	global_load_dwordx4 v[90:93], v[98:99], off offset:192
	s_waitcnt vmcnt(1)
	v_pk_mul_f32 v[86:87], v[86:87], 0.5 op_sel_hi:[1,0]
	v_pk_mul_f32 v[88:89], v[88:89], 0.5 op_sel_hi:[1,0]
	s_waitcnt vmcnt(0)
	v_pk_fma_f32 v[82:83], v[82:83], v[86:87], v[90:91]
	v_pk_fma_f32 v[84:85], v[84:85], v[88:89], v[92:93]
	global_store_dwordx4 v[98:99], v[82:85], off offset:192
	global_load_dwordx4 v[82:85], v[108:109], off offset:256
	s_nop 0
	global_load_dwordx4 v[86:89], v[98:99], off offset:256
	s_waitcnt vmcnt(1)
	v_pk_mul_f32 v[82:83], v[82:83], 0.5 op_sel_hi:[1,0]
	v_pk_mul_f32 v[84:85], v[84:85], 0.5 op_sel_hi:[1,0]
	s_waitcnt vmcnt(0)
	v_pk_fma_f32 v[78:79], v[78:79], v[82:83], v[86:87]
	v_pk_fma_f32 v[80:81], v[80:81], v[84:85], v[88:89]
	global_store_dwordx4 v[98:99], v[78:81], off offset:256
	global_load_dwordx4 v[78:81], v[108:109], off offset:320
	s_nop 0
	global_load_dwordx4 v[82:85], v[98:99], off offset:320
	s_waitcnt vmcnt(1)
	v_pk_mul_f32 v[78:79], v[78:79], 0.5 op_sel_hi:[1,0]
	v_pk_mul_f32 v[80:81], v[80:81], 0.5 op_sel_hi:[1,0]
	s_waitcnt vmcnt(0)
	v_pk_fma_f32 v[74:75], v[74:75], v[78:79], v[82:83]
	v_pk_fma_f32 v[76:77], v[76:77], v[80:81], v[84:85]
	global_store_dwordx4 v[98:99], v[74:77], off offset:320
	global_load_dwordx4 v[74:77], v[108:109], off offset:384
	s_nop 0
	global_load_dwordx4 v[78:81], v[98:99], off offset:384
	s_waitcnt vmcnt(1)
	v_pk_mul_f32 v[74:75], v[74:75], 0.5 op_sel_hi:[1,0]
	v_pk_mul_f32 v[76:77], v[76:77], 0.5 op_sel_hi:[1,0]
	s_waitcnt vmcnt(0)
	v_pk_fma_f32 v[70:71], v[70:71], v[74:75], v[78:79]
	v_pk_fma_f32 v[72:73], v[72:73], v[76:77], v[80:81]
	global_store_dwordx4 v[98:99], v[70:73], off offset:384
	global_load_dwordx4 v[70:73], v[108:109], off offset:448
	s_nop 0
	global_load_dwordx4 v[74:77], v[98:99], off offset:448
	s_waitcnt vmcnt(1)
	v_pk_mul_f32 v[70:71], v[70:71], 0.5 op_sel_hi:[1,0]
	v_pk_mul_f32 v[72:73], v[72:73], 0.5 op_sel_hi:[1,0]
	s_waitcnt vmcnt(0)
	v_pk_fma_f32 v[66:67], v[66:67], v[70:71], v[74:75]
	v_pk_fma_f32 v[68:69], v[68:69], v[72:73], v[76:77]
	global_store_dwordx4 v[98:99], v[66:69], off offset:448
	s_nop 1
	v_or_b32_e32 v66, 32, v114
	v_cmp_lt_i32_e32 vcc, s97, v66
	v_add_u32_e32 v68, 0xffffc020, v114
	v_ashrrev_i32_e32 v67, 31, v66
	v_cndmask_b32_e64 v67, v67, 0, vcc
	v_cndmask_b32_e32 v66, v66, v68, vcc
	v_cndmask_b32_e64 v70, v115, 8, vcc
	v_cndmask_b32_e32 v69, v116, v117, vcc
	v_cndmask_b32_e32 v68, v118, v119, vcc
	v_lshlrev_b64 v[66:67], 12, v[66:67]
	v_lshl_add_u64 v[66:67], v[68:69], 0, v[66:67]
	v_mul_hi_i32_i24_e32 v69, 0x9000, v70
	v_mul_i32_i24_e32 v68, 0x9000, v70
	v_lshl_add_u64 v[68:69], s[14:15], 0, v[68:69]
	v_lshl_add_u64 v[76:77], v[68:69], 0, v[110:111]
	global_load_dwordx4 v[68:71], v[76:77], off
	v_lshl_add_u64 v[66:67], v[66:67], 0, v[110:111]
	global_load_dwordx4 v[72:75], v[66:67], off
	s_waitcnt vmcnt(1)
	v_pk_mul_f32 v[68:69], v[68:69], 0.5 op_sel_hi:[1,0]
	v_pk_mul_f32 v[70:71], v[70:71], 0.5 op_sel_hi:[1,0]
	s_waitcnt vmcnt(0)
	v_pk_fma_f32 v[62:63], v[62:63], v[68:69], v[72:73]
	v_pk_fma_f32 v[64:65], v[64:65], v[70:71], v[74:75]
	global_store_dwordx4 v[66:67], v[62:65], off
	global_load_dwordx4 v[62:65], v[76:77], off offset:64
	s_nop 0
	global_load_dwordx4 v[68:71], v[66:67], off offset:64
	s_waitcnt vmcnt(1)
	v_pk_mul_f32 v[62:63], v[62:63], 0.5 op_sel_hi:[1,0]
	v_pk_mul_f32 v[64:65], v[64:65], 0.5 op_sel_hi:[1,0]
	s_waitcnt vmcnt(0)
	v_pk_fma_f32 v[58:59], v[58:59], v[62:63], v[68:69]
	v_pk_fma_f32 v[60:61], v[60:61], v[64:65], v[70:71]
	global_store_dwordx4 v[66:67], v[58:61], off offset:64
	global_load_dwordx4 v[58:61], v[76:77], off offset:128
	s_nop 0
	global_load_dwordx4 v[62:65], v[66:67], off offset:128
	s_waitcnt vmcnt(1)
	v_pk_mul_f32 v[58:59], v[58:59], 0.5 op_sel_hi:[1,0]
	v_pk_mul_f32 v[60:61], v[60:61], 0.5 op_sel_hi:[1,0]
	s_waitcnt vmcnt(0)
	v_pk_fma_f32 v[54:55], v[54:55], v[58:59], v[62:63]
	v_pk_fma_f32 v[56:57], v[56:57], v[60:61], v[64:65]
	global_store_dwordx4 v[66:67], v[54:57], off offset:128
	global_load_dwordx4 v[54:57], v[76:77], off offset:192
	s_nop 0
	global_load_dwordx4 v[58:61], v[66:67], off offset:192
	s_waitcnt vmcnt(1)
	v_pk_mul_f32 v[54:55], v[54:55], 0.5 op_sel_hi:[1,0]
	v_pk_mul_f32 v[56:57], v[56:57], 0.5 op_sel_hi:[1,0]
	s_waitcnt vmcnt(0)
	v_pk_fma_f32 v[50:51], v[50:51], v[54:55], v[58:59]
	v_pk_fma_f32 v[52:53], v[52:53], v[56:57], v[60:61]
	global_store_dwordx4 v[66:67], v[50:53], off offset:192
	global_load_dwordx4 v[50:53], v[76:77], off offset:256
	s_nop 0
	global_load_dwordx4 v[54:57], v[66:67], off offset:256
	s_waitcnt vmcnt(1)
	v_pk_mul_f32 v[50:51], v[50:51], 0.5 op_sel_hi:[1,0]
	v_pk_mul_f32 v[52:53], v[52:53], 0.5 op_sel_hi:[1,0]
	s_waitcnt vmcnt(0)
	v_pk_fma_f32 v[46:47], v[46:47], v[50:51], v[54:55]
	v_pk_fma_f32 v[48:49], v[48:49], v[52:53], v[56:57]
	global_store_dwordx4 v[66:67], v[46:49], off offset:256
	global_load_dwordx4 v[46:49], v[76:77], off offset:320
	s_nop 0
	global_load_dwordx4 v[50:53], v[66:67], off offset:320
	s_waitcnt vmcnt(1)
	v_pk_mul_f32 v[46:47], v[46:47], 0.5 op_sel_hi:[1,0]
	v_pk_mul_f32 v[48:49], v[48:49], 0.5 op_sel_hi:[1,0]
	s_waitcnt vmcnt(0)
	v_pk_fma_f32 v[42:43], v[42:43], v[46:47], v[50:51]
	v_pk_fma_f32 v[44:45], v[44:45], v[48:49], v[52:53]
	global_store_dwordx4 v[66:67], v[42:45], off offset:320
	global_load_dwordx4 v[42:45], v[76:77], off offset:384
	s_nop 0
	global_load_dwordx4 v[46:49], v[66:67], off offset:384
	s_waitcnt vmcnt(1)
	v_pk_mul_f32 v[42:43], v[42:43], 0.5 op_sel_hi:[1,0]
	v_pk_mul_f32 v[44:45], v[44:45], 0.5 op_sel_hi:[1,0]
	s_waitcnt vmcnt(0)
	v_pk_fma_f32 v[38:39], v[38:39], v[42:43], v[46:47]
	v_pk_fma_f32 v[40:41], v[40:41], v[44:45], v[48:49]
	global_store_dwordx4 v[66:67], v[38:41], off offset:384
	global_load_dwordx4 v[38:41], v[76:77], off offset:448
	s_nop 0
	global_load_dwordx4 v[42:45], v[66:67], off offset:448
	s_waitcnt vmcnt(1)
	v_pk_mul_f32 v[38:39], v[38:39], 0.5 op_sel_hi:[1,0]
	v_pk_mul_f32 v[40:41], v[40:41], 0.5 op_sel_hi:[1,0]
	s_waitcnt vmcnt(0)
	v_pk_fma_f32 v[34:35], v[34:35], v[38:39], v[42:43]
	v_pk_fma_f32 v[36:37], v[36:37], v[40:41], v[44:45]
	global_store_dwordx4 v[66:67], v[34:37], off offset:448
	s_nop 1
	v_or_b32_e32 v34, 48, v114
	v_cmp_lt_i32_e32 vcc, s97, v34
	v_add_u32_e32 v36, 0xffffc030, v114
	v_ashrrev_i32_e32 v35, 31, v34
	v_cndmask_b32_e64 v35, v35, 0, vcc
	v_cndmask_b32_e32 v34, v34, v36, vcc
	v_cndmask_b32_e64 v38, v115, 8, vcc
	v_cndmask_b32_e32 v37, v116, v117, vcc
	v_cndmask_b32_e32 v36, v118, v119, vcc
	v_lshlrev_b64 v[34:35], 12, v[34:35]
	v_lshl_add_u64 v[34:35], v[36:37], 0, v[34:35]
	v_mul_hi_i32_i24_e32 v37, 0x9000, v38
	v_mul_i32_i24_e32 v36, 0x9000, v38
	v_lshl_add_u64 v[36:37], s[14:15], 0, v[36:37]
	v_lshl_add_u64 v[44:45], v[36:37], 0, v[110:111]
	global_load_dwordx4 v[36:39], v[44:45], off
	v_lshl_add_u64 v[34:35], v[34:35], 0, v[110:111]
	global_load_dwordx4 v[40:43], v[34:35], off
	s_waitcnt vmcnt(1)
	v_pk_mul_f32 v[36:37], v[36:37], 0.5 op_sel_hi:[1,0]
	v_pk_mul_f32 v[38:39], v[38:39], 0.5 op_sel_hi:[1,0]
	s_waitcnt vmcnt(0)
	v_pk_fma_f32 v[30:31], v[30:31], v[36:37], v[40:41]
	v_pk_fma_f32 v[32:33], v[32:33], v[38:39], v[42:43]
	global_store_dwordx4 v[34:35], v[30:33], off
	global_load_dwordx4 v[30:33], v[44:45], off offset:64
	s_nop 0
	global_load_dwordx4 v[36:39], v[34:35], off offset:64
	s_waitcnt vmcnt(1)
	v_pk_mul_f32 v[30:31], v[30:31], 0.5 op_sel_hi:[1,0]
	v_pk_mul_f32 v[32:33], v[32:33], 0.5 op_sel_hi:[1,0]
	s_waitcnt vmcnt(0)
	v_pk_fma_f32 v[26:27], v[26:27], v[30:31], v[36:37]
	v_pk_fma_f32 v[28:29], v[28:29], v[32:33], v[38:39]
	global_store_dwordx4 v[34:35], v[26:29], off offset:64
	global_load_dwordx4 v[26:29], v[44:45], off offset:128
	s_nop 0
	global_load_dwordx4 v[30:33], v[34:35], off offset:128
	s_waitcnt vmcnt(1)
	v_pk_mul_f32 v[26:27], v[26:27], 0.5 op_sel_hi:[1,0]
	v_pk_mul_f32 v[28:29], v[28:29], 0.5 op_sel_hi:[1,0]
	s_waitcnt vmcnt(0)
	v_pk_fma_f32 v[22:23], v[22:23], v[26:27], v[30:31]
	v_pk_fma_f32 v[24:25], v[24:25], v[28:29], v[32:33]
	global_store_dwordx4 v[34:35], v[22:25], off offset:128
	global_load_dwordx4 v[22:25], v[44:45], off offset:192
	s_nop 0
	global_load_dwordx4 v[26:29], v[34:35], off offset:192
	s_waitcnt vmcnt(1)
	v_pk_mul_f32 v[22:23], v[22:23], 0.5 op_sel_hi:[1,0]
	v_pk_mul_f32 v[24:25], v[24:25], 0.5 op_sel_hi:[1,0]
	s_waitcnt vmcnt(0)
	v_pk_fma_f32 v[18:19], v[18:19], v[22:23], v[26:27]
	v_pk_fma_f32 v[20:21], v[20:21], v[24:25], v[28:29]
	global_store_dwordx4 v[34:35], v[18:21], off offset:192
	global_load_dwordx4 v[18:21], v[44:45], off offset:256
	s_nop 0
	global_load_dwordx4 v[22:25], v[34:35], off offset:256
	s_waitcnt vmcnt(1)
	v_pk_mul_f32 v[18:19], v[18:19], 0.5 op_sel_hi:[1,0]
	v_pk_mul_f32 v[20:21], v[20:21], 0.5 op_sel_hi:[1,0]
	s_waitcnt vmcnt(0)
	v_pk_fma_f32 v[14:15], v[14:15], v[18:19], v[22:23]
	v_pk_fma_f32 v[16:17], v[16:17], v[20:21], v[24:25]
	global_store_dwordx4 v[34:35], v[14:17], off offset:256
	global_load_dwordx4 v[14:17], v[44:45], off offset:320
	s_nop 0
	global_load_dwordx4 v[18:21], v[34:35], off offset:320
	s_waitcnt vmcnt(1)
	v_pk_mul_f32 v[14:15], v[14:15], 0.5 op_sel_hi:[1,0]
	v_pk_mul_f32 v[16:17], v[16:17], 0.5 op_sel_hi:[1,0]
	s_waitcnt vmcnt(0)
	v_pk_fma_f32 v[10:11], v[10:11], v[14:15], v[18:19]
	v_pk_fma_f32 v[12:13], v[12:13], v[16:17], v[20:21]
	global_store_dwordx4 v[34:35], v[10:13], off offset:320
	global_load_dwordx4 v[10:13], v[44:45], off offset:384
	s_nop 0
	global_load_dwordx4 v[14:17], v[34:35], off offset:384
	s_waitcnt vmcnt(1)
	v_pk_mul_f32 v[10:11], v[10:11], 0.5 op_sel_hi:[1,0]
	v_pk_mul_f32 v[12:13], v[12:13], 0.5 op_sel_hi:[1,0]
	s_waitcnt vmcnt(0)
	v_pk_fma_f32 v[6:7], v[6:7], v[10:11], v[14:15]
	v_pk_fma_f32 v[8:9], v[8:9], v[12:13], v[16:17]
	global_store_dwordx4 v[34:35], v[6:9], off offset:384
	global_load_dwordx4 v[6:9], v[44:45], off offset:448
	s_nop 0
	global_load_dwordx4 v[10:13], v[34:35], off offset:448
	s_waitcnt vmcnt(1)
	v_pk_mul_f32 v[6:7], v[6:7], 0.5 op_sel_hi:[1,0]
	v_pk_mul_f32 v[8:9], v[8:9], 0.5 op_sel_hi:[1,0]
	s_waitcnt vmcnt(0)
	v_pk_fma_f32 v[2:3], v[2:3], v[6:7], v[10:11]
	v_pk_fma_f32 v[4:5], v[4:5], v[8:9], v[12:13]
	global_store_dwordx4 v[34:35], v[2:5], off offset:448
	s_add_i32 s18, s18, s11
	s_cmpk_gt_i32 s18, 0xff
	s_cbranch_scc0 .LBB0_1527
	s_setprio 0
